# GEMM epilogue output stores tagged nt (non-temporal) so streamed outputs do not displace the operand panels in L2
# baseline (speedup 1.0000x reference)
.LBB0_130:
	s_and_b32 s1, s14, 0xfffffc
	s_sub_i32 s1, s48, s1
	s_lshl_b32 s1, s1, 8
	s_add_u32 s5, s10, s52
	s_addc_u32 s14, s11, s53
	s_and_b64 s[50:51], exec, s[50:51]
	s_cselect_b32 s14, s9, s14
	s_cselect_b32 s5, s8, s5
	s_or_b32 s50, s1, s67
	s_ashr_i32 s51, s50, 31
	s_lshl_b64 s[50:51], s[50:51], 1
	s_add_u32 s50, s5, s50
	v_cmp_gt_i32_e32 vcc, 8, v190
	s_addc_u32 s51, s14, s51
	v_mov_b32_e32 v139, v137
	v_cndmask_b32_e64 v138, 64, 0, vcc
	v_lshlrev_b32_e32 v140, 3, v142
	v_lshl_add_u64 v[138:139], s[50:51], 0, v[138:139]
	v_ashrrev_i32_e32 v141, 31, v140
	v_lshl_add_u64 v[144:145], v[140:141], 1, v[138:139]
	v_pk_mul_f32 v[138:139], v[116:117], s[4:5] op_sel_hi:[1,0]
	v_pk_mul_f32 v[154:155], v[106:107], s[4:5] op_sel_hi:[1,0]
	v_pk_mul_f32 v[140:141], v[114:115], s[4:5] op_sel_hi:[1,0]
	v_pk_mul_f32 v[152:153], v[108:109], s[4:5] op_sel_hi:[1,0]
	v_cvt_pk_bf16_f32 v135, v138, v139
	v_cvt_pk_bf16_f32 v143, v154, v155
	v_pk_mul_f32 v[138:139], v[52:53], s[4:5] op_sel_hi:[1,0]
	v_pk_mul_f32 v[154:155], v[42:43], s[4:5] op_sel_hi:[1,0]
	v_cvt_pk_bf16_f32 v133, v140, v141
	v_cvt_pk_bf16_f32 v156, v152, v153
	v_pk_mul_f32 v[140:141], v[50:51], s[4:5] op_sel_hi:[1,0]
	v_pk_mul_f32 v[152:153], v[44:45], s[4:5] op_sel_hi:[1,0]
	v_cvt_pk_bf16_f32 v138, v138, v139
	v_cvt_pk_bf16_f32 v139, v154, v155
	v_cvt_pk_bf16_f32 v140, v140, v141
	v_cvt_pk_bf16_f32 v141, v152, v153
	v_cndmask_b32_e32 v153, v135, v138, vcc
	v_cndmask_b32_e32 v154, v143, v139, vcc
	v_and_or_b32 v131, v190, 7, s41
	v_cndmask_b32_e32 v152, v156, v141, vcc
	v_cndmask_b32_e32 v155, v133, v140, vcc
	v_mov_b32_dpp v157, v153 row_ror:8 row_mask:0xf bank_mask:0xf bound_ctrl:1
	v_mov_b32_dpp v158, v154 row_ror:8 row_mask:0xf bank_mask:0xf bound_ctrl:1
	v_mov_b32_dpp v160, v155 row_ror:8 row_mask:0xf bank_mask:0xf bound_ctrl:1
	v_mov_b32_dpp v159, v152 row_ror:8 row_mask:0xf bank_mask:0xf bound_ctrl:1
	v_cndmask_b32_e32 v153, v157, v135, vcc
	v_cndmask_b32_e32 v154, v158, v143, vcc
	v_cndmask_b32_e32 v157, v138, v157, vcc
	v_cndmask_b32_e32 v158, v139, v158, vcc
	v_mad_i64_i32 v[138:139], s[50:51], s0, v131, 0
	s_lshl_b32 s14, s0, 4
	v_cndmask_b32_e32 v155, v159, v156, vcc
	v_cndmask_b32_e32 v152, v160, v133, vcc
	v_lshl_add_u64 v[138:139], v[138:139], 1, v[144:145]
	v_cndmask_b32_e32 v159, v141, v159, vcc
	v_cndmask_b32_e32 v156, v140, v160, vcc
	global_store_dwordx4 v[138:139], v[152:155], off nt
	v_lshl_add_u64 v[138:139], v[138:139], 0, s[14:15]
	v_pk_mul_f32 v[140:141], v[102:103], s[4:5] op_sel_hi:[1,0]
	global_store_dwordx4 v[138:139], v[156:159], off nt
	v_pk_mul_f32 v[138:139], v[104:105], s[4:5] op_sel_hi:[1,0]
	v_pk_mul_f32 v[152:153], v[96:97], s[4:5] op_sel_hi:[1,0]
	v_pk_mul_f32 v[154:155], v[94:95], s[4:5] op_sel_hi:[1,0]
	v_cvt_pk_bf16_f32 v133, v140, v141
	v_pk_mul_f32 v[140:141], v[38:39], s[4:5] op_sel_hi:[1,0]
	v_cvt_pk_bf16_f32 v135, v138, v139
	v_cvt_pk_bf16_f32 v143, v154, v155
	v_cvt_pk_bf16_f32 v156, v152, v153
	v_pk_mul_f32 v[138:139], v[40:41], s[4:5] op_sel_hi:[1,0]
	v_pk_mul_f32 v[152:153], v[32:33], s[4:5] op_sel_hi:[1,0]
	v_pk_mul_f32 v[154:155], v[30:31], s[4:5] op_sel_hi:[1,0]
	v_cvt_pk_bf16_f32 v140, v140, v141
	v_cvt_pk_bf16_f32 v138, v138, v139
	v_cvt_pk_bf16_f32 v139, v154, v155
	v_cvt_pk_bf16_f32 v141, v152, v153
	v_cndmask_b32_e32 v155, v133, v140, vcc
	v_cndmask_b32_e32 v152, v156, v141, vcc
	v_cndmask_b32_e32 v153, v135, v138, vcc
	v_cndmask_b32_e32 v154, v143, v139, vcc
	v_mov_b32_dpp v160, v155 row_ror:8 row_mask:0xf bank_mask:0xf bound_ctrl:1
	v_mov_b32_dpp v157, v153 row_ror:8 row_mask:0xf bank_mask:0xf bound_ctrl:1
	v_mov_b32_dpp v158, v154 row_ror:8 row_mask:0xf bank_mask:0xf bound_ctrl:1
	v_mov_b32_dpp v159, v152 row_ror:8 row_mask:0xf bank_mask:0xf bound_ctrl:1
	v_cndmask_b32_e32 v152, v160, v133, vcc
	v_or_b32_e32 v133, 16, v131
	v_cndmask_b32_e32 v153, v157, v135, vcc
	v_cndmask_b32_e32 v154, v158, v143, vcc
	v_cndmask_b32_e32 v157, v138, v157, vcc
	v_cndmask_b32_e32 v158, v139, v158, vcc
	v_mad_i64_i32 v[138:139], s[50:51], s0, v133, 0
	v_cndmask_b32_e32 v155, v159, v156, vcc
	v_lshl_add_u64 v[138:139], v[138:139], 1, v[144:145]
	v_cndmask_b32_e32 v159, v141, v159, vcc
	v_cndmask_b32_e32 v156, v140, v160, vcc
	global_store_dwordx4 v[138:139], v[152:155], off nt
	v_lshl_add_u64 v[138:139], v[138:139], 0, s[14:15]
	v_pk_mul_f32 v[140:141], v[82:83], s[4:5] op_sel_hi:[1,0]
	global_store_dwordx4 v[138:139], v[156:159], off nt
	v_pk_mul_f32 v[138:139], v[84:85], s[4:5] op_sel_hi:[1,0]
	v_pk_mul_f32 v[152:153], v[76:77], s[4:5] op_sel_hi:[1,0]
	v_pk_mul_f32 v[154:155], v[74:75], s[4:5] op_sel_hi:[1,0]
	v_cvt_pk_bf16_f32 v133, v140, v141
	v_pk_mul_f32 v[140:141], v[18:19], s[4:5] op_sel_hi:[1,0]
	v_cvt_pk_bf16_f32 v135, v138, v139
	v_cvt_pk_bf16_f32 v143, v154, v155
	v_cvt_pk_bf16_f32 v156, v152, v153
	v_pk_mul_f32 v[138:139], v[20:21], s[4:5] op_sel_hi:[1,0]
	v_pk_mul_f32 v[152:153], v[16:17], s[4:5] op_sel_hi:[1,0]
	v_pk_mul_f32 v[154:155], v[14:15], s[4:5] op_sel_hi:[1,0]
	v_cvt_pk_bf16_f32 v140, v140, v141
	v_cvt_pk_bf16_f32 v138, v138, v139
	v_cvt_pk_bf16_f32 v139, v154, v155
	v_cvt_pk_bf16_f32 v141, v152, v153
	v_cndmask_b32_e32 v155, v133, v140, vcc
	v_cndmask_b32_e32 v152, v156, v141, vcc
	v_cndmask_b32_e32 v153, v135, v138, vcc
	v_cndmask_b32_e32 v154, v143, v139, vcc
	v_mov_b32_dpp v160, v155 row_ror:8 row_mask:0xf bank_mask:0xf bound_ctrl:1
	v_mov_b32_dpp v157, v153 row_ror:8 row_mask:0xf bank_mask:0xf bound_ctrl:1
	v_mov_b32_dpp v158, v154 row_ror:8 row_mask:0xf bank_mask:0xf bound_ctrl:1
	v_mov_b32_dpp v159, v152 row_ror:8 row_mask:0xf bank_mask:0xf bound_ctrl:1
	v_cndmask_b32_e32 v152, v160, v133, vcc
	v_or_b32_e32 v133, 32, v131
	v_cndmask_b32_e32 v153, v157, v135, vcc
	v_cndmask_b32_e32 v154, v158, v143, vcc
	v_cndmask_b32_e32 v157, v138, v157, vcc
	v_cndmask_b32_e32 v158, v139, v158, vcc
	v_mad_i64_i32 v[138:139], s[50:51], s0, v133, 0
	v_cndmask_b32_e32 v155, v159, v156, vcc
	v_lshl_add_u64 v[138:139], v[138:139], 1, v[144:145]
	v_cndmask_b32_e32 v159, v141, v159, vcc
	v_cndmask_b32_e32 v156, v140, v160, vcc
	global_store_dwordx4 v[138:139], v[152:155], off nt
	v_lshl_add_u64 v[138:139], v[138:139], 0, s[14:15]
	v_pk_mul_f32 v[140:141], v[70:71], s[4:5] op_sel_hi:[1,0]
	global_store_dwordx4 v[138:139], v[156:159], off nt
	v_pk_mul_f32 v[138:139], v[72:73], s[4:5] op_sel_hi:[1,0]
	v_pk_mul_f32 v[152:153], v[68:69], s[4:5] op_sel_hi:[1,0]
	v_pk_mul_f32 v[154:155], v[66:67], s[4:5] op_sel_hi:[1,0]
	v_cvt_pk_bf16_f32 v133, v140, v141
	v_pk_mul_f32 v[140:141], v[6:7], s[4:5] op_sel_hi:[1,0]
	v_cvt_pk_bf16_f32 v135, v138, v139
	v_cvt_pk_bf16_f32 v143, v154, v155
	v_cvt_pk_bf16_f32 v156, v152, v153
	v_pk_mul_f32 v[138:139], v[8:9], s[4:5] op_sel_hi:[1,0]
	v_pk_mul_f32 v[152:153], v[4:5], s[4:5] op_sel_hi:[1,0]
	v_pk_mul_f32 v[154:155], v[2:3], s[4:5] op_sel_hi:[1,0]
	v_cvt_pk_bf16_f32 v140, v140, v141
	v_cvt_pk_bf16_f32 v138, v138, v139
	v_cvt_pk_bf16_f32 v139, v154, v155
	v_cvt_pk_bf16_f32 v141, v152, v153
	v_cndmask_b32_e32 v155, v133, v140, vcc
	v_cndmask_b32_e32 v152, v156, v141, vcc
	v_cndmask_b32_e32 v153, v135, v138, vcc
	v_cndmask_b32_e32 v154, v143, v139, vcc
	v_mov_b32_dpp v160, v155 row_ror:8 row_mask:0xf bank_mask:0xf bound_ctrl:1
	v_mov_b32_dpp v157, v153 row_ror:8 row_mask:0xf bank_mask:0xf bound_ctrl:1
	v_mov_b32_dpp v158, v154 row_ror:8 row_mask:0xf bank_mask:0xf bound_ctrl:1
	v_mov_b32_dpp v159, v152 row_ror:8 row_mask:0xf bank_mask:0xf bound_ctrl:1
	v_cndmask_b32_e32 v152, v160, v133, vcc
	v_or_b32_e32 v133, 48, v131
	v_cndmask_b32_e32 v153, v157, v135, vcc
	v_cndmask_b32_e32 v154, v158, v143, vcc
	v_cndmask_b32_e32 v157, v138, v157, vcc
	v_cndmask_b32_e32 v158, v139, v158, vcc
	v_mad_i64_i32 v[138:139], s[50:51], s0, v133, 0
	v_cndmask_b32_e32 v155, v159, v156, vcc
	v_lshl_add_u64 v[138:139], v[138:139], 1, v[144:145]
	v_cndmask_b32_e32 v159, v141, v159, vcc
	v_cndmask_b32_e32 v156, v140, v160, vcc
	global_store_dwordx4 v[138:139], v[152:155], off nt
	v_lshl_add_u64 v[138:139], v[138:139], 0, s[14:15]
	global_store_dwordx4 v[138:139], v[156:159], off nt
	v_pk_mul_f32 v[138:139], v[128:129], s[4:5] op_sel_hi:[1,0]
	v_pk_mul_f32 v[140:141], v[126:127], s[4:5] op_sel_hi:[1,0]
	v_pk_mul_f32 v[152:153], v[124:125], s[4:5] op_sel_hi:[1,0]
	v_pk_mul_f32 v[154:155], v[122:123], s[4:5] op_sel_hi:[1,0]
	v_cvt_pk_bf16_f32 v135, v140, v141
	v_cvt_pk_bf16_f32 v143, v138, v139
	v_cvt_pk_bf16_f32 v156, v154, v155
	v_cvt_pk_bf16_f32 v157, v152, v153
	v_pk_mul_f32 v[138:139], v[64:65], s[4:5] op_sel_hi:[1,0]
	v_pk_mul_f32 v[140:141], v[62:63], s[4:5] op_sel_hi:[1,0]
	v_pk_mul_f32 v[152:153], v[60:61], s[4:5] op_sel_hi:[1,0]
	v_pk_mul_f32 v[154:155], v[58:59], s[4:5] op_sel_hi:[1,0]
	v_cvt_pk_bf16_f32 v140, v140, v141
	v_cvt_pk_bf16_f32 v138, v138, v139
	v_cvt_pk_bf16_f32 v139, v154, v155
	v_cvt_pk_bf16_f32 v141, v152, v153
	v_cndmask_b32_e32 v152, v157, v141, vcc
	v_cndmask_b32_e32 v153, v143, v138, vcc
	v_cndmask_b32_e32 v154, v156, v139, vcc
	v_add_u32_e32 v133, 0x80, v131
	v_cndmask_b32_e32 v155, v135, v140, vcc
	v_mov_b32_dpp v158, v153 row_ror:8 row_mask:0xf bank_mask:0xf bound_ctrl:1
	v_mov_b32_dpp v161, v154 row_ror:8 row_mask:0xf bank_mask:0xf bound_ctrl:1
	v_mov_b32_dpp v159, v152 row_ror:8 row_mask:0xf bank_mask:0xf bound_ctrl:1
	v_mov_b32_dpp v160, v155 row_ror:8 row_mask:0xf bank_mask:0xf bound_ctrl:1
	v_cndmask_b32_e32 v155, v159, v157, vcc
	v_cndmask_b32_e32 v153, v158, v143, vcc
	v_cndmask_b32_e32 v157, v138, v158, vcc
	v_cndmask_b32_e32 v158, v139, v161, vcc
	v_mad_i64_i32 v[138:139], s[50:51], s0, v133, 0
	v_cndmask_b32_e32 v154, v161, v156, vcc
	v_cndmask_b32_e32 v152, v160, v135, vcc
	v_lshl_add_u64 v[138:139], v[138:139], 1, v[144:145]
	v_cndmask_b32_e32 v159, v141, v159, vcc
	v_cndmask_b32_e32 v156, v140, v160, vcc
	global_store_dwordx4 v[138:139], v[152:155], off nt
	v_lshl_add_u64 v[138:139], v[138:139], 0, s[14:15]
	v_pk_mul_f32 v[140:141], v[118:119], s[4:5] op_sel_hi:[1,0]
	global_store_dwordx4 v[138:139], v[156:159], off nt
	v_pk_mul_f32 v[138:139], v[120:121], s[4:5] op_sel_hi:[1,0]
	v_pk_mul_f32 v[152:153], v[112:113], s[4:5] op_sel_hi:[1,0]
	v_pk_mul_f32 v[154:155], v[110:111], s[4:5] op_sel_hi:[1,0]
	v_cvt_pk_bf16_f32 v133, v140, v141
	v_pk_mul_f32 v[140:141], v[54:55], s[4:5] op_sel_hi:[1,0]
	v_cvt_pk_bf16_f32 v135, v138, v139
	v_cvt_pk_bf16_f32 v143, v154, v155
	v_cvt_pk_bf16_f32 v156, v152, v153
	v_pk_mul_f32 v[138:139], v[56:57], s[4:5] op_sel_hi:[1,0]
	v_pk_mul_f32 v[152:153], v[48:49], s[4:5] op_sel_hi:[1,0]
	v_pk_mul_f32 v[154:155], v[46:47], s[4:5] op_sel_hi:[1,0]
	v_cvt_pk_bf16_f32 v140, v140, v141
	v_cvt_pk_bf16_f32 v138, v138, v139
	v_cvt_pk_bf16_f32 v139, v154, v155
	v_cvt_pk_bf16_f32 v141, v152, v153
	v_cndmask_b32_e32 v155, v133, v140, vcc
	v_cndmask_b32_e32 v152, v156, v141, vcc
	v_cndmask_b32_e32 v153, v135, v138, vcc
	v_cndmask_b32_e32 v154, v143, v139, vcc
	v_mov_b32_dpp v160, v155 row_ror:8 row_mask:0xf bank_mask:0xf bound_ctrl:1
	v_mov_b32_dpp v157, v153 row_ror:8 row_mask:0xf bank_mask:0xf bound_ctrl:1
	v_mov_b32_dpp v158, v154 row_ror:8 row_mask:0xf bank_mask:0xf bound_ctrl:1
	v_mov_b32_dpp v159, v152 row_ror:8 row_mask:0xf bank_mask:0xf bound_ctrl:1
	v_cndmask_b32_e32 v152, v160, v133, vcc
	v_add_u32_e32 v133, 0x90, v131
	v_cndmask_b32_e32 v153, v157, v135, vcc
	v_cndmask_b32_e32 v154, v158, v143, vcc
	v_cndmask_b32_e32 v157, v138, v157, vcc
	v_cndmask_b32_e32 v158, v139, v158, vcc
	v_mad_i64_i32 v[138:139], s[50:51], s0, v133, 0
	v_cndmask_b32_e32 v155, v159, v156, vcc
	v_lshl_add_u64 v[138:139], v[138:139], 1, v[144:145]
	v_cndmask_b32_e32 v159, v141, v159, vcc
	v_cndmask_b32_e32 v156, v140, v160, vcc
	global_store_dwordx4 v[138:139], v[152:155], off nt
	v_lshl_add_u64 v[138:139], v[138:139], 0, s[14:15]
	v_pk_mul_f32 v[140:141], v[98:99], s[4:5] op_sel_hi:[1,0]
	global_store_dwordx4 v[138:139], v[156:159], off nt
	v_pk_mul_f32 v[138:139], v[100:101], s[4:5] op_sel_hi:[1,0]
	v_pk_mul_f32 v[152:153], v[92:93], s[4:5] op_sel_hi:[1,0]
	v_pk_mul_f32 v[154:155], v[90:91], s[4:5] op_sel_hi:[1,0]
	v_cvt_pk_bf16_f32 v133, v140, v141
	v_pk_mul_f32 v[140:141], v[34:35], s[4:5] op_sel_hi:[1,0]
	v_cvt_pk_bf16_f32 v135, v138, v139
	v_cvt_pk_bf16_f32 v143, v154, v155
	v_cvt_pk_bf16_f32 v156, v152, v153
	v_pk_mul_f32 v[138:139], v[36:37], s[4:5] op_sel_hi:[1,0]
	v_pk_mul_f32 v[152:153], v[28:29], s[4:5] op_sel_hi:[1,0]
	v_pk_mul_f32 v[154:155], v[26:27], s[4:5] op_sel_hi:[1,0]
	v_cvt_pk_bf16_f32 v140, v140, v141
	v_cvt_pk_bf16_f32 v138, v138, v139
	v_cvt_pk_bf16_f32 v139, v154, v155
	v_cvt_pk_bf16_f32 v141, v152, v153
	v_cndmask_b32_e32 v155, v133, v140, vcc
	v_cndmask_b32_e32 v152, v156, v141, vcc
	v_cndmask_b32_e32 v153, v135, v138, vcc
	v_cndmask_b32_e32 v154, v143, v139, vcc
	v_mov_b32_dpp v160, v155 row_ror:8 row_mask:0xf bank_mask:0xf bound_ctrl:1
	v_mov_b32_dpp v157, v153 row_ror:8 row_mask:0xf bank_mask:0xf bound_ctrl:1
	v_mov_b32_dpp v158, v154 row_ror:8 row_mask:0xf bank_mask:0xf bound_ctrl:1
	v_mov_b32_dpp v159, v152 row_ror:8 row_mask:0xf bank_mask:0xf bound_ctrl:1
	v_cndmask_b32_e32 v152, v160, v133, vcc
	v_add_u32_e32 v133, 0xa0, v131
	v_cndmask_b32_e32 v153, v157, v135, vcc
	v_cndmask_b32_e32 v154, v158, v143, vcc
	v_cndmask_b32_e32 v157, v138, v157, vcc
	v_cndmask_b32_e32 v158, v139, v158, vcc
	v_mad_i64_i32 v[138:139], s[50:51], s0, v133, 0
	v_cndmask_b32_e32 v155, v159, v156, vcc
	v_lshl_add_u64 v[138:139], v[138:139], 1, v[144:145]
	v_cndmask_b32_e32 v159, v141, v159, vcc
	v_cndmask_b32_e32 v156, v140, v160, vcc
	global_store_dwordx4 v[138:139], v[152:155], off nt
	v_lshl_add_u64 v[138:139], v[138:139], 0, s[14:15]
	global_store_dwordx4 v[138:139], v[156:159], off nt
	v_pk_mul_f32 v[138:139], v[88:89], s[4:5] op_sel_hi:[1,0]
	v_pk_mul_f32 v[154:155], v[78:79], s[4:5] op_sel_hi:[1,0]
	v_pk_mul_f32 v[140:141], v[86:87], s[4:5] op_sel_hi:[1,0]
	v_pk_mul_f32 v[152:153], v[80:81], s[4:5] op_sel_hi:[1,0]
	v_cvt_pk_bf16_f32 v135, v138, v139
	v_cvt_pk_bf16_f32 v143, v154, v155
	v_pk_mul_f32 v[138:139], v[24:25], s[4:5] op_sel_hi:[1,0]
	v_pk_mul_f32 v[154:155], v[10:11], s[4:5] op_sel_hi:[1,0]
	v_cvt_pk_bf16_f32 v133, v140, v141
	v_cvt_pk_bf16_f32 v156, v152, v153
	v_pk_mul_f32 v[140:141], v[22:23], s[4:5] op_sel_hi:[1,0]
	v_pk_mul_f32 v[152:153], v[12:13], s[4:5] op_sel_hi:[1,0]
	v_cvt_pk_bf16_f32 v138, v138, v139
	v_cvt_pk_bf16_f32 v139, v154, v155
	v_cvt_pk_bf16_f32 v140, v140, v141
	v_cvt_pk_bf16_f32 v141, v152, v153
	v_cndmask_b32_e32 v153, v135, v138, vcc
	v_cndmask_b32_e32 v154, v143, v139, vcc
	v_cndmask_b32_e32 v152, v156, v141, vcc
	v_cndmask_b32_e32 v155, v133, v140, vcc
	v_mov_b32_dpp v157, v153 row_ror:8 row_mask:0xf bank_mask:0xf bound_ctrl:1
	v_mov_b32_dpp v158, v154 row_ror:8 row_mask:0xf bank_mask:0xf bound_ctrl:1
	v_add_u32_e32 v131, 0xb0, v131
	v_mov_b32_dpp v160, v155 row_ror:8 row_mask:0xf bank_mask:0xf bound_ctrl:1
	v_mov_b32_dpp v159, v152 row_ror:8 row_mask:0xf bank_mask:0xf bound_ctrl:1
	v_cndmask_b32_e32 v153, v157, v135, vcc
	v_cndmask_b32_e32 v154, v158, v143, vcc
	v_cndmask_b32_e32 v157, v138, v157, vcc
	v_cndmask_b32_e32 v158, v139, v158, vcc
	v_mad_i64_i32 v[138:139], s[0:1], s0, v131, 0
	v_cndmask_b32_e32 v155, v159, v156, vcc
	v_cndmask_b32_e32 v152, v160, v133, vcc
	v_lshl_add_u64 v[138:139], v[138:139], 1, v[144:145]
	v_cndmask_b32_e32 v159, v141, v159, vcc
	v_cndmask_b32_e32 v156, v140, v160, vcc
	global_store_dwordx4 v[138:139], v[152:155], off nt
	v_lshl_add_u64 v[138:139], v[138:139], 0, s[14:15]
	s_mov_b64 s[0:1], 0
	global_store_dwordx4 v[138:139], v[156:159], off nt
.LBB0_131:
	s_and_b64 vcc, exec, s[0:1]
	s_cbranch_vccz .LBB0_286
	s_cmp_eq_u32 s7, 1
	s_cselect_b64 s[0:1], -1, 0
	s_and_b64 s[4:5], s[0:1], exec
	s_mov_b32 s0, 0x17a00000
	s_cselect_b32 s0, s0, 0x1bb00000
	s_add_u32 s0, s10, s0
	s_addc_u32 s1, s11, 0
	s_lshl_b32 s43, s48, 1
	s_and_b32 s43, s43, 6
	s_ashr_i32 s6, s6, 1
	s_or_b32 s43, s43, s68
	s_and_b32 s6, s6, -8
	s_and_b32 s41, s41, 0xfc0
	s_or_b32 s43, s43, s6
	s_add_i32 s14, s41, 64
	s_mul_i32 s48, s43, 0x104000
	s_mul_hi_i32 s6, s43, 0x104000
	s_add_u32 s0, s0, s48
	s_addc_u32 s1, s1, s6
	s_cmp_eq_u32 s7, 2
	s_mov_b64 s[6:7], -1
	v_cvt_pk_bf16_f32 v208, v114, v115
	v_cvt_pk_bf16_f32 v209, v116, v117
	v_cvt_pk_bf16_f32 v210, v106, v107
	v_cvt_pk_bf16_f32 v211, v108, v109
	v_cvt_pk_bf16_f32 v204, v50, v51
	v_cvt_pk_bf16_f32 v205, v52, v53
	v_cvt_pk_bf16_f32 v206, v42, v43
	v_cvt_pk_bf16_f32 v207, v44, v45
	v_cvt_pk_bf16_f32 v200, v102, v103
	v_cvt_pk_bf16_f32 v201, v104, v105
	v_cvt_pk_bf16_f32 v202, v94, v95
	v_cvt_pk_bf16_f32 v203, v96, v97
	v_cvt_pk_bf16_f32 v196, v38, v39
	v_cvt_pk_bf16_f32 v197, v40, v41
	v_cvt_pk_bf16_f32 v198, v30, v31
	v_cvt_pk_bf16_f32 v199, v32, v33
	v_cvt_pk_bf16_f32 v192, v82, v83
	v_cvt_pk_bf16_f32 v193, v84, v85
	v_cvt_pk_bf16_f32 v194, v74, v75
	v_cvt_pk_bf16_f32 v195, v76, v77
	v_cvt_pk_bf16_f32 v187, v18, v19
	v_cvt_pk_bf16_f32 v188, v20, v21
	v_cvt_pk_bf16_f32 v189, v14, v15
	v_cvt_pk_bf16_f32 v191, v16, v17
	v_cvt_pk_bf16_f32 v183, v70, v71
	v_cvt_pk_bf16_f32 v184, v72, v73
	v_cvt_pk_bf16_f32 v185, v66, v67
	v_cvt_pk_bf16_f32 v186, v68, v69
	v_cvt_pk_bf16_f32 v179, v6, v7
	v_cvt_pk_bf16_f32 v180, v8, v9
	v_cvt_pk_bf16_f32 v181, v2, v3
	v_cvt_pk_bf16_f32 v182, v4, v5
	v_cvt_pk_bf16_f32 v175, v126, v127
	v_cvt_pk_bf16_f32 v176, v128, v129
	v_cvt_pk_bf16_f32 v177, v122, v123
	v_cvt_pk_bf16_f32 v178, v124, v125
	v_cvt_pk_bf16_f32 v171, v62, v63
	v_cvt_pk_bf16_f32 v172, v64, v65
	v_cvt_pk_bf16_f32 v173, v58, v59
	v_cvt_pk_bf16_f32 v174, v60, v61
	v_cvt_pk_bf16_f32 v167, v118, v119
	v_cvt_pk_bf16_f32 v168, v120, v121
	v_cvt_pk_bf16_f32 v169, v110, v111
	v_cvt_pk_bf16_f32 v170, v112, v113
	v_cvt_pk_bf16_f32 v163, v54, v55
	v_cvt_pk_bf16_f32 v164, v56, v57
	v_cvt_pk_bf16_f32 v165, v46, v47
	v_cvt_pk_bf16_f32 v166, v48, v49
	v_cvt_pk_bf16_f32 v159, v98, v99
	v_cvt_pk_bf16_f32 v160, v100, v101
	v_cvt_pk_bf16_f32 v161, v90, v91
	v_cvt_pk_bf16_f32 v162, v92, v93
	v_cvt_pk_bf16_f32 v155, v34, v35
	v_cvt_pk_bf16_f32 v156, v36, v37
	v_cvt_pk_bf16_f32 v157, v26, v27
	v_cvt_pk_bf16_f32 v158, v28, v29
	v_cvt_pk_bf16_f32 v145, v86, v87
	v_cvt_pk_bf16_f32 v152, v88, v89
	v_cvt_pk_bf16_f32 v153, v78, v79
	v_cvt_pk_bf16_f32 v154, v80, v81
	v_cvt_pk_bf16_f32 v131, v22, v23
	v_cvt_pk_bf16_f32 v133, v24, v25
	v_cvt_pk_bf16_f32 v135, v10, v11
	v_cvt_pk_bf16_f32 v144, v12, v13
	s_cbranch_scc1 .LBB0_140
	s_lshl_b32 s6, s69, 1
	s_add_u32 s6, s0, s6
	v_cmp_gt_i32_e32 vcc, 8, v190
	s_addc_u32 s7, s1, 0
	v_mov_b32_e32 v139, v137
	v_cndmask_b32_e64 v138, 64, 0, vcc
	v_lshlrev_b32_e32 v140, 3, v142
	v_lshl_add_u64 v[138:139], s[6:7], 0, v[138:139]
	v_ashrrev_i32_e32 v141, 31, v140
	v_lshl_add_u64 v[138:139], v[140:141], 1, v[138:139]
	v_cndmask_b32_e32 v140, v211, v207, vcc
	v_cndmask_b32_e32 v141, v210, v206, vcc
	v_and_or_b32 v143, v190, 7, s14
	v_mov_b32_dpp v140, v140 row_ror:8 row_mask:0xf bank_mask:0xf bound_ctrl:1
	v_mov_b32_dpp v141, v141 row_ror:8 row_mask:0xf bank_mask:0xf bound_ctrl:1
	v_cndmask_b32_e32 v212, v209, v205, vcc
	v_cndmask_b32_e32 v213, v208, v204, vcc
	v_cndmask_b32_e32 v215, v140, v211, vcc
	v_cndmask_b32_e32 v214, v141, v210, vcc
	v_cndmask_b32_e32 v219, v207, v140, vcc
	v_cndmask_b32_e32 v218, v206, v141, vcc
	v_lshlrev_b32_e32 v140, 8, v143
	v_mov_b32_e32 v141, v137
	v_mov_b32_dpp v216, v213 row_ror:8 row_mask:0xf bank_mask:0xf bound_ctrl:1
	v_mov_b32_dpp v217, v212 row_ror:8 row_mask:0xf bank_mask:0xf bound_ctrl:1
	v_lshl_add_u64 v[138:139], v[138:139], 0, v[140:141]
	v_cndmask_b32_e32 v140, v203, v199, vcc
	v_cndmask_b32_e32 v213, v217, v209, vcc
	v_cndmask_b32_e32 v212, v216, v208, vcc
	v_cndmask_b32_e32 v141, v202, v198, vcc
	v_mov_b32_dpp v140, v140 row_ror:8 row_mask:0xf bank_mask:0xf bound_ctrl:1
	s_movk_i32 s6, 0x1000
	v_cndmask_b32_e32 v217, v205, v217, vcc
	v_cndmask_b32_e32 v216, v204, v216, vcc
	global_store_dwordx4 v[138:139], v[212:215], off nt
	global_store_dwordx4 v[138:139], v[216:219], off offset:2048 nt
	v_mov_b32_dpp v141, v141 row_ror:8 row_mask:0xf bank_mask:0xf bound_ctrl:1
	v_cndmask_b32_e32 v215, v140, v203, vcc
	v_cndmask_b32_e32 v219, v199, v140, vcc
	v_add_co_u32_e64 v140, s[6:7], s6, v138
	v_cndmask_b32_e32 v214, v141, v202, vcc
	v_cndmask_b32_e32 v218, v198, v141, vcc
	v_addc_co_u32_e64 v141, s[6:7], 0, v139, s[6:7]
	v_cndmask_b32_e32 v143, v201, v197, vcc
	v_cndmask_b32_e32 v212, v200, v196, vcc
	s_movk_i32 s6, 0x2000
	v_mov_b32_dpp v143, v143 row_ror:8 row_mask:0xf bank_mask:0xf bound_ctrl:1
	v_mov_b32_dpp v216, v212 row_ror:8 row_mask:0xf bank_mask:0xf bound_ctrl:1
	v_add_co_u32_e64 v220, s[6:7], s6, v138
	v_cndmask_b32_e32 v213, v143, v201, vcc
	v_cndmask_b32_e32 v212, v216, v200, vcc
	v_addc_co_u32_e64 v221, s[6:7], 0, v139, s[6:7]
	v_cndmask_b32_e32 v217, v197, v143, vcc
	v_cndmask_b32_e32 v216, v196, v216, vcc
	global_store_dwordx4 v[220:221], v[212:215], off offset:-4096 nt
	global_store_dwordx4 v[140:141], v[216:219], off offset:2048 nt
	v_cndmask_b32_e32 v140, v195, v191, vcc
	v_cndmask_b32_e32 v141, v194, v189, vcc
	v_cndmask_b32_e32 v143, v193, v188, vcc
	v_cndmask_b32_e32 v212, v192, v187, vcc
	v_mov_b32_dpp v141, v141 row_ror:8 row_mask:0xf bank_mask:0xf bound_ctrl:1
	v_mov_b32_dpp v143, v143 row_ror:8 row_mask:0xf bank_mask:0xf bound_ctrl:1
	v_mov_b32_dpp v216, v212 row_ror:8 row_mask:0xf bank_mask:0xf bound_ctrl:1
	v_mov_b32_dpp v140, v140 row_ror:8 row_mask:0xf bank_mask:0xf bound_ctrl:1
	v_cndmask_b32_e32 v215, v140, v195, vcc
	v_cndmask_b32_e32 v214, v141, v194, vcc
	v_cndmask_b32_e32 v213, v143, v193, vcc
	v_cndmask_b32_e32 v212, v216, v192, vcc
	v_cndmask_b32_e32 v219, v191, v140, vcc
	v_cndmask_b32_e32 v140, v186, v182, vcc
	v_cndmask_b32_e32 v218, v189, v141, vcc
	v_cndmask_b32_e32 v217, v188, v143, vcc
	v_cndmask_b32_e32 v216, v187, v216, vcc
	global_store_dwordx4 v[220:221], v[212:215], off nt
	global_store_dwordx4 v[220:221], v[216:219], off offset:2048 nt
	v_cndmask_b32_e32 v141, v185, v181, vcc
	v_cndmask_b32_e32 v143, v184, v180, vcc
	v_cndmask_b32_e32 v212, v183, v179, vcc
	v_mov_b32_dpp v140, v140 row_ror:8 row_mask:0xf bank_mask:0xf bound_ctrl:1
	s_movk_i32 s6, 0x3000
	v_mov_b32_dpp v216, v212 row_ror:8 row_mask:0xf bank_mask:0xf bound_ctrl:1
	v_mov_b32_dpp v143, v143 row_ror:8 row_mask:0xf bank_mask:0xf bound_ctrl:1
	v_mov_b32_dpp v141, v141 row_ror:8 row_mask:0xf bank_mask:0xf bound_ctrl:1
	v_cndmask_b32_e32 v215, v140, v186, vcc
	v_cndmask_b32_e32 v219, v182, v140, vcc
	v_add_co_u32_e64 v140, s[6:7], s6, v138
	v_cndmask_b32_e32 v214, v141, v185, vcc
	v_cndmask_b32_e32 v213, v143, v184, vcc
	v_cndmask_b32_e32 v212, v216, v183, vcc
	v_cndmask_b32_e32 v218, v181, v141, vcc
	v_addc_co_u32_e64 v141, s[6:7], 0, v139, s[6:7]
	v_cndmask_b32_e32 v217, v180, v143, vcc
	v_cndmask_b32_e32 v216, v179, v216, vcc
	global_store_dwordx4 v[140:141], v[212:215], off nt
	global_store_dwordx4 v[140:141], v[216:219], off offset:2048 nt
	v_cndmask_b32_e32 v140, v178, v174, vcc
	v_cndmask_b32_e32 v141, v177, v173, vcc
	s_mov_b32 s6, 0x8000
	v_mov_b32_dpp v140, v140 row_ror:8 row_mask:0xf bank_mask:0xf bound_ctrl:1
	v_mov_b32_dpp v141, v141 row_ror:8 row_mask:0xf bank_mask:0xf bound_ctrl:1
	v_cndmask_b32_e32 v215, v140, v178, vcc
	v_cndmask_b32_e32 v219, v174, v140, vcc
	v_add_co_u32_e64 v140, s[6:7], s6, v138
	v_cndmask_b32_e32 v214, v141, v177, vcc
	v_cndmask_b32_e32 v218, v173, v141, vcc
	v_addc_co_u32_e64 v141, s[6:7], 0, v139, s[6:7]
	v_cndmask_b32_e32 v143, v176, v172, vcc
	v_cndmask_b32_e32 v212, v175, v171, vcc
	s_mov_b32 s6, 0x9000
	v_mov_b32_dpp v143, v143 row_ror:8 row_mask:0xf bank_mask:0xf bound_ctrl:1
	v_mov_b32_dpp v216, v212 row_ror:8 row_mask:0xf bank_mask:0xf bound_ctrl:1
	v_add_co_u32_e64 v220, s[6:7], s6, v138
	v_cndmask_b32_e32 v213, v143, v176, vcc
	v_cndmask_b32_e32 v212, v216, v175, vcc
	v_addc_co_u32_e64 v221, s[6:7], 0, v139, s[6:7]
	v_cndmask_b32_e32 v217, v172, v143, vcc
	v_cndmask_b32_e32 v216, v171, v216, vcc
	global_store_dwordx4 v[220:221], v[212:215], off offset:-4096 nt
	global_store_dwordx4 v[140:141], v[216:219], off offset:2048 nt
	v_cndmask_b32_e32 v140, v170, v166, vcc
	v_cndmask_b32_e32 v141, v169, v165, vcc
	v_cndmask_b32_e32 v143, v168, v164, vcc
	v_cndmask_b32_e32 v212, v167, v163, vcc
	v_mov_b32_dpp v141, v141 row_ror:8 row_mask:0xf bank_mask:0xf bound_ctrl:1
	v_mov_b32_dpp v143, v143 row_ror:8 row_mask:0xf bank_mask:0xf bound_ctrl:1
	v_mov_b32_dpp v216, v212 row_ror:8 row_mask:0xf bank_mask:0xf bound_ctrl:1
	v_mov_b32_dpp v140, v140 row_ror:8 row_mask:0xf bank_mask:0xf bound_ctrl:1
	v_cndmask_b32_e32 v215, v140, v170, vcc
	v_cndmask_b32_e32 v214, v141, v169, vcc
	v_cndmask_b32_e32 v213, v143, v168, vcc
	v_cndmask_b32_e32 v212, v216, v167, vcc
	v_cndmask_b32_e32 v219, v166, v140, vcc
	v_cndmask_b32_e32 v140, v162, v158, vcc
	v_cndmask_b32_e32 v218, v165, v141, vcc
	v_cndmask_b32_e32 v217, v164, v143, vcc
	v_cndmask_b32_e32 v216, v163, v216, vcc
	global_store_dwordx4 v[220:221], v[212:215], off nt
	global_store_dwordx4 v[220:221], v[216:219], off offset:2048 nt
	v_cndmask_b32_e32 v141, v161, v157, vcc
	v_cndmask_b32_e32 v143, v160, v156, vcc
	v_cndmask_b32_e32 v212, v159, v155, vcc
	v_mov_b32_dpp v140, v140 row_ror:8 row_mask:0xf bank_mask:0xf bound_ctrl:1
	s_mov_b32 s6, 0xa000
	v_mov_b32_dpp v216, v212 row_ror:8 row_mask:0xf bank_mask:0xf bound_ctrl:1
	v_mov_b32_dpp v143, v143 row_ror:8 row_mask:0xf bank_mask:0xf bound_ctrl:1
	v_mov_b32_dpp v141, v141 row_ror:8 row_mask:0xf bank_mask:0xf bound_ctrl:1
	v_cndmask_b32_e32 v215, v140, v162, vcc
	v_cndmask_b32_e32 v219, v158, v140, vcc
	v_add_co_u32_e64 v140, s[6:7], s6, v138
	v_cndmask_b32_e32 v214, v141, v161, vcc
	v_cndmask_b32_e32 v213, v143, v160, vcc
	v_cndmask_b32_e32 v212, v216, v159, vcc
	v_cndmask_b32_e32 v218, v157, v141, vcc
	v_addc_co_u32_e64 v141, s[6:7], 0, v139, s[6:7]
	v_cndmask_b32_e32 v217, v156, v143, vcc
	v_cndmask_b32_e32 v216, v155, v216, vcc
	global_store_dwordx4 v[140:141], v[212:215], off nt
	global_store_dwordx4 v[140:141], v[216:219], off offset:2048 nt
	v_cndmask_b32_e32 v140, v154, v144, vcc
	v_cndmask_b32_e32 v141, v153, v135, vcc
	v_cndmask_b32_e32 v143, v152, v133, vcc
	v_cndmask_b32_e32 v212, v145, v131, vcc
	v_mov_b32_dpp v141, v141 row_ror:8 row_mask:0xf bank_mask:0xf bound_ctrl:1
	v_mov_b32_dpp v143, v143 row_ror:8 row_mask:0xf bank_mask:0xf bound_ctrl:1
	v_mov_b32_dpp v216, v212 row_ror:8 row_mask:0xf bank_mask:0xf bound_ctrl:1
	v_mov_b32_dpp v140, v140 row_ror:8 row_mask:0xf bank_mask:0xf bound_ctrl:1
	v_cndmask_b32_e32 v215, v140, v154, vcc
	v_cndmask_b32_e32 v214, v141, v153, vcc
	v_cndmask_b32_e32 v213, v143, v152, vcc
	v_cndmask_b32_e32 v212, v216, v145, vcc
	v_cndmask_b32_e32 v219, v144, v140, vcc
	v_cndmask_b32_e32 v218, v135, v141, vcc
	v_cndmask_b32_e32 v217, v133, v143, vcc
	v_cndmask_b32_e32 v216, v131, v216, vcc
	v_add_co_u32_e32 v138, vcc, 0xb000, v138
	s_nop 1
	v_addc_co_u32_e32 v139, vcc, 0, v139, vcc
	s_mov_b64 vcc, s[4:5]
	global_store_dwordx4 v[138:139], v[212:215], off nt
	global_store_dwordx4 v[138:139], v[216:219], off offset:2048 nt
	s_cbranch_vccz .LBB0_139
	v_mul_f32_e32 v69, v69, v69
	v_fmac_f32_e32 v69, v68, v68
	v_mul_f32_e32 v68, v71, v71
	v_fmac_f32_e32 v68, v70, v70
	v_mul_f32_e32 v70, v73, v73
	v_fmac_f32_e32 v70, v72, v72
	v_mul_f32_e32 v67, v67, v67
	v_add_f32_e32 v68, v68, v70
	v_fmac_f32_e32 v67, v66, v66
	v_add_f32_e32 v66, v68, v67
	v_add_f32_e32 v66, v69, v66
	v_mul_f32_e32 v68, v127, v127
	v_mul_f32_e32 v69, v129, v129
	v_mul_f32_e32 v109, v109, v109
	v_mul_f32_e32 v97, v97, v97
	v_fmac_f32_e32 v68, v126, v126
	v_fmac_f32_e32 v69, v128, v128
	v_fmac_f32_e32 v109, v108, v108
	v_mul_f32_e32 v108, v115, v115
	v_fmac_f32_e32 v97, v96, v96
	v_mul_f32_e32 v96, v103, v103
	v_mul_f32_e32 v77, v77, v77
	v_add_f32_e32 v68, v68, v69
	v_mul_f32_e32 v69, v123, v123
	v_fmac_f32_e32 v108, v114, v114
	v_mul_f32_e32 v114, v117, v117
	v_fmac_f32_e32 v96, v102, v102
	v_mul_f32_e32 v102, v105, v105
	v_fmac_f32_e32 v77, v76, v76
	v_mul_f32_e32 v76, v83, v83
	v_fmac_f32_e32 v69, v122, v122
	v_fmac_f32_e32 v114, v116, v116
	v_mul_f32_e32 v107, v107, v107
	v_fmac_f32_e32 v102, v104, v104
	v_mul_f32_e32 v95, v95, v95
	v_fmac_f32_e32 v76, v82, v82
	v_mul_f32_e32 v82, v85, v85
	v_add_f32_e32 v68, v68, v69
	v_mul_f32_e32 v69, v119, v119
	v_mul_f32_e32 v70, v121, v121
	v_add_f32_e32 v108, v108, v114
	v_fmac_f32_e32 v107, v106, v106
	v_add_f32_e32 v96, v96, v102
	v_fmac_f32_e32 v95, v94, v94
	v_fmac_f32_e32 v82, v84, v84
	v_mul_f32_e32 v75, v75, v75
	v_mul_f32_e32 v67, v125, v125
	v_fmac_f32_e32 v69, v118, v118
	v_fmac_f32_e32 v70, v120, v120
	v_add_f32_e32 v106, v108, v107
	v_add_f32_e32 v94, v96, v95
	v_add_f32_e32 v76, v76, v82
	v_fmac_f32_e32 v75, v74, v74
	v_fmac_f32_e32 v67, v124, v124
	v_add_f32_e32 v69, v69, v70
	v_mul_f32_e32 v70, v111, v111
	v_add_f32_e32 v106, v109, v106
	v_add_f32_e32 v94, v97, v94
	v_add_f32_e32 v74, v76, v75
	v_add_f32_e32 v67, v67, v68
	v_mul_f32_e32 v68, v113, v113
	v_fmac_f32_e32 v70, v110, v110
	v_max3_f32 v94, v106, 0, v94
	v_add_f32_e32 v74, v77, v74
	v_fmac_f32_e32 v68, v112, v112
	v_add_f32_e32 v69, v69, v70
	v_max3_f32 v66, v94, v74, v66
	v_add_f32_e32 v68, v68, v69
	v_max3_f32 v66, v66, v67, v68
	v_mul_f32_e32 v68, v99, v99
	v_mul_f32_e32 v69, v101, v101
	v_fmac_f32_e32 v68, v98, v98
	v_fmac_f32_e32 v69, v100, v100
	v_add_f32_e32 v68, v68, v69
	v_mul_f32_e32 v69, v91, v91
	v_fmac_f32_e32 v69, v90, v90
	v_add_f32_e32 v68, v68, v69
	v_mul_f32_e32 v69, v87, v87
	v_mul_f32_e32 v70, v89, v89
	v_mul_f32_e32 v67, v93, v93
	v_fmac_f32_e32 v69, v86, v86
	v_fmac_f32_e32 v70, v88, v88
	v_fmac_f32_e32 v67, v92, v92
	v_add_f32_e32 v69, v69, v70
	v_mul_f32_e32 v70, v79, v79
	v_add_f32_e32 v67, v67, v68
	v_mul_f32_e32 v68, v81, v81
	v_fmac_f32_e32 v70, v78, v78
	v_fmac_f32_e32 v68, v80, v80
	v_add_f32_e32 v69, v69, v70
	v_add_f32_e32 v68, v68, v69
	v_max3_f32 v68, v66, v67, v68
	v_and_b32_e32 v67, 64, v151
	v_xor_b32_e32 v66, 1, v151
	v_add_u32_e32 v69, 64, v67
	v_cmp_lt_i32_e32 vcc, v66, v69
	v_xor_b32_e32 v67, 2, v151
	v_xor_b32_e32 v71, 4, v151
	v_cndmask_b32_e32 v66, v151, v66, vcc
	v_lshlrev_b32_e32 v66, 2, v66
	ds_bpermute_b32 v70, v66, v68
	v_cmp_lt_i32_e32 vcc, v67, v69
	s_lshl_b32 s4, s43, 4
	s_or_b32 s4, s4, s70
	v_cndmask_b32_e32 v67, v151, v67, vcc
	s_waitcnt lgkmcnt(0)
	v_max_f32_e32 v70, v70, v70
	v_lshlrev_b32_e32 v67, 2, v67
	v_max_f32_e32 v70, v68, v70
	ds_bpermute_b32 v72, v67, v70
	v_cmp_lt_i32_e32 vcc, v71, v69
	s_ashr_i32 s5, s4, 31
	v_ashrrev_i32_e32 v143, 31, v142
	v_cndmask_b32_e32 v68, v151, v71, vcc
	s_waitcnt lgkmcnt(0)
	v_max_f32_e32 v72, v72, v72
	v_lshlrev_b32_e32 v68, 2, v68
	v_max_f32_e32 v70, v70, v72
	ds_bpermute_b32 v72, v68, v70
	v_xor_b32_e32 v71, 8, v151
	v_cmp_lt_i32_e32 vcc, v71, v69
	s_nop 1
	v_cndmask_b32_e32 v69, v151, v71, vcc
	s_waitcnt lgkmcnt(0)
	v_max_f32_e32 v71, v72, v72
	v_lshlrev_b32_e32 v69, 2, v69
	v_max_f32_e32 v70, v70, v71
	ds_bpermute_b32 v71, v69, v70
	v_cmp_eq_u32_e32 vcc, 0, v190
	s_and_saveexec_b64 s[6:7], vcc
	s_cbranch_execz .LBB0_136
	s_lshl_b64 s[48:49], s[4:5], 2
	s_add_u32 s48, s71, s48
	s_waitcnt lgkmcnt(0)
	v_max_f32_e32 v71, v71, v71
	v_max_f32_e32 v70, v70, v70
	s_addc_u32 s49, s72, s49
	v_max_f32_e32 v72, v70, v71
	v_lshl_add_u64 v[70:71], v[142:143], 2, s[48:49]
	global_atomic_umax v[70:71], v72, off

.LBB0_150:
	s_or_b64 exec, exec, s[48:49]
	v_lshrrev_b32_e32 v6, 1, v190
	v_and_b32_e32 v8, 0xffffffc, v6
	v_and_or_b32 v6, v190, 3, s69
	v_lshl_add_u32 v9, v142, 3, v6
	v_lshlrev_b32_e32 v6, 2, v190
	v_and_b32_e32 v6, 16, v6
	v_mov_b32_e32 v7, v137
	v_lshl_add_u64 v[10:11], s[0:1], 0, v[6:7]
	s_lshl_b32 s14, s14, 8
	v_add_lshl_u32 v6, v9, v8, 4
	v_lshl_add_u64 v[12:13], v[10:11], 0, s[14:15]
	v_ashrrev_i32_e32 v7, 31, v6
	v_lshl_add_u64 v[8:9], v[6:7], 1, v[12:13]
	global_store_dwordx4 v[8:9], v[2:5], off nt
	s_nop 1
	v_cndmask_b32_e64 v2, v204, v206, s[4:5]
	v_cndmask_b32_e64 v3, v205, v207, s[4:5]
	s_nop 0
	v_mov_b32_dpp v2, v2 row_ror:8 row_mask:0xf bank_mask:0xf bound_ctrl:1
	v_mov_b32_dpp v3, v3 row_ror:8 row_mask:0xf bank_mask:0xf bound_ctrl:1
	v_cndmask_b32_e64 v4, v207, v3, s[4:5]
	v_cndmask_b32_e64 v5, v206, v2, s[4:5]
	v_cndmask_b32_e64 v3, v3, v205, s[4:5]
	v_cndmask_b32_e64 v2, v2, v204, s[4:5]
	v_cndmask_b32_e64 v8, v2, v3, s[6:7]
	v_cndmask_b32_e64 v9, v5, v4, s[6:7]
	s_nop 0
	v_mov_b32_dpp v14, v8 quad_perm:[2,3,0,1] row_mask:0xf bank_mask:0xf bound_ctrl:1
	v_mov_b32_dpp v9, v9 quad_perm:[2,3,0,1] row_mask:0xf bank_mask:0xf bound_ctrl:1
	v_cndmask_b32_e64 v8, v4, v9, s[6:7]
	v_cndmask_b32_e64 v5, v9, v5, s[6:7]
	v_cndmask_b32_e64 v4, v3, v14, s[6:7]
	v_cndmask_b32_e64 v3, v14, v2, s[6:7]
	v_mov_b32_dpp v14, v5 quad_perm:[1,0,3,2] row_mask:0xf bank_mask:0xf bound_ctrl:1
	v_mov_b32_dpp v15, v4 quad_perm:[1,0,3,2] row_mask:0xf bank_mask:0xf bound_ctrl:1
	v_mov_b32_dpp v16, v3 quad_perm:[1,0,3,2] row_mask:0xf bank_mask:0xf bound_ctrl:1
	v_mov_b32_dpp v9, v8 quad_perm:[1,0,3,2] row_mask:0xf bank_mask:0xf bound_ctrl:1
	s_and_saveexec_b64 s[0:1], vcc
	s_xor_b64 s[0:1], exec, s[0:1]
	s_cbranch_execnz .LBB0_296
	s_andn2_saveexec_b64 s[0:1], s[0:1]
	s_cbranch_execnz .LBB0_297

.LBB0_159:
	s_or_b64 exec, exec, s[0:1]
	v_add_u32_e32 v8, 0x200, v6
	v_ashrrev_i32_e32 v9, 31, v8
	v_lshl_add_u64 v[14:15], v[8:9], 1, v[12:13]
	global_store_dwordx4 v[14:15], v[2:5], off nt
	s_nop 1
	v_cndmask_b32_e64 v2, v200, v202, s[4:5]
	v_cndmask_b32_e64 v3, v201, v203, s[4:5]
	s_nop 0
	v_mov_b32_dpp v2, v2 row_ror:8 row_mask:0xf bank_mask:0xf bound_ctrl:1
	v_mov_b32_dpp v3, v3 row_ror:8 row_mask:0xf bank_mask:0xf bound_ctrl:1
	v_cndmask_b32_e64 v4, v203, v3, s[4:5]
	v_cndmask_b32_e64 v5, v202, v2, s[4:5]
	v_cndmask_b32_e64 v3, v3, v201, s[4:5]
	v_cndmask_b32_e64 v2, v2, v200, s[4:5]
	v_cndmask_b32_e64 v14, v2, v3, s[6:7]
	v_cndmask_b32_e64 v15, v5, v4, s[6:7]
	s_nop 0
	v_mov_b32_dpp v16, v14 quad_perm:[2,3,0,1] row_mask:0xf bank_mask:0xf bound_ctrl:1
	v_mov_b32_dpp v15, v15 quad_perm:[2,3,0,1] row_mask:0xf bank_mask:0xf bound_ctrl:1
	v_cndmask_b32_e64 v14, v4, v15, s[6:7]
	v_cndmask_b32_e64 v5, v15, v5, s[6:7]
	v_cndmask_b32_e64 v4, v3, v16, s[6:7]
	v_cndmask_b32_e64 v3, v16, v2, s[6:7]
	v_mov_b32_dpp v16, v5 quad_perm:[1,0,3,2] row_mask:0xf bank_mask:0xf bound_ctrl:1
	v_mov_b32_dpp v17, v4 quad_perm:[1,0,3,2] row_mask:0xf bank_mask:0xf bound_ctrl:1
	v_mov_b32_dpp v18, v3 quad_perm:[1,0,3,2] row_mask:0xf bank_mask:0xf bound_ctrl:1
	v_mov_b32_dpp v15, v14 quad_perm:[1,0,3,2] row_mask:0xf bank_mask:0xf bound_ctrl:1
	s_and_saveexec_b64 s[0:1], vcc
	s_xor_b64 s[0:1], exec, s[0:1]
	s_cbranch_execnz .LBB0_303
	s_andn2_saveexec_b64 s[0:1], s[0:1]
	s_cbranch_execnz .LBB0_304

.LBB0_168:
	s_or_b64 exec, exec, s[0:1]
	s_mov_b64 s[0:1], 0x1000
	v_lshl_add_u64 v[14:15], v[12:13], 0, s[0:1]
	v_lshl_add_u64 v[16:17], v[6:7], 1, v[14:15]
	global_store_dwordx4 v[16:17], v[2:5], off nt
	s_nop 1
	v_cndmask_b32_e64 v2, v196, v198, s[4:5]
	v_cndmask_b32_e64 v3, v197, v199, s[4:5]
	s_nop 0
	v_mov_b32_dpp v2, v2 row_ror:8 row_mask:0xf bank_mask:0xf bound_ctrl:1
	v_mov_b32_dpp v3, v3 row_ror:8 row_mask:0xf bank_mask:0xf bound_ctrl:1
	v_cndmask_b32_e64 v4, v199, v3, s[4:5]
	v_cndmask_b32_e64 v5, v198, v2, s[4:5]
	v_cndmask_b32_e64 v3, v3, v197, s[4:5]
	v_cndmask_b32_e64 v2, v2, v196, s[4:5]
	v_cndmask_b32_e64 v16, v2, v3, s[6:7]
	v_cndmask_b32_e64 v17, v5, v4, s[6:7]
	s_nop 0
	v_mov_b32_dpp v18, v16 quad_perm:[2,3,0,1] row_mask:0xf bank_mask:0xf bound_ctrl:1
	v_mov_b32_dpp v17, v17 quad_perm:[2,3,0,1] row_mask:0xf bank_mask:0xf bound_ctrl:1
	v_cndmask_b32_e64 v16, v4, v17, s[6:7]
	v_cndmask_b32_e64 v5, v17, v5, s[6:7]
	v_cndmask_b32_e64 v4, v3, v18, s[6:7]
	v_cndmask_b32_e64 v3, v18, v2, s[6:7]
	v_mov_b32_dpp v18, v5 quad_perm:[1,0,3,2] row_mask:0xf bank_mask:0xf bound_ctrl:1
	v_mov_b32_dpp v19, v4 quad_perm:[1,0,3,2] row_mask:0xf bank_mask:0xf bound_ctrl:1
	v_mov_b32_dpp v20, v3 quad_perm:[1,0,3,2] row_mask:0xf bank_mask:0xf bound_ctrl:1
	v_mov_b32_dpp v17, v16 quad_perm:[1,0,3,2] row_mask:0xf bank_mask:0xf bound_ctrl:1
	s_and_saveexec_b64 s[0:1], vcc
	s_xor_b64 s[0:1], exec, s[0:1]
	s_cbranch_execnz .LBB0_310
	s_andn2_saveexec_b64 s[0:1], s[0:1]
	s_cbranch_execnz .LBB0_311

.LBB0_177:
	s_or_b64 exec, exec, s[0:1]
	v_lshl_add_u64 v[14:15], v[8:9], 1, v[14:15]
	global_store_dwordx4 v[14:15], v[2:5], off nt
	s_nop 1
	v_cndmask_b32_e64 v2, v192, v194, s[4:5]
	v_cndmask_b32_e64 v3, v193, v195, s[4:5]
	s_nop 0
	v_mov_b32_dpp v2, v2 row_ror:8 row_mask:0xf bank_mask:0xf bound_ctrl:1
	v_mov_b32_dpp v3, v3 row_ror:8 row_mask:0xf bank_mask:0xf bound_ctrl:1
	v_cndmask_b32_e64 v4, v195, v3, s[4:5]
	v_cndmask_b32_e64 v5, v194, v2, s[4:5]
	v_cndmask_b32_e64 v3, v3, v193, s[4:5]
	v_cndmask_b32_e64 v2, v2, v192, s[4:5]
	v_cndmask_b32_e64 v14, v2, v3, s[6:7]
	v_cndmask_b32_e64 v15, v5, v4, s[6:7]
	s_nop 0
	v_mov_b32_dpp v16, v14 quad_perm:[2,3,0,1] row_mask:0xf bank_mask:0xf bound_ctrl:1
	v_mov_b32_dpp v15, v15 quad_perm:[2,3,0,1] row_mask:0xf bank_mask:0xf bound_ctrl:1
	v_cndmask_b32_e64 v14, v4, v15, s[6:7]
	v_cndmask_b32_e64 v5, v15, v5, s[6:7]
	v_cndmask_b32_e64 v4, v3, v16, s[6:7]
	v_cndmask_b32_e64 v3, v16, v2, s[6:7]
	v_mov_b32_dpp v16, v5 quad_perm:[1,0,3,2] row_mask:0xf bank_mask:0xf bound_ctrl:1
	v_mov_b32_dpp v17, v4 quad_perm:[1,0,3,2] row_mask:0xf bank_mask:0xf bound_ctrl:1
	v_mov_b32_dpp v18, v3 quad_perm:[1,0,3,2] row_mask:0xf bank_mask:0xf bound_ctrl:1
	v_mov_b32_dpp v15, v14 quad_perm:[1,0,3,2] row_mask:0xf bank_mask:0xf bound_ctrl:1
	s_and_saveexec_b64 s[0:1], vcc
	s_xor_b64 s[0:1], exec, s[0:1]
	s_cbranch_execnz .LBB0_317
	s_andn2_saveexec_b64 s[0:1], s[0:1]
	s_cbranch_execnz .LBB0_318

.LBB0_186:
	s_or_b64 exec, exec, s[0:1]
	v_lshl_add_u64 v[14:15], v[12:13], 0, s[26:27]
	v_lshl_add_u64 v[16:17], v[6:7], 1, v[14:15]
	global_store_dwordx4 v[16:17], v[2:5], off nt
	s_nop 1
	v_cndmask_b32_e64 v2, v187, v189, s[4:5]
	v_cndmask_b32_e64 v3, v188, v191, s[4:5]
	s_nop 0
	v_mov_b32_dpp v2, v2 row_ror:8 row_mask:0xf bank_mask:0xf bound_ctrl:1
	v_mov_b32_dpp v3, v3 row_ror:8 row_mask:0xf bank_mask:0xf bound_ctrl:1
	v_cndmask_b32_e64 v4, v191, v3, s[4:5]
	v_cndmask_b32_e64 v5, v189, v2, s[4:5]
	v_cndmask_b32_e64 v3, v3, v188, s[4:5]
	v_cndmask_b32_e64 v2, v2, v187, s[4:5]
	v_cndmask_b32_e64 v16, v2, v3, s[6:7]
	v_cndmask_b32_e64 v17, v5, v4, s[6:7]
	s_nop 0
	v_mov_b32_dpp v18, v16 quad_perm:[2,3,0,1] row_mask:0xf bank_mask:0xf bound_ctrl:1
	v_mov_b32_dpp v17, v17 quad_perm:[2,3,0,1] row_mask:0xf bank_mask:0xf bound_ctrl:1
	v_cndmask_b32_e64 v16, v4, v17, s[6:7]
	v_cndmask_b32_e64 v5, v17, v5, s[6:7]
	v_cndmask_b32_e64 v4, v3, v18, s[6:7]
	v_cndmask_b32_e64 v3, v18, v2, s[6:7]
	v_mov_b32_dpp v18, v5 quad_perm:[1,0,3,2] row_mask:0xf bank_mask:0xf bound_ctrl:1
	v_mov_b32_dpp v19, v4 quad_perm:[1,0,3,2] row_mask:0xf bank_mask:0xf bound_ctrl:1
	v_mov_b32_dpp v20, v3 quad_perm:[1,0,3,2] row_mask:0xf bank_mask:0xf bound_ctrl:1
	v_mov_b32_dpp v17, v16 quad_perm:[1,0,3,2] row_mask:0xf bank_mask:0xf bound_ctrl:1
	s_and_saveexec_b64 s[0:1], vcc
	s_xor_b64 s[0:1], exec, s[0:1]
	s_cbranch_execnz .LBB0_324
	s_andn2_saveexec_b64 s[0:1], s[0:1]
	s_cbranch_execnz .LBB0_325

.LBB0_195:
	s_or_b64 exec, exec, s[0:1]
	v_lshl_add_u64 v[14:15], v[8:9], 1, v[14:15]
	global_store_dwordx4 v[14:15], v[2:5], off nt
	s_nop 1
	v_cndmask_b32_e64 v2, v183, v185, s[4:5]
	v_cndmask_b32_e64 v3, v184, v186, s[4:5]
	s_nop 0
	v_mov_b32_dpp v2, v2 row_ror:8 row_mask:0xf bank_mask:0xf bound_ctrl:1
	v_mov_b32_dpp v3, v3 row_ror:8 row_mask:0xf bank_mask:0xf bound_ctrl:1
	v_cndmask_b32_e64 v4, v186, v3, s[4:5]
	v_cndmask_b32_e64 v5, v185, v2, s[4:5]
	v_cndmask_b32_e64 v3, v3, v184, s[4:5]
	v_cndmask_b32_e64 v2, v2, v183, s[4:5]
	v_cndmask_b32_e64 v14, v2, v3, s[6:7]
	v_cndmask_b32_e64 v15, v5, v4, s[6:7]
	s_nop 0
	v_mov_b32_dpp v16, v14 quad_perm:[2,3,0,1] row_mask:0xf bank_mask:0xf bound_ctrl:1
	v_mov_b32_dpp v15, v15 quad_perm:[2,3,0,1] row_mask:0xf bank_mask:0xf bound_ctrl:1
	v_cndmask_b32_e64 v14, v4, v15, s[6:7]
	v_cndmask_b32_e64 v5, v15, v5, s[6:7]
	v_cndmask_b32_e64 v4, v3, v16, s[6:7]
	v_cndmask_b32_e64 v3, v16, v2, s[6:7]
	v_mov_b32_dpp v16, v5 quad_perm:[1,0,3,2] row_mask:0xf bank_mask:0xf bound_ctrl:1
	v_mov_b32_dpp v17, v4 quad_perm:[1,0,3,2] row_mask:0xf bank_mask:0xf bound_ctrl:1
	v_mov_b32_dpp v18, v3 quad_perm:[1,0,3,2] row_mask:0xf bank_mask:0xf bound_ctrl:1
	v_mov_b32_dpp v15, v14 quad_perm:[1,0,3,2] row_mask:0xf bank_mask:0xf bound_ctrl:1
	s_and_saveexec_b64 s[0:1], vcc
	s_xor_b64 s[0:1], exec, s[0:1]
	s_cbranch_execnz .LBB0_331
	s_andn2_saveexec_b64 s[0:1], s[0:1]
	s_cbranch_execnz .LBB0_332

.LBB0_204:
	s_or_b64 exec, exec, s[0:1]
	v_lshl_add_u64 v[12:13], v[12:13], 0, s[28:29]
	v_lshl_add_u64 v[14:15], v[6:7], 1, v[12:13]
	global_store_dwordx4 v[14:15], v[2:5], off nt
	s_nop 1
	v_cndmask_b32_e64 v2, v179, v181, s[4:5]
	v_cndmask_b32_e64 v3, v180, v182, s[4:5]
	s_nop 0
	v_mov_b32_dpp v2, v2 row_ror:8 row_mask:0xf bank_mask:0xf bound_ctrl:1
	v_mov_b32_dpp v3, v3 row_ror:8 row_mask:0xf bank_mask:0xf bound_ctrl:1
	v_cndmask_b32_e64 v4, v182, v3, s[4:5]
	v_cndmask_b32_e64 v5, v181, v2, s[4:5]
	v_cndmask_b32_e64 v3, v3, v180, s[4:5]
	v_cndmask_b32_e64 v2, v2, v179, s[4:5]
	v_cndmask_b32_e64 v14, v2, v3, s[6:7]
	v_cndmask_b32_e64 v15, v5, v4, s[6:7]
	s_nop 0
	v_mov_b32_dpp v16, v14 quad_perm:[2,3,0,1] row_mask:0xf bank_mask:0xf bound_ctrl:1
	v_mov_b32_dpp v15, v15 quad_perm:[2,3,0,1] row_mask:0xf bank_mask:0xf bound_ctrl:1
	v_cndmask_b32_e64 v14, v4, v15, s[6:7]
	v_cndmask_b32_e64 v5, v15, v5, s[6:7]
	v_cndmask_b32_e64 v4, v3, v16, s[6:7]
	v_cndmask_b32_e64 v3, v16, v2, s[6:7]
	v_mov_b32_dpp v16, v5 quad_perm:[1,0,3,2] row_mask:0xf bank_mask:0xf bound_ctrl:1
	v_mov_b32_dpp v17, v4 quad_perm:[1,0,3,2] row_mask:0xf bank_mask:0xf bound_ctrl:1
	v_mov_b32_dpp v18, v3 quad_perm:[1,0,3,2] row_mask:0xf bank_mask:0xf bound_ctrl:1
	v_mov_b32_dpp v15, v14 quad_perm:[1,0,3,2] row_mask:0xf bank_mask:0xf bound_ctrl:1
	s_and_saveexec_b64 s[0:1], vcc
	s_xor_b64 s[0:1], exec, s[0:1]
	s_cbranch_execnz .LBB0_338
	s_andn2_saveexec_b64 s[0:1], s[0:1]
	s_cbranch_execnz .LBB0_339

.LBB0_213:
	s_or_b64 exec, exec, s[0:1]
	v_lshl_add_u64 v[12:13], v[8:9], 1, v[12:13]
	global_store_dwordx4 v[12:13], v[2:5], off nt
	s_nop 1
	v_cndmask_b32_e64 v2, v175, v177, s[4:5]
	v_cndmask_b32_e64 v3, v176, v178, s[4:5]
	s_nop 0
	v_mov_b32_dpp v2, v2 row_ror:8 row_mask:0xf bank_mask:0xf bound_ctrl:1
	v_mov_b32_dpp v3, v3 row_ror:8 row_mask:0xf bank_mask:0xf bound_ctrl:1
	v_cndmask_b32_e64 v4, v178, v3, s[4:5]
	v_cndmask_b32_e64 v5, v177, v2, s[4:5]
	v_cndmask_b32_e64 v3, v3, v176, s[4:5]
	v_cndmask_b32_e64 v2, v2, v175, s[4:5]
	v_cndmask_b32_e64 v12, v2, v3, s[6:7]
	v_cndmask_b32_e64 v13, v5, v4, s[6:7]
	s_nop 0
	v_mov_b32_dpp v14, v12 quad_perm:[2,3,0,1] row_mask:0xf bank_mask:0xf bound_ctrl:1
	v_mov_b32_dpp v13, v13 quad_perm:[2,3,0,1] row_mask:0xf bank_mask:0xf bound_ctrl:1
	v_cndmask_b32_e64 v12, v4, v13, s[6:7]
	v_cndmask_b32_e64 v5, v13, v5, s[6:7]
	v_cndmask_b32_e64 v4, v3, v14, s[6:7]
	v_cndmask_b32_e64 v3, v14, v2, s[6:7]
	v_mov_b32_dpp v14, v5 quad_perm:[1,0,3,2] row_mask:0xf bank_mask:0xf bound_ctrl:1
	v_mov_b32_dpp v15, v4 quad_perm:[1,0,3,2] row_mask:0xf bank_mask:0xf bound_ctrl:1
	v_mov_b32_dpp v16, v3 quad_perm:[1,0,3,2] row_mask:0xf bank_mask:0xf bound_ctrl:1
	v_mov_b32_dpp v13, v12 quad_perm:[1,0,3,2] row_mask:0xf bank_mask:0xf bound_ctrl:1
	s_and_saveexec_b64 s[0:1], vcc
	s_xor_b64 s[0:1], exec, s[0:1]
	s_cbranch_execnz .LBB0_345
	s_andn2_saveexec_b64 s[0:1], s[0:1]
	s_cbranch_execnz .LBB0_346

.LBB0_222:
	s_or_b64 exec, exec, s[0:1]
	s_lshl_b32 s14, s41, 8
	v_lshl_add_u64 v[10:11], v[10:11], 0, s[14:15]
	v_lshl_add_u64 v[12:13], v[10:11], 0, s[30:31]
	v_lshl_add_u64 v[14:15], v[6:7], 1, v[12:13]
	global_store_dwordx4 v[14:15], v[2:5], off nt
	s_nop 1
	v_cndmask_b32_e64 v2, v171, v173, s[4:5]
	v_cndmask_b32_e64 v3, v172, v174, s[4:5]
	s_nop 0
	v_mov_b32_dpp v2, v2 row_ror:8 row_mask:0xf bank_mask:0xf bound_ctrl:1
	v_mov_b32_dpp v3, v3 row_ror:8 row_mask:0xf bank_mask:0xf bound_ctrl:1
	v_cndmask_b32_e64 v4, v174, v3, s[4:5]
	v_cndmask_b32_e64 v5, v173, v2, s[4:5]
	v_cndmask_b32_e64 v3, v3, v172, s[4:5]
	v_cndmask_b32_e64 v2, v2, v171, s[4:5]
	v_cndmask_b32_e64 v14, v2, v3, s[6:7]
	v_cndmask_b32_e64 v15, v5, v4, s[6:7]
	s_nop 0
	v_mov_b32_dpp v16, v14 quad_perm:[2,3,0,1] row_mask:0xf bank_mask:0xf bound_ctrl:1
	v_mov_b32_dpp v15, v15 quad_perm:[2,3,0,1] row_mask:0xf bank_mask:0xf bound_ctrl:1
	v_cndmask_b32_e64 v14, v4, v15, s[6:7]
	v_cndmask_b32_e64 v5, v15, v5, s[6:7]
	v_cndmask_b32_e64 v4, v3, v16, s[6:7]
	v_cndmask_b32_e64 v3, v16, v2, s[6:7]
	v_mov_b32_dpp v16, v5 quad_perm:[1,0,3,2] row_mask:0xf bank_mask:0xf bound_ctrl:1
	v_mov_b32_dpp v17, v4 quad_perm:[1,0,3,2] row_mask:0xf bank_mask:0xf bound_ctrl:1
	v_mov_b32_dpp v18, v3 quad_perm:[1,0,3,2] row_mask:0xf bank_mask:0xf bound_ctrl:1
	v_mov_b32_dpp v15, v14 quad_perm:[1,0,3,2] row_mask:0xf bank_mask:0xf bound_ctrl:1
	s_and_saveexec_b64 s[0:1], vcc
	s_xor_b64 s[0:1], exec, s[0:1]
	s_cbranch_execnz .LBB0_352
	s_andn2_saveexec_b64 s[0:1], s[0:1]
	s_cbranch_execnz .LBB0_353

.LBB0_231:
	s_or_b64 exec, exec, s[0:1]
	v_lshl_add_u64 v[12:13], v[8:9], 1, v[12:13]
	global_store_dwordx4 v[12:13], v[2:5], off nt
	s_nop 1
	v_cndmask_b32_e64 v2, v167, v169, s[4:5]
	v_cndmask_b32_e64 v3, v168, v170, s[4:5]
	s_nop 0
	v_mov_b32_dpp v2, v2 row_ror:8 row_mask:0xf bank_mask:0xf bound_ctrl:1
	v_mov_b32_dpp v3, v3 row_ror:8 row_mask:0xf bank_mask:0xf bound_ctrl:1
	v_cndmask_b32_e64 v4, v170, v3, s[4:5]
	v_cndmask_b32_e64 v5, v169, v2, s[4:5]
	v_cndmask_b32_e64 v3, v3, v168, s[4:5]
	v_cndmask_b32_e64 v2, v2, v167, s[4:5]
	v_cndmask_b32_e64 v12, v2, v3, s[6:7]
	v_cndmask_b32_e64 v13, v5, v4, s[6:7]
	s_nop 0
	v_mov_b32_dpp v14, v12 quad_perm:[2,3,0,1] row_mask:0xf bank_mask:0xf bound_ctrl:1
	v_mov_b32_dpp v13, v13 quad_perm:[2,3,0,1] row_mask:0xf bank_mask:0xf bound_ctrl:1
	v_cndmask_b32_e64 v12, v4, v13, s[6:7]
	v_cndmask_b32_e64 v5, v13, v5, s[6:7]
	v_cndmask_b32_e64 v4, v3, v14, s[6:7]
	v_cndmask_b32_e64 v3, v14, v2, s[6:7]
	v_mov_b32_dpp v14, v5 quad_perm:[1,0,3,2] row_mask:0xf bank_mask:0xf bound_ctrl:1
	v_mov_b32_dpp v15, v4 quad_perm:[1,0,3,2] row_mask:0xf bank_mask:0xf bound_ctrl:1
	v_mov_b32_dpp v16, v3 quad_perm:[1,0,3,2] row_mask:0xf bank_mask:0xf bound_ctrl:1
	v_mov_b32_dpp v13, v12 quad_perm:[1,0,3,2] row_mask:0xf bank_mask:0xf bound_ctrl:1
	s_and_saveexec_b64 s[0:1], vcc
	s_xor_b64 s[0:1], exec, s[0:1]
	s_cbranch_execnz .LBB0_359
	s_andn2_saveexec_b64 s[0:1], s[0:1]
	s_cbranch_execnz .LBB0_360

.LBB0_240:
	s_or_b64 exec, exec, s[0:1]
	v_lshl_add_u64 v[12:13], v[10:11], 0, s[34:35]
	v_lshl_add_u64 v[14:15], v[6:7], 1, v[12:13]
	global_store_dwordx4 v[14:15], v[2:5], off nt
	s_nop 1
	v_cndmask_b32_e64 v2, v163, v165, s[4:5]
	v_cndmask_b32_e64 v3, v164, v166, s[4:5]
	s_nop 0
	v_mov_b32_dpp v2, v2 row_ror:8 row_mask:0xf bank_mask:0xf bound_ctrl:1
	v_mov_b32_dpp v3, v3 row_ror:8 row_mask:0xf bank_mask:0xf bound_ctrl:1
	v_cndmask_b32_e64 v4, v166, v3, s[4:5]
	v_cndmask_b32_e64 v5, v165, v2, s[4:5]
	v_cndmask_b32_e64 v3, v3, v164, s[4:5]
	v_cndmask_b32_e64 v2, v2, v163, s[4:5]
	v_cndmask_b32_e64 v14, v2, v3, s[6:7]
	v_cndmask_b32_e64 v15, v5, v4, s[6:7]
	s_nop 0
	v_mov_b32_dpp v16, v14 quad_perm:[2,3,0,1] row_mask:0xf bank_mask:0xf bound_ctrl:1
	v_mov_b32_dpp v15, v15 quad_perm:[2,3,0,1] row_mask:0xf bank_mask:0xf bound_ctrl:1
	v_cndmask_b32_e64 v14, v4, v15, s[6:7]
	v_cndmask_b32_e64 v5, v15, v5, s[6:7]
	v_cndmask_b32_e64 v4, v3, v16, s[6:7]
	v_cndmask_b32_e64 v3, v16, v2, s[6:7]
	v_mov_b32_dpp v16, v5 quad_perm:[1,0,3,2] row_mask:0xf bank_mask:0xf bound_ctrl:1
	v_mov_b32_dpp v17, v4 quad_perm:[1,0,3,2] row_mask:0xf bank_mask:0xf bound_ctrl:1
	v_mov_b32_dpp v18, v3 quad_perm:[1,0,3,2] row_mask:0xf bank_mask:0xf bound_ctrl:1
	v_mov_b32_dpp v15, v14 quad_perm:[1,0,3,2] row_mask:0xf bank_mask:0xf bound_ctrl:1
	s_and_saveexec_b64 s[0:1], vcc
	s_xor_b64 s[0:1], exec, s[0:1]
	s_cbranch_execnz .LBB0_366
	s_andn2_saveexec_b64 s[0:1], s[0:1]
	s_cbranch_execnz .LBB0_367

.LBB0_249:
	s_or_b64 exec, exec, s[0:1]
	v_lshl_add_u64 v[12:13], v[8:9], 1, v[12:13]
	global_store_dwordx4 v[12:13], v[2:5], off nt
	s_nop 1
	v_cndmask_b32_e64 v2, v159, v161, s[4:5]
	v_cndmask_b32_e64 v3, v160, v162, s[4:5]
	s_nop 0
	v_mov_b32_dpp v2, v2 row_ror:8 row_mask:0xf bank_mask:0xf bound_ctrl:1
	v_mov_b32_dpp v3, v3 row_ror:8 row_mask:0xf bank_mask:0xf bound_ctrl:1
	v_cndmask_b32_e64 v4, v162, v3, s[4:5]
	v_cndmask_b32_e64 v5, v161, v2, s[4:5]
	v_cndmask_b32_e64 v3, v3, v160, s[4:5]
	v_cndmask_b32_e64 v2, v2, v159, s[4:5]
	v_cndmask_b32_e64 v12, v2, v3, s[6:7]
	v_cndmask_b32_e64 v13, v5, v4, s[6:7]
	s_nop 0
	v_mov_b32_dpp v14, v12 quad_perm:[2,3,0,1] row_mask:0xf bank_mask:0xf bound_ctrl:1
	v_mov_b32_dpp v13, v13 quad_perm:[2,3,0,1] row_mask:0xf bank_mask:0xf bound_ctrl:1
	v_cndmask_b32_e64 v12, v4, v13, s[6:7]
	v_cndmask_b32_e64 v5, v13, v5, s[6:7]
	v_cndmask_b32_e64 v4, v3, v14, s[6:7]
	v_cndmask_b32_e64 v3, v14, v2, s[6:7]
	v_mov_b32_dpp v14, v5 quad_perm:[1,0,3,2] row_mask:0xf bank_mask:0xf bound_ctrl:1
	v_mov_b32_dpp v15, v4 quad_perm:[1,0,3,2] row_mask:0xf bank_mask:0xf bound_ctrl:1
	v_mov_b32_dpp v16, v3 quad_perm:[1,0,3,2] row_mask:0xf bank_mask:0xf bound_ctrl:1
	v_mov_b32_dpp v13, v12 quad_perm:[1,0,3,2] row_mask:0xf bank_mask:0xf bound_ctrl:1
	s_and_saveexec_b64 s[0:1], vcc
	s_xor_b64 s[0:1], exec, s[0:1]
	s_cbranch_execnz .LBB0_373
	s_andn2_saveexec_b64 s[0:1], s[0:1]
	s_cbranch_execnz .LBB0_374

.LBB0_258:
	s_or_b64 exec, exec, s[0:1]
	v_lshl_add_u64 v[12:13], v[10:11], 0, s[36:37]
	v_lshl_add_u64 v[14:15], v[6:7], 1, v[12:13]
	global_store_dwordx4 v[14:15], v[2:5], off nt
	s_nop 1
	v_cndmask_b32_e64 v2, v155, v157, s[4:5]
	v_cndmask_b32_e64 v3, v156, v158, s[4:5]
	s_nop 0
	v_mov_b32_dpp v2, v2 row_ror:8 row_mask:0xf bank_mask:0xf bound_ctrl:1
	v_mov_b32_dpp v3, v3 row_ror:8 row_mask:0xf bank_mask:0xf bound_ctrl:1
	v_cndmask_b32_e64 v4, v158, v3, s[4:5]
	v_cndmask_b32_e64 v5, v157, v2, s[4:5]
	v_cndmask_b32_e64 v3, v3, v156, s[4:5]
	v_cndmask_b32_e64 v2, v2, v155, s[4:5]
	v_cndmask_b32_e64 v14, v2, v3, s[6:7]
	v_cndmask_b32_e64 v15, v5, v4, s[6:7]
	s_nop 0
	v_mov_b32_dpp v16, v14 quad_perm:[2,3,0,1] row_mask:0xf bank_mask:0xf bound_ctrl:1
	v_mov_b32_dpp v15, v15 quad_perm:[2,3,0,1] row_mask:0xf bank_mask:0xf bound_ctrl:1
	v_cndmask_b32_e64 v14, v4, v15, s[6:7]
	v_cndmask_b32_e64 v5, v15, v5, s[6:7]
	v_cndmask_b32_e64 v4, v3, v16, s[6:7]
	v_cndmask_b32_e64 v3, v16, v2, s[6:7]
	v_mov_b32_dpp v16, v5 quad_perm:[1,0,3,2] row_mask:0xf bank_mask:0xf bound_ctrl:1
	v_mov_b32_dpp v17, v4 quad_perm:[1,0,3,2] row_mask:0xf bank_mask:0xf bound_ctrl:1
	v_mov_b32_dpp v18, v3 quad_perm:[1,0,3,2] row_mask:0xf bank_mask:0xf bound_ctrl:1
	v_mov_b32_dpp v15, v14 quad_perm:[1,0,3,2] row_mask:0xf bank_mask:0xf bound_ctrl:1
	s_and_saveexec_b64 s[0:1], vcc
	s_xor_b64 s[0:1], exec, s[0:1]
	s_cbranch_execnz .LBB0_380
	s_andn2_saveexec_b64 s[0:1], s[0:1]
	s_cbranch_execnz .LBB0_381

.LBB0_267:
	s_or_b64 exec, exec, s[0:1]
	v_lshl_add_u64 v[12:13], v[8:9], 1, v[12:13]
	global_store_dwordx4 v[12:13], v[2:5], off nt
	s_nop 1
	v_cndmask_b32_e64 v2, v145, v153, s[4:5]
	v_cndmask_b32_e64 v3, v152, v154, s[4:5]
	s_nop 0
	v_mov_b32_dpp v2, v2 row_ror:8 row_mask:0xf bank_mask:0xf bound_ctrl:1
	v_mov_b32_dpp v3, v3 row_ror:8 row_mask:0xf bank_mask:0xf bound_ctrl:1
	v_cndmask_b32_e64 v4, v154, v3, s[4:5]
	v_cndmask_b32_e64 v5, v153, v2, s[4:5]
	v_cndmask_b32_e64 v3, v3, v152, s[4:5]
	v_cndmask_b32_e64 v2, v2, v145, s[4:5]
	v_cndmask_b32_e64 v12, v2, v3, s[6:7]
	v_cndmask_b32_e64 v13, v5, v4, s[6:7]
	s_nop 0
	v_mov_b32_dpp v14, v12 quad_perm:[2,3,0,1] row_mask:0xf bank_mask:0xf bound_ctrl:1
	v_mov_b32_dpp v13, v13 quad_perm:[2,3,0,1] row_mask:0xf bank_mask:0xf bound_ctrl:1
	v_cndmask_b32_e64 v12, v4, v13, s[6:7]
	v_cndmask_b32_e64 v5, v13, v5, s[6:7]
	v_cndmask_b32_e64 v4, v3, v14, s[6:7]
	v_cndmask_b32_e64 v3, v14, v2, s[6:7]
	v_mov_b32_dpp v14, v5 quad_perm:[1,0,3,2] row_mask:0xf bank_mask:0xf bound_ctrl:1
	v_mov_b32_dpp v15, v4 quad_perm:[1,0,3,2] row_mask:0xf bank_mask:0xf bound_ctrl:1
	v_mov_b32_dpp v16, v3 quad_perm:[1,0,3,2] row_mask:0xf bank_mask:0xf bound_ctrl:1
	v_mov_b32_dpp v13, v12 quad_perm:[1,0,3,2] row_mask:0xf bank_mask:0xf bound_ctrl:1
	s_and_saveexec_b64 s[0:1], vcc
	s_xor_b64 s[0:1], exec, s[0:1]
	s_cbranch_execnz .LBB0_387
	s_andn2_saveexec_b64 s[0:1], s[0:1]
	s_cbranch_execnz .LBB0_388

.LBB0_276:
	s_or_b64 exec, exec, s[0:1]
	v_lshl_add_u64 v[10:11], v[10:11], 0, s[38:39]
	v_lshl_add_u64 v[6:7], v[6:7], 1, v[10:11]
	global_store_dwordx4 v[6:7], v[2:5], off nt
	s_nop 1
	v_cndmask_b32_e64 v2, v131, v135, s[4:5]
	v_cndmask_b32_e64 v3, v133, v144, s[4:5]
	s_nop 0
	v_mov_b32_dpp v2, v2 row_ror:8 row_mask:0xf bank_mask:0xf bound_ctrl:1
	v_mov_b32_dpp v3, v3 row_ror:8 row_mask:0xf bank_mask:0xf bound_ctrl:1
	v_cndmask_b32_e64 v4, v144, v3, s[4:5]
	v_cndmask_b32_e64 v5, v135, v2, s[4:5]
	v_cndmask_b32_e64 v3, v3, v133, s[4:5]
	v_cndmask_b32_e64 v2, v2, v131, s[4:5]
	v_cndmask_b32_e64 v6, v2, v3, s[6:7]
	v_cndmask_b32_e64 v7, v5, v4, s[6:7]
	s_nop 0
	v_mov_b32_dpp v12, v6 quad_perm:[2,3,0,1] row_mask:0xf bank_mask:0xf bound_ctrl:1
	v_mov_b32_dpp v7, v7 quad_perm:[2,3,0,1] row_mask:0xf bank_mask:0xf bound_ctrl:1
	v_cndmask_b32_e64 v6, v4, v7, s[6:7]
	v_cndmask_b32_e64 v5, v7, v5, s[6:7]
	v_cndmask_b32_e64 v4, v3, v12, s[6:7]
	v_cndmask_b32_e64 v3, v12, v2, s[6:7]
	v_mov_b32_dpp v12, v5 quad_perm:[1,0,3,2] row_mask:0xf bank_mask:0xf bound_ctrl:1
	v_mov_b32_dpp v13, v4 quad_perm:[1,0,3,2] row_mask:0xf bank_mask:0xf bound_ctrl:1
	v_mov_b32_dpp v14, v3 quad_perm:[1,0,3,2] row_mask:0xf bank_mask:0xf bound_ctrl:1
	v_mov_b32_dpp v7, v6 quad_perm:[1,0,3,2] row_mask:0xf bank_mask:0xf bound_ctrl:1
	s_and_saveexec_b64 s[0:1], vcc
	s_xor_b64 s[0:1], exec, s[0:1]
	s_cbranch_execnz .LBB0_394
	s_andn2_saveexec_b64 s[0:1], s[0:1]
	s_cbranch_execnz .LBB0_395

.LBB0_285:
	s_or_b64 exec, exec, s[0:1]
	v_lshl_add_u64 v[6:7], v[8:9], 1, v[10:11]
	global_store_dwordx4 v[6:7], v[2:5], off nt

.LBB0_694:
	s_andn2_b64 vcc, exec, s[2:3]
	s_mov_b64 s[0:1], -1
	global_store_dwordx4 v[152:153], v[130:133], off offset:256 nt
	s_cbranch_vccnz .LBB0_678
	s_branch .LBB0_697
.LBB0_695:
	v_lshl_add_u64 v[130:131], v[150:151], 1, s[0:1]
	v_lshlrev_b64 v[132:133], 11, v[146:147]
	v_lshl_add_u64 v[154:155], v[130:131], 0, v[132:133]
	v_cvt_pk_bf16_f32 v130, v126, v127
	v_cvt_pk_bf16_f32 v131, v128, v129
	v_cvt_pk_bf16_f32 v132, v122, v123
	v_cvt_pk_bf16_f32 v133, v124, v125
	global_store_dwordx4 v[154:155], v[130:133], off nt
	v_add_co_u32_e32 v156, vcc, s67, v154
	s_nop 0
	v_cvt_pk_bf16_f32 v130, v118, v119
	v_cvt_pk_bf16_f32 v131, v120, v121
	v_cvt_pk_bf16_f32 v132, v114, v115
	v_cvt_pk_bf16_f32 v133, v116, v117
	global_store_dwordx4 v[154:155], v[130:133], off offset:256 nt
	v_addc_co_u32_e32 v157, vcc, 0, v155, vcc
	s_nop 0
	v_cvt_pk_bf16_f32 v130, v110, v111
	v_cvt_pk_bf16_f32 v131, v112, v113
	v_cvt_pk_bf16_f32 v132, v106, v107
	v_cvt_pk_bf16_f32 v133, v108, v109
	s_mov_b32 s4, 0x10000
	v_lshl_add_u64 v[152:153], v[154:155], 0, s[22:23]
	global_store_dwordx4 v[156:157], v[130:133], off nt
	v_add_co_u32_e32 v156, vcc, s4, v154
	s_nop 0
	v_cvt_pk_bf16_f32 v130, v102, v103
	v_cvt_pk_bf16_f32 v131, v104, v105
	v_cvt_pk_bf16_f32 v132, v98, v99
	v_cvt_pk_bf16_f32 v133, v100, v101
	global_store_dwordx4 v[152:153], v[130:133], off offset:256 nt
	v_addc_co_u32_e32 v157, vcc, 0, v155, vcc
	s_nop 0
	v_cvt_pk_bf16_f32 v130, v94, v95
	v_cvt_pk_bf16_f32 v131, v96, v97
	v_cvt_pk_bf16_f32 v132, v90, v91
	v_cvt_pk_bf16_f32 v133, v92, v93
	v_lshl_add_u64 v[152:153], v[154:155], 0, s[24:25]
	global_store_dwordx4 v[156:157], v[130:133], off nt
	v_add_co_u32_e32 v156, vcc, s66, v154
	s_nop 0
	v_cvt_pk_bf16_f32 v130, v86, v87
	v_cvt_pk_bf16_f32 v131, v88, v89
	v_cvt_pk_bf16_f32 v132, v82, v83
	v_cvt_pk_bf16_f32 v133, v84, v85
	global_store_dwordx4 v[152:153], v[130:133], off offset:256 nt
	v_addc_co_u32_e32 v157, vcc, 0, v155, vcc
	s_nop 0
	v_cvt_pk_bf16_f32 v130, v78, v79
	v_cvt_pk_bf16_f32 v131, v80, v81
	v_cvt_pk_bf16_f32 v132, v74, v75
	v_cvt_pk_bf16_f32 v133, v76, v77
	v_lshl_add_u64 v[152:153], v[154:155], 0, s[26:27]
	global_store_dwordx4 v[156:157], v[130:133], off nt
	v_add_co_u32_e32 v156, vcc, s72, v154
	s_nop 0
	v_cvt_pk_bf16_f32 v130, v70, v71
	v_cvt_pk_bf16_f32 v131, v72, v73
	v_cvt_pk_bf16_f32 v132, v66, v67
	v_cvt_pk_bf16_f32 v133, v68, v69
	global_store_dwordx4 v[152:153], v[130:133], off offset:256 nt
	s_mov_b64 s[4:5], 0x40000
	v_addc_co_u32_e32 v157, vcc, 0, v155, vcc
	v_cvt_pk_bf16_f32 v130, v62, v63
	v_cvt_pk_bf16_f32 v131, v64, v65
	v_cvt_pk_bf16_f32 v132, v58, v59
	v_cvt_pk_bf16_f32 v133, v60, v61
	v_lshl_add_u64 v[152:153], v[154:155], 0, s[4:5]
	global_store_dwordx4 v[156:157], v[130:133], off nt
	v_add_co_u32_e32 v156, vcc, s73, v154
	s_nop 0
	v_cvt_pk_bf16_f32 v130, v54, v55
	v_cvt_pk_bf16_f32 v131, v56, v57
	v_cvt_pk_bf16_f32 v132, v50, v51
	v_cvt_pk_bf16_f32 v133, v52, v53
	global_store_dwordx4 v[152:153], v[130:133], off offset:256 nt
	v_addc_co_u32_e32 v157, vcc, 0, v155, vcc
	s_nop 0
	v_cvt_pk_bf16_f32 v130, v46, v47
	v_cvt_pk_bf16_f32 v131, v48, v49
	v_cvt_pk_bf16_f32 v132, v42, v43
	v_cvt_pk_bf16_f32 v133, v44, v45
	v_lshl_add_u64 v[152:153], v[154:155], 0, s[28:29]
	global_store_dwordx4 v[156:157], v[130:133], off nt
	v_add_co_u32_e32 v156, vcc, s74, v154
	s_nop 0
	v_cvt_pk_bf16_f32 v130, v38, v39
	v_cvt_pk_bf16_f32 v131, v40, v41
	v_cvt_pk_bf16_f32 v132, v34, v35
	v_cvt_pk_bf16_f32 v133, v36, v37
	global_store_dwordx4 v[152:153], v[130:133], off offset:256 nt
	v_addc_co_u32_e32 v157, vcc, 0, v155, vcc
	s_nop 0
	v_cvt_pk_bf16_f32 v130, v6, v7
	v_cvt_pk_bf16_f32 v131, v8, v9
	v_cvt_pk_bf16_f32 v132, v2, v3
	v_cvt_pk_bf16_f32 v133, v4, v5
	v_lshl_add_u64 v[152:153], v[154:155], 0, s[30:31]
	global_store_dwordx4 v[156:157], v[130:133], off nt
	s_nop 1
	v_cvt_pk_bf16_f32 v130, v14, v15
	v_cvt_pk_bf16_f32 v131, v16, v17
	v_cvt_pk_bf16_f32 v132, v10, v11
	v_cvt_pk_bf16_f32 v133, v12, v13
	global_store_dwordx4 v[152:153], v[130:133], off offset:256 nt
	v_lshl_add_u64 v[152:153], v[154:155], 0, s[34:35]
	v_add_co_u32_e32 v154, vcc, s75, v154
	v_cvt_pk_bf16_f32 v130, v22, v23
	v_cvt_pk_bf16_f32 v131, v24, v25
	v_cvt_pk_bf16_f32 v132, v18, v19
	v_cvt_pk_bf16_f32 v133, v20, v21
	v_addc_co_u32_e32 v155, vcc, 0, v155, vcc
	global_store_dwordx4 v[154:155], v[130:133], off nt
	s_nop 1
	v_cvt_pk_bf16_f32 v130, v30, v31
	v_cvt_pk_bf16_f32 v131, v32, v33
	v_cvt_pk_bf16_f32 v132, v26, v27
	v_cvt_pk_bf16_f32 v133, v28, v29
	s_cbranch_execnz .LBB0_694
.LBB0_696:
	s_lshl_b32 s4, s78, 3
	s_and_b32 s4, s4, -16
	s_ashr_i32 s5, s4, 31
	s_lshl_b64 s[4:5], s[4:5], 2
	s_add_u32 s4, s60, s4
	s_addc_u32 s5, s61, s5
	v_ashrrev_i32_e32 v149, 31, v148
	v_lshl_add_u64 v[150:151], v[150:151], 1, s[0:1]
	v_lshlrev_b64 v[130:131], 12, v[146:147]
	v_lshl_add_u64 v[154:155], v[150:151], 0, v[130:131]
	v_lshl_add_u64 v[152:153], v[148:149], 4, s[4:5]
	v_lshlrev_b64 v[130:131], 8, v[146:147]
	v_lshl_add_u64 v[130:131], v[152:153], 0, v[130:131]
	global_load_dwordx4 v[164:167], v[154:155], off
	global_load_dwordx4 v[168:171], v[130:131], off
	v_add_u32_e32 v130, 16, v146
	v_ashrrev_i32_e32 v131, 31, v130
	v_lshlrev_b64 v[132:133], 8, v[130:131]
	v_lshl_add_u64 v[132:133], v[152:153], 0, v[132:133]
	global_load_dwordx4 v[172:175], v[132:133], off
	global_load_dwordx4 v[176:179], v[154:155], off offset:256
	v_mul_f32_e32 v132, 0xbfb8aa3b, v126
	v_mul_f32_e32 v135, 0xbfb8aa3b, v127
	v_mul_f32_e32 v133, 0xbfb8aa3b, v122
	v_mul_f32_e32 v156, 0xbfb8aa3b, v129
	v_mul_f32_e32 v157, 0xbfb8aa3b, v125
	v_exp_f32_e32 v163, v132
	v_exp_f32_e32 v135, v135
	v_lshlrev_b64 v[130:131], 12, v[130:131]
	v_exp_f32_e32 v184, v133
	v_exp_f32_e32 v185, v156
	v_exp_f32_e32 v186, v157
	v_lshl_add_u64 v[156:157], v[150:151], 0, v[130:131]
	global_load_dwordx4 v[180:183], v[156:157], off
	global_load_dwordx4 v[130:133], v[156:157], off offset:256
	v_add_f32_e32 v163, 1.0, v163
	v_add_f32_e32 v135, 1.0, v135
	v_add_f32_e32 v187, 1.0, v184
	v_add_f32_e32 v189, 1.0, v185
	v_rcp_f32_e32 v184, v163
	v_rcp_f32_e32 v185, v135
	v_mul_f32_e32 v137, 0xbfb8aa3b, v123
	v_mul_f32_e32 v147, 0xbfb8aa3b, v124
	v_exp_f32_e32 v137, v137
	v_pk_mul_f32 v[184:185], v[126:127], v[184:185]
	v_exp_f32_e32 v147, v147
	v_mov_b64_e32 v[148:149], s[38:39]
	v_mul_f32_e32 v139, 0xbfb8aa3b, v128
	v_exp_f32_e32 v139, v139
	v_add_f32_e32 v137, 1.0, v137
	v_add_f32_e32 v147, 1.0, v147
	v_add_f32_e32 v191, 1.0, v186
	v_rcp_f32_e32 v186, v187
	v_rcp_f32_e32 v187, v137
	v_rcp_f32_e32 v190, v147
	v_rcp_f32_e32 v191, v191
	v_add_f32_e32 v139, 1.0, v139
	v_rcp_f32_e32 v188, v139
	v_rcp_f32_e32 v189, v189
	v_pk_mul_f32 v[124:125], v[124:125], v[190:191]
	v_pk_mul_f32 v[122:123], v[122:123], v[186:187]
	v_pk_mul_f32 v[128:129], v[128:129], v[188:189]
	s_waitcnt vmcnt(0)
	v_lshlrev_b32_e32 v192, 16, v166
	v_mov_b32_e32 v126, v169
	v_mov_b32_e32 v127, v170
	v_mov_b32_e32 v169, v171
	v_pk_add_f32 v[126:127], v[126:127], v[168:169]
	v_and_b32_e32 v193, 0xffff0000, v166
	v_mov_b32_e32 v170, v173
	v_mov_b32_e32 v171, v174
	v_mov_b32_e32 v173, v175
	v_pk_add_f32 v[168:169], v[170:171], v[172:173]
	v_pk_add_f32 v[126:127], v[126:127], v[126:127] op_sel:[0,1] op_sel_hi:[1,0]
	v_pk_add_f32 v[168:169], v[168:169], v[168:169] op_sel:[0,1] op_sel_hi:[1,0]
	v_mov_b32_e32 v127, v126
	v_mov_b32_e32 v135, v168
	s_nop 0
	v_permlane16_swap_b32_e32 v126, v127
	v_permlane16_swap_b32_e32 v168, v135
	v_add_f32_e32 v127, v126, v127
	v_add_f32_e32 v126, v168, v135
	v_mov_b32_e32 v169, v127
	v_mov_b32_e32 v168, v126
	s_nop 0
	v_permlane32_swap_b32_e32 v127, v169
	v_permlane32_swap_b32_e32 v126, v168
	v_pk_add_f32 v[126:127], v[126:127], v[168:169]
	v_lshlrev_b32_e32 v166, 16, v167
	v_pk_fma_f32 v[126:127], v[126:127], s[36:37], v[148:149] op_sel_hi:[1,0,0]
	v_and_b32_e32 v167, 0xffff0000, v167
	v_mul_f32_e32 v135, 0x4b800000, v127
	v_cmp_gt_f32_e32 vcc, s76, v127
	v_pk_mul_f32 v[122:123], v[122:123], v[192:193]
	v_pk_mul_f32 v[124:125], v[124:125], v[166:167]
	v_cndmask_b32_e32 v127, v127, v135, vcc
	v_rsq_f32_e32 v127, v127
	v_lshlrev_b32_e32 v188, 16, v164
	v_and_b32_e32 v189, 0xffff0000, v164
	v_lshlrev_b32_e32 v164, 16, v165
	v_mul_f32_e32 v135, 0x45800000, v127
	v_cndmask_b32_e32 v168, v127, v135, vcc
	v_and_b32_e32 v165, 0xffff0000, v165
	v_pk_mul_f32 v[166:167], v[124:125], v[168:169] op_sel_hi:[1,0]
	v_pk_mul_f32 v[124:125], v[122:123], v[168:169] op_sel_hi:[1,0]
	v_pk_mul_f32 v[128:129], v[128:129], v[164:165]
	v_cvt_pk_bf16_f32 v124, v124, v125
	v_mul_f32_e32 v125, 0xbfb8aa3b, v118
	v_pk_mul_f32 v[128:129], v[128:129], v[168:169] op_sel_hi:[1,0]
	v_exp_f32_e32 v127, v125
	v_mul_f32_e32 v125, 0xbfb8aa3b, v114
	v_cvt_pk_bf16_f32 v123, v128, v129
	v_exp_f32_e32 v129, v125
	v_add_f32_e32 v127, 1.0, v127
	v_mul_f32_e32 v137, 0x4b800000, v126
	v_cmp_gt_f32_e64 s[4:5], s76, v126
	v_rcp_f32_e32 v128, v127
	v_add_f32_e32 v127, 1.0, v129
	v_mul_f32_e32 v129, 0xbfb8aa3b, v119
	v_cndmask_b32_e64 v126, v126, v137, s[4:5]
	v_exp_f32_e32 v129, v129
	v_mul_f32_e32 v135, 0xbfb8aa3b, v115
	v_rsq_f32_e32 v126, v126
	v_exp_f32_e32 v135, v135
	v_pk_mul_f32 v[170:171], v[184:185], v[188:189]
	v_cvt_pk_bf16_f32 v125, v166, v167
	v_pk_mul_f32 v[164:165], v[170:171], v[168:169] op_sel_hi:[1,0]
	v_mul_f32_e32 v137, 0x45800000, v126
	v_cvt_pk_bf16_f32 v122, v164, v165
	v_rcp_f32_e32 v164, v127
	v_add_f32_e32 v127, 1.0, v129
	v_rcp_f32_e32 v129, v127
	v_add_f32_e32 v127, 1.0, v135
	v_mul_f32_e32 v135, 0xbfb8aa3b, v120
	v_cndmask_b32_e64 v126, v126, v137, s[4:5]
	v_exp_f32_e32 v135, v135
	v_mul_f32_e32 v137, 0xbfb8aa3b, v116
	v_exp_f32_e32 v137, v137
	v_rcp_f32_e32 v165, v127
	v_add_f32_e32 v127, 1.0, v135
	v_mul_f32_e32 v135, 0xbfb8aa3b, v121
	v_rcp_f32_e32 v166, v127
	v_add_f32_e32 v127, 1.0, v137
	v_exp_f32_e32 v135, v135
	v_mul_f32_e32 v137, 0xbfb8aa3b, v117
	v_exp_f32_e32 v137, v137
	v_rcp_f32_e32 v170, v127
	v_add_f32_e32 v127, 1.0, v135
	v_rcp_f32_e32 v167, v127
	v_add_f32_e32 v127, 1.0, v137
	v_rcp_f32_e32 v171, v127
	v_lshlrev_b32_e32 v172, 16, v176
	v_and_b32_e32 v173, 0xffff0000, v176
	v_lshlrev_b32_e32 v174, 16, v177
	v_and_b32_e32 v175, 0xffff0000, v177
	v_lshlrev_b32_e32 v176, 16, v178
	v_and_b32_e32 v177, 0xffff0000, v178
	v_lshlrev_b32_e32 v178, 16, v179
	v_and_b32_e32 v179, 0xffff0000, v179
	v_pk_mul_f32 v[116:117], v[116:117], v[170:171]
	v_pk_mul_f32 v[114:115], v[114:115], v[164:165]
	v_pk_mul_f32 v[118:119], v[118:119], v[128:129]
	v_pk_mul_f32 v[114:115], v[114:115], v[176:177]
	v_pk_mul_f32 v[116:117], v[116:117], v[178:179]
	v_pk_mul_f32 v[120:121], v[120:121], v[166:167]
	v_pk_mul_f32 v[118:119], v[118:119], v[172:173]
	v_pk_mul_f32 v[128:129], v[116:117], v[168:169] op_sel_hi:[1,0]
	v_pk_mul_f32 v[116:117], v[114:115], v[168:169] op_sel_hi:[1,0]
	v_pk_mul_f32 v[120:121], v[120:121], v[174:175]
	v_pk_mul_f32 v[118:119], v[118:119], v[168:169] op_sel_hi:[1,0]
	v_cvt_pk_bf16_f32 v116, v116, v117
	v_mul_f32_e32 v117, 0xbfb8aa3b, v110
	v_pk_mul_f32 v[120:121], v[120:121], v[168:169] op_sel_hi:[1,0]
	v_cvt_pk_bf16_f32 v114, v118, v119
	v_exp_f32_e32 v118, v117
	v_mul_f32_e32 v117, 0xbfb8aa3b, v106
	v_cvt_pk_bf16_f32 v115, v120, v121
	v_exp_f32_e32 v119, v117
	v_mul_f32_e32 v120, 0xbfb8aa3b, v111
	v_mul_f32_e32 v121, 0xbfb8aa3b, v107
	v_exp_f32_e32 v120, v120
	v_exp_f32_e32 v121, v121
	v_add_f32_e32 v119, 1.0, v119
	v_cvt_pk_bf16_f32 v117, v128, v129
	v_rcp_f32_e32 v128, v119
	v_add_f32_e32 v119, 1.0, v120
	v_add_f32_e32 v120, 1.0, v121
	v_mul_f32_e32 v121, 0xbfb8aa3b, v112
	v_mul_f32_e32 v127, 0xbfb8aa3b, v108
	v_exp_f32_e32 v121, v121
	v_exp_f32_e32 v127, v127
	v_rcp_f32_e32 v129, v120
	v_add_f32_e32 v118, 1.0, v118
	v_add_f32_e32 v120, 1.0, v121
	v_add_f32_e32 v121, 1.0, v127
	v_mul_f32_e32 v127, 0xbfb8aa3b, v113
	v_exp_f32_e32 v127, v127
	v_rcp_f32_e32 v164, v121
	v_rcp_f32_e32 v118, v118
	v_rcp_f32_e32 v119, v119
	v_add_f32_e32 v121, 1.0, v127
	v_rcp_f32_e32 v120, v120
	v_rcp_f32_e32 v121, v121
	v_add_u32_e32 v174, 48, v146
	v_add_u32_e32 v176, 32, v146
	v_lshlrev_b32_e32 v166, 16, v180
	v_and_b32_e32 v167, 0xffff0000, v180
	v_lshlrev_b32_e32 v168, 16, v181
	v_and_b32_e32 v169, 0xffff0000, v181
	v_pk_mul_f32 v[112:113], v[112:113], v[120:121]
	v_pk_mul_f32 v[110:111], v[110:111], v[118:119]
	v_ashrrev_i32_e32 v175, 31, v174
	v_ashrrev_i32_e32 v177, 31, v176
	v_pk_mul_f32 v[166:167], v[110:111], v[166:167]
	v_pk_mul_f32 v[168:169], v[112:113], v[168:169]
	v_lshlrev_b64 v[110:111], 8, v[174:175]
	v_lshlrev_b64 v[112:113], 8, v[176:177]
	v_lshl_add_u64 v[110:111], v[152:153], 0, v[110:111]
	v_lshl_add_u64 v[118:119], v[152:153], 0, v[112:113]
	global_load_dwordx4 v[110:113], v[110:111], off
	s_nop 0
	global_load_dwordx4 v[118:121], v[118:119], off
	v_mul_f32_e32 v135, 0xbfb8aa3b, v109
	v_exp_f32_e32 v135, v135
	v_lshlrev_b32_e32 v170, 16, v182
	v_and_b32_e32 v171, 0xffff0000, v182
	v_lshlrev_b32_e32 v172, 16, v183
	v_add_f32_e32 v127, 1.0, v135
	v_rcp_f32_e32 v165, v127
	v_and_b32_e32 v173, 0xffff0000, v183
	v_pk_mul_f32 v[106:107], v[106:107], v[128:129]
	v_pk_mul_f32 v[166:167], v[166:167], v[126:127] op_sel_hi:[1,0]
	v_pk_mul_f32 v[108:109], v[108:109], v[164:165]
	v_pk_mul_f32 v[106:107], v[106:107], v[170:171]
	v_pk_mul_f32 v[108:109], v[108:109], v[172:173]
	v_pk_mul_f32 v[106:107], v[106:107], v[126:127] op_sel_hi:[1,0]
	v_pk_mul_f32 v[108:109], v[108:109], v[126:127] op_sel_hi:[1,0]
	v_cvt_pk_bf16_f32 v164, v166, v167
	v_cvt_pk_bf16_f32 v166, v106, v107
	v_mul_f32_e32 v107, 0xbfb8aa3b, v98
	v_cvt_pk_bf16_f32 v167, v108, v109
	v_mul_f32_e32 v108, 0xbfb8aa3b, v103
	v_exp_f32_e32 v107, v107
	v_exp_f32_e32 v109, v108
	v_mul_f32_e32 v108, 0xbfb8aa3b, v99
	v_pk_mul_f32 v[168:169], v[168:169], v[126:127] op_sel_hi:[1,0]
	v_exp_f32_e32 v127, v108
	v_add_f32_e32 v107, 1.0, v107
	v_rcp_f32_e32 v108, v107
	v_add_f32_e32 v107, 1.0, v109
	v_add_f32_e32 v109, 1.0, v127
	v_mul_f32_e32 v127, 0xbfb8aa3b, v104
	v_exp_f32_e32 v127, v127
	v_mul_f32_e32 v128, 0xbfb8aa3b, v100
	v_exp_f32_e32 v129, v128
	v_mul_f32_e32 v106, 0xbfb8aa3b, v102
	v_add_f32_e32 v127, 1.0, v127
	v_rcp_f32_e32 v128, v127
	v_add_f32_e32 v127, 1.0, v129
	v_mul_f32_e32 v129, 0xbfb8aa3b, v105
	v_exp_f32_e32 v129, v129
	v_mul_f32_e32 v135, 0xbfb8aa3b, v101
	v_exp_f32_e32 v106, v106
	v_exp_f32_e32 v135, v135
	v_rcp_f32_e32 v109, v109
	v_cvt_pk_bf16_f32 v165, v168, v169
	v_rcp_f32_e32 v168, v127
	v_add_f32_e32 v127, 1.0, v129
	v_add_f32_e32 v106, 1.0, v106
	v_rcp_f32_e32 v129, v127
	v_add_f32_e32 v127, 1.0, v135
	v_rcp_f32_e32 v106, v106
	v_rcp_f32_e32 v107, v107
	v_rcp_f32_e32 v169, v127
	v_lshlrev_b32_e32 v172, 16, v132
	v_and_b32_e32 v173, 0xffff0000, v132
	v_pk_mul_f32 v[98:99], v[98:99], v[108:109]
	v_pk_mul_f32 v[104:105], v[104:105], v[128:129]
	v_pk_mul_f32 v[98:99], v[98:99], v[172:173]
	v_lshlrev_b32_e32 v170, 16, v130
	v_pk_mul_f32 v[98:99], v[98:99], v[126:127] op_sel_hi:[1,0]
	v_and_b32_e32 v171, 0xffff0000, v130
	v_cvt_pk_bf16_f32 v128, v98, v99
	v_lshlrev_b64 v[98:99], 12, v[176:177]
	v_lshlrev_b32_e32 v130, 16, v131
	v_and_b32_e32 v131, 0xffff0000, v131
	v_lshlrev_b32_e32 v132, 16, v133
	v_and_b32_e32 v133, 0xffff0000, v133
	v_pk_mul_f32 v[102:103], v[102:103], v[106:107]
	v_pk_mul_f32 v[100:101], v[100:101], v[168:169]
	v_lshl_add_u64 v[108:109], v[150:151], 0, v[98:99]
	v_pk_mul_f32 v[102:103], v[102:103], v[170:171]
	v_pk_mul_f32 v[104:105], v[104:105], v[130:131]
	v_pk_mul_f32 v[100:101], v[100:101], v[132:133]
	global_load_dwordx4 v[130:133], v[108:109], off offset:256
	global_load_dwordx4 v[168:171], v[108:109], off
	v_lshlrev_b64 v[98:99], 12, v[174:175]
	v_pk_mul_f32 v[104:105], v[104:105], v[126:127] op_sel_hi:[1,0]
	v_pk_mul_f32 v[102:103], v[102:103], v[126:127] op_sel_hi:[1,0]
	v_pk_mul_f32 v[100:101], v[100:101], v[126:127] op_sel_hi:[1,0]
	v_lshl_add_u64 v[106:107], v[150:151], 0, v[98:99]
	v_cvt_pk_bf16_f32 v126, v102, v103
	v_cvt_pk_bf16_f32 v127, v104, v105
	v_cvt_pk_bf16_f32 v129, v100, v101
	global_load_dwordx4 v[98:101], v[106:107], off offset:256
	global_load_dwordx4 v[102:105], v[106:107], off
	s_nop 0
	global_store_dwordx4 v[154:155], v[122:125], off nt
	global_store_dwordx4 v[154:155], v[114:117], off offset:256 nt
	global_store_dwordx4 v[156:157], v[164:167], off nt
	global_store_dwordx4 v[156:157], v[126:129], off offset:256 nt
	s_waitcnt vmcnt(0)
	v_mov_b32_e32 v114, v119
	v_mov_b32_e32 v115, v120
	v_mov_b32_e32 v119, v121
	v_pk_add_f32 v[114:115], v[114:115], v[118:119]
	v_mov_b32_e32 v118, v111
	v_mov_b32_e32 v119, v112
	v_mov_b32_e32 v111, v113
	v_pk_add_f32 v[110:111], v[118:119], v[110:111]
	v_pk_add_f32 v[114:115], v[114:115], v[114:115] op_sel:[0,1] op_sel_hi:[1,0]
	v_pk_add_f32 v[110:111], v[110:111], v[110:111] op_sel:[0,1] op_sel_hi:[1,0]
	v_mov_b32_e32 v115, v114
	v_mov_b32_e32 v111, v110
	s_nop 0
	v_permlane16_swap_b32_e32 v114, v115
	v_permlane16_swap_b32_e32 v110, v111
	v_add_f32_e32 v115, v114, v115
	v_add_f32_e32 v114, v110, v111
	v_mov_b32_e32 v117, v115
	v_mov_b32_e32 v116, v114
	s_nop 0
	v_permlane32_swap_b32_e32 v115, v117
	v_permlane32_swap_b32_e32 v114, v116
	v_pk_add_f32 v[110:111], v[114:115], v[116:117]
	v_mul_f32_e32 v113, 0xbfb8aa3b, v94
	v_pk_fma_f32 v[110:111], v[110:111], s[36:37], v[148:149] op_sel_hi:[1,0,0]
	v_exp_f32_e32 v113, v113
	v_mul_f32_e32 v112, 0x4b800000, v111
	v_cmp_gt_f32_e32 vcc, s76, v111
	v_cmp_gt_f32_e64 s[4:5], s76, v110
	v_mul_f32_e32 v114, 0xbfb8aa3b, v90
	v_cndmask_b32_e32 v111, v111, v112, vcc
	v_mul_f32_e32 v112, 0x4b800000, v110
	v_rsq_f32_e32 v111, v111
	v_cndmask_b32_e64 v110, v110, v112, s[4:5]
	v_rsq_f32_e32 v110, v110
	v_exp_f32_e32 v115, v114
	v_mul_f32_e32 v112, 0x45800000, v111
	v_cndmask_b32_e32 v112, v111, v112, vcc
	v_mul_f32_e32 v111, 0x45800000, v110
	v_cndmask_b32_e64 v110, v110, v111, s[4:5]
	v_add_f32_e32 v111, 1.0, v113
	v_mul_f32_e32 v113, 0xbfb8aa3b, v95
	v_rcp_f32_e32 v114, v111
	v_add_f32_e32 v111, 1.0, v115
	v_exp_f32_e32 v113, v113
	v_mul_f32_e32 v115, 0xbfb8aa3b, v91
	v_exp_f32_e32 v117, v115
	v_rcp_f32_e32 v116, v111
	v_add_f32_e32 v111, 1.0, v113
	v_mul_f32_e32 v113, 0xbfb8aa3b, v96
	v_rcp_f32_e32 v115, v111
	v_add_f32_e32 v111, 1.0, v117
	v_exp_f32_e32 v113, v113
	v_mul_f32_e32 v117, 0xbfb8aa3b, v92
	v_exp_f32_e32 v119, v117
	v_rcp_f32_e32 v117, v111
	v_add_f32_e32 v111, 1.0, v113
	v_mul_f32_e32 v113, 0xbfb8aa3b, v97
	v_rcp_f32_e32 v118, v111
	v_add_f32_e32 v111, 1.0, v119
	v_exp_f32_e32 v113, v113
	v_mul_f32_e32 v119, 0xbfb8aa3b, v93
	v_exp_f32_e32 v121, v119
	v_rcp_f32_e32 v120, v111
	v_add_f32_e32 v111, 1.0, v113
	v_rcp_f32_e32 v119, v111
	v_add_f32_e32 v111, 1.0, v121
	v_rcp_f32_e32 v121, v111
	v_lshlrev_b32_e32 v126, 16, v170
	v_and_b32_e32 v127, 0xffff0000, v170
	v_lshlrev_b32_e32 v128, 16, v171
	v_and_b32_e32 v129, 0xffff0000, v171
	v_pk_mul_f32 v[92:93], v[92:93], v[120:121]
	v_pk_mul_f32 v[90:91], v[90:91], v[116:117]
	v_lshlrev_b32_e32 v122, 16, v168
	v_and_b32_e32 v123, 0xffff0000, v168
	v_lshlrev_b32_e32 v124, 16, v169
	v_and_b32_e32 v125, 0xffff0000, v169
	v_pk_mul_f32 v[96:97], v[96:97], v[118:119]
	v_pk_mul_f32 v[94:95], v[94:95], v[114:115]
	v_pk_mul_f32 v[90:91], v[90:91], v[126:127]
	v_pk_mul_f32 v[92:93], v[92:93], v[128:129]
	v_pk_mul_f32 v[94:95], v[94:95], v[122:123]
	v_pk_mul_f32 v[96:97], v[96:97], v[124:125]
	v_pk_mul_f32 v[114:115], v[92:93], v[112:113] op_sel_hi:[1,0]
	v_pk_mul_f32 v[92:93], v[90:91], v[112:113] op_sel_hi:[1,0]
	v_pk_mul_f32 v[96:97], v[96:97], v[112:113] op_sel_hi:[1,0]
	v_pk_mul_f32 v[94:95], v[94:95], v[112:113] op_sel_hi:[1,0]
	v_cvt_pk_bf16_f32 v92, v92, v93
	v_mul_f32_e32 v93, 0xbfb8aa3b, v86
	v_cvt_pk_bf16_f32 v90, v94, v95
	v_cvt_pk_bf16_f32 v91, v96, v97
	v_exp_f32_e32 v94, v93
	v_mul_f32_e32 v93, 0xbfb8aa3b, v82
	v_mul_f32_e32 v96, 0xbfb8aa3b, v87
	v_exp_f32_e32 v95, v93
	v_exp_f32_e32 v97, v96
	v_mul_f32_e32 v96, 0xbfb8aa3b, v83
	v_exp_f32_e32 v111, v96
	v_add_f32_e32 v95, 1.0, v95
	v_rcp_f32_e32 v96, v95
	v_add_f32_e32 v95, 1.0, v97
	v_add_f32_e32 v97, 1.0, v111
	v_mul_f32_e32 v111, 0xbfb8aa3b, v88
	v_exp_f32_e32 v111, v111
	v_mul_f32_e32 v113, 0xbfb8aa3b, v84
	v_exp_f32_e32 v113, v113
	v_cvt_pk_bf16_f32 v93, v114, v115
	v_add_f32_e32 v111, 1.0, v111
	v_rcp_f32_e32 v114, v111
	v_add_f32_e32 v111, 1.0, v113
	v_mul_f32_e32 v113, 0xbfb8aa3b, v89
	v_exp_f32_e32 v113, v113
	v_mul_f32_e32 v115, 0xbfb8aa3b, v85
	v_exp_f32_e32 v117, v115
	v_rcp_f32_e32 v116, v111
	v_add_f32_e32 v111, 1.0, v113
	v_rcp_f32_e32 v115, v111
	v_add_f32_e32 v111, 1.0, v117
	v_add_f32_e32 v94, 1.0, v94
	v_rcp_f32_e32 v97, v97
	v_rcp_f32_e32 v117, v111
	v_rcp_f32_e32 v94, v94
	v_rcp_f32_e32 v95, v95
	v_lshlrev_b32_e32 v122, 16, v132
	v_and_b32_e32 v123, 0xffff0000, v132
	v_lshlrev_b32_e32 v124, 16, v133
	v_and_b32_e32 v125, 0xffff0000, v133
	v_pk_mul_f32 v[84:85], v[84:85], v[116:117]
	v_pk_mul_f32 v[82:83], v[82:83], v[96:97]
	v_lshlrev_b32_e32 v118, 16, v130
	v_and_b32_e32 v119, 0xffff0000, v130
	v_pk_mul_f32 v[86:87], v[86:87], v[94:95]
	v_pk_mul_f32 v[82:83], v[82:83], v[122:123]
	v_pk_mul_f32 v[84:85], v[84:85], v[124:125]
	v_lshlrev_b32_e32 v120, 16, v131
	v_and_b32_e32 v121, 0xffff0000, v131
	v_pk_mul_f32 v[88:89], v[88:89], v[114:115]
	v_pk_mul_f32 v[86:87], v[86:87], v[118:119]
	v_pk_mul_f32 v[94:95], v[84:85], v[112:113] op_sel_hi:[1,0]
	v_pk_mul_f32 v[84:85], v[82:83], v[112:113] op_sel_hi:[1,0]
	v_pk_mul_f32 v[88:89], v[88:89], v[120:121]
	v_pk_mul_f32 v[86:87], v[86:87], v[112:113] op_sel_hi:[1,0]
	v_cvt_pk_bf16_f32 v84, v84, v85
	v_mul_f32_e32 v85, 0xbfb8aa3b, v78
	v_pk_mul_f32 v[88:89], v[88:89], v[112:113] op_sel_hi:[1,0]
	v_cvt_pk_bf16_f32 v82, v86, v87
	v_exp_f32_e32 v86, v85
	v_mul_f32_e32 v85, 0xbfb8aa3b, v74
	v_cvt_pk_bf16_f32 v83, v88, v89
	v_exp_f32_e32 v87, v85
	v_mul_f32_e32 v88, 0xbfb8aa3b, v79
	v_mul_f32_e32 v89, 0xbfb8aa3b, v75
	v_exp_f32_e32 v88, v88
	v_exp_f32_e32 v89, v89
	v_add_f32_e32 v87, 1.0, v87
	v_cvt_pk_bf16_f32 v85, v94, v95
	v_rcp_f32_e32 v94, v87
	v_add_f32_e32 v87, 1.0, v88
	v_add_f32_e32 v88, 1.0, v89
	v_mul_f32_e32 v89, 0xbfb8aa3b, v80
	v_mul_f32_e32 v95, 0xbfb8aa3b, v76
	v_exp_f32_e32 v89, v89
	v_exp_f32_e32 v96, v95
	v_rcp_f32_e32 v95, v88
	v_add_f32_e32 v86, 1.0, v86
	v_add_f32_e32 v88, 1.0, v89
	v_add_f32_e32 v89, 1.0, v96
	v_mul_f32_e32 v96, 0xbfb8aa3b, v81
	v_exp_f32_e32 v97, v96
	v_mul_f32_e32 v96, 0xbfb8aa3b, v77
	v_exp_f32_e32 v111, v96
	v_rcp_f32_e32 v96, v89
	v_add_f32_e32 v89, 1.0, v97
	v_rcp_f32_e32 v86, v86
	v_rcp_f32_e32 v87, v87
	v_rcp_f32_e32 v88, v88
	v_rcp_f32_e32 v89, v89
	v_add_u32_e32 v116, 0x90, v146
	v_add_u32_e32 v118, 0x80, v146
	v_lshlrev_b32_e32 v112, 16, v102
	v_and_b32_e32 v113, 0xffff0000, v102
	v_lshlrev_b32_e32 v102, 16, v103
	v_and_b32_e32 v103, 0xffff0000, v103
	v_pk_mul_f32 v[80:81], v[80:81], v[88:89]
	v_pk_mul_f32 v[78:79], v[78:79], v[86:87]
	v_ashrrev_i32_e32 v117, 31, v116
	v_ashrrev_i32_e32 v119, 31, v118
	v_pk_mul_f32 v[112:113], v[78:79], v[112:113]
	v_pk_mul_f32 v[102:103], v[80:81], v[102:103]
	v_lshlrev_b64 v[78:79], 8, v[116:117]
	v_lshlrev_b64 v[80:81], 8, v[118:119]
	v_lshl_add_u64 v[78:79], v[152:153], 0, v[78:79]
	v_lshl_add_u64 v[86:87], v[152:153], 0, v[80:81]
	global_load_dwordx4 v[78:81], v[78:79], off
	s_nop 0
	global_load_dwordx4 v[86:89], v[86:87], off
	v_add_f32_e32 v97, 1.0, v111
	v_rcp_f32_e32 v97, v97
	v_lshlrev_b32_e32 v114, 16, v104
	v_and_b32_e32 v115, 0xffff0000, v104
	v_lshlrev_b32_e32 v104, 16, v105
	v_and_b32_e32 v105, 0xffff0000, v105
	v_pk_mul_f32 v[76:77], v[76:77], v[96:97]
	v_pk_mul_f32 v[74:75], v[74:75], v[94:95]
	v_pk_mul_f32 v[76:77], v[76:77], v[104:105]
	v_pk_mul_f32 v[74:75], v[74:75], v[114:115]
	v_pk_mul_f32 v[76:77], v[76:77], v[110:111] op_sel_hi:[1,0]
	v_pk_mul_f32 v[74:75], v[74:75], v[110:111] op_sel_hi:[1,0]
	v_cvt_pk_bf16_f32 v97, v76, v77
	v_cvt_pk_bf16_f32 v96, v74, v75
	v_mul_f32_e32 v75, 0xbfb8aa3b, v66
	v_mul_f32_e32 v76, 0xbfb8aa3b, v71
	v_pk_mul_f32 v[102:103], v[102:103], v[110:111] op_sel_hi:[1,0]
	v_exp_f32_e32 v75, v75
	v_exp_f32_e32 v77, v76
	v_mul_f32_e32 v76, 0xbfb8aa3b, v67
	v_cvt_pk_bf16_f32 v95, v102, v103
	v_exp_f32_e32 v102, v76
	v_mul_f32_e32 v103, 0xbfb8aa3b, v68
	v_mul_f32_e32 v104, 0xbfb8aa3b, v73
	v_add_f32_e32 v75, 1.0, v75
	v_exp_f32_e32 v103, v103
	v_exp_f32_e32 v105, v104
	v_mul_f32_e32 v104, 0xbfb8aa3b, v69
	v_pk_mul_f32 v[112:113], v[112:113], v[110:111] op_sel_hi:[1,0]
	v_mul_f32_e32 v74, 0xbfb8aa3b, v70
	v_rcp_f32_e32 v76, v75
	v_add_f32_e32 v75, 1.0, v77
	v_add_f32_e32 v77, 1.0, v102
	v_mul_f32_e32 v102, 0xbfb8aa3b, v72
	v_exp_f32_e32 v111, v104
	v_exp_f32_e32 v74, v74
	v_exp_f32_e32 v102, v102
	v_rcp_f32_e32 v77, v77
	v_add_f32_e32 v103, 1.0, v103
	v_rcp_f32_e32 v104, v103
	v_add_f32_e32 v103, 1.0, v105
	v_add_f32_e32 v105, 1.0, v111
	v_add_f32_e32 v74, 1.0, v74
	v_add_f32_e32 v102, 1.0, v102
	v_rcp_f32_e32 v105, v105
	v_rcp_f32_e32 v74, v74
	v_rcp_f32_e32 v75, v75
	v_rcp_f32_e32 v102, v102
	v_rcp_f32_e32 v103, v103
	v_lshlrev_b32_e32 v114, 16, v100
	v_and_b32_e32 v115, 0xffff0000, v100
	v_pk_mul_f32 v[66:67], v[66:67], v[76:77]
	v_lshlrev_b32_e32 v100, 16, v101
	v_pk_mul_f32 v[66:67], v[66:67], v[114:115]
	v_and_b32_e32 v101, 0xffff0000, v101
	v_pk_mul_f32 v[68:69], v[68:69], v[104:105]
	v_pk_mul_f32 v[66:67], v[66:67], v[110:111] op_sel_hi:[1,0]
	v_cvt_pk_bf16_f32 v94, v112, v113
	v_lshlrev_b32_e32 v112, 16, v98
	v_and_b32_e32 v113, 0xffff0000, v98
	v_lshlrev_b32_e32 v98, 16, v99
	v_and_b32_e32 v99, 0xffff0000, v99
	v_pk_mul_f32 v[72:73], v[72:73], v[102:103]
	v_pk_mul_f32 v[70:71], v[70:71], v[74:75]
	v_pk_mul_f32 v[68:69], v[68:69], v[100:101]
	v_cvt_pk_bf16_f32 v100, v66, v67
	v_lshlrev_b64 v[66:67], 12, v[118:119]
	v_pk_mul_f32 v[70:71], v[70:71], v[112:113]
	v_pk_mul_f32 v[72:73], v[72:73], v[98:99]
	v_lshl_add_u64 v[74:75], v[150:151], 0, v[66:67]
	v_pk_mul_f32 v[72:73], v[72:73], v[110:111] op_sel_hi:[1,0]
	v_pk_mul_f32 v[70:71], v[70:71], v[110:111] op_sel_hi:[1,0]
	v_pk_mul_f32 v[68:69], v[68:69], v[110:111] op_sel_hi:[1,0]
	global_load_dwordx4 v[102:105], v[74:75], off offset:256
	global_load_dwordx4 v[110:113], v[74:75], off
	v_lshlrev_b64 v[66:67], 12, v[116:117]
	v_lshl_add_u64 v[76:77], v[150:151], 0, v[66:67]
	v_cvt_pk_bf16_f32 v98, v70, v71
	v_cvt_pk_bf16_f32 v99, v72, v73
	v_cvt_pk_bf16_f32 v101, v68, v69
	global_load_dwordx4 v[66:69], v[76:77], off offset:256
	global_load_dwordx4 v[70:73], v[76:77], off
	s_nop 0
	global_store_dwordx4 v[108:109], v[90:93], off nt
	global_store_dwordx4 v[108:109], v[82:85], off offset:256 nt
	global_store_dwordx4 v[106:107], v[94:97], off nt
	global_store_dwordx4 v[106:107], v[98:101], off offset:256 nt
	s_waitcnt vmcnt(0)
	v_mov_b32_e32 v82, v87
	v_mov_b32_e32 v83, v88
	v_mov_b32_e32 v87, v89
	v_pk_add_f32 v[82:83], v[82:83], v[86:87]
	v_mov_b32_e32 v86, v79
	v_mov_b32_e32 v87, v80
	v_mov_b32_e32 v79, v81
	v_pk_add_f32 v[78:79], v[86:87], v[78:79]
	v_pk_add_f32 v[82:83], v[82:83], v[82:83] op_sel:[0,1] op_sel_hi:[1,0]
	v_pk_add_f32 v[78:79], v[78:79], v[78:79] op_sel:[0,1] op_sel_hi:[1,0]
	v_mov_b32_e32 v83, v82
	v_mov_b32_e32 v79, v78
	s_nop 0
	v_permlane16_swap_b32_e32 v82, v83
	v_permlane16_swap_b32_e32 v78, v79
	v_add_f32_e32 v83, v82, v83
	v_add_f32_e32 v82, v78, v79
	v_mov_b32_e32 v85, v83
	v_mov_b32_e32 v84, v82
	s_nop 0
	v_permlane32_swap_b32_e32 v83, v85
	v_permlane32_swap_b32_e32 v82, v84
	v_pk_add_f32 v[78:79], v[82:83], v[84:85]
	v_mul_f32_e32 v81, 0xbfb8aa3b, v62
	v_pk_fma_f32 v[78:79], v[78:79], s[36:37], v[148:149] op_sel_hi:[1,0,0]
	v_exp_f32_e32 v81, v81
	v_mul_f32_e32 v80, 0x4b800000, v79
	v_cmp_gt_f32_e32 vcc, s76, v79
	v_cmp_gt_f32_e64 s[4:5], s76, v78
	v_mul_f32_e32 v82, 0xbfb8aa3b, v58
	v_cndmask_b32_e32 v79, v79, v80, vcc
	v_mul_f32_e32 v80, 0x4b800000, v78
	v_rsq_f32_e32 v79, v79
	v_cndmask_b32_e64 v78, v78, v80, s[4:5]
	v_rsq_f32_e32 v78, v78
	v_exp_f32_e32 v83, v82
	v_mul_f32_e32 v80, 0x45800000, v79
	v_cndmask_b32_e32 v80, v79, v80, vcc
	v_mul_f32_e32 v79, 0x45800000, v78
	v_cndmask_b32_e64 v78, v78, v79, s[4:5]
	v_add_f32_e32 v79, 1.0, v81
	v_mul_f32_e32 v81, 0xbfb8aa3b, v63
	v_rcp_f32_e32 v82, v79
	v_add_f32_e32 v79, 1.0, v83
	v_exp_f32_e32 v81, v81
	v_mul_f32_e32 v83, 0xbfb8aa3b, v59
	v_exp_f32_e32 v85, v83
	v_rcp_f32_e32 v84, v79
	v_add_f32_e32 v79, 1.0, v81
	v_mul_f32_e32 v81, 0xbfb8aa3b, v64
	v_rcp_f32_e32 v83, v79
	v_add_f32_e32 v79, 1.0, v85
	v_exp_f32_e32 v81, v81
	v_mul_f32_e32 v85, 0xbfb8aa3b, v60
	v_exp_f32_e32 v87, v85
	v_rcp_f32_e32 v85, v79
	v_add_f32_e32 v79, 1.0, v81
	v_mul_f32_e32 v81, 0xbfb8aa3b, v65
	v_rcp_f32_e32 v86, v79
	v_add_f32_e32 v79, 1.0, v87
	v_exp_f32_e32 v81, v81
	v_mul_f32_e32 v87, 0xbfb8aa3b, v61
	v_exp_f32_e32 v89, v87
	v_rcp_f32_e32 v88, v79
	v_add_f32_e32 v79, 1.0, v81
	v_rcp_f32_e32 v87, v79
	v_add_f32_e32 v79, 1.0, v89
	v_rcp_f32_e32 v89, v79
	v_pk_mul_f32 v[58:59], v[58:59], v[84:85]
	v_lshlrev_b32_e32 v94, 16, v112
	v_and_b32_e32 v95, 0xffff0000, v112
	v_lshlrev_b32_e32 v96, 16, v113
	v_and_b32_e32 v97, 0xffff0000, v113
	v_pk_mul_f32 v[60:61], v[60:61], v[88:89]
	v_lshlrev_b32_e32 v90, 16, v110
	v_and_b32_e32 v91, 0xffff0000, v110
	v_lshlrev_b32_e32 v92, 16, v111
	v_and_b32_e32 v93, 0xffff0000, v111
	v_pk_mul_f32 v[64:65], v[64:65], v[86:87]
	v_pk_mul_f32 v[62:63], v[62:63], v[82:83]
	v_pk_mul_f32 v[58:59], v[58:59], v[94:95]
	v_pk_mul_f32 v[60:61], v[60:61], v[96:97]
	v_pk_mul_f32 v[62:63], v[62:63], v[90:91]
	v_pk_mul_f32 v[64:65], v[64:65], v[92:93]
	v_pk_mul_f32 v[82:83], v[60:61], v[80:81] op_sel_hi:[1,0]
	v_pk_mul_f32 v[60:61], v[58:59], v[80:81] op_sel_hi:[1,0]
	v_pk_mul_f32 v[64:65], v[64:65], v[80:81] op_sel_hi:[1,0]
	v_pk_mul_f32 v[62:63], v[62:63], v[80:81] op_sel_hi:[1,0]
	v_cvt_pk_bf16_f32 v60, v60, v61
	v_mul_f32_e32 v61, 0xbfb8aa3b, v54
	v_cvt_pk_bf16_f32 v58, v62, v63
	v_cvt_pk_bf16_f32 v59, v64, v65
	v_exp_f32_e32 v62, v61
	v_mul_f32_e32 v61, 0xbfb8aa3b, v50
	v_mul_f32_e32 v64, 0xbfb8aa3b, v55
	v_exp_f32_e32 v63, v61
	v_exp_f32_e32 v65, v64
	v_mul_f32_e32 v64, 0xbfb8aa3b, v51
	v_exp_f32_e32 v79, v64
	v_add_f32_e32 v63, 1.0, v63
	v_rcp_f32_e32 v64, v63
	v_add_f32_e32 v63, 1.0, v65
	v_add_f32_e32 v65, 1.0, v79
	v_mul_f32_e32 v79, 0xbfb8aa3b, v56
	v_exp_f32_e32 v79, v79
	v_mul_f32_e32 v81, 0xbfb8aa3b, v52
	v_exp_f32_e32 v81, v81
	v_cvt_pk_bf16_f32 v61, v82, v83
	v_add_f32_e32 v79, 1.0, v79
	v_rcp_f32_e32 v82, v79
	v_add_f32_e32 v79, 1.0, v81
	v_mul_f32_e32 v81, 0xbfb8aa3b, v57
	v_exp_f32_e32 v81, v81
	v_mul_f32_e32 v83, 0xbfb8aa3b, v53
	v_exp_f32_e32 v85, v83
	v_rcp_f32_e32 v84, v79
	v_add_f32_e32 v79, 1.0, v81
	v_rcp_f32_e32 v83, v79
	v_add_f32_e32 v79, 1.0, v85
	v_add_f32_e32 v62, 1.0, v62
	v_rcp_f32_e32 v65, v65
	v_rcp_f32_e32 v85, v79
	v_rcp_f32_e32 v62, v62
	v_rcp_f32_e32 v63, v63
	v_lshlrev_b32_e32 v90, 16, v104
	v_and_b32_e32 v91, 0xffff0000, v104
	v_lshlrev_b32_e32 v92, 16, v105
	v_and_b32_e32 v93, 0xffff0000, v105
	v_pk_mul_f32 v[52:53], v[52:53], v[84:85]
	v_pk_mul_f32 v[50:51], v[50:51], v[64:65]
	v_lshlrev_b32_e32 v86, 16, v102
	v_and_b32_e32 v87, 0xffff0000, v102
	v_pk_mul_f32 v[54:55], v[54:55], v[62:63]
	v_pk_mul_f32 v[50:51], v[50:51], v[90:91]
	v_pk_mul_f32 v[52:53], v[52:53], v[92:93]
	v_lshlrev_b32_e32 v88, 16, v103
	v_and_b32_e32 v89, 0xffff0000, v103
	v_pk_mul_f32 v[56:57], v[56:57], v[82:83]
	v_pk_mul_f32 v[54:55], v[54:55], v[86:87]
	v_pk_mul_f32 v[62:63], v[52:53], v[80:81] op_sel_hi:[1,0]
	v_pk_mul_f32 v[52:53], v[50:51], v[80:81] op_sel_hi:[1,0]
	v_pk_mul_f32 v[56:57], v[56:57], v[88:89]
	v_pk_mul_f32 v[54:55], v[54:55], v[80:81] op_sel_hi:[1,0]
	v_cvt_pk_bf16_f32 v52, v52, v53
	v_mul_f32_e32 v53, 0xbfb8aa3b, v46
	v_pk_mul_f32 v[56:57], v[56:57], v[80:81] op_sel_hi:[1,0]
	v_cvt_pk_bf16_f32 v50, v54, v55
	v_exp_f32_e32 v54, v53
	v_mul_f32_e32 v53, 0xbfb8aa3b, v42
	v_cvt_pk_bf16_f32 v51, v56, v57
	v_exp_f32_e32 v55, v53
	v_mul_f32_e32 v56, 0xbfb8aa3b, v47
	v_mul_f32_e32 v57, 0xbfb8aa3b, v43
	v_exp_f32_e32 v56, v56
	v_exp_f32_e32 v57, v57
	v_add_f32_e32 v55, 1.0, v55
	v_cvt_pk_bf16_f32 v53, v62, v63
	v_rcp_f32_e32 v62, v55
	v_add_f32_e32 v55, 1.0, v56
	v_add_f32_e32 v56, 1.0, v57
	v_mul_f32_e32 v57, 0xbfb8aa3b, v48
	v_mul_f32_e32 v63, 0xbfb8aa3b, v44
	v_exp_f32_e32 v57, v57
	v_exp_f32_e32 v64, v63
	v_rcp_f32_e32 v63, v56
	v_add_f32_e32 v54, 1.0, v54
	v_add_f32_e32 v56, 1.0, v57
	v_add_f32_e32 v57, 1.0, v64
	v_mul_f32_e32 v64, 0xbfb8aa3b, v49
	v_exp_f32_e32 v65, v64
	v_mul_f32_e32 v64, 0xbfb8aa3b, v45
	v_exp_f32_e32 v79, v64
	v_rcp_f32_e32 v64, v57
	v_add_f32_e32 v57, 1.0, v65
	v_rcp_f32_e32 v54, v54
	v_rcp_f32_e32 v55, v55
	v_rcp_f32_e32 v56, v56
	v_rcp_f32_e32 v57, v57
	v_lshlrev_b32_e32 v80, 16, v70
	v_and_b32_e32 v81, 0xffff0000, v70
	v_lshlrev_b32_e32 v70, 16, v71
	v_and_b32_e32 v71, 0xffff0000, v71
	v_pk_mul_f32 v[48:49], v[48:49], v[56:57]
	v_pk_mul_f32 v[46:47], v[46:47], v[54:55]
	v_add_u32_e32 v84, 0xb0, v146
	v_add_u32_e32 v86, 0xa0, v146
	v_pk_mul_f32 v[80:81], v[46:47], v[80:81]
	v_pk_mul_f32 v[46:47], v[48:49], v[70:71]
	v_ashrrev_i32_e32 v85, 31, v84
	v_ashrrev_i32_e32 v87, 31, v86
	v_pk_mul_f32 v[70:71], v[46:47], v[78:79] op_sel_hi:[1,0]
	v_lshlrev_b64 v[46:47], 8, v[84:85]
	v_lshlrev_b64 v[48:49], 8, v[86:87]
	v_lshl_add_u64 v[46:47], v[152:153], 0, v[46:47]
	v_lshl_add_u64 v[54:55], v[152:153], 0, v[48:49]
	global_load_dwordx4 v[46:49], v[46:47], off
	s_nop 0
	global_load_dwordx4 v[54:57], v[54:55], off
	v_add_f32_e32 v65, 1.0, v79
	v_rcp_f32_e32 v65, v65
	v_lshlrev_b32_e32 v82, 16, v72
	v_and_b32_e32 v83, 0xffff0000, v72
	v_lshlrev_b32_e32 v72, 16, v73
	v_and_b32_e32 v73, 0xffff0000, v73
	v_pk_mul_f32 v[44:45], v[44:45], v[64:65]
	v_pk_mul_f32 v[42:43], v[42:43], v[62:63]
	v_pk_mul_f32 v[44:45], v[44:45], v[72:73]
	v_pk_mul_f32 v[42:43], v[42:43], v[82:83]
	v_pk_mul_f32 v[44:45], v[44:45], v[78:79] op_sel_hi:[1,0]
	v_pk_mul_f32 v[42:43], v[42:43], v[78:79] op_sel_hi:[1,0]
	v_cvt_pk_bf16_f32 v65, v44, v45
	v_cvt_pk_bf16_f32 v64, v42, v43
	v_mul_f32_e32 v43, 0xbfb8aa3b, v34
	v_mul_f32_e32 v44, 0xbfb8aa3b, v39
	v_exp_f32_e32 v43, v43
	v_exp_f32_e32 v45, v44
	v_mul_f32_e32 v44, 0xbfb8aa3b, v35
	v_cvt_pk_bf16_f32 v63, v70, v71
	v_exp_f32_e32 v70, v44
	v_add_f32_e32 v43, 1.0, v43
	v_rcp_f32_e32 v44, v43
	v_add_f32_e32 v43, 1.0, v45
	v_add_f32_e32 v45, 1.0, v70
	v_mul_f32_e32 v70, 0xbfb8aa3b, v40
	v_exp_f32_e32 v70, v70
	v_mul_f32_e32 v71, 0xbfb8aa3b, v36
	v_exp_f32_e32 v71, v71
	v_pk_mul_f32 v[80:81], v[80:81], v[78:79] op_sel_hi:[1,0]
	v_add_f32_e32 v70, 1.0, v70
	v_cvt_pk_bf16_f32 v62, v80, v81
	v_rcp_f32_e32 v80, v70
	v_add_f32_e32 v70, 1.0, v71
	v_rcp_f32_e32 v82, v70
	v_mul_f32_e32 v70, 0xbfb8aa3b, v41
	v_exp_f32_e32 v79, v70
	v_mul_f32_e32 v70, 0xbfb8aa3b, v37
	v_exp_f32_e32 v83, v70
	v_lshlrev_b64 v[70:71], 12, v[84:85]
	v_lshl_add_u64 v[152:153], v[150:151], 0, v[70:71]
	global_load_dwordx4 v[70:73], v[152:153], off offset:256
	v_mul_f32_e32 v42, 0xbfb8aa3b, v38
	v_exp_f32_e32 v42, v42
	v_add_f32_e32 v79, 1.0, v79
	v_rcp_f32_e32 v81, v79
	v_add_f32_e32 v79, 1.0, v83
	v_add_f32_e32 v42, 1.0, v42
	v_rcp_f32_e32 v42, v42
	v_rcp_f32_e32 v43, v43
	v_rcp_f32_e32 v45, v45
	v_rcp_f32_e32 v83, v79
	v_lshlrev_b32_e32 v84, 16, v66
	v_and_b32_e32 v85, 0xffff0000, v66
	v_lshlrev_b32_e32 v66, 16, v67
	v_and_b32_e32 v67, 0xffff0000, v67
	v_lshlrev_b32_e32 v88, 16, v68
	v_and_b32_e32 v89, 0xffff0000, v68
	v_lshlrev_b32_e32 v68, 16, v69
	v_and_b32_e32 v69, 0xffff0000, v69
	v_pk_mul_f32 v[40:41], v[40:41], v[80:81]
	v_pk_mul_f32 v[38:39], v[38:39], v[42:43]
	v_pk_mul_f32 v[36:37], v[36:37], v[82:83]
	v_pk_mul_f32 v[34:35], v[34:35], v[44:45]
	v_pk_mul_f32 v[38:39], v[38:39], v[84:85]
	v_pk_mul_f32 v[40:41], v[40:41], v[66:67]
	v_pk_mul_f32 v[34:35], v[34:35], v[88:89]
	v_pk_mul_f32 v[36:37], v[36:37], v[68:69]
	v_pk_mul_f32 v[40:41], v[40:41], v[78:79] op_sel_hi:[1,0]
	v_pk_mul_f32 v[38:39], v[38:39], v[78:79] op_sel_hi:[1,0]
	v_pk_mul_f32 v[36:37], v[36:37], v[78:79] op_sel_hi:[1,0]
	v_pk_mul_f32 v[34:35], v[34:35], v[78:79] op_sel_hi:[1,0]
	global_load_dwordx4 v[78:81], v[152:153], off
	v_cvt_pk_bf16_f32 v68, v34, v35
	v_lshlrev_b64 v[34:35], 12, v[86:87]
	v_lshl_add_u64 v[42:43], v[150:151], 0, v[34:35]
	v_cvt_pk_bf16_f32 v66, v38, v39
	v_cvt_pk_bf16_f32 v67, v40, v41
	v_cvt_pk_bf16_f32 v69, v36, v37
	global_load_dwordx4 v[38:41], v[42:43], off offset:256
	global_load_dwordx4 v[34:37], v[42:43], off
	s_nop 0
	global_store_dwordx4 v[74:75], v[58:61], off nt
	global_store_dwordx4 v[74:75], v[50:53], off offset:256 nt
	global_store_dwordx4 v[76:77], v[62:65], off nt
	global_store_dwordx4 v[76:77], v[66:69], off offset:256 nt
	s_waitcnt vmcnt(0)
	v_mov_b32_e32 v52, v47
	v_mov_b32_e32 v53, v48
	v_mov_b32_e32 v47, v49
	v_mov_b32_e32 v44, v55
	v_mov_b32_e32 v45, v56
	v_mov_b32_e32 v55, v57
	v_pk_add_f32 v[46:47], v[52:53], v[46:47]
	v_pk_add_f32 v[44:45], v[44:45], v[54:55]
	v_pk_add_f32 v[46:47], v[46:47], v[46:47] op_sel:[0,1] op_sel_hi:[1,0]
	v_pk_add_f32 v[44:45], v[44:45], v[44:45] op_sel:[0,1] op_sel_hi:[1,0]
	v_mul_f32_e32 v47, 0xbfb8aa3b, v30
	v_mov_b32_e32 v45, v44
	v_exp_f32_e32 v47, v47
	s_nop 0
	v_permlane16_swap_b32_e32 v44, v45
	v_add_f32_e32 v44, v44, v45
	v_mov_b32_e32 v45, v46
	s_nop 1
	v_permlane16_swap_b32_e32 v46, v45
	v_add_f32_e32 v45, v46, v45
	v_add_f32_e32 v46, 1.0, v47
	v_mul_f32_e32 v47, 0xbfb8aa3b, v31
	v_exp_f32_e32 v47, v47
	v_rcp_f32_e32 v46, v46
	v_mul_f32_e32 v53, 0xbfb8aa3b, v27
	v_exp_f32_e32 v53, v53
	v_add_f32_e32 v47, 1.0, v47
	v_rcp_f32_e32 v47, v47
	v_mul_f32_e32 v54, 0xbfb8aa3b, v28
	v_mul_f32_e32 v55, 0xbfb8aa3b, v29
	v_exp_f32_e32 v54, v54
	v_pk_mul_f32 v[30:31], v[30:31], v[46:47]
	v_mul_f32_e32 v47, 0xbfb8aa3b, v26
	v_exp_f32_e32 v52, v47
	v_exp_f32_e32 v55, v55
	v_add_f32_e32 v53, 1.0, v53
	v_add_f32_e32 v54, 1.0, v54
	v_add_f32_e32 v52, 1.0, v52
	v_rcp_f32_e32 v52, v52
	v_add_f32_e32 v55, 1.0, v55
	v_rcp_f32_e32 v53, v53
	v_rcp_f32_e32 v54, v54
	v_rcp_f32_e32 v55, v55
	v_lshlrev_b32_e32 v46, 16, v70
	v_and_b32_e32 v47, 0xffff0000, v70
	v_pk_mul_f32 v[30:31], v[30:31], v[46:47]
	v_pk_mul_f32 v[26:27], v[26:27], v[52:53]
	v_mul_f32_e32 v47, 0xbfb8aa3b, v22
	v_mul_f32_e32 v53, 0xbfb8aa3b, v23
	v_pk_mul_f32 v[28:29], v[28:29], v[54:55]
	v_exp_f32_e32 v52, v47
	v_exp_f32_e32 v53, v53
	v_mul_f32_e32 v54, 0xbfb8aa3b, v24
	v_mul_f32_e32 v55, 0xbfb8aa3b, v25
	v_mul_f32_e32 v48, 0xbfb8aa3b, v32
	v_mul_f32_e32 v49, 0xbfb8aa3b, v33
	v_exp_f32_e32 v54, v54
	v_exp_f32_e32 v55, v55
	v_exp_f32_e32 v48, v48
	v_exp_f32_e32 v49, v49
	v_add_f32_e32 v52, 1.0, v52
	v_add_f32_e32 v53, 1.0, v53
	v_rcp_f32_e32 v52, v52
	v_add_f32_e32 v54, 1.0, v54
	v_add_f32_e32 v55, 1.0, v55
	v_rcp_f32_e32 v53, v53
	v_add_f32_e32 v48, 1.0, v48
	v_add_f32_e32 v49, 1.0, v49
	v_rcp_f32_e32 v54, v54
	v_rcp_f32_e32 v55, v55
	v_rcp_f32_e32 v48, v48
	v_rcp_f32_e32 v49, v49
	v_lshlrev_b32_e32 v46, 16, v72
	v_and_b32_e32 v47, 0xffff0000, v72
	v_pk_mul_f32 v[26:27], v[26:27], v[46:47]
	v_pk_mul_f32 v[22:23], v[22:23], v[52:53]
	v_mul_f32_e32 v47, 0xbfb8aa3b, v18
	v_mul_f32_e32 v53, 0xbfb8aa3b, v19
	v_mov_b32_e32 v50, v44
	v_mov_b32_e32 v51, v45
	v_pk_mul_f32 v[24:25], v[24:25], v[54:55]
	v_exp_f32_e32 v52, v47
	v_exp_f32_e32 v53, v53
	v_mul_f32_e32 v54, 0xbfb8aa3b, v20
	v_mul_f32_e32 v55, 0xbfb8aa3b, v21
	v_permlane32_swap_b32_e32 v44, v50
	v_permlane32_swap_b32_e32 v45, v51
	v_pk_mul_f32 v[32:33], v[32:33], v[48:49]
	v_lshlrev_b32_e32 v48, 16, v71
	v_and_b32_e32 v49, 0xffff0000, v71
	v_exp_f32_e32 v54, v54
	v_exp_f32_e32 v55, v55
	v_pk_mul_f32 v[32:33], v[32:33], v[48:49]
	v_lshlrev_b32_e32 v48, 16, v73
	v_and_b32_e32 v49, 0xffff0000, v73
	v_pk_add_f32 v[44:45], v[44:45], v[50:51]
	v_pk_mul_f32 v[28:29], v[28:29], v[48:49]
	v_lshlrev_b32_e32 v48, 16, v79
	v_and_b32_e32 v49, 0xffff0000, v79
	v_pk_fma_f32 v[44:45], v[44:45], s[36:37], v[148:149] op_sel_hi:[1,0,0]
	v_add_f32_e32 v52, 1.0, v52
	v_add_f32_e32 v53, 1.0, v53
	v_pk_mul_f32 v[24:25], v[24:25], v[48:49]
	v_mul_f32_e32 v49, 0x4b800000, v45
	v_cmp_gt_f32_e32 vcc, s76, v45
	v_rcp_f32_e32 v52, v52
	v_add_f32_e32 v54, 1.0, v54
	v_add_f32_e32 v55, 1.0, v55
	v_rcp_f32_e32 v53, v53
	v_cndmask_b32_e32 v45, v45, v49, vcc
	v_rcp_f32_e32 v54, v54
	v_rcp_f32_e32 v55, v55
	v_rsq_f32_e32 v45, v45
	v_lshlrev_b32_e32 v46, 16, v78
	v_and_b32_e32 v47, 0xffff0000, v78
	v_pk_mul_f32 v[22:23], v[22:23], v[46:47]
	v_pk_mul_f32 v[18:19], v[18:19], v[52:53]
	v_lshlrev_b32_e32 v46, 16, v80
	v_and_b32_e32 v47, 0xffff0000, v80
	v_pk_mul_f32 v[20:21], v[20:21], v[54:55]
	v_lshlrev_b32_e32 v48, 16, v81
	v_and_b32_e32 v49, 0xffff0000, v81
	v_pk_mul_f32 v[46:47], v[18:19], v[46:47]
	v_mul_f32_e32 v18, 0x45800000, v45
	v_pk_mul_f32 v[20:21], v[20:21], v[48:49]
	v_cndmask_b32_e32 v48, v45, v18, vcc
	v_pk_mul_f32 v[18:19], v[32:33], v[48:49] op_sel_hi:[1,0]
	v_cmp_gt_f32_e32 vcc, s76, v44
	v_cvt_pk_bf16_f32 v131, v18, v19
	v_pk_mul_f32 v[18:19], v[28:29], v[48:49] op_sel_hi:[1,0]
	v_pk_mul_f32 v[26:27], v[26:27], v[48:49] op_sel_hi:[1,0]
	v_cvt_pk_bf16_f32 v133, v18, v19
	v_pk_mul_f32 v[18:19], v[22:23], v[48:49] op_sel_hi:[1,0]
	v_pk_mul_f32 v[22:23], v[20:21], v[48:49] op_sel_hi:[1,0]
	v_pk_mul_f32 v[20:21], v[46:47], v[48:49] op_sel_hi:[1,0]
	v_cvt_pk_bf16_f32 v132, v26, v27
	v_cvt_pk_bf16_f32 v20, v20, v21
	v_cvt_pk_bf16_f32 v21, v22, v23
	v_mul_f32_e32 v23, 0xbfb8aa3b, v14
	v_exp_f32_e32 v23, v23
	v_mul_f32_e32 v22, 0x4b800000, v44
	v_cndmask_b32_e32 v22, v44, v22, vcc
	v_rsq_f32_e32 v26, v22
	v_add_f32_e32 v22, 1.0, v23
	v_mul_f32_e32 v23, 0xbfb8aa3b, v15
	v_exp_f32_e32 v23, v23
	v_pk_mul_f32 v[24:25], v[24:25], v[48:49] op_sel_hi:[1,0]
	v_cvt_pk_bf16_f32 v18, v18, v19
	v_cvt_pk_bf16_f32 v19, v24, v25
	v_add_f32_e32 v23, 1.0, v23
	v_rcp_f32_e32 v22, v22
	v_mul_f32_e32 v24, 0xbfb8aa3b, v16
	v_mul_f32_e32 v25, 0xbfb8aa3b, v17
	v_rcp_f32_e32 v23, v23
	v_exp_f32_e32 v24, v24
	v_exp_f32_e32 v25, v25
	v_mul_f32_e32 v27, 0x45800000, v26
	v_pk_mul_f32 v[14:15], v[14:15], v[22:23]
	v_lshlrev_b32_e32 v22, 16, v38
	v_and_b32_e32 v23, 0xffff0000, v38
	v_add_f32_e32 v24, 1.0, v24
	v_add_f32_e32 v25, 1.0, v25
	v_pk_mul_f32 v[14:15], v[14:15], v[22:23]
	v_mul_f32_e32 v22, 0xbfb8aa3b, v10
	v_mul_f32_e32 v23, 0xbfb8aa3b, v11
	v_rcp_f32_e32 v24, v24
	v_rcp_f32_e32 v25, v25
	v_exp_f32_e32 v22, v22
	v_exp_f32_e32 v23, v23
	v_cndmask_b32_e32 v26, v26, v27, vcc
	v_pk_mul_f32 v[16:17], v[16:17], v[24:25]
	v_lshlrev_b32_e32 v24, 16, v39
	v_and_b32_e32 v25, 0xffff0000, v39
	v_add_f32_e32 v22, 1.0, v22
	v_add_f32_e32 v23, 1.0, v23
	v_pk_mul_f32 v[16:17], v[16:17], v[24:25]
	v_rcp_f32_e32 v22, v22
	v_mul_f32_e32 v24, 0xbfb8aa3b, v12
	v_mul_f32_e32 v25, 0xbfb8aa3b, v13
	v_rcp_f32_e32 v23, v23
	v_exp_f32_e32 v24, v24
	v_exp_f32_e32 v25, v25
	v_pk_mul_f32 v[16:17], v[16:17], v[26:27] op_sel_hi:[1,0]
	v_pk_mul_f32 v[14:15], v[14:15], v[26:27] op_sel_hi:[1,0]
	v_pk_mul_f32 v[10:11], v[10:11], v[22:23]
	v_cvt_pk_bf16_f32 v14, v14, v15
	v_cvt_pk_bf16_f32 v15, v16, v17
	v_lshlrev_b32_e32 v16, 16, v40
	v_and_b32_e32 v17, 0xffff0000, v40
	v_add_f32_e32 v24, 1.0, v24
	v_add_f32_e32 v25, 1.0, v25
	v_pk_mul_f32 v[10:11], v[10:11], v[16:17]
	v_mul_f32_e32 v16, 0xbfb8aa3b, v6
	v_rcp_f32_e32 v24, v24
	v_rcp_f32_e32 v25, v25
	v_exp_f32_e32 v16, v16
	v_lshlrev_b32_e32 v22, 16, v41
	v_and_b32_e32 v23, 0xffff0000, v41
	v_pk_mul_f32 v[12:13], v[12:13], v[24:25]
	v_add_f32_e32 v16, 1.0, v16
	v_mul_f32_e32 v17, 0xbfb8aa3b, v8
	v_pk_mul_f32 v[12:13], v[12:13], v[22:23]
	v_rcp_f32_e32 v22, v16
	v_mul_f32_e32 v16, 0xbfb8aa3b, v7
	v_exp_f32_e32 v17, v17
	v_mul_f32_e32 v23, 0xbfb8aa3b, v9
	v_exp_f32_e32 v16, v16
	v_exp_f32_e32 v23, v23
	v_add_f32_e32 v17, 1.0, v17
	v_rcp_f32_e32 v24, v17
	v_add_f32_e32 v16, 1.0, v16
	v_add_f32_e32 v17, 1.0, v23
	v_rcp_f32_e32 v25, v17
	v_rcp_f32_e32 v23, v16
	v_pk_mul_f32 v[12:13], v[12:13], v[26:27] op_sel_hi:[1,0]
	v_pk_mul_f32 v[10:11], v[10:11], v[26:27] op_sel_hi:[1,0]
	v_cvt_pk_bf16_f32 v17, v12, v13
	v_cvt_pk_bf16_f32 v16, v10, v11
	v_pk_mul_f32 v[8:9], v[8:9], v[24:25]
	v_pk_mul_f32 v[6:7], v[6:7], v[22:23]
	v_lshlrev_b32_e32 v10, 16, v34
	v_and_b32_e32 v11, 0xffff0000, v34
	v_lshlrev_b32_e32 v12, 16, v35
	v_and_b32_e32 v13, 0xffff0000, v35
	v_pk_mul_f32 v[6:7], v[6:7], v[10:11]
	v_mul_f32_e32 v10, 0xbfb8aa3b, v2
	v_pk_mul_f32 v[8:9], v[8:9], v[12:13]
	v_mul_f32_e32 v11, 0xbfb8aa3b, v3
	v_mul_f32_e32 v12, 0xbfb8aa3b, v4
	v_mul_f32_e32 v13, 0xbfb8aa3b, v5
	v_exp_f32_e32 v10, v10
	v_exp_f32_e32 v11, v11
	v_exp_f32_e32 v12, v12
	v_exp_f32_e32 v13, v13
	v_add_f32_e32 v10, 1.0, v10
	v_add_f32_e32 v11, 1.0, v11
	v_add_f32_e32 v12, 1.0, v12
	v_add_f32_e32 v13, 1.0, v13
	v_rcp_f32_e32 v10, v10
	v_rcp_f32_e32 v12, v12
	v_rcp_f32_e32 v13, v13
	v_rcp_f32_e32 v11, v11
	v_pk_mul_f32 v[8:9], v[8:9], v[26:27] op_sel_hi:[1,0]
	v_pk_mul_f32 v[6:7], v[6:7], v[26:27] op_sel_hi:[1,0]
	v_pk_mul_f32 v[4:5], v[4:5], v[12:13]
	v_cvt_pk_bf16_f32 v6, v6, v7
	v_cvt_pk_bf16_f32 v7, v8, v9
	v_pk_mul_f32 v[2:3], v[2:3], v[10:11]
	v_lshlrev_b32_e32 v8, 16, v36
	v_and_b32_e32 v9, 0xffff0000, v36
	v_lshlrev_b32_e32 v10, 16, v37
	v_and_b32_e32 v11, 0xffff0000, v37
	v_pk_mul_f32 v[2:3], v[2:3], v[8:9]
	v_pk_mul_f32 v[4:5], v[4:5], v[10:11]
	v_pk_mul_f32 v[30:31], v[30:31], v[48:49] op_sel_hi:[1,0]
	v_pk_mul_f32 v[4:5], v[4:5], v[26:27] op_sel_hi:[1,0]
	v_pk_mul_f32 v[2:3], v[2:3], v[26:27] op_sel_hi:[1,0]
	v_cvt_pk_bf16_f32 v130, v30, v31
	v_cvt_pk_bf16_f32 v8, v2, v3
	v_cvt_pk_bf16_f32 v9, v4, v5
	global_store_dwordx4 v[42:43], v[6:9], off nt
	global_store_dwordx4 v[42:43], v[14:17], off offset:256 nt
	global_store_dwordx4 v[152:153], v[18:21], off nt
	s_andn2_b64 vcc, exec, s[2:3]
	s_mov_b64 s[0:1], -1
	global_store_dwordx4 v[152:153], v[130:133], off offset:256 nt
	s_cbranch_vccnz .LBB0_678

.LBB0_774:
	v_lshl_or_b32 v132, s53, 8, v179
	v_lshl_add_u32 v130, s34, 8, v1
	v_ashrrev_i32_e32 v133, 31, v132
	v_lshlrev_b64 v[166:167], 1, v[132:133]
	v_ashrrev_i32_e32 v131, 31, v130
	v_lshl_add_u64 v[168:169], s[12:13], 0, v[166:167]
	v_lshlrev_b64 v[170:171], 11, v[130:131]
	v_lshl_add_u64 v[132:133], v[168:169], 0, v[170:171]
	s_waitcnt vmcnt(8)
	v_mov_b32_e32 v184, v226
	v_mov_b32_e32 v185, v227
	v_mov_b32_e32 v186, v228
	v_mov_b32_e32 v187, v229
	v_mov_b32_e32 v188, v230
	v_mov_b32_e32 v189, v231
	v_mov_b32_e32 v190, v232
	v_mov_b32_e32 v191, v233
	v_or_b32_e32 v132, 16, v130
	v_or_b32_e32 v134, 32, v130
	v_or_b32_e32 v130, 48, v130
	v_ashrrev_i32_e32 v133, 31, v132
	v_ashrrev_i32_e32 v135, 31, v134
	v_ashrrev_i32_e32 v131, 31, v130
	v_lshlrev_b64 v[176:177], 11, v[132:133]
	v_lshlrev_b64 v[174:175], 11, v[134:135]
	v_lshlrev_b64 v[172:173], 11, v[130:131]
	v_lshl_add_u64 v[130:131], v[168:169], 0, v[176:177]
	v_lshl_add_u64 v[132:133], v[168:169], 0, v[174:175]
	v_lshl_add_u64 v[196:197], v[168:169], 0, v[172:173]
	v_mov_b32_e32 v192, v234
	v_mov_b32_e32 v193, v235
	v_mov_b32_e32 v194, v236
	v_mov_b32_e32 v195, v237
	v_mov_b32_e32 v146, v238
	v_mov_b32_e32 v147, v239
	v_mov_b32_e32 v148, v240
	v_mov_b32_e32 v149, v241
	v_mov_b32_e32 v142, v242
	v_mov_b32_e32 v143, v243
	v_mov_b32_e32 v144, v244
	v_mov_b32_e32 v145, v245
	v_mov_b32_e32 v138, v246
	v_mov_b32_e32 v139, v247
	v_mov_b32_e32 v140, v248
	v_mov_b32_e32 v141, v249
	v_mov_b32_e32 v134, v250
	v_mov_b32_e32 v135, v251
	v_mov_b32_e32 v136, v252
	v_mov_b32_e32 v137, v253
	s_nop 0
	v_mov_b32_e32 v130, v162
	v_mov_b32_e32 v131, v163
	v_mov_b32_e32 v132, v164
	v_mov_b32_e32 v133, v165
	s_andn2_b64 vcc, exec, s[2:3]
	s_mov_b64 s[0:1], -1
	s_waitcnt vmcnt(8)
	v_lshlrev_b32_e32 v183, 16, v184
	v_and_b32_e32 v184, 0xffff0000, v184
	v_lshlrev_b32_e32 v197, 16, v186
	v_lshlrev_b32_e32 v196, 16, v185
	v_and_b32_e32 v185, 0xffff0000, v185
	v_and_b32_e32 v186, 0xffff0000, v186
	v_lshlrev_b32_e32 v198, 16, v187
	v_and_b32_e32 v187, 0xffff0000, v187
	v_lshlrev_b32_e32 v202, 16, v191
	v_and_b32_e32 v203, 0xffff0000, v191
	v_mul_f32_e32 v183, 0xbfb8aa3b, v183
	v_mul_f32_e32 v191, 0xbfb8aa3b, v197
	v_mul_f32_e32 v184, 0xbfb8aa3b, v184
	v_lshlrev_b32_e32 v199, 16, v188
	v_and_b32_e32 v188, 0xffff0000, v188
	v_lshlrev_b32_e32 v200, 16, v189
	v_and_b32_e32 v201, 0xffff0000, v189
	v_lshlrev_b32_e32 v189, 16, v190
	v_mul_f32_e32 v186, 0xbfb8aa3b, v186
	v_mul_f32_e32 v196, 0xbfb8aa3b, v196
	v_mul_f32_e32 v197, 0xbfb8aa3b, v198
	v_mul_f32_e32 v185, 0xbfb8aa3b, v185
	v_mul_f32_e32 v187, 0xbfb8aa3b, v187
	v_exp_f32_e32 v183, v183
	v_exp_f32_e32 v191, v191
	v_exp_f32_e32 v184, v184
	v_mul_f32_e32 v189, 0xbfb8aa3b, v189
	v_mul_f32_e32 v188, 0xbfb8aa3b, v188
	v_exp_f32_e32 v186, v186
	v_exp_f32_e32 v196, v196
	v_exp_f32_e32 v197, v197
	v_exp_f32_e32 v185, v185
	v_exp_f32_e32 v187, v187
	v_and_b32_e32 v190, 0xffff0000, v190
	v_exp_f32_e32 v189, v189
	v_exp_f32_e32 v188, v188
	v_mul_f32_e32 v190, 0xbfb8aa3b, v190
	v_mul_f32_e32 v198, 0xbfb8aa3b, v199
	v_exp_f32_e32 v199, v190
	v_add_f32_e32 v183, 1.0, v183
	v_add_f32_e32 v190, 1.0, v191
	v_add_f32_e32 v191, 1.0, v184
	v_add_f32_e32 v204, 1.0, v186
	v_add_f32_e32 v196, 1.0, v196
	v_add_f32_e32 v197, 1.0, v197
	v_add_f32_e32 v205, 1.0, v185
	v_add_f32_e32 v206, 1.0, v187
	v_rcp_f32_e32 v184, v183
	v_rcp_f32_e32 v185, v191
	v_add_f32_e32 v207, 1.0, v189
	v_add_f32_e32 v208, 1.0, v188
	v_rcp_f32_e32 v186, v190
	v_rcp_f32_e32 v187, v204
	v_rcp_f32_e32 v188, v196
	v_rcp_f32_e32 v190, v197
	v_rcp_f32_e32 v189, v205
	v_rcp_f32_e32 v191, v206
	v_pk_mul_f32 v[126:127], v[126:127], v[184:185]
	v_exp_f32_e32 v198, v198
	v_pk_mul_f32 v[128:129], v[128:129], v[188:189]
	v_pk_mul_f32 v[184:185], v[124:125], v[190:191]
	v_pk_mul_f32 v[124:125], v[122:123], v[186:187]
	v_cvt_pk_bf16_f32 v122, v126, v127
	v_mul_f32_e32 v127, 0xbfb8aa3b, v202
	v_cvt_pk_bf16_f32 v123, v128, v129
	v_mul_f32_e32 v126, 0xbfb8aa3b, v200
	v_exp_f32_e32 v127, v127
	v_mul_f32_e32 v128, 0xbfb8aa3b, v201
	v_exp_f32_e32 v126, v126
	v_exp_f32_e32 v129, v128
	v_mul_f32_e32 v128, 0xbfb8aa3b, v203
	v_cvt_pk_bf16_f32 v124, v124, v125
	v_cvt_pk_bf16_f32 v125, v184, v185
	v_exp_f32_e32 v184, v128
	v_add_f32_e32 v127, 1.0, v127
	v_add_f32_e32 v126, 1.0, v126
	v_rcp_f32_e32 v128, v127
	v_add_f32_e32 v127, 1.0, v129
	v_add_f32_e32 v198, 1.0, v198
	v_add_f32_e32 v183, 1.0, v199
	v_rcp_f32_e32 v126, v126
	v_rcp_f32_e32 v127, v127
	v_add_f32_e32 v129, 1.0, v184
	v_rcp_f32_e32 v196, v198
	v_rcp_f32_e32 v198, v207
	v_rcp_f32_e32 v129, v129
	v_rcp_f32_e32 v199, v183
	v_pk_mul_f32 v[120:121], v[120:121], v[126:127]
	v_rcp_f32_e32 v197, v208
	v_pk_mul_f32 v[126:127], v[116:117], v[128:129]
	v_pk_mul_f32 v[116:117], v[114:115], v[198:199]
	v_cvt_pk_bf16_f32 v115, v120, v121
	v_lshlrev_b32_e32 v121, 16, v193
	v_cvt_pk_bf16_f32 v116, v116, v117
	v_cvt_pk_bf16_f32 v117, v126, v127
	v_and_b32_e32 v126, 0xffff0000, v194
	v_lshlrev_b32_e32 v128, 16, v195
	v_mul_f32_e32 v121, 0xbfb8aa3b, v121
	v_mul_f32_e32 v126, 0xbfb8aa3b, v126
	v_exp_f32_e32 v121, v121
	v_mul_f32_e32 v128, 0xbfb8aa3b, v128
	v_exp_f32_e32 v126, v126
	v_exp_f32_e32 v128, v128
	v_pk_mul_f32 v[118:119], v[118:119], v[196:197]
	v_and_b32_e32 v127, 0xffff0000, v193
	v_cvt_pk_bf16_f32 v114, v118, v119
	v_lshlrev_b32_e32 v118, 16, v192
	v_and_b32_e32 v119, 0xffff0000, v192
	v_lshlrev_b32_e32 v120, 16, v194
	v_and_b32_e32 v129, 0xffff0000, v195
	v_add_f32_e32 v121, 1.0, v121
	v_mul_f32_e32 v127, 0xbfb8aa3b, v127
	v_mul_f32_e32 v118, 0xbfb8aa3b, v118
	v_mul_f32_e32 v120, 0xbfb8aa3b, v120
	v_mul_f32_e32 v119, 0xbfb8aa3b, v119
	v_add_f32_e32 v183, 1.0, v126
	v_rcp_f32_e32 v126, v121
	v_add_f32_e32 v121, 1.0, v128
	v_exp_f32_e32 v127, v127
	v_mul_f32_e32 v128, 0xbfb8aa3b, v129
	v_exp_f32_e32 v118, v118
	v_exp_f32_e32 v120, v120
	v_exp_f32_e32 v119, v119
	v_exp_f32_e32 v129, v128
	v_rcp_f32_e32 v128, v121
	v_add_f32_e32 v121, 1.0, v127
	v_add_f32_e32 v118, 1.0, v118
	v_add_f32_e32 v120, 1.0, v120
	v_add_f32_e32 v119, 1.0, v119
	v_rcp_f32_e32 v127, v121
	v_add_f32_e32 v121, 1.0, v129
	v_rcp_f32_e32 v118, v118
	v_rcp_f32_e32 v120, v120
	v_rcp_f32_e32 v119, v119
	v_rcp_f32_e32 v129, v121
	v_rcp_f32_e32 v121, v183
	v_pk_mul_f32 v[112:113], v[112:113], v[126:127]
	v_pk_mul_f32 v[110:111], v[110:111], v[118:119]
	v_pk_mul_f32 v[118:119], v[108:109], v[128:129]
	v_pk_mul_f32 v[108:109], v[106:107], v[120:121]
	v_cvt_pk_bf16_f32 v107, v112, v113
	v_lshlrev_b32_e32 v113, 16, v147
	v_cvt_pk_bf16_f32 v108, v108, v109
	v_cvt_pk_bf16_f32 v109, v118, v119
	v_and_b32_e32 v118, 0xffff0000, v148
	v_lshlrev_b32_e32 v120, 16, v149
	v_mul_f32_e32 v113, 0xbfb8aa3b, v113
	v_mul_f32_e32 v118, 0xbfb8aa3b, v118
	v_exp_f32_e32 v113, v113
	v_mul_f32_e32 v120, 0xbfb8aa3b, v120
	v_exp_f32_e32 v118, v118
	v_exp_f32_e32 v120, v120
	v_and_b32_e32 v119, 0xffff0000, v147
	v_cvt_pk_bf16_f32 v106, v110, v111
	v_lshlrev_b32_e32 v110, 16, v146
	v_and_b32_e32 v111, 0xffff0000, v146
	v_lshlrev_b32_e32 v112, 16, v148
	v_and_b32_e32 v121, 0xffff0000, v149
	v_add_f32_e32 v113, 1.0, v113
	v_mul_f32_e32 v119, 0xbfb8aa3b, v119
	v_mul_f32_e32 v110, 0xbfb8aa3b, v110
	v_mul_f32_e32 v112, 0xbfb8aa3b, v112
	v_mul_f32_e32 v111, 0xbfb8aa3b, v111
	v_add_f32_e32 v126, 1.0, v118
	v_rcp_f32_e32 v118, v113
	v_add_f32_e32 v113, 1.0, v120
	v_exp_f32_e32 v119, v119
	v_mul_f32_e32 v120, 0xbfb8aa3b, v121
	v_exp_f32_e32 v110, v110
	v_exp_f32_e32 v112, v112
	v_exp_f32_e32 v111, v111
	v_exp_f32_e32 v121, v120
	v_rcp_f32_e32 v120, v113
	v_add_f32_e32 v113, 1.0, v119
	v_add_f32_e32 v110, 1.0, v110
	v_add_f32_e32 v112, 1.0, v112
	v_add_f32_e32 v111, 1.0, v111
	v_rcp_f32_e32 v119, v113
	v_add_f32_e32 v113, 1.0, v121
	v_rcp_f32_e32 v110, v110
	v_rcp_f32_e32 v112, v112
	v_rcp_f32_e32 v111, v111
	v_rcp_f32_e32 v121, v113
	v_rcp_f32_e32 v113, v126
	v_pk_mul_f32 v[104:105], v[104:105], v[118:119]
	v_pk_mul_f32 v[102:103], v[102:103], v[110:111]
	v_pk_mul_f32 v[110:111], v[100:101], v[120:121]
	v_pk_mul_f32 v[100:101], v[98:99], v[112:113]
	v_cvt_pk_bf16_f32 v99, v104, v105
	v_lshlrev_b32_e32 v105, 16, v143
	v_cvt_pk_bf16_f32 v100, v100, v101
	v_cvt_pk_bf16_f32 v101, v110, v111
	v_and_b32_e32 v110, 0xffff0000, v144
	v_lshlrev_b32_e32 v112, 16, v145
	v_mul_f32_e32 v105, 0xbfb8aa3b, v105
	v_mul_f32_e32 v110, 0xbfb8aa3b, v110
	v_exp_f32_e32 v105, v105
	v_mul_f32_e32 v112, 0xbfb8aa3b, v112
	v_exp_f32_e32 v110, v110
	v_exp_f32_e32 v112, v112
	v_and_b32_e32 v111, 0xffff0000, v143
	v_cvt_pk_bf16_f32 v98, v102, v103
	v_lshlrev_b32_e32 v102, 16, v142
	v_and_b32_e32 v103, 0xffff0000, v142
	v_lshlrev_b32_e32 v104, 16, v144
	v_and_b32_e32 v113, 0xffff0000, v145
	v_add_f32_e32 v105, 1.0, v105
	v_mul_f32_e32 v111, 0xbfb8aa3b, v111
	v_mul_f32_e32 v102, 0xbfb8aa3b, v102
	v_mul_f32_e32 v104, 0xbfb8aa3b, v104
	v_mul_f32_e32 v103, 0xbfb8aa3b, v103
	v_add_f32_e32 v118, 1.0, v110
	v_rcp_f32_e32 v110, v105
	v_add_f32_e32 v105, 1.0, v112
	v_exp_f32_e32 v111, v111
	v_mul_f32_e32 v112, 0xbfb8aa3b, v113
	v_exp_f32_e32 v102, v102
	v_exp_f32_e32 v104, v104
	v_exp_f32_e32 v103, v103
	v_exp_f32_e32 v113, v112
	v_rcp_f32_e32 v112, v105
	v_add_f32_e32 v105, 1.0, v111
	v_add_f32_e32 v102, 1.0, v102
	v_add_f32_e32 v104, 1.0, v104
	v_add_f32_e32 v103, 1.0, v103
	v_rcp_f32_e32 v111, v105
	v_add_f32_e32 v105, 1.0, v113
	v_rcp_f32_e32 v102, v102
	v_rcp_f32_e32 v104, v104
	v_rcp_f32_e32 v103, v103
	v_rcp_f32_e32 v113, v105
	v_rcp_f32_e32 v105, v118
	v_pk_mul_f32 v[96:97], v[96:97], v[110:111]
	v_pk_mul_f32 v[94:95], v[94:95], v[102:103]
	v_pk_mul_f32 v[102:103], v[92:93], v[112:113]
	v_pk_mul_f32 v[92:93], v[90:91], v[104:105]
	v_cvt_pk_bf16_f32 v91, v96, v97
	v_lshlrev_b32_e32 v97, 16, v139
	v_cvt_pk_bf16_f32 v92, v92, v93
	v_cvt_pk_bf16_f32 v93, v102, v103
	v_and_b32_e32 v102, 0xffff0000, v140
	v_lshlrev_b32_e32 v104, 16, v141
	v_mul_f32_e32 v97, 0xbfb8aa3b, v97
	v_mul_f32_e32 v102, 0xbfb8aa3b, v102
	v_exp_f32_e32 v97, v97
	v_mul_f32_e32 v104, 0xbfb8aa3b, v104
	v_exp_f32_e32 v102, v102
	v_exp_f32_e32 v104, v104
	v_and_b32_e32 v103, 0xffff0000, v139
	v_and_b32_e32 v105, 0xffff0000, v141
	v_add_f32_e32 v97, 1.0, v97
	v_mul_f32_e32 v103, 0xbfb8aa3b, v103
	v_cvt_pk_bf16_f32 v90, v94, v95
	v_lshlrev_b32_e32 v94, 16, v138
	v_and_b32_e32 v95, 0xffff0000, v138
	v_add_f32_e32 v110, 1.0, v102
	v_rcp_f32_e32 v102, v97
	v_add_f32_e32 v97, 1.0, v104
	v_exp_f32_e32 v103, v103
	v_mul_f32_e32 v104, 0xbfb8aa3b, v105
	v_mul_f32_e32 v94, 0xbfb8aa3b, v94
	v_mul_f32_e32 v95, 0xbfb8aa3b, v95
	v_exp_f32_e32 v105, v104
	v_lshlrev_b32_e32 v96, 16, v140
	v_exp_f32_e32 v94, v94
	v_exp_f32_e32 v95, v95
	v_mul_f32_e32 v96, 0xbfb8aa3b, v96
	v_exp_f32_e32 v96, v96
	v_rcp_f32_e32 v104, v97
	v_add_f32_e32 v97, 1.0, v103
	v_rcp_f32_e32 v103, v97
	v_add_f32_e32 v97, 1.0, v105
	v_add_f32_e32 v94, 1.0, v94
	v_add_f32_e32 v95, 1.0, v95
	v_rcp_f32_e32 v105, v97
	v_rcp_f32_e32 v94, v94
	v_rcp_f32_e32 v95, v95
	v_add_f32_e32 v96, 1.0, v96
	v_rcp_f32_e32 v96, v96
	v_rcp_f32_e32 v97, v110
	v_pk_mul_f32 v[84:85], v[84:85], v[104:105]
	v_pk_mul_f32 v[88:89], v[88:89], v[102:103]
	v_pk_mul_f32 v[86:87], v[86:87], v[94:95]
	v_cvt_pk_bf16_f32 v105, v84, v85
	v_lshlrev_b32_e32 v85, 16, v135
	v_cvt_pk_bf16_f32 v102, v86, v87
	v_cvt_pk_bf16_f32 v103, v88, v89
	v_and_b32_e32 v86, 0xffff0000, v136
	v_lshlrev_b32_e32 v88, 16, v137
	v_mul_f32_e32 v85, 0xbfb8aa3b, v85
	v_pk_mul_f32 v[82:83], v[82:83], v[96:97]
	v_and_b32_e32 v87, 0xffff0000, v135
	v_mul_f32_e32 v86, 0xbfb8aa3b, v86
	v_exp_f32_e32 v85, v85
	v_mul_f32_e32 v88, 0xbfb8aa3b, v88
	v_cvt_pk_bf16_f32 v104, v82, v83
	v_lshlrev_b32_e32 v82, 16, v134
	v_and_b32_e32 v83, 0xffff0000, v134
	v_exp_f32_e32 v86, v86
	v_exp_f32_e32 v88, v88
	v_mul_f32_e32 v87, 0xbfb8aa3b, v87
	v_mul_f32_e32 v82, 0xbfb8aa3b, v82
	v_mul_f32_e32 v83, 0xbfb8aa3b, v83
	v_exp_f32_e32 v87, v87
	v_exp_f32_e32 v82, v82
	v_exp_f32_e32 v83, v83
	v_and_b32_e32 v89, 0xffff0000, v137
	v_add_f32_e32 v85, 1.0, v85
	v_add_f32_e32 v94, 1.0, v86
	v_rcp_f32_e32 v86, v85
	v_add_f32_e32 v85, 1.0, v88
	v_mul_f32_e32 v88, 0xbfb8aa3b, v89
	v_exp_f32_e32 v89, v88
	v_rcp_f32_e32 v88, v85
	v_add_f32_e32 v85, 1.0, v87
	v_add_f32_e32 v82, 1.0, v82
	v_add_f32_e32 v83, 1.0, v83
	v_rcp_f32_e32 v87, v85
	v_rcp_f32_e32 v82, v82
	v_rcp_f32_e32 v83, v83
	v_add_f32_e32 v85, 1.0, v89
	v_pk_mul_f32 v[80:81], v[80:81], v[86:87]
	v_lshl_add_u64 v[86:87], v[170:171], 0, s[18:19]
	v_pk_mul_f32 v[78:79], v[78:79], v[82:83]
	v_lshl_add_u64 v[82:83], v[168:169], 0, v[86:87]
	global_load_dwordx4 v[110:113], v[82:83], off offset:256
	global_load_dwordx4 v[126:129], v[82:83], off
	v_rcp_f32_e32 v89, v85
	v_lshlrev_b32_e32 v84, 16, v136
	v_mul_f32_e32 v84, 0xbfb8aa3b, v84
	v_exp_f32_e32 v84, v84
	v_pk_mul_f32 v[76:77], v[76:77], v[88:89]
	v_cvt_pk_bf16_f32 v118, v78, v79
	v_cvt_pk_bf16_f32 v121, v76, v77
	v_lshlrev_b32_e32 v77, 16, v131
	v_cvt_pk_bf16_f32 v119, v80, v81
	v_and_b32_e32 v78, 0xffff0000, v132
	v_lshlrev_b32_e32 v80, 16, v133
	v_mul_f32_e32 v77, 0xbfb8aa3b, v77
	v_add_f32_e32 v84, 1.0, v84
	v_mul_f32_e32 v78, 0xbfb8aa3b, v78
	v_exp_f32_e32 v77, v77
	v_mul_f32_e32 v80, 0xbfb8aa3b, v80
	v_rcp_f32_e32 v84, v84
	v_rcp_f32_e32 v85, v94
	v_exp_f32_e32 v78, v78
	v_exp_f32_e32 v80, v80
	v_and_b32_e32 v79, 0xffff0000, v131
	v_lshlrev_b32_e32 v76, 16, v132
	v_and_b32_e32 v81, 0xffff0000, v133
	v_add_f32_e32 v77, 1.0, v77
	v_mul_f32_e32 v79, 0xbfb8aa3b, v79
	v_pk_mul_f32 v[74:75], v[74:75], v[84:85]
	v_mul_f32_e32 v76, 0xbfb8aa3b, v76
	v_add_f32_e32 v84, 1.0, v78
	v_rcp_f32_e32 v78, v77
	v_add_f32_e32 v77, 1.0, v80
	v_exp_f32_e32 v79, v79
	v_mul_f32_e32 v80, 0xbfb8aa3b, v81
	v_exp_f32_e32 v76, v76
	v_exp_f32_e32 v81, v80
	v_rcp_f32_e32 v80, v77
	v_add_f32_e32 v77, 1.0, v79
	v_add_f32_e32 v76, 1.0, v76
	v_rcp_f32_e32 v79, v77
	v_add_f32_e32 v77, 1.0, v81
	v_rcp_f32_e32 v76, v76
	v_rcp_f32_e32 v81, v77
	v_rcp_f32_e32 v77, v84
	v_lshl_add_u64 v[88:89], v[170:171], 0, s[20:21]
	v_cvt_pk_bf16_f32 v120, v74, v75
	v_lshlrev_b32_e32 v74, 16, v130
	v_pk_mul_f32 v[66:67], v[66:67], v[76:77]
	v_and_b32_e32 v75, 0xffff0000, v130
	v_cvt_pk_bf16_f32 v132, v66, v67
	v_lshl_add_u64 v[66:67], v[168:169], 0, v[88:89]
	global_load_dwordx4 v[134:137], v[66:67], off offset:256
	global_load_dwordx4 v[82:85], v[66:67], off
	v_mul_f32_e32 v74, 0xbfb8aa3b, v74
	v_mul_f32_e32 v75, 0xbfb8aa3b, v75
	v_exp_f32_e32 v74, v74
	v_exp_f32_e32 v75, v75
	v_lshl_add_u64 v[94:95], v[170:171], 0, s[22:23]
	v_lshl_add_u64 v[66:67], v[168:169], 0, v[94:95]
	v_add_f32_e32 v74, 1.0, v74
	v_add_f32_e32 v75, 1.0, v75
	v_rcp_f32_e32 v74, v74
	v_rcp_f32_e32 v75, v75
	v_lshl_add_u64 v[96:97], v[170:171], 0, s[8:9]
	v_lshl_add_u64 v[138:139], s[6:7], 0, v[170:171]
	v_pk_mul_f32 v[72:73], v[72:73], v[78:79]
	v_pk_mul_f32 v[70:71], v[70:71], v[74:75]
	v_pk_mul_f32 v[68:69], v[68:69], v[80:81]
	global_load_dwordx4 v[78:81], v[66:67], off offset:256
	global_load_dwordx4 v[74:77], v[66:67], off
	v_lshl_add_u64 v[66:67], v[168:169], 0, v[96:97]
	v_lshl_add_u64 v[138:139], v[138:139], 0, v[166:167]
	v_cvt_pk_bf16_f32 v130, v70, v71
	v_cvt_pk_bf16_f32 v131, v72, v73
	v_cvt_pk_bf16_f32 v133, v68, v69
	global_load_dwordx4 v[70:73], v[66:67], off offset:256
	s_nop 0
	global_load_dwordx4 v[66:69], v[66:67], off
	s_nop 0
	global_store_dwordx4 v[138:139], v[122:125], off nt
	global_store_dwordx4 v[138:139], v[114:117], off offset:256 nt
	s_nop 1
	v_lshl_add_u64 v[114:115], s[6:7], 0, v[176:177]
	v_lshl_add_u64 v[114:115], v[114:115], 0, v[166:167]
	global_store_dwordx4 v[114:115], v[106:109], off nt
	global_store_dwordx4 v[114:115], v[98:101], off offset:256 nt
	s_nop 1
	v_lshl_add_u64 v[98:99], s[6:7], 0, v[174:175]
	v_lshl_add_u64 v[98:99], v[98:99], 0, v[166:167]
	global_store_dwordx4 v[98:99], v[90:93], off nt
	global_store_dwordx4 v[98:99], v[102:105], off offset:256 nt
	s_waitcnt vmcnt(13)
	v_lshlrev_b32_e32 v98, 16, v111
	v_lshlrev_b32_e32 v92, 16, v110
	v_and_b32_e32 v93, 0xffff0000, v110
	v_and_b32_e32 v99, 0xffff0000, v111
	v_mul_f32_e32 v92, 0xbfb8aa3b, v92
	v_mul_f32_e32 v93, 0xbfb8aa3b, v93
	v_mul_f32_e32 v98, 0xbfb8aa3b, v98
	v_mul_f32_e32 v99, 0xbfb8aa3b, v99
	v_exp_f32_e32 v92, v92
	v_exp_f32_e32 v93, v93
	v_exp_f32_e32 v98, v98
	v_exp_f32_e32 v99, v99
	v_lshl_add_u64 v[90:91], s[6:7], 0, v[172:173]
	v_lshl_add_u64 v[90:91], v[90:91], 0, v[166:167]
	global_store_dwordx4 v[90:91], v[118:121], off nt
	v_lshlrev_b32_e32 v100, 16, v112
	global_store_dwordx4 v[90:91], v[130:133], off offset:256 nt
	v_and_b32_e32 v91, 0xffff0000, v112
	v_add_f32_e32 v92, 1.0, v92
	v_add_f32_e32 v93, 1.0, v93
	v_add_f32_e32 v98, 1.0, v98
	v_add_f32_e32 v99, 1.0, v99
	v_mul_f32_e32 v100, 0xbfb8aa3b, v100
	v_mul_f32_e32 v91, 0xbfb8aa3b, v91
	v_rcp_f32_e32 v92, v92
	v_rcp_f32_e32 v93, v93
	v_rcp_f32_e32 v98, v98
	v_rcp_f32_e32 v99, v99
	v_exp_f32_e32 v100, v100
	v_exp_f32_e32 v91, v91
	v_pk_mul_f32 v[62:63], v[62:63], v[92:93]
	v_pk_mul_f32 v[64:65], v[64:65], v[98:99]
	v_add_f32_e32 v90, 1.0, v100
	v_add_f32_e32 v91, 1.0, v91
	v_rcp_f32_e32 v90, v90
	v_rcp_f32_e32 v91, v91
	v_cvt_pk_bf16_f32 v62, v62, v63
	v_cvt_pk_bf16_f32 v63, v64, v65
	s_waitcnt vmcnt(14)
	v_lshlrev_b32_e32 v64, 16, v126
	v_mul_f32_e32 v64, 0xbfb8aa3b, v64
	v_exp_f32_e32 v65, v64
	v_and_b32_e32 v64, 0xffff0000, v126
	v_mul_f32_e32 v64, 0xbfb8aa3b, v64
	v_pk_mul_f32 v[58:59], v[58:59], v[90:91]
	v_exp_f32_e32 v90, v64
	v_lshlrev_b32_e32 v92, 16, v113
	v_and_b32_e32 v93, 0xffff0000, v113
	v_mul_f32_e32 v92, 0xbfb8aa3b, v92
	v_mul_f32_e32 v93, 0xbfb8aa3b, v93
	v_cvt_pk_bf16_f32 v64, v58, v59
	v_add_f32_e32 v58, 1.0, v65
	v_lshlrev_b32_e32 v65, 16, v127
	v_exp_f32_e32 v92, v92
	v_exp_f32_e32 v93, v93
	v_add_f32_e32 v59, 1.0, v90
	v_mul_f32_e32 v65, 0xbfb8aa3b, v65
	v_and_b32_e32 v90, 0xffff0000, v127
	v_exp_f32_e32 v65, v65
	v_mul_f32_e32 v90, 0xbfb8aa3b, v90
	v_exp_f32_e32 v91, v90
	v_rcp_f32_e32 v58, v58
	v_rcp_f32_e32 v59, v59
	v_add_f32_e32 v92, 1.0, v92
	v_add_f32_e32 v93, 1.0, v93
	v_rcp_f32_e32 v92, v92
	v_rcp_f32_e32 v93, v93
	v_add_f32_e32 v65, 1.0, v65
	v_rcp_f32_e32 v90, v65
	v_add_f32_e32 v65, 1.0, v91
	v_rcp_f32_e32 v91, v65
	v_lshlrev_b32_e32 v65, 16, v128
	v_pk_mul_f32 v[54:55], v[54:55], v[58:59]
	v_and_b32_e32 v59, 0xffff0000, v128
	v_mul_f32_e32 v65, 0xbfb8aa3b, v65
	v_mul_f32_e32 v59, 0xbfb8aa3b, v59
	v_pk_mul_f32 v[60:61], v[60:61], v[92:93]
	v_exp_f32_e32 v92, v65
	v_exp_f32_e32 v59, v59
	v_pk_mul_f32 v[56:57], v[56:57], v[90:91]
	v_cvt_pk_bf16_f32 v54, v54, v55
	v_add_f32_e32 v58, 1.0, v92
	v_add_f32_e32 v59, 1.0, v59
	v_rcp_f32_e32 v58, v58
	v_rcp_f32_e32 v59, v59
	v_cvt_pk_bf16_f32 v55, v56, v57
	s_waitcnt vmcnt(13)
	v_lshlrev_b32_e32 v56, 16, v134
	v_mul_f32_e32 v56, 0xbfb8aa3b, v56
	v_exp_f32_e32 v57, v56
	v_and_b32_e32 v56, 0xffff0000, v134
	v_mul_f32_e32 v56, 0xbfb8aa3b, v56
	v_pk_mul_f32 v[50:51], v[50:51], v[58:59]
	v_exp_f32_e32 v58, v56
	v_cvt_pk_bf16_f32 v65, v60, v61
	v_lshlrev_b32_e32 v60, 16, v129
	v_and_b32_e32 v61, 0xffff0000, v129
	v_mul_f32_e32 v60, 0xbfb8aa3b, v60
	v_mul_f32_e32 v61, 0xbfb8aa3b, v61
	v_cvt_pk_bf16_f32 v56, v50, v51
	v_add_f32_e32 v50, 1.0, v57
	v_lshlrev_b32_e32 v57, 16, v135
	v_exp_f32_e32 v60, v60
	v_exp_f32_e32 v61, v61
	v_add_f32_e32 v51, 1.0, v58
	v_mul_f32_e32 v57, 0xbfb8aa3b, v57
	v_and_b32_e32 v58, 0xffff0000, v135
	v_exp_f32_e32 v57, v57
	v_mul_f32_e32 v58, 0xbfb8aa3b, v58
	v_exp_f32_e32 v59, v58
	v_rcp_f32_e32 v50, v50
	v_rcp_f32_e32 v51, v51
	v_add_f32_e32 v60, 1.0, v60
	v_add_f32_e32 v61, 1.0, v61
	v_rcp_f32_e32 v60, v60
	v_rcp_f32_e32 v61, v61
	v_add_f32_e32 v57, 1.0, v57
	v_rcp_f32_e32 v58, v57
	v_add_f32_e32 v57, 1.0, v59
	v_rcp_f32_e32 v59, v57
	v_lshlrev_b32_e32 v57, 16, v136
	v_pk_mul_f32 v[46:47], v[46:47], v[50:51]
	v_and_b32_e32 v51, 0xffff0000, v136
	v_mul_f32_e32 v57, 0xbfb8aa3b, v57
	v_mul_f32_e32 v51, 0xbfb8aa3b, v51
	v_pk_mul_f32 v[52:53], v[52:53], v[60:61]
	v_exp_f32_e32 v60, v57
	v_exp_f32_e32 v51, v51
	v_pk_mul_f32 v[48:49], v[48:49], v[58:59]
	v_cvt_pk_bf16_f32 v46, v46, v47
	v_add_f32_e32 v50, 1.0, v60
	v_add_f32_e32 v51, 1.0, v51
	v_rcp_f32_e32 v50, v50
	v_rcp_f32_e32 v51, v51
	v_cvt_pk_bf16_f32 v47, v48, v49
	s_waitcnt vmcnt(12)
	v_lshlrev_b32_e32 v48, 16, v82
	v_mul_f32_e32 v48, 0xbfb8aa3b, v48
	v_exp_f32_e32 v49, v48
	v_and_b32_e32 v48, 0xffff0000, v82
	v_mul_f32_e32 v48, 0xbfb8aa3b, v48
	v_pk_mul_f32 v[42:43], v[42:43], v[50:51]
	v_exp_f32_e32 v50, v48
	v_cvt_pk_bf16_f32 v57, v52, v53
	v_lshlrev_b32_e32 v52, 16, v137
	v_and_b32_e32 v53, 0xffff0000, v137
	v_mul_f32_e32 v52, 0xbfb8aa3b, v52
	v_mul_f32_e32 v53, 0xbfb8aa3b, v53
	v_cvt_pk_bf16_f32 v48, v42, v43
	v_add_f32_e32 v42, 1.0, v49
	v_lshlrev_b32_e32 v49, 16, v83
	v_exp_f32_e32 v52, v52
	v_exp_f32_e32 v53, v53
	v_add_f32_e32 v43, 1.0, v50
	v_mul_f32_e32 v49, 0xbfb8aa3b, v49
	v_and_b32_e32 v50, 0xffff0000, v83
	v_exp_f32_e32 v49, v49
	v_mul_f32_e32 v50, 0xbfb8aa3b, v50
	v_exp_f32_e32 v51, v50
	v_rcp_f32_e32 v42, v42
	v_rcp_f32_e32 v43, v43
	v_add_f32_e32 v52, 1.0, v52
	v_add_f32_e32 v53, 1.0, v53
	v_rcp_f32_e32 v52, v52
	v_rcp_f32_e32 v53, v53
	v_add_f32_e32 v49, 1.0, v49
	v_rcp_f32_e32 v50, v49
	v_add_f32_e32 v49, 1.0, v51
	v_rcp_f32_e32 v51, v49
	v_lshlrev_b32_e32 v49, 16, v84
	v_pk_mul_f32 v[38:39], v[38:39], v[42:43]
	v_and_b32_e32 v43, 0xffff0000, v84
	v_mul_f32_e32 v49, 0xbfb8aa3b, v49
	v_mul_f32_e32 v43, 0xbfb8aa3b, v43
	v_pk_mul_f32 v[44:45], v[44:45], v[52:53]
	v_exp_f32_e32 v52, v49
	v_exp_f32_e32 v43, v43
	v_pk_mul_f32 v[40:41], v[40:41], v[50:51]
	v_cvt_pk_bf16_f32 v38, v38, v39
	v_add_f32_e32 v42, 1.0, v52
	v_add_f32_e32 v43, 1.0, v43
	v_rcp_f32_e32 v42, v42
	v_rcp_f32_e32 v43, v43
	v_cvt_pk_bf16_f32 v39, v40, v41
	s_waitcnt vmcnt(11)
	v_lshlrev_b32_e32 v40, 16, v78
	v_mul_f32_e32 v40, 0xbfb8aa3b, v40
	v_exp_f32_e32 v41, v40
	v_and_b32_e32 v40, 0xffff0000, v78
	v_mul_f32_e32 v40, 0xbfb8aa3b, v40
	v_pk_mul_f32 v[34:35], v[34:35], v[42:43]
	v_exp_f32_e32 v42, v40
	v_cvt_pk_bf16_f32 v49, v44, v45
	v_lshlrev_b32_e32 v44, 16, v85
	v_and_b32_e32 v45, 0xffff0000, v85
	v_mul_f32_e32 v44, 0xbfb8aa3b, v44
	v_mul_f32_e32 v45, 0xbfb8aa3b, v45
	v_cvt_pk_bf16_f32 v40, v34, v35
	v_add_f32_e32 v34, 1.0, v41
	v_lshlrev_b32_e32 v41, 16, v79
	v_exp_f32_e32 v44, v44
	v_exp_f32_e32 v45, v45
	v_add_f32_e32 v35, 1.0, v42
	v_mul_f32_e32 v41, 0xbfb8aa3b, v41
	v_and_b32_e32 v42, 0xffff0000, v79
	v_exp_f32_e32 v41, v41
	v_mul_f32_e32 v42, 0xbfb8aa3b, v42
	v_exp_f32_e32 v43, v42
	v_rcp_f32_e32 v34, v34
	v_rcp_f32_e32 v35, v35
	v_add_f32_e32 v44, 1.0, v44
	v_add_f32_e32 v45, 1.0, v45
	v_rcp_f32_e32 v44, v44
	v_rcp_f32_e32 v45, v45
	v_add_f32_e32 v41, 1.0, v41
	v_rcp_f32_e32 v42, v41
	v_add_f32_e32 v41, 1.0, v43
	v_rcp_f32_e32 v43, v41
	v_lshlrev_b32_e32 v41, 16, v80
	v_pk_mul_f32 v[30:31], v[30:31], v[34:35]
	v_and_b32_e32 v35, 0xffff0000, v80
	v_mul_f32_e32 v41, 0xbfb8aa3b, v41
	v_mul_f32_e32 v35, 0xbfb8aa3b, v35
	v_pk_mul_f32 v[36:37], v[36:37], v[44:45]
	v_exp_f32_e32 v44, v41
	v_exp_f32_e32 v35, v35
	v_pk_mul_f32 v[32:33], v[32:33], v[42:43]
	v_cvt_pk_bf16_f32 v30, v30, v31
	v_add_f32_e32 v34, 1.0, v44
	v_add_f32_e32 v35, 1.0, v35
	v_rcp_f32_e32 v34, v34
	v_rcp_f32_e32 v35, v35
	v_cvt_pk_bf16_f32 v31, v32, v33
	s_waitcnt vmcnt(10)
	v_lshlrev_b32_e32 v32, 16, v74
	v_mul_f32_e32 v32, 0xbfb8aa3b, v32
	v_exp_f32_e32 v33, v32
	v_and_b32_e32 v32, 0xffff0000, v74
	v_mul_f32_e32 v32, 0xbfb8aa3b, v32
	v_pk_mul_f32 v[26:27], v[26:27], v[34:35]
	v_exp_f32_e32 v34, v32
	v_cvt_pk_bf16_f32 v41, v36, v37
	v_lshlrev_b32_e32 v36, 16, v81
	v_and_b32_e32 v37, 0xffff0000, v81
	v_mul_f32_e32 v36, 0xbfb8aa3b, v36
	v_mul_f32_e32 v37, 0xbfb8aa3b, v37
	v_cvt_pk_bf16_f32 v32, v26, v27
	v_add_f32_e32 v26, 1.0, v33
	v_lshlrev_b32_e32 v33, 16, v75
	v_exp_f32_e32 v36, v36
	v_exp_f32_e32 v37, v37
	v_add_f32_e32 v27, 1.0, v34
	v_mul_f32_e32 v33, 0xbfb8aa3b, v33
	v_and_b32_e32 v34, 0xffff0000, v75
	v_exp_f32_e32 v33, v33
	v_mul_f32_e32 v34, 0xbfb8aa3b, v34
	v_exp_f32_e32 v35, v34
	v_rcp_f32_e32 v26, v26
	v_rcp_f32_e32 v27, v27
	v_add_f32_e32 v36, 1.0, v36
	v_add_f32_e32 v37, 1.0, v37
	v_rcp_f32_e32 v36, v36
	v_rcp_f32_e32 v37, v37
	v_add_f32_e32 v33, 1.0, v33
	v_rcp_f32_e32 v34, v33
	v_add_f32_e32 v33, 1.0, v35
	v_rcp_f32_e32 v35, v33
	v_lshlrev_b32_e32 v33, 16, v76
	v_pk_mul_f32 v[22:23], v[22:23], v[26:27]
	v_and_b32_e32 v27, 0xffff0000, v76
	v_mul_f32_e32 v33, 0xbfb8aa3b, v33
	v_mul_f32_e32 v27, 0xbfb8aa3b, v27
	v_pk_mul_f32 v[28:29], v[28:29], v[36:37]
	v_exp_f32_e32 v36, v33
	v_exp_f32_e32 v27, v27
	v_pk_mul_f32 v[24:25], v[24:25], v[34:35]
	v_cvt_pk_bf16_f32 v22, v22, v23
	v_add_f32_e32 v26, 1.0, v36
	v_add_f32_e32 v27, 1.0, v27
	v_rcp_f32_e32 v26, v26
	v_rcp_f32_e32 v27, v27
	v_cvt_pk_bf16_f32 v23, v24, v25
	s_waitcnt vmcnt(9)
	v_lshlrev_b32_e32 v24, 16, v70
	v_mul_f32_e32 v24, 0xbfb8aa3b, v24
	v_exp_f32_e32 v25, v24
	v_and_b32_e32 v24, 0xffff0000, v70
	v_mul_f32_e32 v24, 0xbfb8aa3b, v24
	v_pk_mul_f32 v[18:19], v[18:19], v[26:27]
	v_exp_f32_e32 v26, v24
	v_cvt_pk_bf16_f32 v33, v28, v29
	v_lshlrev_b32_e32 v28, 16, v77
	v_and_b32_e32 v29, 0xffff0000, v77
	v_mul_f32_e32 v28, 0xbfb8aa3b, v28
	v_mul_f32_e32 v29, 0xbfb8aa3b, v29
	v_cvt_pk_bf16_f32 v24, v18, v19
	v_add_f32_e32 v18, 1.0, v25
	v_lshlrev_b32_e32 v25, 16, v71
	v_exp_f32_e32 v28, v28
	v_exp_f32_e32 v29, v29
	v_add_f32_e32 v19, 1.0, v26
	v_mul_f32_e32 v25, 0xbfb8aa3b, v25
	v_and_b32_e32 v26, 0xffff0000, v71
	v_exp_f32_e32 v25, v25
	v_mul_f32_e32 v26, 0xbfb8aa3b, v26
	v_exp_f32_e32 v27, v26
	v_rcp_f32_e32 v18, v18
	v_rcp_f32_e32 v19, v19
	v_add_f32_e32 v28, 1.0, v28
	v_add_f32_e32 v29, 1.0, v29
	v_rcp_f32_e32 v28, v28
	v_rcp_f32_e32 v29, v29
	v_add_f32_e32 v25, 1.0, v25
	v_rcp_f32_e32 v26, v25
	v_add_f32_e32 v25, 1.0, v27
	v_rcp_f32_e32 v27, v25
	v_lshlrev_b32_e32 v25, 16, v72
	v_pk_mul_f32 v[14:15], v[14:15], v[18:19]
	v_and_b32_e32 v19, 0xffff0000, v72
	v_mul_f32_e32 v25, 0xbfb8aa3b, v25
	v_mul_f32_e32 v19, 0xbfb8aa3b, v19
	v_pk_mul_f32 v[20:21], v[20:21], v[28:29]
	v_exp_f32_e32 v28, v25
	v_exp_f32_e32 v19, v19
	v_pk_mul_f32 v[16:17], v[16:17], v[26:27]
	v_cvt_pk_bf16_f32 v14, v14, v15
	v_add_f32_e32 v18, 1.0, v28
	v_add_f32_e32 v19, 1.0, v19
	v_rcp_f32_e32 v18, v18
	v_rcp_f32_e32 v19, v19
	v_cvt_pk_bf16_f32 v15, v16, v17
	s_waitcnt vmcnt(8)
	v_lshlrev_b32_e32 v16, 16, v66
	v_mul_f32_e32 v16, 0xbfb8aa3b, v16
	v_exp_f32_e32 v17, v16
	v_and_b32_e32 v16, 0xffff0000, v66
	v_mul_f32_e32 v16, 0xbfb8aa3b, v16
	v_pk_mul_f32 v[10:11], v[10:11], v[18:19]
	v_exp_f32_e32 v18, v16
	v_cvt_pk_bf16_f32 v25, v20, v21
	v_lshlrev_b32_e32 v20, 16, v73
	v_and_b32_e32 v21, 0xffff0000, v73
	v_mul_f32_e32 v20, 0xbfb8aa3b, v20
	v_mul_f32_e32 v21, 0xbfb8aa3b, v21
	v_exp_f32_e32 v20, v20
	v_exp_f32_e32 v21, v21
	v_cvt_pk_bf16_f32 v16, v10, v11
	v_add_f32_e32 v10, 1.0, v17
	v_lshlrev_b32_e32 v17, 16, v67
	v_add_f32_e32 v11, 1.0, v18
	v_mul_f32_e32 v17, 0xbfb8aa3b, v17
	v_and_b32_e32 v18, 0xffff0000, v67
	v_exp_f32_e32 v17, v17
	v_mul_f32_e32 v18, 0xbfb8aa3b, v18
	v_exp_f32_e32 v19, v18
	v_add_f32_e32 v20, 1.0, v20
	v_add_f32_e32 v21, 1.0, v21
	v_rcp_f32_e32 v20, v20
	v_rcp_f32_e32 v21, v21
	v_rcp_f32_e32 v10, v10
	v_rcp_f32_e32 v11, v11
	v_add_f32_e32 v17, 1.0, v17
	v_rcp_f32_e32 v18, v17
	v_add_f32_e32 v17, 1.0, v19
	v_rcp_f32_e32 v19, v17
	v_lshlrev_b32_e32 v17, 16, v68
	v_pk_mul_f32 v[12:13], v[12:13], v[20:21]
	v_mul_f32_e32 v17, 0xbfb8aa3b, v17
	v_pk_mul_f32 v[6:7], v[6:7], v[10:11]
	v_and_b32_e32 v11, 0xffff0000, v68
	v_exp_f32_e32 v20, v17
	v_cvt_pk_bf16_f32 v17, v12, v13
	v_mul_f32_e32 v11, 0xbfb8aa3b, v11
	v_lshlrev_b32_e32 v12, 16, v69
	v_and_b32_e32 v13, 0xffff0000, v69
	v_exp_f32_e32 v11, v11
	v_mul_f32_e32 v12, 0xbfb8aa3b, v12
	v_mul_f32_e32 v13, 0xbfb8aa3b, v13
	v_exp_f32_e32 v12, v12
	v_exp_f32_e32 v13, v13
	v_add_f32_e32 v10, 1.0, v20
	v_add_f32_e32 v11, 1.0, v11
	v_rcp_f32_e32 v10, v10
	v_add_f32_e32 v12, 1.0, v12
	v_add_f32_e32 v13, 1.0, v13
	v_rcp_f32_e32 v11, v11
	v_rcp_f32_e32 v12, v12
	v_rcp_f32_e32 v13, v13
	v_pk_mul_f32 v[8:9], v[8:9], v[18:19]
	v_pk_mul_f32 v[2:3], v[2:3], v[10:11]
	v_cvt_pk_bf16_f32 v6, v6, v7
	v_cvt_pk_bf16_f32 v7, v8, v9
	v_pk_mul_f32 v[4:5], v[4:5], v[12:13]
	v_cvt_pk_bf16_f32 v8, v2, v3
	v_lshl_add_u64 v[2:3], s[6:7], 0, v[96:97]
	v_cvt_pk_bf16_f32 v9, v4, v5
	v_lshl_add_u64 v[2:3], v[2:3], 0, v[166:167]
	global_store_dwordx4 v[2:3], v[6:9], off nt
	global_store_dwordx4 v[2:3], v[14:17], off offset:256 nt
	v_lshl_add_u64 v[2:3], s[6:7], 0, v[94:95]
	v_lshl_add_u64 v[2:3], v[2:3], 0, v[166:167]
	global_store_dwordx4 v[2:3], v[22:25], off nt
	global_store_dwordx4 v[2:3], v[30:33], off offset:256 nt
	v_lshl_add_u64 v[2:3], s[6:7], 0, v[88:89]
	v_lshl_add_u64 v[2:3], v[2:3], 0, v[166:167]
	global_store_dwordx4 v[2:3], v[38:41], off nt
	global_store_dwordx4 v[2:3], v[46:49], off offset:256 nt
	v_lshl_add_u64 v[2:3], s[6:7], 0, v[86:87]
	v_lshl_add_u64 v[2:3], v[2:3], 0, v[166:167]
	global_store_dwordx4 v[2:3], v[54:57], off nt
	global_store_dwordx4 v[2:3], v[62:65], off offset:256 nt
	s_cbranch_vccnz .LBB0_763
	s_andn2_b64 vcc, exec, s[10:11]
	s_cbranch_vccnz .LBB0_762
	s_barrier
	s_branch .LBB0_762

.LBB0_799:
	v_lshl_add_u32 v156, s26, 8, v1
	v_lshl_or_b32 v154, s49, 8, v161
	v_ashrrev_i32_e32 v157, 31, v156
	v_ashrrev_i32_e32 v155, 31, v154
	v_lshlrev_b64 v[130:131], 10, v[156:157]
	v_lshl_add_u64 v[130:131], v[130:131], 0, v[154:155]
	v_lshlrev_b64 v[130:131], 1, v[130:131]
	v_lshl_add_u64 v[132:133], s[8:9], 0, v[130:131]
	s_waitcnt vmcnt(8)
	v_mov_b32_e32 v166, v226
	v_mov_b32_e32 v167, v227
	v_mov_b32_e32 v168, v228
	v_mov_b32_e32 v169, v229
	v_lshl_add_u64 v[132:133], s[10:11], 0, v[130:131]
	v_or_b32_e32 v130, 0x100, v130
	v_mov_b32_e32 v170, v230
	v_mov_b32_e32 v171, v231
	v_mov_b32_e32 v172, v232
	v_mov_b32_e32 v173, v233
	v_lshl_add_u64 v[132:133], s[8:9], 0, v[130:131]
	v_lshl_add_u64 v[130:131], s[10:11], 0, v[130:131]
	v_mov_b32_e32 v174, v234
	v_mov_b32_e32 v175, v235
	v_mov_b32_e32 v176, v236
	v_mov_b32_e32 v177, v237
	v_mov_b32_e32 v178, v238
	v_mov_b32_e32 v179, v239
	v_mov_b32_e32 v180, v240
	v_mov_b32_e32 v181, v241
	v_or_b32_e32 v158, 16, v156
	v_ashrrev_i32_e32 v159, 31, v158
	v_lshlrev_b64 v[130:131], 10, v[158:159]
	v_lshl_add_u64 v[130:131], v[130:131], 0, v[154:155]
	v_lshlrev_b64 v[130:131], 1, v[130:131]
	v_lshl_add_u64 v[132:133], s[8:9], 0, v[130:131]
	v_lshl_add_u64 v[134:135], s[10:11], 0, v[130:131]
	v_mov_b32_e32 v182, v242
	v_mov_b32_e32 v183, v243
	v_mov_b32_e32 v184, v244
	v_mov_b32_e32 v185, v245
	v_mov_b32_e32 v186, v246
	v_mov_b32_e32 v187, v247
	v_mov_b32_e32 v188, v248
	v_mov_b32_e32 v189, v249
	v_or_b32_e32 v130, 0x100, v130
	v_lshl_add_u64 v[132:133], s[8:9], 0, v[130:131]
	v_lshl_add_u64 v[130:131], s[10:11], 0, v[130:131]
	v_mov_b32_e32 v134, v250
	v_mov_b32_e32 v135, v251
	v_mov_b32_e32 v136, v252
	v_mov_b32_e32 v137, v253
	s_nop 0
	v_mov_b32_e32 v130, v150
	v_mov_b32_e32 v131, v151
	v_mov_b32_e32 v132, v152
	v_mov_b32_e32 v133, v153
	s_andn2_b64 vcc, exec, s[2:3]
	s_mov_b64 s[0:1], -1
	s_waitcnt vmcnt(8)
	v_lshlrev_b32_e32 v165, 16, v166
	v_and_b32_e32 v190, 0xffff0000, v166
	v_lshlrev_b32_e32 v191, 16, v167
	v_lshlrev_b32_e32 v193, 16, v168
	v_and_b32_e32 v194, 0xffff0000, v168
	v_lshlrev_b32_e32 v195, 16, v169
	v_and_b32_e32 v196, 0xffff0000, v169
	v_and_b32_e32 v192, 0xffff0000, v167
	v_mul_f32_e32 v165, 0xbfb8aa3b, v165
	v_mul_f32_e32 v193, 0xbfb8aa3b, v193
	v_mul_f32_e32 v190, 0xbfb8aa3b, v190
	v_mul_f32_e32 v194, 0xbfb8aa3b, v194
	v_mul_f32_e32 v191, 0xbfb8aa3b, v191
	v_mul_f32_e32 v195, 0xbfb8aa3b, v195
	v_mul_f32_e32 v196, 0xbfb8aa3b, v196
	v_mul_f32_e32 v192, 0xbfb8aa3b, v192
	v_lshlrev_b32_e32 v202, 16, v176
	v_and_b32_e32 v203, 0xffff0000, v176
	v_lshlrev_b32_e32 v204, 16, v177
	v_and_b32_e32 v205, 0xffff0000, v177
	v_lshlrev_b32_e32 v176, 16, v179
	v_and_b32_e32 v177, 0xffff0000, v179
	v_exp_f32_e32 v165, v165
	v_exp_f32_e32 v179, v193
	v_exp_f32_e32 v190, v190
	v_exp_f32_e32 v193, v194
	v_exp_f32_e32 v191, v191
	v_exp_f32_e32 v194, v195
	v_exp_f32_e32 v195, v196
	v_exp_f32_e32 v192, v192
	v_add_f32_e32 v165, 1.0, v165
	v_add_f32_e32 v179, 1.0, v179
	v_add_f32_e32 v196, 1.0, v190
	v_add_f32_e32 v193, 1.0, v193
	v_add_f32_e32 v197, 1.0, v191
	v_add_f32_e32 v206, 1.0, v194
	v_add_f32_e32 v208, 1.0, v195
	v_add_f32_e32 v207, 1.0, v192
	v_rcp_f32_e32 v190, v165
	v_rcp_f32_e32 v192, v179
	v_rcp_f32_e32 v191, v196
	v_rcp_f32_e32 v194, v197
	v_rcp_f32_e32 v196, v206
	v_rcp_f32_e32 v197, v208
	v_rcp_f32_e32 v193, v193
	v_rcp_f32_e32 v195, v207
	v_lshlrev_b32_e32 v166, 16, v170
	v_and_b32_e32 v167, 0xffff0000, v170
	v_lshlrev_b32_e32 v168, 16, v171
	v_and_b32_e32 v169, 0xffff0000, v171
	v_lshlrev_b32_e32 v170, 16, v172
	v_and_b32_e32 v171, 0xffff0000, v172
	v_lshlrev_b32_e32 v172, 16, v173
	v_and_b32_e32 v173, 0xffff0000, v173
	v_lshlrev_b32_e32 v200, 16, v175
	v_pk_fma_f32 v[126:127], v[126:127], v[190:191], v[166:167]
	v_pk_fma_f32 v[166:167], v[124:125], v[196:197], v[172:173]
	v_pk_fma_f32 v[124:125], v[122:123], v[192:193], v[170:171]
	v_pk_fma_f32 v[128:129], v[128:129], v[194:195], v[168:169]
	v_cvt_pk_bf16_f32 v124, v124, v125
	v_cvt_pk_bf16_f32 v125, v166, v167
	v_mul_f32_e32 v167, 0xbfb8aa3b, v200
	v_and_b32_e32 v199, 0xffff0000, v174
	v_cvt_pk_bf16_f32 v123, v128, v129
	v_mul_f32_e32 v129, 0xbfb8aa3b, v202
	v_exp_f32_e32 v167, v167
	v_mul_f32_e32 v168, 0xbfb8aa3b, v204
	v_exp_f32_e32 v129, v129
	v_mul_f32_e32 v165, 0xbfb8aa3b, v199
	v_exp_f32_e32 v169, v168
	v_exp_f32_e32 v165, v165
	v_and_b32_e32 v201, 0xffff0000, v175
	v_add_f32_e32 v167, 1.0, v167
	v_add_f32_e32 v129, 1.0, v129
	v_rcp_f32_e32 v168, v167
	v_add_f32_e32 v167, 1.0, v169
	v_mul_f32_e32 v169, 0xbfb8aa3b, v201
	v_rcp_f32_e32 v166, v129
	v_add_f32_e32 v129, 1.0, v165
	v_mul_f32_e32 v165, 0xbfb8aa3b, v203
	v_exp_f32_e32 v169, v169
	v_mul_f32_e32 v170, 0xbfb8aa3b, v205
	v_exp_f32_e32 v165, v165
	v_exp_f32_e32 v171, v170
	v_rcp_f32_e32 v170, v167
	v_add_f32_e32 v167, 1.0, v169
	v_add_f32_e32 v165, 1.0, v165
	v_rcp_f32_e32 v169, v167
	v_add_f32_e32 v167, 1.0, v171
	v_rcp_f32_e32 v171, v167
	v_rcp_f32_e32 v167, v165
	v_lshlrev_b32_e32 v198, 16, v174
	v_cvt_pk_bf16_f32 v122, v126, v127
	v_mul_f32_e32 v126, 0xbfb8aa3b, v198
	v_lshlrev_b32_e32 v174, 16, v178
	v_and_b32_e32 v175, 0xffff0000, v178
	v_lshlrev_b32_e32 v178, 16, v180
	v_exp_f32_e32 v128, v126
	v_and_b32_e32 v179, 0xffff0000, v180
	v_lshlrev_b32_e32 v126, 16, v181
	v_and_b32_e32 v127, 0xffff0000, v181
	v_pk_fma_f32 v[126:127], v[116:117], v[170:171], v[126:127]
	v_pk_fma_f32 v[116:117], v[114:115], v[166:167], v[178:179]
	v_and_b32_e32 v165, 0xffff0000, v182
	v_cvt_pk_bf16_f32 v116, v116, v117
	v_cvt_pk_bf16_f32 v117, v126, v127
	v_lshlrev_b32_e32 v127, 16, v182
	v_lshlrev_b32_e32 v166, 16, v184
	v_mul_f32_e32 v127, 0xbfb8aa3b, v127
	v_exp_f32_e32 v167, v127
	v_mul_f32_e32 v166, 0xbfb8aa3b, v166
	v_mul_f32_e32 v165, 0xbfb8aa3b, v165
	v_pk_fma_f32 v[120:121], v[120:121], v[168:169], v[176:177]
	v_exp_f32_e32 v168, v166
	v_exp_f32_e32 v165, v165
	v_lshlrev_b32_e32 v169, 16, v183
	v_add_f32_e32 v167, 1.0, v167
	v_and_b32_e32 v170, 0xffff0000, v184
	v_lshlrev_b32_e32 v172, 16, v185
	v_rcp_f32_e32 v166, v167
	v_add_f32_e32 v167, 1.0, v168
	v_add_f32_e32 v165, 1.0, v165
	v_mul_f32_e32 v169, 0xbfb8aa3b, v169
	v_rcp_f32_e32 v168, v167
	v_rcp_f32_e32 v167, v165
	v_mul_f32_e32 v165, 0xbfb8aa3b, v170
	v_exp_f32_e32 v169, v169
	v_mul_f32_e32 v170, 0xbfb8aa3b, v172
	v_exp_f32_e32 v172, v170
	v_and_b32_e32 v171, 0xffff0000, v183
	v_and_b32_e32 v173, 0xffff0000, v185
	v_add_f32_e32 v169, 1.0, v169
	v_mul_f32_e32 v171, 0xbfb8aa3b, v171
	v_rcp_f32_e32 v170, v169
	v_add_f32_e32 v169, 1.0, v172
	v_exp_f32_e32 v171, v171
	v_mul_f32_e32 v172, 0xbfb8aa3b, v173
	v_exp_f32_e32 v173, v172
	v_exp_f32_e32 v165, v165
	v_add_f32_e32 v128, 1.0, v128
	v_rcp_f32_e32 v172, v169
	v_add_f32_e32 v169, 1.0, v171
	v_rcp_f32_e32 v128, v128
	v_rcp_f32_e32 v129, v129
	v_rcp_f32_e32 v171, v169
	v_add_f32_e32 v169, 1.0, v173
	v_rcp_f32_e32 v173, v169
	v_add_f32_e32 v165, 1.0, v165
	v_rcp_f32_e32 v169, v165
	v_pk_fma_f32 v[118:119], v[118:119], v[128:129], v[174:175]
	v_lshlrev_b32_e32 v128, 16, v189
	v_and_b32_e32 v129, 0xffff0000, v189
	v_cvt_pk_bf16_f32 v115, v120, v121
	v_lshlrev_b32_e32 v120, 16, v187
	v_and_b32_e32 v121, 0xffff0000, v187
	v_pk_fma_f32 v[108:109], v[108:109], v[172:173], v[128:129]
	v_lshlrev_b32_e32 v126, 16, v188
	v_and_b32_e32 v127, 0xffff0000, v188
	v_pk_fma_f32 v[112:113], v[112:113], v[170:171], v[120:121]
	v_cvt_pk_bf16_f32 v121, v108, v109
	v_or_b32_e32 v108, 32, v156
	v_pk_fma_f32 v[106:107], v[106:107], v[168:169], v[126:127]
	v_ashrrev_i32_e32 v109, 31, v108
	v_cvt_pk_bf16_f32 v120, v106, v107
	v_lshlrev_b64 v[106:107], 10, v[108:109]
	v_cvt_pk_bf16_f32 v114, v118, v119
	v_lshlrev_b32_e32 v118, 16, v186
	v_and_b32_e32 v119, 0xffff0000, v186
	v_lshl_add_u64 v[106:107], v[106:107], 0, v[154:155]
	v_pk_fma_f32 v[110:111], v[110:111], v[166:167], v[118:119]
	v_lshlrev_b64 v[106:107], 1, v[106:107]
	v_cvt_pk_bf16_f32 v118, v110, v111
	v_or_b32_e32 v110, 0x100, v106
	v_mov_b32_e32 v111, v107
	v_cvt_pk_bf16_f32 v119, v112, v113
	v_lshl_add_u64 v[112:113], s[8:9], 0, v[110:111]
	v_lshlrev_b32_e32 v165, 16, v134
	v_and_b32_e32 v174, 0xffff0000, v134
	v_lshlrev_b32_e32 v175, 16, v135
	v_and_b32_e32 v177, 0xffff0000, v135
	v_lshl_add_u64 v[134:135], s[8:9], 0, v[106:107]
	global_load_dwordx4 v[126:129], v[112:113], off
	global_load_dwordx4 v[166:169], v[134:135], off
	v_lshl_add_u64 v[110:111], s[10:11], 0, v[110:111]
	v_lshl_add_u64 v[106:107], s[10:11], 0, v[106:107]
	v_lshlrev_b32_e32 v176, 16, v136
	v_and_b32_e32 v178, 0xffff0000, v136
	v_lshlrev_b32_e32 v179, 16, v137
	v_and_b32_e32 v180, 0xffff0000, v137
	global_load_dwordx4 v[134:137], v[110:111], off
	global_load_dwordx4 v[170:173], v[106:107], off
	v_mul_f32_e32 v107, 0xbfb8aa3b, v165
	v_exp_f32_e32 v165, v107
	v_lshlrev_b32_e32 v110, 16, v133
	v_and_b32_e32 v111, 0xffff0000, v133
	v_mul_f32_e32 v133, 0xbfb8aa3b, v176
	v_lshlrev_b32_e32 v106, 16, v132
	v_and_b32_e32 v107, 0xffff0000, v132
	v_add_f32_e32 v132, 1.0, v165
	v_exp_f32_e32 v133, v133
	v_mul_f32_e32 v165, 0xbfb8aa3b, v174
	v_exp_f32_e32 v165, v165
	v_mul_f32_e32 v175, 0xbfb8aa3b, v175
	v_add_f32_e32 v133, 1.0, v133
	v_exp_f32_e32 v175, v175
	v_mul_f32_e32 v176, 0xbfb8aa3b, v179
	v_rcp_f32_e32 v174, v133
	v_add_f32_e32 v133, 1.0, v165
	v_mul_f32_e32 v165, 0xbfb8aa3b, v178
	v_exp_f32_e32 v178, v176
	v_add_f32_e32 v175, 1.0, v175
	v_mul_f32_e32 v177, 0xbfb8aa3b, v177
	v_rcp_f32_e32 v176, v175
	v_add_f32_e32 v175, 1.0, v178
	v_exp_f32_e32 v177, v177
	v_mul_f32_e32 v178, 0xbfb8aa3b, v180
	v_exp_f32_e32 v179, v178
	v_exp_f32_e32 v165, v165
	v_rcp_f32_e32 v178, v175
	v_add_f32_e32 v175, 1.0, v177
	v_rcp_f32_e32 v177, v175
	v_add_f32_e32 v175, 1.0, v179
	v_add_f32_e32 v165, 1.0, v165
	v_rcp_f32_e32 v179, v175
	v_rcp_f32_e32 v175, v165
	v_rcp_f32_e32 v132, v132
	v_rcp_f32_e32 v133, v133
	v_pk_fma_f32 v[100:101], v[100:101], v[178:179], v[110:111]
	v_or_b32_e32 v110, 48, v156
	v_lshlrev_b32_e32 v112, 16, v130
	v_and_b32_e32 v113, 0xffff0000, v130
	v_pk_fma_f32 v[98:99], v[98:99], v[174:175], v[106:107]
	v_ashrrev_i32_e32 v111, 31, v110
	v_pk_fma_f32 v[102:103], v[102:103], v[132:133], v[112:113]
	v_cvt_pk_bf16_f32 v132, v98, v99
	v_lshlrev_b64 v[98:99], 10, v[110:111]
	v_lshl_add_u64 v[98:99], v[98:99], 0, v[154:155]
	v_lshlrev_b64 v[98:99], 1, v[98:99]
	v_lshlrev_b32_e32 v130, 16, v131
	v_and_b32_e32 v131, 0xffff0000, v131
	v_cvt_pk_bf16_f32 v133, v100, v101
	v_or_b32_e32 v100, 0x100, v98
	v_mov_b32_e32 v101, v99
	v_pk_fma_f32 v[104:105], v[104:105], v[176:177], v[130:131]
	v_cvt_pk_bf16_f32 v130, v102, v103
	v_lshl_add_u64 v[102:103], s[8:9], 0, v[100:101]
	v_cvt_pk_bf16_f32 v131, v104, v105
	v_lshl_add_u64 v[106:107], s[8:9], 0, v[98:99]
	global_load_dwordx4 v[102:105], v[102:103], off
	s_nop 0
	global_load_dwordx4 v[174:177], v[106:107], off
	v_lshl_add_u64 v[100:101], s[10:11], 0, v[100:101]
	v_lshl_add_u64 v[106:107], s[10:11], 0, v[98:99]
	global_load_dwordx4 v[98:101], v[100:101], off
	s_nop 0
	global_load_dwordx4 v[178:181], v[106:107], off
	v_lshlrev_b64 v[106:107], 11, v[156:157]
	v_lshl_add_u64 v[112:113], s[12:13], 0, v[106:107]
	v_lshlrev_b64 v[106:107], 1, v[154:155]
	v_lshl_add_u64 v[112:113], v[112:113], 0, v[106:107]
	global_store_dwordx4 v[112:113], v[122:125], off nt
	global_store_dwordx4 v[112:113], v[114:117], off offset:256 nt
	v_lshlrev_b64 v[112:113], 11, v[158:159]
	v_lshl_add_u64 v[112:113], s[12:13], 0, v[112:113]
	v_lshl_add_u64 v[112:113], v[112:113], 0, v[106:107]
	global_store_dwordx4 v[112:113], v[118:121], off nt
	global_store_dwordx4 v[112:113], v[130:133], off offset:256 nt
	v_lshlrev_b64 v[108:109], 11, v[108:109]
	v_lshl_add_u64 v[108:109], s[12:13], 0, v[108:109]
	s_waitcnt vmcnt(10)
	v_lshlrev_b32_e32 v117, 16, v166
	v_lshlrev_b32_e32 v123, 16, v167
	v_lshlrev_b32_e32 v121, 16, v168
	v_and_b32_e32 v120, 0xffff0000, v166
	v_and_b32_e32 v124, 0xffff0000, v168
	v_lshlrev_b32_e32 v130, 16, v169
	v_mul_f32_e32 v117, 0xbfb8aa3b, v117
	v_mul_f32_e32 v121, 0xbfb8aa3b, v121
	v_mul_f32_e32 v123, 0xbfb8aa3b, v123
	v_exp_f32_e32 v122, v117
	v_exp_f32_e32 v121, v121
	v_mul_f32_e32 v120, 0xbfb8aa3b, v120
	v_mul_f32_e32 v124, 0xbfb8aa3b, v124
	v_exp_f32_e32 v123, v123
	v_mul_f32_e32 v130, 0xbfb8aa3b, v130
	v_exp_f32_e32 v132, v120
	v_exp_f32_e32 v124, v124
	v_exp_f32_e32 v130, v130
	v_and_b32_e32 v125, 0xffff0000, v167
	v_and_b32_e32 v131, 0xffff0000, v169
	v_add_f32_e32 v122, 1.0, v122
	v_add_f32_e32 v121, 1.0, v121
	v_add_f32_e32 v123, 1.0, v123
	v_mul_f32_e32 v125, 0xbfb8aa3b, v125
	v_rcp_f32_e32 v120, v122
	v_rcp_f32_e32 v122, v121
	v_add_f32_e32 v121, 1.0, v132
	v_add_f32_e32 v132, 1.0, v124
	v_rcp_f32_e32 v124, v123
	v_add_f32_e32 v123, 1.0, v130
	v_exp_f32_e32 v125, v125
	v_mul_f32_e32 v130, 0xbfb8aa3b, v131
	v_exp_f32_e32 v131, v130
	v_rcp_f32_e32 v130, v123
	v_add_f32_e32 v123, 1.0, v125
	v_rcp_f32_e32 v125, v123
	v_add_f32_e32 v123, 1.0, v131
	v_rcp_f32_e32 v121, v121
	v_rcp_f32_e32 v131, v123
	v_rcp_f32_e32 v123, v132
	s_waitcnt vmcnt(8)
	v_lshlrev_b32_e32 v112, 16, v170
	v_and_b32_e32 v113, 0xffff0000, v170
	v_lshlrev_b32_e32 v116, 16, v172
	v_and_b32_e32 v117, 0xffff0000, v172
	v_lshlrev_b32_e32 v118, 16, v173
	v_and_b32_e32 v119, 0xffff0000, v173
	v_pk_fma_f32 v[94:95], v[94:95], v[120:121], v[112:113]
	v_pk_fma_f32 v[112:113], v[92:93], v[130:131], v[118:119]
	v_pk_fma_f32 v[92:93], v[90:91], v[122:123], v[116:117]
	v_lshlrev_b32_e32 v119, 16, v127
	v_cvt_pk_bf16_f32 v92, v92, v93
	v_cvt_pk_bf16_f32 v93, v112, v113
	v_lshlrev_b32_e32 v113, 16, v126
	v_lshlrev_b32_e32 v117, 16, v128
	v_and_b32_e32 v116, 0xffff0000, v126
	v_and_b32_e32 v120, 0xffff0000, v128
	v_lshlrev_b32_e32 v122, 16, v129
	v_mul_f32_e32 v113, 0xbfb8aa3b, v113
	v_mul_f32_e32 v117, 0xbfb8aa3b, v117
	v_mul_f32_e32 v119, 0xbfb8aa3b, v119
	v_lshlrev_b32_e32 v114, 16, v171
	v_and_b32_e32 v115, 0xffff0000, v171
	v_exp_f32_e32 v118, v113
	v_exp_f32_e32 v117, v117
	v_mul_f32_e32 v116, 0xbfb8aa3b, v116
	v_mul_f32_e32 v120, 0xbfb8aa3b, v120
	v_exp_f32_e32 v119, v119
	v_mul_f32_e32 v122, 0xbfb8aa3b, v122
	v_pk_fma_f32 v[96:97], v[96:97], v[124:125], v[114:115]
	v_exp_f32_e32 v124, v116
	v_exp_f32_e32 v120, v120
	v_exp_f32_e32 v122, v122
	v_and_b32_e32 v121, 0xffff0000, v127
	v_and_b32_e32 v123, 0xffff0000, v129
	v_add_f32_e32 v118, 1.0, v118
	v_add_f32_e32 v117, 1.0, v117
	v_add_f32_e32 v119, 1.0, v119
	v_mul_f32_e32 v121, 0xbfb8aa3b, v121
	v_rcp_f32_e32 v116, v118
	v_rcp_f32_e32 v118, v117
	v_add_f32_e32 v117, 1.0, v124
	v_add_f32_e32 v124, 1.0, v120
	v_rcp_f32_e32 v120, v119
	v_add_f32_e32 v119, 1.0, v122
	v_exp_f32_e32 v121, v121
	v_mul_f32_e32 v122, 0xbfb8aa3b, v123
	v_exp_f32_e32 v123, v122
	v_rcp_f32_e32 v122, v119
	v_add_f32_e32 v119, 1.0, v121
	v_rcp_f32_e32 v121, v119
	v_add_f32_e32 v119, 1.0, v123
	v_rcp_f32_e32 v117, v117
	v_rcp_f32_e32 v123, v119
	v_rcp_f32_e32 v119, v124
	v_cvt_pk_bf16_f32 v90, v94, v95
	v_lshlrev_b32_e32 v94, 16, v134
	v_and_b32_e32 v95, 0xffff0000, v134
	v_lshlrev_b32_e32 v112, 16, v136
	v_and_b32_e32 v113, 0xffff0000, v136
	v_lshlrev_b32_e32 v114, 16, v137
	v_and_b32_e32 v115, 0xffff0000, v137
	v_pk_fma_f32 v[86:87], v[86:87], v[116:117], v[94:95]
	v_pk_fma_f32 v[94:95], v[84:85], v[122:123], v[114:115]
	v_pk_fma_f32 v[84:85], v[82:83], v[118:119], v[112:113]
	s_waitcnt vmcnt(6)
	v_lshlrev_b32_e32 v115, 16, v175
	v_cvt_pk_bf16_f32 v84, v84, v85
	v_cvt_pk_bf16_f32 v85, v94, v95
	v_lshlrev_b32_e32 v95, 16, v174
	v_lshlrev_b32_e32 v113, 16, v176
	v_and_b32_e32 v112, 0xffff0000, v174
	v_and_b32_e32 v116, 0xffff0000, v176
	v_lshlrev_b32_e32 v118, 16, v177
	v_mul_f32_e32 v95, 0xbfb8aa3b, v95
	v_mul_f32_e32 v113, 0xbfb8aa3b, v113
	v_mul_f32_e32 v115, 0xbfb8aa3b, v115
	v_cvt_pk_bf16_f32 v91, v96, v97
	v_lshlrev_b32_e32 v96, 16, v135
	v_and_b32_e32 v97, 0xffff0000, v135
	v_exp_f32_e32 v114, v95
	v_exp_f32_e32 v113, v113
	v_mul_f32_e32 v112, 0xbfb8aa3b, v112
	v_mul_f32_e32 v116, 0xbfb8aa3b, v116
	v_exp_f32_e32 v115, v115
	v_mul_f32_e32 v118, 0xbfb8aa3b, v118
	v_pk_fma_f32 v[88:89], v[88:89], v[120:121], v[96:97]
	v_exp_f32_e32 v120, v112
	v_exp_f32_e32 v116, v116
	v_exp_f32_e32 v118, v118
	v_and_b32_e32 v117, 0xffff0000, v175
	v_and_b32_e32 v119, 0xffff0000, v177
	v_add_f32_e32 v114, 1.0, v114
	v_add_f32_e32 v113, 1.0, v113
	v_add_f32_e32 v115, 1.0, v115
	v_mul_f32_e32 v117, 0xbfb8aa3b, v117
	v_rcp_f32_e32 v112, v114
	v_rcp_f32_e32 v114, v113
	v_add_f32_e32 v113, 1.0, v120
	v_add_f32_e32 v120, 1.0, v116
	v_rcp_f32_e32 v116, v115
	v_add_f32_e32 v115, 1.0, v118
	v_exp_f32_e32 v117, v117
	v_mul_f32_e32 v118, 0xbfb8aa3b, v119
	v_exp_f32_e32 v119, v118
	v_rcp_f32_e32 v118, v115
	v_add_f32_e32 v115, 1.0, v117
	v_rcp_f32_e32 v117, v115
	v_add_f32_e32 v115, 1.0, v119
	v_rcp_f32_e32 v113, v113
	v_rcp_f32_e32 v119, v115
	v_rcp_f32_e32 v115, v120
	v_cvt_pk_bf16_f32 v82, v86, v87
	v_cvt_pk_bf16_f32 v83, v88, v89
	s_waitcnt vmcnt(4)
	v_lshlrev_b32_e32 v86, 16, v178
	v_and_b32_e32 v87, 0xffff0000, v178
	v_lshlrev_b32_e32 v88, 16, v179
	v_and_b32_e32 v89, 0xffff0000, v179
	v_lshlrev_b32_e32 v94, 16, v180
	v_and_b32_e32 v95, 0xffff0000, v180
	v_pk_fma_f32 v[80:81], v[80:81], v[116:117], v[88:89]
	v_pk_fma_f32 v[78:79], v[78:79], v[112:113], v[86:87]
	v_pk_fma_f32 v[74:75], v[74:75], v[114:115], v[94:95]
	v_lshlrev_b32_e32 v96, 16, v181
	v_and_b32_e32 v97, 0xffff0000, v181
	v_cvt_pk_bf16_f32 v78, v78, v79
	v_cvt_pk_bf16_f32 v79, v80, v81
	v_cvt_pk_bf16_f32 v80, v74, v75
	v_add_u32_e32 v74, 0x80, v156
	v_pk_fma_f32 v[76:77], v[76:77], v[118:119], v[96:97]
	v_ashrrev_i32_e32 v75, 31, v74
	v_cvt_pk_bf16_f32 v81, v76, v77
	v_lshlrev_b64 v[76:77], 10, v[74:75]
	v_lshl_add_u64 v[76:77], v[76:77], 0, v[154:155]
	v_lshlrev_b64 v[76:77], 1, v[76:77]
	v_lshlrev_b32_e32 v118, 16, v102
	v_and_b32_e32 v119, 0xffff0000, v102
	v_lshlrev_b32_e32 v121, 16, v103
	v_and_b32_e32 v123, 0xffff0000, v103
	v_or_b32_e32 v102, 0x100, v76
	v_mov_b32_e32 v103, v77
	v_lshl_add_u64 v[86:87], s[8:9], 0, v[102:103]
	v_lshl_add_u64 v[94:95], s[8:9], 0, v[76:77]
	global_load_dwordx4 v[86:89], v[86:87], off
	s_nop 0
	global_load_dwordx4 v[94:97], v[94:95], off
	v_and_b32_e32 v122, 0xffff0000, v104
	v_lshlrev_b32_e32 v124, 16, v105
	v_mul_f32_e32 v121, 0xbfb8aa3b, v121
	v_lshl_add_u64 v[102:103], s[10:11], 0, v[102:103]
	v_mul_f32_e32 v122, 0xbfb8aa3b, v122
	v_exp_f32_e32 v121, v121
	v_mul_f32_e32 v124, 0xbfb8aa3b, v124
	v_lshlrev_b32_e32 v120, 16, v104
	v_and_b32_e32 v125, 0xffff0000, v105
	v_lshl_add_u64 v[76:77], s[10:11], 0, v[76:77]
	global_load_dwordx4 v[102:105], v[102:103], off
	s_nop 0
	global_load_dwordx4 v[112:115], v[76:77], off
	v_exp_f32_e32 v122, v122
	v_exp_f32_e32 v124, v124
	v_add_f32_e32 v121, 1.0, v121
	v_mul_f32_e32 v123, 0xbfb8aa3b, v123
	v_mul_f32_e32 v120, 0xbfb8aa3b, v120
	v_add_f32_e32 v126, 1.0, v122
	v_rcp_f32_e32 v122, v121
	v_add_f32_e32 v121, 1.0, v124
	v_exp_f32_e32 v123, v123
	v_mul_f32_e32 v124, 0xbfb8aa3b, v125
	v_exp_f32_e32 v120, v120
	v_exp_f32_e32 v125, v124
	v_lshlrev_b32_e32 v76, 16, v99
	v_and_b32_e32 v77, 0xffff0000, v99
	v_mul_f32_e32 v99, 0xbfb8aa3b, v118
	v_mul_f32_e32 v119, 0xbfb8aa3b, v119
	v_rcp_f32_e32 v124, v121
	v_add_f32_e32 v121, 1.0, v123
	v_exp_f32_e32 v118, v99
	v_exp_f32_e32 v119, v119
	v_add_f32_e32 v120, 1.0, v120
	v_rcp_f32_e32 v123, v121
	v_add_f32_e32 v121, 1.0, v125
	v_rcp_f32_e32 v120, v120
	v_rcp_f32_e32 v125, v121
	v_rcp_f32_e32 v121, v126
	v_lshlrev_b32_e32 v116, 16, v98
	v_and_b32_e32 v117, 0xffff0000, v98
	v_lshlrev_b32_e32 v98, 16, v100
	v_and_b32_e32 v99, 0xffff0000, v100
	v_add_f32_e32 v118, 1.0, v118
	v_add_f32_e32 v119, 1.0, v119
	v_pk_fma_f32 v[72:73], v[72:73], v[122:123], v[76:77]
	v_add_u32_e32 v76, 0x90, v156
	v_lshlrev_b32_e32 v100, 16, v101
	v_and_b32_e32 v101, 0xffff0000, v101
	v_rcp_f32_e32 v118, v118
	v_rcp_f32_e32 v119, v119
	v_pk_fma_f32 v[66:67], v[66:67], v[120:121], v[98:99]
	v_ashrrev_i32_e32 v77, 31, v76
	v_pk_fma_f32 v[68:69], v[68:69], v[124:125], v[100:101]
	v_cvt_pk_bf16_f32 v100, v66, v67
	v_lshlrev_b64 v[66:67], 10, v[76:77]
	v_lshl_add_u64 v[66:67], v[66:67], 0, v[154:155]
	v_lshlrev_b64 v[66:67], 1, v[66:67]
	v_pk_fma_f32 v[70:71], v[70:71], v[118:119], v[116:117]
	v_cvt_pk_bf16_f32 v101, v68, v69
	v_or_b32_e32 v68, 0x100, v66
	v_mov_b32_e32 v69, v67
	v_cvt_pk_bf16_f32 v98, v70, v71
	v_lshl_add_u64 v[70:71], s[8:9], 0, v[68:69]
	v_lshl_add_u64 v[116:117], s[8:9], 0, v[66:67]
	v_cvt_pk_bf16_f32 v99, v72, v73
	global_load_dwordx4 v[70:73], v[70:71], off
	s_nop 0
	global_load_dwordx4 v[116:119], v[116:117], off
	v_lshl_add_u64 v[68:69], s[10:11], 0, v[68:69]
	v_lshl_add_u64 v[120:121], s[10:11], 0, v[66:67]
	global_load_dwordx4 v[66:69], v[68:69], off
	s_nop 0
	global_load_dwordx4 v[120:123], v[120:121], off
	v_lshl_add_u64 v[108:109], v[108:109], 0, v[106:107]
	global_store_dwordx4 v[108:109], v[90:93], off nt
	global_store_dwordx4 v[108:109], v[82:85], off offset:256 nt
	v_lshlrev_b64 v[74:75], 11, v[74:75]
	v_lshl_add_u64 v[74:75], s[12:13], 0, v[74:75]
	v_lshlrev_b64 v[82:83], 11, v[110:111]
	v_lshl_add_u64 v[82:83], s[12:13], 0, v[82:83]
	v_lshl_add_u64 v[82:83], v[82:83], 0, v[106:107]
	global_store_dwordx4 v[82:83], v[78:81], off nt
	global_store_dwordx4 v[82:83], v[98:101], off offset:256 nt
	v_lshl_add_u64 v[74:75], v[74:75], 0, v[106:107]
	s_waitcnt vmcnt(10)
	v_lshlrev_b32_e32 v83, 16, v94
	v_lshlrev_b32_e32 v93, 16, v95
	v_lshlrev_b32_e32 v91, 16, v96
	v_and_b32_e32 v90, 0xffff0000, v94
	v_and_b32_e32 v94, 0xffff0000, v96
	v_lshlrev_b32_e32 v96, 16, v97
	v_mul_f32_e32 v83, 0xbfb8aa3b, v83
	v_mul_f32_e32 v91, 0xbfb8aa3b, v91
	v_mul_f32_e32 v93, 0xbfb8aa3b, v93
	v_exp_f32_e32 v92, v83
	v_exp_f32_e32 v91, v91
	v_mul_f32_e32 v90, 0xbfb8aa3b, v90
	v_mul_f32_e32 v94, 0xbfb8aa3b, v94
	v_exp_f32_e32 v93, v93
	v_mul_f32_e32 v96, 0xbfb8aa3b, v96
	v_exp_f32_e32 v98, v90
	v_exp_f32_e32 v94, v94
	v_exp_f32_e32 v96, v96
	v_and_b32_e32 v95, 0xffff0000, v95
	v_and_b32_e32 v97, 0xffff0000, v97
	v_add_f32_e32 v92, 1.0, v92
	v_add_f32_e32 v91, 1.0, v91
	v_add_f32_e32 v93, 1.0, v93
	v_mul_f32_e32 v95, 0xbfb8aa3b, v95
	v_rcp_f32_e32 v90, v92
	v_rcp_f32_e32 v92, v91
	v_add_f32_e32 v91, 1.0, v98
	v_add_f32_e32 v98, 1.0, v94
	v_rcp_f32_e32 v94, v93
	v_add_f32_e32 v93, 1.0, v96
	v_exp_f32_e32 v95, v95
	v_mul_f32_e32 v96, 0xbfb8aa3b, v97
	v_exp_f32_e32 v97, v96
	v_rcp_f32_e32 v96, v93
	v_add_f32_e32 v93, 1.0, v95
	v_rcp_f32_e32 v95, v93
	v_add_f32_e32 v93, 1.0, v97
	v_rcp_f32_e32 v91, v91
	v_rcp_f32_e32 v97, v93
	v_rcp_f32_e32 v93, v98
	s_waitcnt vmcnt(8)
	v_lshlrev_b32_e32 v78, 16, v112
	v_and_b32_e32 v79, 0xffff0000, v112
	v_lshlrev_b32_e32 v82, 16, v114
	v_and_b32_e32 v83, 0xffff0000, v114
	v_lshlrev_b32_e32 v84, 16, v115
	v_and_b32_e32 v85, 0xffff0000, v115
	v_pk_fma_f32 v[62:63], v[62:63], v[90:91], v[78:79]
	v_pk_fma_f32 v[78:79], v[60:61], v[96:97], v[84:85]
	v_pk_fma_f32 v[60:61], v[58:59], v[92:93], v[82:83]
	v_lshlrev_b32_e32 v85, 16, v87
	v_cvt_pk_bf16_f32 v60, v60, v61
	v_cvt_pk_bf16_f32 v61, v78, v79
	v_lshlrev_b32_e32 v79, 16, v86
	v_lshlrev_b32_e32 v83, 16, v88
	v_and_b32_e32 v82, 0xffff0000, v86
	v_and_b32_e32 v86, 0xffff0000, v88
	v_lshlrev_b32_e32 v88, 16, v89
	v_mul_f32_e32 v79, 0xbfb8aa3b, v79
	v_mul_f32_e32 v83, 0xbfb8aa3b, v83
	v_mul_f32_e32 v85, 0xbfb8aa3b, v85
	v_exp_f32_e32 v84, v79
	v_exp_f32_e32 v83, v83
	v_mul_f32_e32 v82, 0xbfb8aa3b, v82
	v_mul_f32_e32 v86, 0xbfb8aa3b, v86
	v_exp_f32_e32 v85, v85
	v_mul_f32_e32 v88, 0xbfb8aa3b, v88
	v_exp_f32_e32 v90, v82
	v_exp_f32_e32 v86, v86
	v_exp_f32_e32 v88, v88
	v_and_b32_e32 v87, 0xffff0000, v87
	v_and_b32_e32 v89, 0xffff0000, v89
	v_add_f32_e32 v84, 1.0, v84
	v_add_f32_e32 v83, 1.0, v83
	v_add_f32_e32 v85, 1.0, v85
	v_mul_f32_e32 v87, 0xbfb8aa3b, v87
	v_rcp_f32_e32 v82, v84
	v_rcp_f32_e32 v84, v83
	v_add_f32_e32 v83, 1.0, v90
	v_add_f32_e32 v90, 1.0, v86
	v_rcp_f32_e32 v86, v85
	v_add_f32_e32 v85, 1.0, v88
	v_exp_f32_e32 v87, v87
	v_mul_f32_e32 v88, 0xbfb8aa3b, v89
	v_exp_f32_e32 v89, v88
	v_rcp_f32_e32 v88, v85
	v_add_f32_e32 v85, 1.0, v87
	v_rcp_f32_e32 v87, v85
	v_add_f32_e32 v85, 1.0, v89
	v_rcp_f32_e32 v83, v83
	v_rcp_f32_e32 v89, v85
	v_rcp_f32_e32 v85, v90
	v_lshlrev_b32_e32 v80, 16, v113
	v_and_b32_e32 v81, 0xffff0000, v113
	v_pk_fma_f32 v[64:65], v[64:65], v[94:95], v[80:81]
	v_cvt_pk_bf16_f32 v58, v62, v63
	v_lshlrev_b32_e32 v62, 16, v102
	v_and_b32_e32 v63, 0xffff0000, v102
	v_lshlrev_b32_e32 v78, 16, v104
	v_and_b32_e32 v79, 0xffff0000, v104
	v_lshlrev_b32_e32 v80, 16, v105
	v_and_b32_e32 v81, 0xffff0000, v105
	v_pk_fma_f32 v[54:55], v[54:55], v[82:83], v[62:63]
	v_pk_fma_f32 v[62:63], v[52:53], v[88:89], v[80:81]
	v_pk_fma_f32 v[52:53], v[50:51], v[84:85], v[78:79]
	s_waitcnt vmcnt(6)
	v_lshlrev_b32_e32 v81, 16, v117
	v_cvt_pk_bf16_f32 v52, v52, v53
	v_cvt_pk_bf16_f32 v53, v62, v63
	v_lshlrev_b32_e32 v63, 16, v116
	v_lshlrev_b32_e32 v79, 16, v118
	v_and_b32_e32 v78, 0xffff0000, v116
	v_and_b32_e32 v82, 0xffff0000, v118
	v_lshlrev_b32_e32 v84, 16, v119
	v_mul_f32_e32 v63, 0xbfb8aa3b, v63
	v_mul_f32_e32 v79, 0xbfb8aa3b, v79
	v_mul_f32_e32 v81, 0xbfb8aa3b, v81
	v_cvt_pk_bf16_f32 v59, v64, v65
	v_lshlrev_b32_e32 v64, 16, v103
	v_and_b32_e32 v65, 0xffff0000, v103
	v_exp_f32_e32 v80, v63
	v_exp_f32_e32 v79, v79
	v_mul_f32_e32 v78, 0xbfb8aa3b, v78
	v_mul_f32_e32 v82, 0xbfb8aa3b, v82
	v_exp_f32_e32 v81, v81
	v_mul_f32_e32 v84, 0xbfb8aa3b, v84
	v_pk_fma_f32 v[56:57], v[56:57], v[86:87], v[64:65]
	v_exp_f32_e32 v86, v78
	v_exp_f32_e32 v82, v82
	v_exp_f32_e32 v84, v84
	v_and_b32_e32 v83, 0xffff0000, v117
	v_and_b32_e32 v85, 0xffff0000, v119
	v_add_f32_e32 v80, 1.0, v80
	v_add_f32_e32 v79, 1.0, v79
	v_add_f32_e32 v81, 1.0, v81
	v_mul_f32_e32 v83, 0xbfb8aa3b, v83
	v_rcp_f32_e32 v78, v80
	v_rcp_f32_e32 v80, v79
	v_add_f32_e32 v79, 1.0, v86
	v_add_f32_e32 v86, 1.0, v82
	v_rcp_f32_e32 v82, v81
	v_add_f32_e32 v81, 1.0, v84
	v_exp_f32_e32 v83, v83
	v_mul_f32_e32 v84, 0xbfb8aa3b, v85
	v_exp_f32_e32 v85, v84
	v_rcp_f32_e32 v84, v81
	v_add_f32_e32 v81, 1.0, v83
	v_rcp_f32_e32 v79, v79
	v_rcp_f32_e32 v83, v81
	v_add_f32_e32 v81, 1.0, v85
	v_rcp_f32_e32 v85, v81
	v_rcp_f32_e32 v81, v86
	v_cvt_pk_bf16_f32 v50, v54, v55
	s_waitcnt vmcnt(4)
	v_lshlrev_b32_e32 v54, 16, v120
	v_and_b32_e32 v55, 0xffff0000, v120
	v_lshlrev_b32_e32 v62, 16, v122
	v_and_b32_e32 v63, 0xffff0000, v122
	v_pk_fma_f32 v[46:47], v[46:47], v[78:79], v[54:55]
	v_add_u32_e32 v54, 0xb0, v156
	v_lshlrev_b32_e32 v64, 16, v123
	v_and_b32_e32 v65, 0xffff0000, v123
	v_pk_fma_f32 v[42:43], v[42:43], v[80:81], v[62:63]
	v_ashrrev_i32_e32 v55, 31, v54
	v_pk_fma_f32 v[44:45], v[44:45], v[84:85], v[64:65]
	v_cvt_pk_bf16_f32 v64, v42, v43
	v_lshlrev_b64 v[42:43], 10, v[54:55]
	v_lshl_add_u64 v[42:43], v[42:43], 0, v[154:155]
	v_cvt_pk_bf16_f32 v62, v46, v47
	v_lshlrev_b64 v[46:47], 1, v[42:43]
	v_or_b32_e32 v42, 0x100, v46
	v_mov_b32_e32 v43, v47
	v_cvt_pk_bf16_f32 v65, v44, v45
	v_lshlrev_b32_e32 v85, 16, v72
	v_lshl_add_u64 v[44:45], s[8:9], 0, v[42:43]
	v_cvt_pk_bf16_f32 v51, v56, v57
	v_lshlrev_b32_e32 v56, 16, v121
	v_and_b32_e32 v57, 0xffff0000, v121
	global_load_dwordx4 v[78:81], v[44:45], off
	v_lshlrev_b32_e32 v44, 16, v66
	v_and_b32_e32 v45, 0xffff0000, v66
	v_mul_f32_e32 v66, 0xbfb8aa3b, v85
	v_pk_fma_f32 v[48:49], v[48:49], v[82:83], v[56:57]
	v_and_b32_e32 v57, 0xffff0000, v70
	v_exp_f32_e32 v66, v66
	v_mul_f32_e32 v57, 0xbfb8aa3b, v57
	v_exp_f32_e32 v57, v57
	v_and_b32_e32 v72, 0xffff0000, v72
	v_add_f32_e32 v66, 1.0, v66
	v_lshl_add_u64 v[42:43], s[10:11], 0, v[42:43]
	v_cvt_pk_bf16_f32 v63, v48, v49
	v_lshlrev_b32_e32 v56, 16, v70
	v_lshlrev_b32_e32 v70, 16, v71
	v_lshlrev_b32_e32 v48, 16, v67
	v_and_b32_e32 v49, 0xffff0000, v67
	v_lshlrev_b32_e32 v82, 16, v68
	v_and_b32_e32 v83, 0xffff0000, v68
	v_lshlrev_b32_e32 v84, 16, v69
	v_and_b32_e32 v85, 0xffff0000, v69
	v_rcp_f32_e32 v86, v66
	global_load_dwordx4 v[66:69], v[42:43], off
	v_mul_f32_e32 v43, 0xbfb8aa3b, v72
	v_add_f32_e32 v42, 1.0, v57
	v_exp_f32_e32 v43, v43
	v_mul_f32_e32 v57, 0xbfb8aa3b, v70
	v_exp_f32_e32 v70, v57
	v_lshlrev_b32_e32 v88, 16, v73
	v_mul_f32_e32 v56, 0xbfb8aa3b, v56
	v_and_b32_e32 v71, 0xffff0000, v71
	v_exp_f32_e32 v56, v56
	v_rcp_f32_e32 v57, v42
	v_add_f32_e32 v42, 1.0, v43
	v_mul_f32_e32 v43, 0xbfb8aa3b, v88
	v_rcp_f32_e32 v87, v42
	v_add_f32_e32 v42, 1.0, v70
	v_exp_f32_e32 v43, v43
	v_mul_f32_e32 v70, 0xbfb8aa3b, v71
	v_exp_f32_e32 v70, v70
	v_and_b32_e32 v73, 0xffff0000, v73
	v_add_f32_e32 v56, 1.0, v56
	v_rcp_f32_e32 v56, v56
	v_add_f32_e32 v71, 1.0, v43
	v_mul_f32_e32 v43, 0xbfb8aa3b, v73
	v_exp_f32_e32 v72, v43
	v_add_f32_e32 v43, 1.0, v70
	v_rcp_f32_e32 v42, v42
	v_rcp_f32_e32 v43, v43
	v_pk_fma_f32 v[38:39], v[38:39], v[56:57], v[44:45]
	v_add_u32_e32 v56, 0xa0, v156
	v_ashrrev_i32_e32 v57, 31, v56
	v_pk_fma_f32 v[40:41], v[40:41], v[42:43], v[48:49]
	v_lshlrev_b64 v[42:43], 10, v[56:57]
	v_lshl_add_u64 v[42:43], v[42:43], 0, v[154:155]
	v_lshlrev_b64 v[48:49], 1, v[42:43]
	v_add_f32_e32 v70, 1.0, v72
	v_or_b32_e32 v90, 0x100, v48
	v_mov_b32_e32 v91, v49
	v_rcp_f32_e32 v88, v71
	v_rcp_f32_e32 v89, v70
	v_lshl_add_u64 v[42:43], s[8:9], 0, v[90:91]
	v_lshl_add_u64 v[70:71], s[8:9], 0, v[46:47]
	global_load_dwordx4 v[42:45], v[42:43], off
	s_nop 0
	global_load_dwordx4 v[70:73], v[70:71], off
	v_pk_fma_f32 v[34:35], v[34:35], v[86:87], v[82:83]
	v_pk_fma_f32 v[36:37], v[36:37], v[88:89], v[84:85]
	v_cvt_pk_bf16_f32 v84, v34, v35
	v_lshl_add_u64 v[34:35], s[8:9], 0, v[48:49]
	v_cvt_pk_bf16_f32 v82, v38, v39
	v_cvt_pk_bf16_f32 v83, v40, v41
	global_load_dwordx4 v[38:41], v[34:35], off
	v_lshl_add_u64 v[34:35], s[10:11], 0, v[46:47]
	global_load_dwordx4 v[86:89], v[34:35], off
	v_cvt_pk_bf16_f32 v85, v36, v37
	v_lshl_add_u64 v[34:35], s[10:11], 0, v[90:91]
	v_lshl_add_u64 v[36:37], s[10:11], 0, v[48:49]
	global_load_dwordx4 v[46:49], v[34:35], off
	s_nop 0
	global_load_dwordx4 v[34:37], v[36:37], off
	s_nop 0
	global_store_dwordx4 v[74:75], v[58:61], off nt
	global_store_dwordx4 v[74:75], v[50:53], off offset:256 nt
	s_waitcnt vmcnt(8)
	v_lshlrev_b32_e32 v58, 16, v66
	v_lshlrev_b32_e32 v52, 16, v78
	v_and_b32_e32 v53, 0xffff0000, v78
	v_mul_f32_e32 v52, 0xbfb8aa3b, v52
	v_mul_f32_e32 v53, 0xbfb8aa3b, v53
	v_exp_f32_e32 v52, v52
	v_exp_f32_e32 v53, v53
	v_lshlrev_b64 v[50:51], 11, v[76:77]
	v_lshl_add_u64 v[50:51], s[12:13], 0, v[50:51]
	v_lshl_add_u64 v[50:51], v[50:51], 0, v[106:107]
	global_store_dwordx4 v[50:51], v[62:65], off nt
	global_store_dwordx4 v[50:51], v[82:85], off offset:256 nt
	v_add_f32_e32 v50, 1.0, v52
	v_add_f32_e32 v51, 1.0, v53
	v_rcp_f32_e32 v50, v50
	v_rcp_f32_e32 v51, v51
	v_lshlrev_b32_e32 v52, 16, v79
	v_and_b32_e32 v53, 0xffff0000, v79
	v_mul_f32_e32 v52, 0xbfb8aa3b, v52
	v_mul_f32_e32 v53, 0xbfb8aa3b, v53
	v_exp_f32_e32 v52, v52
	v_exp_f32_e32 v53, v53
	v_and_b32_e32 v59, 0xffff0000, v66
	v_pk_fma_f32 v[30:31], v[30:31], v[50:51], v[58:59]
	v_add_f32_e32 v52, 1.0, v52
	v_cvt_pk_bf16_f32 v30, v30, v31
	v_lshlrev_b32_e32 v31, 16, v80
	v_mul_f32_e32 v31, 0xbfb8aa3b, v31
	v_add_f32_e32 v53, 1.0, v53
	v_exp_f32_e32 v50, v31
	v_and_b32_e32 v31, 0xffff0000, v80
	v_rcp_f32_e32 v52, v52
	v_rcp_f32_e32 v53, v53
	v_mul_f32_e32 v31, 0xbfb8aa3b, v31
	v_exp_f32_e32 v51, v31
	v_lshlrev_b32_e32 v60, 16, v67
	v_and_b32_e32 v61, 0xffff0000, v67
	v_pk_fma_f32 v[32:33], v[32:33], v[52:53], v[60:61]
	v_lshlrev_b32_e32 v52, 16, v68
	v_cvt_pk_bf16_f32 v31, v32, v33
	v_add_f32_e32 v32, 1.0, v50
	v_add_f32_e32 v33, 1.0, v51
	v_rcp_f32_e32 v32, v32
	v_rcp_f32_e32 v33, v33
	v_lshlrev_b32_e32 v50, 16, v81
	v_and_b32_e32 v51, 0xffff0000, v81
	v_mul_f32_e32 v50, 0xbfb8aa3b, v50
	v_mul_f32_e32 v51, 0xbfb8aa3b, v51
	v_exp_f32_e32 v50, v50
	v_exp_f32_e32 v51, v51
	v_and_b32_e32 v53, 0xffff0000, v68
	v_pk_fma_f32 v[26:27], v[26:27], v[32:33], v[52:53]
	v_add_f32_e32 v50, 1.0, v50
	v_cvt_pk_bf16_f32 v32, v26, v27
	s_waitcnt vmcnt(8)
	v_lshlrev_b32_e32 v26, 16, v70
	v_and_b32_e32 v27, 0xffff0000, v70
	v_mul_f32_e32 v26, 0xbfb8aa3b, v26
	v_mul_f32_e32 v27, 0xbfb8aa3b, v27
	v_add_f32_e32 v51, 1.0, v51
	v_exp_f32_e32 v26, v26
	v_exp_f32_e32 v27, v27
	v_rcp_f32_e32 v50, v50
	v_rcp_f32_e32 v51, v51
	v_lshlrev_b32_e32 v58, 16, v69
	v_and_b32_e32 v59, 0xffff0000, v69
	v_add_f32_e32 v26, 1.0, v26
	v_add_f32_e32 v27, 1.0, v27
	v_pk_fma_f32 v[28:29], v[28:29], v[50:51], v[58:59]
	v_rcp_f32_e32 v26, v26
	v_rcp_f32_e32 v27, v27
	v_cvt_pk_bf16_f32 v33, v28, v29
	v_lshlrev_b32_e32 v28, 16, v71
	v_and_b32_e32 v29, 0xffff0000, v71
	v_mul_f32_e32 v28, 0xbfb8aa3b, v28
	v_mul_f32_e32 v29, 0xbfb8aa3b, v29
	v_exp_f32_e32 v28, v28
	v_exp_f32_e32 v29, v29
	s_waitcnt vmcnt(6)
	v_lshlrev_b32_e32 v50, 16, v86
	v_and_b32_e32 v51, 0xffff0000, v86
	v_pk_fma_f32 v[22:23], v[22:23], v[26:27], v[50:51]
	v_add_f32_e32 v28, 1.0, v28
	v_cvt_pk_bf16_f32 v22, v22, v23
	v_lshlrev_b32_e32 v23, 16, v72
	v_mul_f32_e32 v23, 0xbfb8aa3b, v23
	v_add_f32_e32 v29, 1.0, v29
	v_exp_f32_e32 v26, v23
	v_and_b32_e32 v23, 0xffff0000, v72
	v_rcp_f32_e32 v28, v28
	v_rcp_f32_e32 v29, v29
	v_mul_f32_e32 v23, 0xbfb8aa3b, v23
	v_exp_f32_e32 v27, v23
	v_lshlrev_b32_e32 v52, 16, v87
	v_and_b32_e32 v53, 0xffff0000, v87
	v_pk_fma_f32 v[24:25], v[24:25], v[28:29], v[52:53]
	v_lshlrev_b32_e32 v28, 16, v88
	v_cvt_pk_bf16_f32 v23, v24, v25
	v_add_f32_e32 v24, 1.0, v26
	v_add_f32_e32 v25, 1.0, v27
	v_rcp_f32_e32 v24, v24
	v_rcp_f32_e32 v25, v25
	v_lshlrev_b32_e32 v26, 16, v73
	v_and_b32_e32 v27, 0xffff0000, v73
	v_mul_f32_e32 v26, 0xbfb8aa3b, v26
	v_mul_f32_e32 v27, 0xbfb8aa3b, v27
	v_exp_f32_e32 v26, v26
	v_exp_f32_e32 v27, v27
	v_and_b32_e32 v29, 0xffff0000, v88
	v_pk_fma_f32 v[18:19], v[18:19], v[24:25], v[28:29]
	v_add_f32_e32 v26, 1.0, v26
	v_cvt_pk_bf16_f32 v24, v18, v19
	v_lshlrev_b32_e32 v18, 16, v42
	v_and_b32_e32 v19, 0xffff0000, v42
	v_mul_f32_e32 v18, 0xbfb8aa3b, v18
	v_mul_f32_e32 v19, 0xbfb8aa3b, v19
	v_add_f32_e32 v27, 1.0, v27
	v_exp_f32_e32 v18, v18
	v_exp_f32_e32 v19, v19
	v_rcp_f32_e32 v26, v26
	v_rcp_f32_e32 v27, v27
	v_lshlrev_b32_e32 v50, 16, v89
	v_and_b32_e32 v51, 0xffff0000, v89
	v_add_f32_e32 v18, 1.0, v18
	v_add_f32_e32 v19, 1.0, v19
	v_pk_fma_f32 v[20:21], v[20:21], v[26:27], v[50:51]
	v_rcp_f32_e32 v18, v18
	v_rcp_f32_e32 v19, v19
	v_cvt_pk_bf16_f32 v25, v20, v21
	v_lshlrev_b32_e32 v20, 16, v43
	v_and_b32_e32 v21, 0xffff0000, v43
	v_mul_f32_e32 v20, 0xbfb8aa3b, v20
	v_mul_f32_e32 v21, 0xbfb8aa3b, v21
	v_exp_f32_e32 v20, v20
	v_exp_f32_e32 v21, v21
	s_waitcnt vmcnt(5)
	v_lshlrev_b32_e32 v26, 16, v46
	v_and_b32_e32 v27, 0xffff0000, v46
	v_pk_fma_f32 v[14:15], v[14:15], v[18:19], v[26:27]
	v_add_f32_e32 v20, 1.0, v20
	v_cvt_pk_bf16_f32 v14, v14, v15
	v_lshlrev_b32_e32 v15, 16, v44
	v_mul_f32_e32 v15, 0xbfb8aa3b, v15
	v_add_f32_e32 v21, 1.0, v21
	v_exp_f32_e32 v18, v15
	v_and_b32_e32 v15, 0xffff0000, v44
	v_rcp_f32_e32 v20, v20
	v_rcp_f32_e32 v21, v21
	v_mul_f32_e32 v15, 0xbfb8aa3b, v15
	v_exp_f32_e32 v19, v15
	v_lshlrev_b32_e32 v28, 16, v47
	v_and_b32_e32 v29, 0xffff0000, v47
	v_pk_fma_f32 v[16:17], v[16:17], v[20:21], v[28:29]
	v_lshlrev_b32_e32 v20, 16, v48
	v_cvt_pk_bf16_f32 v15, v16, v17
	v_add_f32_e32 v16, 1.0, v18
	v_add_f32_e32 v17, 1.0, v19
	v_rcp_f32_e32 v16, v16
	v_rcp_f32_e32 v17, v17
	v_lshlrev_b32_e32 v18, 16, v45
	v_and_b32_e32 v19, 0xffff0000, v45
	v_mul_f32_e32 v18, 0xbfb8aa3b, v18
	v_mul_f32_e32 v19, 0xbfb8aa3b, v19
	v_exp_f32_e32 v18, v18
	v_exp_f32_e32 v19, v19
	v_and_b32_e32 v21, 0xffff0000, v48
	v_pk_fma_f32 v[10:11], v[10:11], v[16:17], v[20:21]
	v_add_f32_e32 v18, 1.0, v18
	v_cvt_pk_bf16_f32 v16, v10, v11
	v_lshlrev_b32_e32 v10, 16, v38
	v_and_b32_e32 v11, 0xffff0000, v38
	v_mul_f32_e32 v10, 0xbfb8aa3b, v10
	v_mul_f32_e32 v11, 0xbfb8aa3b, v11
	v_add_f32_e32 v19, 1.0, v19
	v_exp_f32_e32 v10, v10
	v_exp_f32_e32 v11, v11
	v_rcp_f32_e32 v18, v18
	v_rcp_f32_e32 v19, v19
	v_lshlrev_b32_e32 v26, 16, v49
	v_and_b32_e32 v27, 0xffff0000, v49
	v_add_f32_e32 v10, 1.0, v10
	v_add_f32_e32 v11, 1.0, v11
	v_pk_fma_f32 v[12:13], v[12:13], v[18:19], v[26:27]
	v_rcp_f32_e32 v10, v10
	v_rcp_f32_e32 v11, v11
	v_cvt_pk_bf16_f32 v17, v12, v13
	v_lshlrev_b32_e32 v12, 16, v39
	v_and_b32_e32 v13, 0xffff0000, v39
	v_mul_f32_e32 v12, 0xbfb8aa3b, v12
	v_mul_f32_e32 v13, 0xbfb8aa3b, v13
	v_exp_f32_e32 v12, v12
	v_exp_f32_e32 v13, v13
	s_waitcnt vmcnt(4)
	v_lshlrev_b32_e32 v18, 16, v34
	v_and_b32_e32 v19, 0xffff0000, v34
	v_pk_fma_f32 v[6:7], v[6:7], v[10:11], v[18:19]
	v_add_f32_e32 v12, 1.0, v12
	v_cvt_pk_bf16_f32 v6, v6, v7
	v_lshlrev_b32_e32 v7, 16, v40
	v_mul_f32_e32 v7, 0xbfb8aa3b, v7
	v_add_f32_e32 v13, 1.0, v13
	v_exp_f32_e32 v10, v7
	v_and_b32_e32 v7, 0xffff0000, v40
	v_rcp_f32_e32 v12, v12
	v_rcp_f32_e32 v13, v13
	v_mul_f32_e32 v7, 0xbfb8aa3b, v7
	v_exp_f32_e32 v11, v7
	v_lshlrev_b32_e32 v20, 16, v35
	v_and_b32_e32 v21, 0xffff0000, v35
	v_pk_fma_f32 v[8:9], v[8:9], v[12:13], v[20:21]
	v_lshlrev_b32_e32 v12, 16, v36
	v_cvt_pk_bf16_f32 v7, v8, v9
	v_add_f32_e32 v8, 1.0, v10
	v_add_f32_e32 v9, 1.0, v11
	v_lshlrev_b32_e32 v10, 16, v41
	v_and_b32_e32 v11, 0xffff0000, v41
	v_mul_f32_e32 v10, 0xbfb8aa3b, v10
	v_mul_f32_e32 v11, 0xbfb8aa3b, v11
	v_exp_f32_e32 v10, v10
	v_exp_f32_e32 v11, v11
	v_rcp_f32_e32 v8, v8
	v_rcp_f32_e32 v9, v9
	v_add_f32_e32 v10, 1.0, v10
	v_add_f32_e32 v11, 1.0, v11
	v_rcp_f32_e32 v10, v10
	v_rcp_f32_e32 v11, v11
	v_and_b32_e32 v13, 0xffff0000, v36
	v_pk_fma_f32 v[2:3], v[2:3], v[8:9], v[12:13]
	v_lshlrev_b32_e32 v18, 16, v37
	v_and_b32_e32 v19, 0xffff0000, v37
	v_cvt_pk_bf16_f32 v8, v2, v3
	v_lshlrev_b64 v[2:3], 11, v[56:57]
	v_pk_fma_f32 v[4:5], v[4:5], v[10:11], v[18:19]
	v_lshl_add_u64 v[2:3], s[12:13], 0, v[2:3]
	v_cvt_pk_bf16_f32 v9, v4, v5
	v_lshl_add_u64 v[2:3], v[2:3], 0, v[106:107]
	global_store_dwordx4 v[2:3], v[6:9], off nt
	global_store_dwordx4 v[2:3], v[14:17], off offset:256 nt
	v_lshlrev_b64 v[2:3], 11, v[54:55]
	v_lshl_add_u64 v[2:3], s[12:13], 0, v[2:3]
	v_lshl_add_u64 v[2:3], v[2:3], 0, v[106:107]
	global_store_dwordx4 v[2:3], v[22:25], off nt
	global_store_dwordx4 v[2:3], v[30:33], off offset:256 nt
	s_cbranch_vccnz .LBB0_788
	s_andn2_b64 vcc, exec, s[6:7]
	s_cbranch_vccnz .LBB0_787
	s_barrier
	s_branch .LBB0_787

.LBB0_878:
	v_lshl_add_u32 v180, s36, 8, v1
	v_lshl_or_b32 v178, s10, 8, v191
	v_ashrrev_i32_e32 v179, 31, v178
	v_ashrrev_i32_e32 v181, 31, v180
	v_lshl_add_u64 v[182:183], v[178:179], 2, s[8:9]
	v_lshlrev_b64 v[130:131], 12, v[180:181]
	v_or_b32_e32 v188, 16, v180
	v_lshl_add_u64 v[130:131], v[182:183], 0, v[130:131]
	v_ashrrev_i32_e32 v189, 31, v188
	global_load_dwordx4 v[196:199], v[130:131], off
	global_load_dwordx4 v[200:203], v[130:131], off offset:16
	global_load_dwordx4 v[204:207], v[130:131], off offset:512
	global_load_dwordx4 v[208:211], v[130:131], off offset:528
	v_lshlrev_b64 v[130:131], 12, v[188:189]
	v_lshl_add_u64 v[130:131], v[182:183], 0, v[130:131]
	global_load_dwordx4 v[212:215], v[130:131], off
	global_load_dwordx4 v[216:219], v[130:131], off offset:16
	global_load_dwordx4 v[220:223], v[130:131], off offset:528
	global_load_dwordx4 v[224:227], v[130:131], off offset:512
	v_or_b32_e32 v186, 32, v180
	v_or_b32_e32 v184, 48, v180
	v_ashrrev_i32_e32 v187, 31, v186
	v_ashrrev_i32_e32 v185, 31, v184
	v_lshlrev_b64 v[130:131], 12, v[186:187]
	v_lshlrev_b64 v[132:133], 12, v[184:185]
	v_lshl_add_u64 v[130:131], v[182:183], 0, v[130:131]
	v_lshl_add_u64 v[134:135], v[182:183], 0, v[132:133]
	global_load_dwordx4 v[154:157], v[130:131], off offset:16
	global_load_dwordx4 v[158:161], v[130:131], off
	global_load_dwordx4 v[146:149], v[130:131], off offset:528
	global_load_dwordx4 v[150:153], v[130:131], off offset:512
	global_load_dwordx4 v[138:141], v[134:135], off offset:16
	global_load_dwordx4 v[142:145], v[134:135], off
	s_nop 0
	global_load_dwordx4 v[130:133], v[134:135], off offset:528
	s_nop 0
	global_load_dwordx4 v[134:137], v[134:135], off offset:512
	s_waitcnt vmcnt(0)
	v_pk_add_f32 v[128:129], v[128:129], v[198:199]
	v_pk_add_f32 v[126:127], v[126:127], v[196:197]
	v_pk_add_f32 v[196:197], v[124:125], v[202:203]
	v_pk_add_f32 v[198:199], v[122:123], v[200:201]
	v_pk_add_f32 v[202:203], v[114:115], v[204:205]
	v_pk_add_f32 v[106:107], v[106:107], v[208:209]
	v_pk_add_f32 v[200:201], v[116:117], v[206:207]
	v_cvt_pk_bf16_f32 v116, v198, v199
	v_mul_f32_e32 v195, v199, v199
	v_cvt_pk_bf16_f32 v122, v202, v203
	v_mul_f32_e32 v199, v203, v203
	v_mul_f32_e32 v203, v107, v107
	v_pk_add_f32 v[120:121], v[120:121], v[214:215]
	v_pk_add_f32 v[118:119], v[118:119], v[212:213]
	v_cvt_pk_bf16_f32 v114, v126, v127
	v_mul_f32_e32 v127, v127, v127
	v_cvt_pk_bf16_f32 v124, v106, v107
	v_pk_add_f32 v[110:111], v[110:111], v[216:217]
	v_fmac_f32_e32 v203, v106, v106
	v_cvt_pk_bf16_f32 v106, v118, v119
	v_cvt_pk_bf16_f32 v107, v120, v121
	v_mul_f32_e32 v119, v119, v119
	v_mul_f32_e32 v121, v121, v121
	v_pk_add_f32 v[108:109], v[108:109], v[210:211]
	v_pk_add_f32 v[112:113], v[112:113], v[218:219]
	v_fmac_f32_e32 v127, v126, v126
	v_mul_f32_e32 v126, v111, v111
	v_fmac_f32_e32 v119, v118, v118
	v_fmac_f32_e32 v121, v120, v120
	v_cvt_pk_bf16_f32 v125, v108, v109
	v_mul_f32_e32 v204, v109, v109
	v_cvt_pk_bf16_f32 v109, v112, v113
	v_fmac_f32_e32 v126, v110, v110
	v_add_f32_e32 v118, v119, v121
	v_mul_f32_e32 v113, v113, v113
	v_add_f32_e32 v118, v118, v126
	v_fmac_f32_e32 v113, v112, v112
	v_pk_add_f32 v[102:103], v[102:103], v[224:225]
	v_add_f32_e32 v120, v113, v118
	v_pk_add_f32 v[104:105], v[104:105], v[226:227]
	v_pk_add_f32 v[118:119], v[98:99], v[220:221]
	v_cvt_pk_bf16_f32 v98, v102, v103
	v_mul_f32_e32 v103, v103, v103
	v_fmac_f32_e32 v103, v102, v102
	v_mul_f32_e32 v102, v105, v105
	v_fmac_f32_e32 v102, v104, v104
	v_add_f32_e32 v102, v103, v102
	v_mul_f32_e32 v103, v119, v119
	v_cvt_pk_bf16_f32 v115, v128, v129
	v_mul_f32_e32 v129, v129, v129
	v_cvt_pk_bf16_f32 v123, v200, v201
	v_mul_f32_e32 v201, v201, v201
	v_pk_add_f32 v[112:113], v[100:101], v[222:223]
	v_fmac_f32_e32 v103, v118, v118
	v_fmac_f32_e32 v129, v128, v128
	v_fmac_f32_e32 v199, v202, v202
	v_fmac_f32_e32 v201, v200, v200
	v_add_f32_e32 v102, v102, v103
	v_mul_f32_e32 v103, v113, v113
	v_cvt_pk_bf16_f32 v117, v196, v197
	v_mul_f32_e32 v197, v197, v197
	v_fmac_f32_e32 v195, v198, v198
	v_fmac_f32_e32 v204, v108, v108
	v_cvt_pk_bf16_f32 v108, v110, v111
	v_add_f32_e32 v111, v127, v129
	v_add_f32_e32 v127, v199, v201
	v_fmac_f32_e32 v103, v112, v112
	v_fmac_f32_e32 v197, v196, v196
	v_add_f32_e32 v110, v111, v195
	v_add_f32_e32 v111, v127, v203
	v_add_f32_e32 v102, v103, v102
	v_add_f32_e32 v110, v197, v110
	v_add_f32_e32 v111, v204, v111
	v_add_f32_e32 v102, v120, v102
	v_add_f32_e32 v110, v110, v111
	v_mov_b32_e32 v103, v102
	v_mov_b32_e32 v111, v110
	s_nop 0
	v_permlane16_swap_b32_e32 v102, v103
	v_permlane16_swap_b32_e32 v110, v111
	v_cvt_pk_bf16_f32 v99, v104, v105
	v_add_f32_e32 v104, v102, v103
	v_lshlrev_b64 v[102:103], 11, v[180:181]
	v_add_f32_e32 v110, v110, v111
	v_lshl_add_u64 v[102:103], s[14:15], 0, v[102:103]
	v_mov_b32_e32 v111, v110
	v_mov_b32_e32 v105, v104
	v_lshl_add_u64 v[120:121], v[178:179], 1, v[102:103]
	v_lshlrev_b64 v[102:103], 11, v[188:189]
	v_permlane32_swap_b32_e32 v110, v111
	v_cvt_pk_bf16_f32 v100, v118, v119
	v_cvt_pk_bf16_f32 v101, v112, v113
	v_permlane32_swap_b32_e32 v104, v105
	v_lshl_add_u64 v[102:103], s[14:15], 0, v[102:103]
	global_store_dwordx4 v[120:121], v[114:117], off nt
	global_store_dwordx4 v[120:121], v[122:125], off offset:256 nt
	s_and_saveexec_b64 s[0:1], s[2:3]
	s_xor_b64 s[0:1], exec, s[0:1]
	s_cbranch_execz .LBB0_880
	v_lshl_add_u64 v[102:103], v[178:179], 1, v[102:103]
	global_store_dwordx4 v[102:103], v[106:109], off nt
	global_store_dwordx4 v[102:103], v[98:101], off offset:256 nt
.LBB0_880:
	s_or_saveexec_b64 s[36:37], s[0:1]
	s_lshl_b32 s0, s10, 2
	v_lshlrev_b64 v[112:113], 6, v[180:181]
	s_ashr_i32 s1, s0, 31
	v_lshl_add_u64 v[122:123], s[16:17], 0, v[112:113]
	s_xor_b64 exec, exec, s[36:37]
	s_cbranch_execz .LBB0_882
	s_lshl_b64 s[38:39], s[0:1], 2
	v_add_f32_e32 v112, v104, v105
	v_lshl_add_u64 v[104:105], v[122:123], 0, s[38:39]
	s_lshl_b32 s10, s51, 2
	v_add_f32_e32 v110, v110, v111
	v_lshl_add_u64 v[104:105], v[104:105], 0, s[10:11]
	v_lshl_add_u64 v[102:103], v[178:179], 1, v[102:103]
	global_store_dword v[104:105], v110, off
	global_store_dwordx4 v[102:103], v[106:109], off nt
	global_store_dwordx4 v[102:103], v[98:101], off offset:256 nt
	s_nop 1
	v_lshlrev_b64 v[98:99], 6, v[188:189]
	v_lshl_add_u64 v[98:99], s[16:17], 0, v[98:99]
	v_lshl_add_u64 v[98:99], v[98:99], 0, s[38:39]
	v_lshl_add_u64 v[98:99], v[98:99], 0, s[10:11]
	global_store_dword v[98:99], v112, off
.LBB0_882:
	s_or_b64 exec, exec, s[36:37]
	v_pk_add_f32 v[94:95], v[94:95], v[158:159]
	v_pk_add_f32 v[96:97], v[96:97], v[160:161]
	v_pk_add_f32 v[90:91], v[90:91], v[154:155]
	v_cvt_pk_bf16_f32 v154, v94, v95
	v_mul_f32_e32 v95, v95, v95
	v_add_u32_e32 v126, 0x80, v180
	v_fmac_f32_e32 v95, v94, v94
	v_mul_f32_e32 v94, v97, v97
	v_ashrrev_i32_e32 v127, 31, v126
	v_pk_add_f32 v[92:93], v[92:93], v[156:157]
	v_cvt_pk_bf16_f32 v156, v90, v91
	v_fmac_f32_e32 v94, v96, v96
	v_mul_f32_e32 v91, v91, v91
	v_pk_add_f32 v[128:129], v[88:89], v[152:153]
	v_lshlrev_b64 v[88:89], 12, v[126:127]
	v_add_u32_e32 v124, 0x90, v180
	v_add_f32_e32 v94, v95, v94
	v_fmac_f32_e32 v91, v90, v90
	v_lshl_add_u64 v[88:89], v[182:183], 0, v[88:89]
	v_ashrrev_i32_e32 v125, 31, v124
	v_add_f32_e32 v90, v94, v91
	v_mul_f32_e32 v91, v93, v93
	global_load_dwordx4 v[112:115], v[88:89], off offset:16
	global_load_dwordx4 v[116:119], v[88:89], off
	global_load_dwordx4 v[104:107], v[88:89], off offset:528
	global_load_dwordx4 v[108:111], v[88:89], off offset:512
	v_lshlrev_b64 v[88:89], 12, v[124:125]
	v_cvt_pk_bf16_f32 v157, v92, v93
	v_fmac_f32_e32 v91, v92, v92
	v_lshl_add_u64 v[92:93], v[182:183], 0, v[88:89]
	v_cvt_pk_bf16_f32 v155, v96, v97
	v_add_f32_e32 v158, v91, v90
	global_load_dwordx4 v[96:99], v[92:93], off offset:16
	global_load_dwordx4 v[100:103], v[92:93], off
	global_load_dwordx4 v[88:91], v[92:93], off offset:528
	s_nop 0
	global_load_dwordx4 v[92:95], v[92:93], off offset:512
	v_pk_add_f32 v[86:87], v[86:87], v[150:151]
	v_pk_add_f32 v[78:79], v[78:79], v[146:147]
	v_cvt_pk_bf16_f32 v146, v86, v87
	v_mul_f32_e32 v87, v87, v87
	v_fmac_f32_e32 v87, v86, v86
	v_mul_f32_e32 v86, v129, v129
	v_pk_add_f32 v[80:81], v[80:81], v[148:149]
	v_cvt_pk_bf16_f32 v148, v78, v79
	v_fmac_f32_e32 v86, v128, v128
	v_mul_f32_e32 v79, v79, v79
	v_add_f32_e32 v86, v87, v86
	v_fmac_f32_e32 v79, v78, v78
	v_add_f32_e32 v78, v86, v79
	v_mul_f32_e32 v79, v81, v81
	v_cvt_pk_bf16_f32 v149, v80, v81
	v_fmac_f32_e32 v79, v80, v80
	v_pk_add_f32 v[80:81], v[84:85], v[144:145]
	v_pk_add_f32 v[82:83], v[82:83], v[142:143]
	v_pk_add_f32 v[86:87], v[74:75], v[138:139]
	v_cvt_pk_bf16_f32 v74, v82, v83
	v_cvt_pk_bf16_f32 v75, v80, v81
	v_mul_f32_e32 v83, v83, v83
	v_mul_f32_e32 v81, v81, v81
	v_fmac_f32_e32 v83, v82, v82
	v_fmac_f32_e32 v81, v80, v80
	v_pk_add_f32 v[70:71], v[70:71], v[134:135]
	v_add_f32_e32 v80, v83, v81
	v_mul_f32_e32 v81, v87, v87
	v_pk_add_f32 v[72:73], v[72:73], v[136:137]
	v_pk_add_f32 v[82:83], v[66:67], v[130:131]
	v_cvt_pk_bf16_f32 v66, v70, v71
	v_mul_f32_e32 v71, v71, v71
	v_pk_add_f32 v[84:85], v[76:77], v[140:141]
	v_fmac_f32_e32 v81, v86, v86
	v_fmac_f32_e32 v71, v70, v70
	v_mul_f32_e32 v70, v73, v73
	v_add_f32_e32 v80, v80, v81
	v_mul_f32_e32 v81, v85, v85
	v_fmac_f32_e32 v70, v72, v72
	v_fmac_f32_e32 v81, v84, v84
	v_add_f32_e32 v70, v71, v70
	v_mul_f32_e32 v71, v83, v83
	v_cvt_pk_bf16_f32 v77, v84, v85
	v_add_f32_e32 v84, v81, v80
	v_pk_add_f32 v[80:81], v[68:69], v[132:133]
	v_fmac_f32_e32 v71, v82, v82
	v_add_f32_e32 v70, v70, v71
	v_mul_f32_e32 v71, v81, v81
	v_fmac_f32_e32 v71, v80, v80
	v_add_f32_e32 v70, v71, v70
	v_add_f32_e32 v70, v84, v70
	v_add_f32_e32 v78, v79, v78
	v_mov_b32_e32 v71, v70
	v_add_f32_e32 v78, v158, v78
	s_nop 0
	v_permlane16_swap_b32_e32 v70, v71
	v_mov_b32_e32 v79, v78
	v_cvt_pk_bf16_f32 v67, v72, v73
	v_add_f32_e32 v72, v70, v71
	v_lshlrev_b64 v[70:71], 11, v[186:187]
	v_permlane16_swap_b32_e32 v78, v79
	v_lshl_add_u64 v[70:71], s[14:15], 0, v[70:71]
	v_add_f32_e32 v78, v78, v79
	v_lshl_add_u64 v[70:71], v[178:179], 1, v[70:71]
	v_cvt_pk_bf16_f32 v147, v128, v129
	v_mov_b32_e32 v79, v78
	v_mov_b32_e32 v73, v72
	global_store_dwordx4 v[70:71], v[154:157], off nt
	global_store_dwordx4 v[70:71], v[146:149], off offset:256 nt
	v_lshlrev_b64 v[70:71], 11, v[184:185]
	v_permlane32_swap_b32_e32 v78, v79
	v_cvt_pk_bf16_f32 v76, v86, v87
	v_cvt_pk_bf16_f32 v68, v82, v83
	v_cvt_pk_bf16_f32 v69, v80, v81
	v_permlane32_swap_b32_e32 v72, v73
	v_lshl_add_u64 v[70:71], s[14:15], 0, v[70:71]
	s_and_saveexec_b64 s[36:37], s[2:3]
	s_xor_b64 s[36:37], exec, s[36:37]
	s_cbranch_execz .LBB0_884
	v_lshl_add_u64 v[70:71], v[178:179], 1, v[70:71]
	global_store_dwordx4 v[70:71], v[74:77], off nt
	global_store_dwordx4 v[70:71], v[66:69], off offset:256 nt
.LBB0_884:
	s_andn2_saveexec_b64 s[36:37], s[36:37]
	s_cbranch_execz .LBB0_886
	v_add_f32_e32 v80, v72, v73
	v_lshlrev_b64 v[72:73], 6, v[186:187]
	v_lshl_add_u64 v[72:73], s[16:17], 0, v[72:73]
	s_lshl_b64 s[38:39], s[0:1], 2
	v_lshl_add_u64 v[72:73], v[72:73], 0, s[38:39]
	s_lshl_b32 s10, s51, 2
	v_add_f32_e32 v78, v78, v79
	v_lshl_add_u64 v[72:73], v[72:73], 0, s[10:11]
	v_lshl_add_u64 v[70:71], v[178:179], 1, v[70:71]
	global_store_dword v[72:73], v78, off
	global_store_dwordx4 v[70:71], v[74:77], off nt
	global_store_dwordx4 v[70:71], v[66:69], off offset:256 nt
	s_nop 1
	v_lshlrev_b64 v[66:67], 6, v[184:185]
	v_lshl_add_u64 v[66:67], s[16:17], 0, v[66:67]
	v_lshl_add_u64 v[66:67], v[66:67], 0, s[38:39]
	v_lshl_add_u64 v[66:67], v[66:67], 0, s[10:11]
	global_store_dword v[66:67], v80, off
.LBB0_886:
	s_or_b64 exec, exec, s[36:37]
	s_waitcnt vmcnt(8)
	v_pk_add_f32 v[62:63], v[62:63], v[116:117]
	v_pk_add_f32 v[64:65], v[64:65], v[118:119]
	v_cvt_pk_bf16_f32 v116, v62, v63
	v_mul_f32_e32 v63, v63, v63
	v_pk_add_f32 v[58:59], v[58:59], v[112:113]
	v_fmac_f32_e32 v63, v62, v62
	v_mul_f32_e32 v62, v65, v65
	v_cvt_pk_bf16_f32 v118, v58, v59
	v_fmac_f32_e32 v62, v64, v64
	v_mul_f32_e32 v59, v59, v59
	v_or_b32_e32 v86, 32, v126
	v_add_f32_e32 v62, v63, v62
	v_fmac_f32_e32 v59, v58, v58
	v_ashrrev_i32_e32 v87, 31, v86
	v_add_f32_e32 v128, v62, v59
	v_lshlrev_b64 v[58:59], 12, v[86:87]
	v_lshl_add_u64 v[58:59], v[182:183], 0, v[58:59]
	v_pk_add_f32 v[60:61], v[60:61], v[114:115]
	global_load_dwordx4 v[82:85], v[58:59], off offset:16
	global_load_dwordx4 v[112:115], v[58:59], off
	global_load_dwordx4 v[74:77], v[58:59], off offset:528
	global_load_dwordx4 v[78:81], v[58:59], off offset:512
	v_or_b32_e32 v58, 48, v126
	v_ashrrev_i32_e32 v59, 31, v58
	v_lshlrev_b64 v[58:59], 12, v[58:59]
	v_mul_f32_e32 v129, v61, v61
	v_lshl_add_u64 v[62:63], v[182:183], 0, v[58:59]
	v_cvt_pk_bf16_f32 v117, v64, v65
	v_cvt_pk_bf16_f32 v119, v60, v61
	v_fmac_f32_e32 v129, v60, v60
	global_load_dwordx4 v[66:69], v[62:63], off offset:16
	global_load_dwordx4 v[70:73], v[62:63], off
	global_load_dwordx4 v[58:61], v[62:63], off offset:528
	s_nop 0
	global_load_dwordx4 v[62:65], v[62:63], off offset:512
	s_waitcnt vmcnt(14)
	v_pk_add_f32 v[110:111], v[56:57], v[110:111]
	v_pk_add_f32 v[108:109], v[54:55], v[108:109]
	v_pk_add_f32 v[46:47], v[46:47], v[104:105]
	v_mul_f32_e32 v104, v109, v109
	v_mul_f32_e32 v105, v111, v111
	v_cvt_pk_bf16_f32 v56, v46, v47
	v_fmac_f32_e32 v104, v108, v108
	v_fmac_f32_e32 v105, v110, v110
	v_mul_f32_e32 v47, v47, v47
	v_pk_add_f32 v[48:49], v[48:49], v[106:107]
	v_add_f32_e32 v104, v104, v105
	v_fmac_f32_e32 v47, v46, v46
	v_add_f32_e32 v46, v104, v47
	v_mul_f32_e32 v47, v49, v49
	v_cvt_pk_bf16_f32 v57, v48, v49
	v_fmac_f32_e32 v47, v48, v48
	s_waitcnt vmcnt(12)
	v_pk_add_f32 v[48:49], v[52:53], v[102:103]
	v_pk_add_f32 v[50:51], v[50:51], v[100:101]
	v_pk_add_f32 v[96:97], v[42:43], v[96:97]
	v_cvt_pk_bf16_f32 v42, v50, v51
	v_cvt_pk_bf16_f32 v43, v48, v49
	v_mul_f32_e32 v51, v51, v51
	v_mul_f32_e32 v49, v49, v49
	v_fmac_f32_e32 v51, v50, v50
	v_fmac_f32_e32 v49, v48, v48
	s_waitcnt vmcnt(10)
	v_pk_add_f32 v[38:39], v[38:39], v[92:93]
	v_add_f32_e32 v48, v51, v49
	v_mul_f32_e32 v49, v97, v97
	v_pk_add_f32 v[40:41], v[40:41], v[94:95]
	v_pk_add_f32 v[50:51], v[34:35], v[88:89]
	v_cvt_pk_bf16_f32 v34, v38, v39
	v_mul_f32_e32 v39, v39, v39
	v_pk_add_f32 v[52:53], v[44:45], v[98:99]
	v_fmac_f32_e32 v49, v96, v96
	v_fmac_f32_e32 v39, v38, v38
	v_mul_f32_e32 v38, v41, v41
	v_add_f32_e32 v48, v48, v49
	v_mul_f32_e32 v49, v53, v53
	v_fmac_f32_e32 v38, v40, v40
	v_fmac_f32_e32 v49, v52, v52
	v_add_f32_e32 v38, v39, v38
	v_mul_f32_e32 v39, v51, v51
	v_cvt_pk_bf16_f32 v45, v52, v53
	v_add_f32_e32 v52, v49, v48
	v_pk_add_f32 v[48:49], v[36:37], v[90:91]
	v_fmac_f32_e32 v39, v50, v50
	v_add_f32_e32 v38, v38, v39
	v_mul_f32_e32 v39, v49, v49
	v_fmac_f32_e32 v39, v48, v48
	v_add_f32_e32 v128, v129, v128
	v_add_f32_e32 v46, v47, v46
	v_add_f32_e32 v38, v39, v38
	v_add_f32_e32 v46, v128, v46
	v_add_f32_e32 v38, v52, v38
	v_mov_b32_e32 v47, v46
	v_mov_b32_e32 v39, v38
	s_nop 0
	v_permlane16_swap_b32_e32 v46, v47
	v_permlane16_swap_b32_e32 v38, v39
	v_add_f32_e32 v46, v46, v47
	v_cvt_pk_bf16_f32 v35, v40, v41
	v_add_f32_e32 v38, v38, v39
	v_lshlrev_b64 v[40:41], 11, v[126:127]
	v_mov_b32_e32 v47, v46
	v_mov_b32_e32 v39, v38
	v_lshl_add_u64 v[40:41], s[14:15], 0, v[40:41]
	v_permlane32_swap_b32_e32 v46, v47
	v_cvt_pk_bf16_f32 v44, v96, v97
	v_cvt_pk_bf16_f32 v36, v50, v51
	v_cvt_pk_bf16_f32 v37, v48, v49
	v_permlane32_swap_b32_e32 v38, v39
	v_lshl_add_u64 v[40:41], v[178:179], 1, v[40:41]
	v_cvt_pk_bf16_f32 v54, v108, v109
	v_cvt_pk_bf16_f32 v55, v110, v111
	global_store_dwordx4 v[40:41], v[116:119], off nt
	global_store_dwordx4 v[40:41], v[54:57], off offset:256 nt
	s_and_saveexec_b64 s[36:37], s[2:3]
	s_xor_b64 s[36:37], exec, s[36:37]
	s_cbranch_execz .LBB0_888
	v_add_co_u32_e32 v40, vcc, 0x48000, v120
	v_lshl_add_u64 v[38:39], v[120:121], 0, s[22:23]
	s_nop 0
	v_addc_co_u32_e32 v41, vcc, 0, v121, vcc
	global_store_dwordx4 v[40:41], v[42:45], off nt
	global_store_dwordx4 v[38:39], v[34:37], off offset:256 nt
.LBB0_888:
	s_andn2_saveexec_b64 s[36:37], s[36:37]
	s_cbranch_execz .LBB0_890
	v_add_f32_e32 v40, v38, v39
	v_lshlrev_b64 v[38:39], 6, v[126:127]
	v_lshl_add_u64 v[38:39], s[16:17], 0, v[38:39]
	s_lshl_b64 s[38:39], s[0:1], 2
	v_lshl_add_u64 v[38:39], v[38:39], 0, s[38:39]
	s_lshl_b32 s10, s51, 2
	v_lshl_add_u64 v[38:39], v[38:39], 0, s[10:11]
	v_add_f32_e32 v41, v46, v47
	global_store_dword v[38:39], v41, off
	v_lshlrev_b64 v[38:39], 11, v[124:125]
	v_lshl_add_u64 v[38:39], s[14:15], 0, v[38:39]
	v_lshl_add_u64 v[38:39], v[178:179], 1, v[38:39]
	global_store_dwordx4 v[38:39], v[42:45], off nt
	global_store_dwordx4 v[38:39], v[34:37], off offset:256 nt
	s_nop 1
	v_lshlrev_b64 v[34:35], 6, v[124:125]
	v_lshl_add_u64 v[34:35], s[16:17], 0, v[34:35]
	v_lshl_add_u64 v[34:35], v[34:35], 0, s[38:39]
	v_lshl_add_u64 v[34:35], v[34:35], 0, s[10:11]
	global_store_dword v[34:35], v40, off
.LBB0_890:
	s_or_b64 exec, exec, s[36:37]
	s_waitcnt vmcnt(8)
	v_pk_add_f32 v[32:33], v[32:33], v[114:115]
	v_pk_add_f32 v[30:31], v[30:31], v[112:113]
	v_mul_f32_e32 v35, v33, v33
	v_mul_f32_e32 v34, v31, v31
	v_pk_add_f32 v[26:27], v[26:27], v[82:83]
	v_fmac_f32_e32 v34, v30, v30
	v_fmac_f32_e32 v35, v32, v32
	v_add_f32_e32 v34, v34, v35
	v_mul_f32_e32 v35, v27, v27
	v_pk_add_f32 v[28:29], v[28:29], v[84:85]
	v_fmac_f32_e32 v35, v26, v26
	v_add_f32_e32 v34, v34, v35
	v_mul_f32_e32 v35, v29, v29
	v_fmac_f32_e32 v35, v28, v28
	s_waitcnt vmcnt(6)
	v_pk_add_f32 v[24:25], v[24:25], v[80:81]
	v_pk_add_f32 v[22:23], v[22:23], v[78:79]
	v_add_f32_e32 v36, v35, v34
	v_pk_add_f32 v[34:35], v[18:19], v[74:75]
	v_mul_f32_e32 v18, v23, v23
	v_mul_f32_e32 v19, v25, v25
	v_fmac_f32_e32 v18, v22, v22
	v_fmac_f32_e32 v19, v24, v24
	v_add_f32_e32 v18, v18, v19
	v_mul_f32_e32 v19, v35, v35
	s_waitcnt vmcnt(4)
	v_pk_add_f32 v[14:15], v[14:15], v[70:71]
	v_pk_add_f32 v[20:21], v[20:21], v[76:77]
	v_fmac_f32_e32 v19, v34, v34
	v_pk_add_f32 v[16:17], v[16:17], v[72:73]
	v_pk_add_f32 v[38:39], v[10:11], v[66:67]
	v_cvt_pk_bf16_f32 v10, v14, v15
	v_mul_f32_e32 v15, v15, v15
	v_add_f32_e32 v18, v18, v19
	v_mul_f32_e32 v19, v21, v21
	v_fmac_f32_e32 v15, v14, v14
	v_mul_f32_e32 v14, v17, v17
	v_fmac_f32_e32 v19, v20, v20
	v_fmac_f32_e32 v14, v16, v16
	s_waitcnt vmcnt(2)
	v_pk_add_f32 v[6:7], v[6:7], v[62:63]
	v_add_f32_e32 v18, v19, v18
	v_cvt_pk_bf16_f32 v11, v16, v17
	v_add_f32_e32 v14, v15, v14
	v_mul_f32_e32 v15, v39, v39
	v_pk_add_f32 v[8:9], v[8:9], v[64:65]
	v_pk_add_f32 v[16:17], v[2:3], v[58:59]
	v_cvt_pk_bf16_f32 v2, v6, v7
	v_mul_f32_e32 v7, v7, v7
	v_add_f32_e32 v18, v36, v18
	v_pk_add_f32 v[36:37], v[12:13], v[68:69]
	v_fmac_f32_e32 v15, v38, v38
	v_fmac_f32_e32 v7, v6, v6
	v_mul_f32_e32 v6, v9, v9
	v_add_f32_e32 v14, v14, v15
	v_mul_f32_e32 v15, v37, v37
	v_fmac_f32_e32 v6, v8, v8
	v_fmac_f32_e32 v15, v36, v36
	v_add_f32_e32 v6, v7, v6
	v_mul_f32_e32 v7, v17, v17
	v_cvt_pk_bf16_f32 v13, v36, v37
	v_add_f32_e32 v36, v15, v14
	v_pk_add_f32 v[14:15], v[4:5], v[60:61]
	v_fmac_f32_e32 v7, v16, v16
	v_add_f32_e32 v6, v6, v7
	v_mul_f32_e32 v7, v15, v15
	v_fmac_f32_e32 v7, v14, v14
	v_add_f32_e32 v6, v7, v6
	v_add_f32_e32 v6, v36, v6
	v_mov_b32_e32 v19, v18
	v_mov_b32_e32 v7, v6
	s_nop 0
	v_permlane16_swap_b32_e32 v18, v19
	v_permlane16_swap_b32_e32 v6, v7
	v_add_f32_e32 v18, v18, v19
	v_cvt_pk_bf16_f32 v3, v8, v9
	v_add_f32_e32 v6, v6, v7
	v_lshlrev_b64 v[8:9], 11, v[86:87]
	v_mov_b32_e32 v19, v18
	v_mov_b32_e32 v7, v6
	v_lshl_add_u64 v[8:9], s[14:15], 0, v[8:9]
	v_permlane32_swap_b32_e32 v18, v19
	v_cvt_pk_bf16_f32 v12, v38, v39
	v_cvt_pk_bf16_f32 v4, v16, v17
	v_cvt_pk_bf16_f32 v5, v14, v15
	v_permlane32_swap_b32_e32 v6, v7
	v_cvt_pk_bf16_f32 v14, v22, v23
	v_cvt_pk_bf16_f32 v17, v20, v21
	v_cvt_pk_bf16_f32 v20, v30, v31
	v_cvt_pk_bf16_f32 v21, v32, v33
	v_cvt_pk_bf16_f32 v22, v26, v27
	v_cvt_pk_bf16_f32 v23, v28, v29
	v_lshl_add_u64 v[8:9], v[178:179], 1, v[8:9]
	v_cvt_pk_bf16_f32 v15, v24, v25
	v_cvt_pk_bf16_f32 v16, v34, v35
	global_store_dwordx4 v[8:9], v[20:23], off nt
	global_store_dwordx4 v[8:9], v[14:17], off offset:256 nt
	s_and_saveexec_b64 s[36:37], s[2:3]
	s_xor_b64 s[36:37], exec, s[36:37]
	s_cbranch_execnz .LBB0_893
	s_andn2_saveexec_b64 s[36:37], s[36:37]
	s_cbranch_execnz .LBB0_894

.LBB0_893:
	v_add_co_u32_e32 v8, vcc, 0x58000, v120
	v_lshl_add_u64 v[6:7], v[120:121], 0, s[24:25]
	s_nop 0
	v_addc_co_u32_e32 v9, vcc, 0, v121, vcc
	global_store_dwordx4 v[8:9], v[10:13], off nt
	global_store_dwordx4 v[6:7], v[2:5], off offset:256 nt
	s_andn2_saveexec_b64 s[36:37], s[36:37]
	s_cbranch_execz .LBB0_892
.LBB0_894:
	s_lshl_b64 s[0:1], s[0:1], 2
	v_add_f32_e32 v14, v6, v7
	v_lshl_add_u64 v[6:7], v[122:123], 0, s[0:1]
	s_lshl_b32 s10, s51, 2
	v_lshl_add_u64 v[6:7], v[6:7], 0, s[10:11]
	v_add_co_u32_e32 v6, vcc, 0x2000, v6
	v_add_f32_e32 v8, v18, v19
	s_nop 0
	v_addc_co_u32_e32 v7, vcc, 0, v7, vcc
	global_store_dword v[6:7], v8, off offset:2048
	v_add_u32_e32 v6, 0xb0, v180
	v_ashrrev_i32_e32 v7, 31, v6
	v_lshlrev_b64 v[8:9], 11, v[6:7]
	v_lshl_add_u64 v[8:9], s[14:15], 0, v[8:9]
	v_lshl_add_u64 v[8:9], v[178:179], 1, v[8:9]
	global_store_dwordx4 v[8:9], v[10:13], off nt
	global_store_dwordx4 v[8:9], v[2:5], off offset:256 nt
	s_nop 1
	v_lshlrev_b64 v[2:3], 6, v[6:7]
	v_lshl_add_u64 v[2:3], s[16:17], 0, v[2:3]
	v_lshl_add_u64 v[2:3], v[2:3], 0, s[0:1]
	v_lshl_add_u64 v[2:3], v[2:3], 0, s[10:11]
	global_store_dword v[2:3], v14, off
	s_or_b64 exec, exec, s[36:37]
	s_andn2_b64 vcc, exec, s[4:5]
	s_mov_b64 s[0:1], -1
	s_cbranch_vccnz .LBB0_867

.LBB0_974:
	v_add_u32_e32 v236, s52, v1
	v_lshlrev_b32_e32 v236, 4, v236
	v_lshl_add_u32 v236, v147, 2, v236
	v_add_u32_e32 v236, 0x20800, v236
	ds_read_b32 v228, v236
	ds_read_b32 v229, v236 offset:256
	ds_read_b32 v230, v236 offset:512
	ds_read_b32 v231, v236 offset:768
	ds_read_b32 v232, v236 offset:2048
	ds_read_b32 v233, v236 offset:2304
	ds_read_b32 v234, v236 offset:2560
	ds_read_b32 v235, v236 offset:2816
	s_lshl_b32 s1, s4, 8
	v_mov_b32_e32 v158, v147
	v_mov_b32_e32 v131, v1
	s_add_i32 s1, s1, s52
	v_mov_b64_e32 v[188:189], s[30:31]
	v_add_u32_e32 v138, s1, v131
	v_ashrrev_i32_e32 v159, 31, v158
	v_ashrrev_i32_e32 v139, 31, v138
	v_lshl_add_u64 v[142:143], v[158:159], 4, s[16:17]
	v_lshlrev_b64 v[138:139], 6, v[138:139]
	v_lshl_add_u64 v[138:139], v[142:143], 0, v[138:139]
	v_add_co_u32_e32 v138, vcc, s50, v138
	s_lshl_b32 s0, s5, 8
	s_nop 0
	v_addc_co_u32_e32 v139, vcc, 0, v139, vcc
	s_or_b32 s0, s0, s55
	v_lshlrev_b32_e32 v158, 3, v158
	v_ashrrev_i32_e32 v159, 31, v158
	s_waitcnt lgkmcnt(0)
	v_mov_b32_e32 v138, v143
	v_mov_b32_e32 v139, v144
	v_mov_b32_e32 v143, v145
	v_mov_b32_e32 v144, v161
	v_mov_b32_e32 v145, v162
	v_mov_b32_e32 v161, v163
	v_mov_b32_e32 v156, v165
	v_mov_b32_e32 v157, v166
	v_mov_b32_e32 v165, v167
	v_mov_b32_e32 v162, v169
	v_mov_b32_e32 v163, v170
	v_mov_b32_e32 v169, v171
	v_pk_add_f32 v[138:139], v[138:139], v[142:143]
	v_pk_add_f32 v[142:143], v[144:145], v[160:161]
	v_pk_add_f32 v[144:145], v[156:157], v[164:165]
	v_pk_add_f32 v[156:157], v[162:163], v[168:169]
	v_mov_b32_e32 v138, v228
	v_mov_b32_e32 v139, v228
	v_mov_b32_e32 v142, v229
	v_mov_b32_e32 v143, v229
	v_mov_b32_e32 v144, v230
	v_mov_b32_e32 v145, v230
	v_mov_b32_e32 v156, v231
	v_mov_b32_e32 v157, v231
	v_mov_b32_e32 v133, v138
	v_mov_b32_e32 v135, v142
	v_mov_b32_e32 v143, v144
	v_mov_b32_e32 v145, v156
	v_permlane16_swap_b32_e32 v138, v133
	v_permlane16_swap_b32_e32 v142, v135
	v_permlane16_swap_b32_e32 v144, v143
	v_permlane16_swap_b32_e32 v156, v145
	v_add_f32_e32 v139, v138, v133
	v_add_f32_e32 v138, v142, v135
	v_add_f32_e32 v143, v144, v143
	v_add_f32_e32 v142, v156, v145
	v_mov_b32_e32 v145, v139
	v_mov_b32_e32 v144, v138
	v_mov_b32_e32 v157, v143
	v_mov_b32_e32 v156, v142
	v_permlane32_swap_b32_e32 v139, v145
	v_permlane32_swap_b32_e32 v138, v144
	v_permlane32_swap_b32_e32 v143, v157
	v_permlane32_swap_b32_e32 v142, v156
	v_pk_add_f32 v[138:139], v[138:139], v[144:145]
	v_pk_add_f32 v[142:143], v[142:143], v[156:157]
	v_pk_fma_f32 v[138:139], v[138:139], s[28:29], v[188:189] op_sel_hi:[1,0,0]
	v_pk_fma_f32 v[142:143], v[142:143], s[28:29], v[188:189] op_sel_hi:[1,0,0]
	v_mul_f32_e32 v135, 0x4b800000, v138
	v_mul_f32_e32 v144, 0x4b800000, v143
	v_cmp_gt_f32_e64 s[4:5], s59, v138
	v_cmp_gt_f32_e64 s[6:7], s59, v143
	v_mul_f32_e32 v133, 0x4b800000, v139
	v_mul_f32_e32 v145, 0x4b800000, v142
	v_cmp_gt_f32_e32 vcc, s59, v139
	v_cndmask_b32_e64 v135, v138, v135, s[4:5]
	v_cndmask_b32_e64 v138, v143, v144, s[6:7]
	v_cmp_gt_f32_e64 s[8:9], s59, v142
	v_cndmask_b32_e32 v133, v139, v133, vcc
	v_rsq_f32_e32 v135, v135
	v_cndmask_b32_e64 v139, v142, v145, s[8:9]
	v_rsq_f32_e32 v142, v138
	v_rsq_f32_e32 v133, v133
	v_mov_b32_e32 v160, v173
	v_mov_b32_e32 v161, v174
	v_mov_b32_e32 v173, v175
	v_pk_add_f32 v[162:163], v[160:161], v[172:173]
	v_mul_f32_e32 v143, 0x45800000, v135
	v_mul_f32_e32 v144, 0x45800000, v142
	v_mul_f32_e32 v138, 0x45800000, v133
	v_cndmask_b32_e64 v160, v135, v143, s[4:5]
	v_cndmask_b32_e64 v156, v142, v144, s[6:7]
	v_mov_b32_e32 v142, v232
	v_mov_b32_e32 v143, v232
	v_mov_b32_e32 v162, v177
	v_mov_b32_e32 v163, v178
	v_mov_b32_e32 v177, v179
	v_cndmask_b32_e32 v138, v133, v138, vcc
	v_mov_b32_e32 v133, v142
	v_pk_add_f32 v[162:163], v[162:163], v[176:177]
	s_nop 0
	v_permlane16_swap_b32_e32 v142, v133
	v_mov_b32_e32 v162, v233
	v_mov_b32_e32 v163, v233
	v_add_f32_e32 v143, v142, v133
	v_mov_b32_e32 v133, v162
	s_nop 1
	v_permlane16_swap_b32_e32 v162, v133
	v_add_f32_e32 v142, v162, v133
	v_mov_b32_e32 v145, v143
	v_mov_b32_e32 v144, v142
	s_nop 0
	v_permlane32_swap_b32_e32 v143, v145
	v_permlane32_swap_b32_e32 v142, v144
	v_pk_add_f32 v[142:143], v[142:143], v[144:145]
	v_rsq_f32_e32 v139, v139
	v_pk_fma_f32 v[142:143], v[142:143], s[28:29], v[188:189] op_sel_hi:[1,0,0]
	v_mov_b32_e32 v162, v185
	v_mul_f32_e32 v133, 0x4b800000, v143
	v_cmp_gt_f32_e32 vcc, s59, v143
	v_mul_f32_e32 v135, 0x4b800000, v142
	v_cmp_gt_f32_e64 s[4:5], s59, v142
	v_cndmask_b32_e32 v133, v143, v133, vcc
	v_rsq_f32_e32 v133, v133
	v_cndmask_b32_e64 v135, v142, v135, s[4:5]
	v_mov_b32_e32 v142, v181
	v_mov_b32_e32 v143, v182
	v_mov_b32_e32 v181, v183
	v_mul_f32_e32 v146, 0x45800000, v139
	v_pk_add_f32 v[142:143], v[142:143], v[180:181]
	v_cndmask_b32_e64 v154, v139, v146, s[8:9]
	v_mul_f32_e32 v139, 0x45800000, v133
	v_mov_b32_e32 v142, v234
	v_mov_b32_e32 v143, v234
	v_mov_b32_e32 v163, v186
	v_mov_b32_e32 v185, v187
	v_cndmask_b32_e32 v152, v133, v139, vcc
	v_mov_b32_e32 v139, v142
	v_pk_add_f32 v[162:163], v[162:163], v[184:185]
	s_nop 0
	v_permlane16_swap_b32_e32 v142, v139
	v_mov_b32_e32 v162, v235
	v_mov_b32_e32 v163, v235
	v_add_f32_e32 v143, v142, v139
	v_mov_b32_e32 v139, v162
	s_nop 1
	v_permlane16_swap_b32_e32 v162, v139
	v_add_f32_e32 v142, v162, v139
	v_mov_b32_e32 v145, v143
	v_mov_b32_e32 v144, v142
	s_nop 0
	v_permlane32_swap_b32_e32 v143, v145
	v_permlane32_swap_b32_e32 v142, v144
	v_pk_add_f32 v[142:143], v[142:143], v[144:145]
	v_rsq_f32_e32 v135, v135
	v_pk_fma_f32 v[142:143], v[142:143], s[28:29], v[188:189] op_sel_hi:[1,0,0]
	v_pk_mul_f32 v[106:107], v[106:107], v[160:161] op_sel_hi:[1,0]
	v_mul_f32_e32 v139, 0x4b800000, v143
	v_cmp_gt_f32_e32 vcc, s59, v143
	v_pk_mul_f32 v[104:105], v[104:105], v[160:161] op_sel_hi:[1,0]
	v_pk_mul_f32 v[102:103], v[102:103], v[160:161] op_sel_hi:[1,0]
	v_cndmask_b32_e32 v139, v143, v139, vcc
	v_rsq_f32_e32 v139, v139
	v_pk_mul_f32 v[98:99], v[98:99], v[160:161] op_sel_hi:[1,0]
	v_mul_f32_e32 v133, 0x45800000, v135
	v_mul_f32_e32 v143, 0x4b800000, v142
	v_pk_mul_f32 v[124:125], v[124:125], v[138:139] op_sel_hi:[1,0]
	v_pk_mul_f32 v[122:123], v[122:123], v[138:139] op_sel_hi:[1,0]
	v_pk_mul_f32 v[116:117], v[116:117], v[138:139] op_sel_hi:[1,0]
	v_pk_mul_f32 v[114:115], v[114:115], v[138:139] op_sel_hi:[1,0]
	v_cmp_gt_f32_e64 s[6:7], s59, v142
	v_pk_mul_f32 v[128:129], v[128:129], v[138:139] op_sel_hi:[1,0]
	v_pk_mul_f32 v[126:127], v[126:127], v[138:139] op_sel_hi:[1,0]
	v_max_f32_e32 v122, 0, v122
	v_max_f32_e32 v123, 0, v123
	v_max_f32_e32 v124, 0, v124
	v_max_f32_e32 v125, 0, v125
	v_pk_mul_f32 v[120:121], v[120:121], v[138:139] op_sel_hi:[1,0]
	v_pk_mul_f32 v[118:119], v[118:119], v[138:139] op_sel_hi:[1,0]
	v_max_f32_e32 v114, 0, v114
	v_max_f32_e32 v115, 0, v115
	v_max_f32_e32 v116, 0, v116
	v_max_f32_e32 v117, 0, v117
	v_pk_mul_f32 v[112:113], v[112:113], v[160:161] op_sel_hi:[1,0]
	v_pk_mul_f32 v[110:111], v[110:111], v[160:161] op_sel_hi:[1,0]
	v_pk_mul_f32 v[108:109], v[108:109], v[160:161] op_sel_hi:[1,0]
	v_max_f32_e32 v106, 0, v106
	v_max_f32_e32 v107, 0, v107
	v_pk_mul_f32 v[100:101], v[100:101], v[160:161] op_sel_hi:[1,0]
	v_max_f32_e32 v102, 0, v102
	v_max_f32_e32 v98, 0, v98
	v_max_f32_e32 v103, 0, v103
	v_max_f32_e32 v99, 0, v99
	v_max_f32_e32 v104, 0, v104
	v_max_f32_e32 v105, 0, v105
	v_cndmask_b32_e64 v142, v142, v143, s[6:7]
	v_cndmask_b32_e64 v150, v135, v133, s[4:5]
	v_mul_f32_e32 v133, 0x45800000, v139
	v_max_f32_e32 v126, 0, v126
	v_max_f32_e32 v127, 0, v127
	v_pk_mul_f32 v[122:123], v[122:123], v[122:123]
	v_max_f32_e32 v128, 0, v128
	v_max_f32_e32 v129, 0, v129
	v_pk_mul_f32 v[124:125], v[124:125], v[124:125]
	v_max_f32_e32 v118, 0, v118
	v_max_f32_e32 v119, 0, v119
	v_pk_mul_f32 v[114:115], v[114:115], v[114:115]
	v_max_f32_e32 v120, 0, v120
	v_max_f32_e32 v121, 0, v121
	v_pk_mul_f32 v[116:117], v[116:117], v[116:117]
	v_max_f32_e32 v110, 0, v110
	v_max_f32_e32 v111, 0, v111
	v_pk_mul_f32 v[106:107], v[106:107], v[106:107]
	v_max_f32_e32 v112, 0, v112
	v_max_f32_e32 v108, 0, v108
	v_max_f32_e32 v113, 0, v113
	v_max_f32_e32 v109, 0, v109
	v_pk_mul_f32 v[102:103], v[102:103], v[102:103]
	v_pk_mul_f32 v[98:99], v[98:99], v[98:99]
	v_max_f32_e32 v100, 0, v100
	v_pk_mul_f32 v[104:105], v[104:105], v[104:105]
	v_max_f32_e32 v101, 0, v101
	v_pk_mul_f32 v[90:91], v[90:91], v[156:157] op_sel_hi:[1,0]
	v_pk_mul_f32 v[88:89], v[88:89], v[156:157] op_sel_hi:[1,0]
	v_pk_mul_f32 v[86:87], v[86:87], v[156:157] op_sel_hi:[1,0]
	v_pk_mul_f32 v[82:83], v[82:83], v[156:157] op_sel_hi:[1,0]
	v_rsq_f32_e32 v142, v142
	v_cndmask_b32_e32 v148, v139, v133, vcc
	v_cmp_gt_i32_e32 vcc, 8, v131
	v_pk_mul_f32 v[126:127], v[126:127], v[126:127]
	v_pk_mul_f32 v[128:129], v[128:129], v[128:129]
	v_cvt_pk_bf16_f32 v122, v122, v123
	v_cvt_pk_bf16_f32 v123, v124, v125
	v_pk_mul_f32 v[118:119], v[118:119], v[118:119]
	v_pk_mul_f32 v[120:121], v[120:121], v[120:121]
	v_cvt_pk_bf16_f32 v114, v114, v115
	v_cvt_pk_bf16_f32 v115, v116, v117
	v_pk_mul_f32 v[110:111], v[110:111], v[110:111]
	v_pk_mul_f32 v[112:113], v[112:113], v[112:113]
	v_pk_mul_f32 v[108:109], v[108:109], v[108:109]
	v_cvt_pk_bf16_f32 v106, v106, v107
	v_pk_mul_f32 v[100:101], v[100:101], v[100:101]
	v_cvt_pk_bf16_f32 v102, v102, v103
	v_cvt_pk_bf16_f32 v103, v104, v105
	v_cvt_pk_bf16_f32 v104, v98, v99
	v_pk_mul_f32 v[96:97], v[96:97], v[156:157] op_sel_hi:[1,0]
	v_pk_mul_f32 v[94:95], v[94:95], v[156:157] op_sel_hi:[1,0]
	v_pk_mul_f32 v[92:93], v[92:93], v[156:157] op_sel_hi:[1,0]
	v_max_f32_e32 v90, 0, v90
	v_max_f32_e32 v91, 0, v91
	v_pk_mul_f32 v[84:85], v[84:85], v[156:157] op_sel_hi:[1,0]
	v_max_f32_e32 v86, 0, v86
	v_max_f32_e32 v82, 0, v82
	v_max_f32_e32 v87, 0, v87
	v_max_f32_e32 v83, 0, v83
	v_max_f32_e32 v88, 0, v88
	v_max_f32_e32 v89, 0, v89
	v_and_or_b32 v144, v131, 7, s1
	v_cvt_pk_bf16_f32 v126, v126, v127
	v_cvt_pk_bf16_f32 v127, v128, v129
	v_cvt_pk_bf16_f32 v124, v118, v119
	v_cvt_pk_bf16_f32 v120, v120, v121
	v_cndmask_b32_e32 v116, v123, v115, vcc
	v_cndmask_b32_e32 v117, v122, v114, vcc
	v_cvt_pk_bf16_f32 v110, v110, v111
	v_cvt_pk_bf16_f32 v111, v112, v113
	v_cvt_pk_bf16_f32 v107, v108, v109
	v_cvt_pk_bf16_f32 v105, v100, v101
	v_cndmask_b32_e32 v99, v106, v104, vcc
	v_max_f32_e32 v94, 0, v94
	v_max_f32_e32 v95, 0, v95
	v_pk_mul_f32 v[90:91], v[90:91], v[90:91]
	v_max_f32_e32 v96, 0, v96
	v_max_f32_e32 v92, 0, v92
	v_max_f32_e32 v97, 0, v97
	v_max_f32_e32 v93, 0, v93
	v_pk_mul_f32 v[86:87], v[86:87], v[86:87]
	v_pk_mul_f32 v[82:83], v[82:83], v[82:83]
	v_max_f32_e32 v84, 0, v84
	v_pk_mul_f32 v[88:89], v[88:89], v[88:89]
	v_max_f32_e32 v85, 0, v85
	v_pk_mul_f32 v[74:75], v[74:75], v[154:155] op_sel_hi:[1,0]
	v_pk_mul_f32 v[72:73], v[72:73], v[154:155] op_sel_hi:[1,0]
	v_pk_mul_f32 v[70:71], v[70:71], v[154:155] op_sel_hi:[1,0]
	v_pk_mul_f32 v[66:67], v[66:67], v[154:155] op_sel_hi:[1,0]
	v_cndmask_b32_e32 v118, v127, v120, vcc
	v_cndmask_b32_e32 v119, v126, v124, vcc
	v_mov_b32_dpp v128, v117 row_ror:8 row_mask:0xf bank_mask:0xf bound_ctrl:1
	v_mov_b32_dpp v129, v116 row_ror:8 row_mask:0xf bank_mask:0xf bound_ctrl:1
	v_ashrrev_i32_e32 v145, 31, v144
	v_cndmask_b32_e32 v98, v107, v105, vcc
	v_cndmask_b32_e32 v100, v111, v103, vcc
	v_mov_b32_dpp v112, v99 row_ror:8 row_mask:0xf bank_mask:0xf bound_ctrl:1
	v_pk_mul_f32 v[94:95], v[94:95], v[94:95]
	v_pk_mul_f32 v[96:97], v[96:97], v[96:97]
	v_pk_mul_f32 v[92:93], v[92:93], v[92:93]
	v_cvt_pk_bf16_f32 v90, v90, v91
	v_pk_mul_f32 v[84:85], v[84:85], v[84:85]
	v_cvt_pk_bf16_f32 v86, v86, v87
	v_cvt_pk_bf16_f32 v87, v88, v89
	v_cvt_pk_bf16_f32 v88, v82, v83
	v_pk_mul_f32 v[80:81], v[80:81], v[154:155] op_sel_hi:[1,0]
	v_pk_mul_f32 v[78:79], v[78:79], v[154:155] op_sel_hi:[1,0]
	v_pk_mul_f32 v[76:77], v[76:77], v[154:155] op_sel_hi:[1,0]
	v_max_f32_e32 v74, 0, v74
	v_max_f32_e32 v75, 0, v75
	v_pk_mul_f32 v[68:69], v[68:69], v[154:155] op_sel_hi:[1,0]
	v_max_f32_e32 v70, 0, v70
	v_max_f32_e32 v66, 0, v66
	v_max_f32_e32 v71, 0, v71
	v_max_f32_e32 v67, 0, v67
	v_max_f32_e32 v72, 0, v72
	v_max_f32_e32 v73, 0, v73
	s_ashr_i32 s1, s0, 31
	v_mov_b32_dpp v125, v119 row_ror:8 row_mask:0xf bank_mask:0xf bound_ctrl:1
	v_mov_b32_dpp v121, v118 row_ror:8 row_mask:0xf bank_mask:0xf bound_ctrl:1
	v_cndmask_b32_e32 v119, v129, v123, vcc
	v_cndmask_b32_e32 v118, v128, v122, vcc
	v_cndmask_b32_e32 v123, v115, v129, vcc
	v_cndmask_b32_e32 v122, v114, v128, vcc
	v_lshlrev_b64 v[114:115], 13, v[144:145]
	v_cndmask_b32_e32 v101, v110, v102, vcc
	v_mov_b32_dpp v109, v100 row_ror:8 row_mask:0xf bank_mask:0xf bound_ctrl:1
	v_mov_b32_dpp v113, v98 row_ror:8 row_mask:0xf bank_mask:0xf bound_ctrl:1
	v_cndmask_b32_e32 v100, v112, v106, vcc
	v_or_b32_e32 v106, 16, v144
	v_cvt_pk_bf16_f32 v94, v94, v95
	v_cvt_pk_bf16_f32 v95, v96, v97
	v_cvt_pk_bf16_f32 v91, v92, v93
	v_cvt_pk_bf16_f32 v89, v84, v85
	v_cndmask_b32_e32 v83, v90, v88, vcc
	v_max_f32_e32 v78, 0, v78
	v_max_f32_e32 v79, 0, v79
	v_pk_mul_f32 v[74:75], v[74:75], v[74:75]
	v_max_f32_e32 v80, 0, v80
	v_max_f32_e32 v76, 0, v76
	v_max_f32_e32 v81, 0, v81
	v_max_f32_e32 v77, 0, v77
	v_pk_mul_f32 v[70:71], v[70:71], v[70:71]
	v_pk_mul_f32 v[66:67], v[66:67], v[66:67]
	v_max_f32_e32 v68, 0, v68
	v_pk_mul_f32 v[72:73], v[72:73], v[72:73]
	v_max_f32_e32 v69, 0, v69
	v_mul_f32_e32 v133, 0x45800000, v142
	v_lshl_add_u64 v[114:115], s[18:19], 0, v[114:115]
	s_lshl_b64 s[0:1], s[0:1], 1
	v_mov_b32_dpp v108, v101 row_ror:8 row_mask:0xf bank_mask:0xf bound_ctrl:1
	v_cndmask_b32_e32 v101, v113, v107, vcc
	v_ashrrev_i32_e32 v107, 31, v106
	v_cndmask_b32_e32 v82, v91, v89, vcc
	v_cndmask_b32_e32 v84, v95, v87, vcc
	v_mov_b32_dpp v96, v83 row_ror:8 row_mask:0xf bank_mask:0xf bound_ctrl:1
	v_pk_mul_f32 v[78:79], v[78:79], v[78:79]
	v_pk_mul_f32 v[80:81], v[80:81], v[80:81]
	v_pk_mul_f32 v[76:77], v[76:77], v[76:77]
	v_cvt_pk_bf16_f32 v74, v74, v75
	v_pk_mul_f32 v[68:69], v[68:69], v[68:69]
	v_cvt_pk_bf16_f32 v70, v70, v71
	v_cvt_pk_bf16_f32 v71, v72, v73
	v_cvt_pk_bf16_f32 v72, v66, v67
	v_cndmask_b32_e64 v146, v142, v133, s[6:7]
	v_cndmask_b32_e64 v142, 64, 0, vcc
	v_mov_b32_e32 v143, v137
	v_lshl_add_u64 v[114:115], v[114:115], 0, s[0:1]
	v_lshlrev_b64 v[106:107], 13, v[106:107]
	v_cndmask_b32_e32 v85, v94, v86, vcc
	v_mov_b32_dpp v93, v84 row_ror:8 row_mask:0xf bank_mask:0xf bound_ctrl:1
	v_mov_b32_dpp v97, v82 row_ror:8 row_mask:0xf bank_mask:0xf bound_ctrl:1
	v_cndmask_b32_e32 v84, v96, v90, vcc
	v_or_b32_e32 v90, 32, v144
	v_cvt_pk_bf16_f32 v78, v78, v79
	v_cvt_pk_bf16_f32 v79, v80, v81
	v_cvt_pk_bf16_f32 v75, v76, v77
	v_cvt_pk_bf16_f32 v73, v68, v69
	v_cndmask_b32_e32 v67, v74, v72, vcc
	v_cndmask_b32_e32 v117, v121, v127, vcc
	v_cndmask_b32_e32 v116, v125, v126, vcc
	v_cndmask_b32_e32 v121, v120, v121, vcc
	v_cndmask_b32_e32 v120, v124, v125, vcc
	v_lshl_add_u64 v[124:125], v[114:115], 0, v[142:143]
	v_lshlrev_b64 v[114:115], 1, v[158:159]
	v_lshl_add_u64 v[106:107], s[18:19], 0, v[106:107]
	v_mov_b32_dpp v92, v85 row_ror:8 row_mask:0xf bank_mask:0xf bound_ctrl:1
	v_cndmask_b32_e32 v85, v97, v91, vcc
	v_ashrrev_i32_e32 v91, 31, v90
	v_cndmask_b32_e32 v66, v75, v73, vcc
	v_cndmask_b32_e32 v68, v79, v71, vcc
	v_mov_b32_dpp v80, v67 row_ror:8 row_mask:0xf bank_mask:0xf bound_ctrl:1
	v_lshl_add_u64 v[124:125], v[124:125], 0, v[114:115]
	v_lshl_add_u64 v[106:107], v[106:107], 0, s[0:1]
	v_lshlrev_b64 v[90:91], 13, v[90:91]
	v_cndmask_b32_e32 v69, v78, v70, vcc
	v_mov_b32_dpp v77, v68 row_ror:8 row_mask:0xf bank_mask:0xf bound_ctrl:1
	v_mov_b32_dpp v81, v66 row_ror:8 row_mask:0xf bank_mask:0xf bound_ctrl:1
	v_cndmask_b32_e32 v68, v80, v74, vcc
	v_or_b32_e32 v74, 48, v144
	global_store_dwordx4 v[124:125], v[116:119], off nt
	v_lshl_add_u64 v[106:107], v[106:107], 0, v[142:143]
	v_lshl_add_u64 v[90:91], s[18:19], 0, v[90:91]
	v_add_co_u32_e64 v116, s[4:5], s51, v124
	v_mov_b32_dpp v76, v69 row_ror:8 row_mask:0xf bank_mask:0xf bound_ctrl:1
	v_cndmask_b32_e32 v69, v81, v75, vcc
	v_ashrrev_i32_e32 v75, 31, v74
	v_addc_co_u32_e64 v117, s[4:5], 0, v125, s[4:5]
	v_cndmask_b32_e32 v99, v109, v111, vcc
	v_cndmask_b32_e32 v98, v108, v110, vcc
	v_lshl_add_u64 v[106:107], v[106:107], 0, v[114:115]
	v_lshl_add_u64 v[90:91], v[90:91], 0, s[0:1]
	v_lshlrev_b64 v[74:75], 13, v[74:75]
	global_store_dwordx4 v[106:107], v[98:101], off nt
	v_lshl_add_u64 v[90:91], v[90:91], 0, v[142:143]
	v_lshl_add_u64 v[74:75], s[18:19], 0, v[74:75]
	v_add_co_u32_e64 v98, s[4:5], s51, v106
	v_cndmask_b32_e32 v83, v93, v95, vcc
	s_nop 0
	v_addc_co_u32_e64 v99, s[4:5], 0, v107, s[4:5]
	v_cndmask_b32_e32 v82, v92, v94, vcc
	v_lshl_add_u64 v[90:91], v[90:91], 0, v[114:115]
	v_lshl_add_u64 v[74:75], v[74:75], 0, s[0:1]
	global_store_dwordx4 v[90:91], v[82:85], off nt
	v_lshl_add_u64 v[74:75], v[74:75], 0, v[142:143]
	v_pk_mul_f32 v[60:61], v[60:61], v[152:153] op_sel_hi:[1,0]
	v_add_co_u32_e64 v82, s[4:5], s51, v90
	v_pk_mul_f32 v[58:59], v[58:59], v[152:153] op_sel_hi:[1,0]
	v_pk_mul_f32 v[56:57], v[56:57], v[152:153] op_sel_hi:[1,0]
	v_pk_mul_f32 v[54:55], v[54:55], v[152:153] op_sel_hi:[1,0]
	v_pk_mul_f32 v[52:53], v[52:53], v[152:153] op_sel_hi:[1,0]
	v_pk_mul_f32 v[50:51], v[50:51], v[152:153] op_sel_hi:[1,0]
	v_pk_mul_f32 v[42:43], v[42:43], v[150:151] op_sel_hi:[1,0]
	v_pk_mul_f32 v[40:41], v[40:41], v[150:151] op_sel_hi:[1,0]
	v_pk_mul_f32 v[38:39], v[38:39], v[150:151] op_sel_hi:[1,0]
	v_pk_mul_f32 v[34:35], v[34:35], v[150:151] op_sel_hi:[1,0]
	v_addc_co_u32_e64 v83, s[4:5], 0, v91, s[4:5]
	v_cndmask_b32_e32 v67, v77, v79, vcc
	v_cndmask_b32_e32 v66, v76, v78, vcc
	v_lshl_add_u64 v[74:75], v[74:75], 0, v[114:115]
	v_pk_mul_f32 v[64:65], v[64:65], v[152:153] op_sel_hi:[1,0]
	v_pk_mul_f32 v[62:63], v[62:63], v[152:153] op_sel_hi:[1,0]
	v_max_f32_e32 v58, 0, v58
	v_max_f32_e32 v59, 0, v59
	v_max_f32_e32 v60, 0, v60
	v_max_f32_e32 v61, 0, v61
	v_max_f32_e32 v54, 0, v54
	v_max_f32_e32 v50, 0, v50
	v_max_f32_e32 v55, 0, v55
	v_max_f32_e32 v51, 0, v51
	v_max_f32_e32 v56, 0, v56
	v_max_f32_e32 v52, 0, v52
	v_max_f32_e32 v57, 0, v57
	v_max_f32_e32 v53, 0, v53
	v_pk_mul_f32 v[48:49], v[48:49], v[150:151] op_sel_hi:[1,0]
	v_pk_mul_f32 v[46:47], v[46:47], v[150:151] op_sel_hi:[1,0]
	v_pk_mul_f32 v[44:45], v[44:45], v[150:151] op_sel_hi:[1,0]
	v_max_f32_e32 v42, 0, v42
	v_max_f32_e32 v43, 0, v43
	v_pk_mul_f32 v[36:37], v[36:37], v[150:151] op_sel_hi:[1,0]
	v_max_f32_e32 v38, 0, v38
	v_max_f32_e32 v34, 0, v34
	v_max_f32_e32 v39, 0, v39
	v_max_f32_e32 v35, 0, v35
	v_max_f32_e32 v40, 0, v40
	v_max_f32_e32 v41, 0, v41
	v_pk_mul_f32 v[10:11], v[10:11], v[146:147] op_sel_hi:[1,0]
	v_pk_mul_f32 v[8:9], v[8:9], v[146:147] op_sel_hi:[1,0]
	v_pk_mul_f32 v[6:7], v[6:7], v[146:147] op_sel_hi:[1,0]
	v_pk_mul_f32 v[2:3], v[2:3], v[146:147] op_sel_hi:[1,0]
	global_store_dwordx4 v[74:75], v[66:69], off nt
	v_max_f32_e32 v62, 0, v62
	v_max_f32_e32 v63, 0, v63
	v_add_co_u32_e64 v66, s[4:5], s51, v74
	v_pk_mul_f32 v[58:59], v[58:59], v[58:59]
	v_max_f32_e32 v64, 0, v64
	v_max_f32_e32 v65, 0, v65
	v_pk_mul_f32 v[60:61], v[60:61], v[60:61]
	v_pk_mul_f32 v[54:55], v[54:55], v[54:55]
	v_pk_mul_f32 v[50:51], v[50:51], v[50:51]
	v_pk_mul_f32 v[56:57], v[56:57], v[56:57]
	v_pk_mul_f32 v[52:53], v[52:53], v[52:53]
	v_max_f32_e32 v46, 0, v46
	v_max_f32_e32 v47, 0, v47
	v_pk_mul_f32 v[42:43], v[42:43], v[42:43]
	v_max_f32_e32 v48, 0, v48
	v_max_f32_e32 v44, 0, v44
	v_max_f32_e32 v49, 0, v49
	v_max_f32_e32 v45, 0, v45
	v_pk_mul_f32 v[38:39], v[38:39], v[38:39]
	v_pk_mul_f32 v[34:35], v[34:35], v[34:35]
	v_max_f32_e32 v36, 0, v36
	v_pk_mul_f32 v[40:41], v[40:41], v[40:41]
	v_max_f32_e32 v37, 0, v37
	v_pk_mul_f32 v[26:27], v[26:27], v[148:149] op_sel_hi:[1,0]
	v_pk_mul_f32 v[24:25], v[24:25], v[148:149] op_sel_hi:[1,0]
	v_pk_mul_f32 v[22:23], v[22:23], v[148:149] op_sel_hi:[1,0]
	v_pk_mul_f32 v[18:19], v[18:19], v[148:149] op_sel_hi:[1,0]
	v_pk_mul_f32 v[16:17], v[16:17], v[146:147] op_sel_hi:[1,0]
	v_pk_mul_f32 v[14:15], v[14:15], v[146:147] op_sel_hi:[1,0]
	v_pk_mul_f32 v[12:13], v[12:13], v[146:147] op_sel_hi:[1,0]
	v_max_f32_e32 v10, 0, v10
	v_max_f32_e32 v11, 0, v11
	v_pk_mul_f32 v[4:5], v[4:5], v[146:147] op_sel_hi:[1,0]
	v_max_f32_e32 v6, 0, v6
	v_max_f32_e32 v2, 0, v2
	v_max_f32_e32 v7, 0, v7
	v_max_f32_e32 v3, 0, v3
	v_max_f32_e32 v8, 0, v8
	v_max_f32_e32 v9, 0, v9
	v_cndmask_b32_e32 v73, v73, v81, vcc
	v_cndmask_b32_e32 v72, v72, v80, vcc
	v_cndmask_b32_e32 v71, v71, v77, vcc
	v_cndmask_b32_e32 v70, v70, v76, vcc
	v_addc_co_u32_e64 v67, s[4:5], 0, v75, s[4:5]
	v_pk_mul_f32 v[62:63], v[62:63], v[62:63]
	v_pk_mul_f32 v[64:65], v[64:65], v[64:65]
	v_cvt_pk_bf16_f32 v58, v58, v59
	v_cvt_pk_bf16_f32 v59, v60, v61
	v_cvt_pk_bf16_f32 v54, v54, v55
	v_cvt_pk_bf16_f32 v55, v56, v57
	v_cvt_pk_bf16_f32 v56, v50, v51
	v_cvt_pk_bf16_f32 v57, v52, v53
	v_pk_mul_f32 v[46:47], v[46:47], v[46:47]
	v_pk_mul_f32 v[48:49], v[48:49], v[48:49]
	v_pk_mul_f32 v[44:45], v[44:45], v[44:45]
	v_cvt_pk_bf16_f32 v42, v42, v43
	v_pk_mul_f32 v[36:37], v[36:37], v[36:37]
	v_cvt_pk_bf16_f32 v38, v38, v39
	v_cvt_pk_bf16_f32 v39, v40, v41
	v_cvt_pk_bf16_f32 v40, v34, v35
	v_pk_mul_f32 v[32:33], v[32:33], v[148:149] op_sel_hi:[1,0]
	v_pk_mul_f32 v[30:31], v[30:31], v[148:149] op_sel_hi:[1,0]
	v_pk_mul_f32 v[28:29], v[28:29], v[148:149] op_sel_hi:[1,0]
	v_max_f32_e32 v26, 0, v26
	v_max_f32_e32 v27, 0, v27
	v_pk_mul_f32 v[20:21], v[20:21], v[148:149] op_sel_hi:[1,0]
	v_max_f32_e32 v22, 0, v22
	v_max_f32_e32 v18, 0, v18
	v_max_f32_e32 v23, 0, v23
	v_max_f32_e32 v19, 0, v19
	v_max_f32_e32 v24, 0, v24
	v_max_f32_e32 v25, 0, v25
	v_max_f32_e32 v14, 0, v14
	v_max_f32_e32 v15, 0, v15
	v_pk_mul_f32 v[10:11], v[10:11], v[10:11]
	v_max_f32_e32 v16, 0, v16
	v_max_f32_e32 v12, 0, v12
	v_max_f32_e32 v17, 0, v17
	v_max_f32_e32 v13, 0, v13
	v_pk_mul_f32 v[6:7], v[6:7], v[6:7]
	v_pk_mul_f32 v[2:3], v[2:3], v[2:3]
	v_max_f32_e32 v4, 0, v4
	v_pk_mul_f32 v[8:9], v[8:9], v[8:9]
	v_max_f32_e32 v5, 0, v5
	global_store_dwordx4 v[66:67], v[70:73], off nt
	v_add_u32_e32 v66, 0x80, v144
	v_cvt_pk_bf16_f32 v62, v62, v63
	v_cvt_pk_bf16_f32 v63, v64, v65
	v_cndmask_b32_e32 v50, v59, v57, vcc
	v_cndmask_b32_e32 v51, v58, v56, vcc
	v_cvt_pk_bf16_f32 v46, v46, v47
	v_cvt_pk_bf16_f32 v47, v48, v49
	v_cvt_pk_bf16_f32 v43, v44, v45
	v_cvt_pk_bf16_f32 v41, v36, v37
	v_cndmask_b32_e32 v35, v42, v40, vcc
	v_max_f32_e32 v30, 0, v30
	v_max_f32_e32 v31, 0, v31
	v_pk_mul_f32 v[26:27], v[26:27], v[26:27]
	v_max_f32_e32 v32, 0, v32
	v_max_f32_e32 v28, 0, v28
	v_max_f32_e32 v33, 0, v33
	v_max_f32_e32 v29, 0, v29
	v_pk_mul_f32 v[22:23], v[22:23], v[22:23]
	v_pk_mul_f32 v[18:19], v[18:19], v[18:19]
	v_max_f32_e32 v20, 0, v20
	v_pk_mul_f32 v[24:25], v[24:25], v[24:25]
	v_max_f32_e32 v21, 0, v21
	v_pk_mul_f32 v[14:15], v[14:15], v[14:15]
	v_pk_mul_f32 v[16:17], v[16:17], v[16:17]
	v_pk_mul_f32 v[12:13], v[12:13], v[12:13]
	v_cvt_pk_bf16_f32 v10, v10, v11
	v_pk_mul_f32 v[4:5], v[4:5], v[4:5]
	v_cvt_pk_bf16_f32 v6, v6, v7
	v_cvt_pk_bf16_f32 v7, v8, v9
	v_cvt_pk_bf16_f32 v8, v2, v3
	v_cndmask_b32_e32 v52, v63, v55, vcc
	v_cndmask_b32_e32 v53, v62, v54, vcc
	v_mov_b32_dpp v64, v51 row_ror:8 row_mask:0xf bank_mask:0xf bound_ctrl:1
	v_mov_b32_dpp v65, v50 row_ror:8 row_mask:0xf bank_mask:0xf bound_ctrl:1
	v_ashrrev_i32_e32 v67, 31, v66
	v_cndmask_b32_e32 v34, v43, v41, vcc
	v_cndmask_b32_e32 v36, v47, v39, vcc
	v_mov_b32_dpp v48, v35 row_ror:8 row_mask:0xf bank_mask:0xf bound_ctrl:1
	v_pk_mul_f32 v[30:31], v[30:31], v[30:31]
	v_pk_mul_f32 v[32:33], v[32:33], v[32:33]
	v_pk_mul_f32 v[28:29], v[28:29], v[28:29]
	v_cvt_pk_bf16_f32 v26, v26, v27
	v_pk_mul_f32 v[20:21], v[20:21], v[20:21]
	v_cvt_pk_bf16_f32 v22, v22, v23
	v_cvt_pk_bf16_f32 v23, v24, v25
	v_cvt_pk_bf16_f32 v24, v18, v19
	v_cvt_pk_bf16_f32 v14, v14, v15
	v_cvt_pk_bf16_f32 v15, v16, v17
	v_cvt_pk_bf16_f32 v11, v12, v13
	v_cvt_pk_bf16_f32 v9, v4, v5
	v_cndmask_b32_e32 v3, v10, v8, vcc
	v_mov_b32_dpp v60, v53 row_ror:8 row_mask:0xf bank_mask:0xf bound_ctrl:1
	v_mov_b32_dpp v61, v52 row_ror:8 row_mask:0xf bank_mask:0xf bound_ctrl:1
	v_cndmask_b32_e32 v53, v65, v59, vcc
	v_cndmask_b32_e32 v52, v64, v58, vcc
	v_lshlrev_b64 v[58:59], 13, v[66:67]
	v_cndmask_b32_e32 v37, v46, v38, vcc
	v_mov_b32_dpp v45, v36 row_ror:8 row_mask:0xf bank_mask:0xf bound_ctrl:1
	v_mov_b32_dpp v49, v34 row_ror:8 row_mask:0xf bank_mask:0xf bound_ctrl:1
	v_cndmask_b32_e32 v36, v48, v42, vcc
	v_add_u32_e32 v42, 0x90, v144
	v_cvt_pk_bf16_f32 v30, v30, v31
	v_cvt_pk_bf16_f32 v31, v32, v33
	v_cvt_pk_bf16_f32 v27, v28, v29
	v_cvt_pk_bf16_f32 v25, v20, v21
	v_cndmask_b32_e32 v19, v26, v24, vcc
	v_cndmask_b32_e32 v2, v11, v9, vcc
	v_cndmask_b32_e32 v4, v15, v7, vcc
	v_mov_b32_dpp v16, v3 row_ror:8 row_mask:0xf bank_mask:0xf bound_ctrl:1
	v_lshl_add_u64 v[58:59], s[18:19], 0, v[58:59]
	v_mov_b32_dpp v44, v37 row_ror:8 row_mask:0xf bank_mask:0xf bound_ctrl:1
	v_cndmask_b32_e32 v37, v49, v43, vcc
	v_ashrrev_i32_e32 v43, 31, v42
	v_cndmask_b32_e32 v18, v27, v25, vcc
	v_cndmask_b32_e32 v20, v31, v23, vcc
	v_mov_b32_dpp v32, v19 row_ror:8 row_mask:0xf bank_mask:0xf bound_ctrl:1
	v_cndmask_b32_e32 v5, v14, v6, vcc
	v_mov_b32_dpp v13, v4 row_ror:8 row_mask:0xf bank_mask:0xf bound_ctrl:1
	v_mov_b32_dpp v17, v2 row_ror:8 row_mask:0xf bank_mask:0xf bound_ctrl:1
	v_cndmask_b32_e32 v4, v16, v10, vcc
	v_add_u32_e32 v10, 0xb0, v144
	v_lshl_add_u64 v[58:59], v[58:59], 0, s[0:1]
	v_lshlrev_b64 v[42:43], 13, v[42:43]
	v_cndmask_b32_e32 v21, v30, v22, vcc
	v_mov_b32_dpp v29, v20 row_ror:8 row_mask:0xf bank_mask:0xf bound_ctrl:1
	v_mov_b32_dpp v33, v18 row_ror:8 row_mask:0xf bank_mask:0xf bound_ctrl:1
	v_cndmask_b32_e32 v20, v32, v26, vcc
	v_add_u32_e32 v26, 0xa0, v144
	v_mov_b32_dpp v12, v5 row_ror:8 row_mask:0xf bank_mask:0xf bound_ctrl:1
	v_cndmask_b32_e32 v5, v17, v11, vcc
	v_ashrrev_i32_e32 v11, 31, v10
	v_lshl_add_u64 v[58:59], v[58:59], 0, v[142:143]
	v_lshl_add_u64 v[42:43], s[18:19], 0, v[42:43]
	v_mov_b32_dpp v28, v21 row_ror:8 row_mask:0xf bank_mask:0xf bound_ctrl:1
	v_cndmask_b32_e32 v21, v33, v27, vcc
	v_ashrrev_i32_e32 v27, 31, v26
	v_lshlrev_b64 v[10:11], 13, v[10:11]
	v_cndmask_b32_e32 v51, v61, v63, vcc
	v_cndmask_b32_e32 v50, v60, v62, vcc
	v_lshl_add_u64 v[58:59], v[58:59], 0, v[114:115]
	v_lshl_add_u64 v[42:43], v[42:43], 0, s[0:1]
	v_lshlrev_b64 v[26:27], 13, v[26:27]
	v_lshl_add_u64 v[10:11], s[18:19], 0, v[10:11]
	global_store_dwordx4 v[58:59], v[50:53], off nt
	v_lshl_add_u64 v[42:43], v[42:43], 0, v[142:143]
	v_lshl_add_u64 v[26:27], s[18:19], 0, v[26:27]
	v_add_co_u32_e64 v50, s[4:5], s51, v58
	v_lshl_add_u64 v[10:11], v[10:11], 0, s[0:1]
	s_nop 0
	v_addc_co_u32_e64 v51, s[4:5], 0, v59, s[4:5]
	v_cndmask_b32_e32 v35, v45, v47, vcc
	v_cndmask_b32_e32 v34, v44, v46, vcc
	v_lshl_add_u64 v[42:43], v[42:43], 0, v[114:115]
	v_lshl_add_u64 v[26:27], v[26:27], 0, s[0:1]
	v_lshl_add_u64 v[10:11], v[10:11], 0, v[142:143]
	global_store_dwordx4 v[42:43], v[34:37], off nt
	v_lshl_add_u64 v[26:27], v[26:27], 0, v[142:143]
	v_cndmask_b32_e32 v3, v13, v15, vcc
	v_add_co_u32_e64 v34, s[4:5], s51, v42
	v_cndmask_b32_e32 v2, v12, v14, vcc
	v_lshl_add_u64 v[10:11], v[10:11], 0, v[114:115]
	v_cndmask_b32_e32 v105, v105, v113, vcc
	v_cndmask_b32_e32 v104, v104, v112, vcc
	v_cndmask_b32_e32 v103, v103, v109, vcc
	v_cndmask_b32_e32 v102, v102, v108, vcc
	v_cndmask_b32_e32 v89, v89, v97, vcc
	v_cndmask_b32_e32 v88, v88, v96, vcc
	v_cndmask_b32_e32 v87, v87, v93, vcc
	v_cndmask_b32_e32 v86, v86, v92, vcc
	v_cndmask_b32_e32 v57, v57, v65, vcc
	v_cndmask_b32_e32 v56, v56, v64, vcc
	v_cndmask_b32_e32 v55, v55, v61, vcc
	v_cndmask_b32_e32 v54, v54, v60, vcc
	v_cndmask_b32_e32 v41, v41, v49, vcc
	v_cndmask_b32_e32 v40, v40, v48, vcc
	v_cndmask_b32_e32 v39, v39, v45, vcc
	v_cndmask_b32_e32 v38, v38, v44, vcc
	v_addc_co_u32_e64 v35, s[4:5], 0, v43, s[4:5]
	v_cndmask_b32_e32 v19, v29, v31, vcc
	v_cndmask_b32_e32 v18, v28, v30, vcc
	v_cndmask_b32_e32 v25, v25, v33, vcc
	v_cndmask_b32_e32 v24, v24, v32, vcc
	v_cndmask_b32_e32 v23, v23, v29, vcc
	v_cndmask_b32_e32 v22, v22, v28, vcc
	v_lshl_add_u64 v[26:27], v[26:27], 0, v[114:115]
	v_cndmask_b32_e32 v9, v9, v17, vcc
	v_cndmask_b32_e32 v8, v8, v16, vcc
	v_cndmask_b32_e32 v7, v7, v13, vcc
	v_cndmask_b32_e32 v6, v6, v12, vcc
	global_store_dwordx4 v[10:11], v[2:5], off nt
	global_store_dwordx4 v[26:27], v[18:21], off nt
	s_mov_b64 s[0:1], -1
	v_add_co_u32_e32 v2, vcc, 0x10000, v10
	v_add_co_u32_e64 v18, s[4:5], s51, v26
	s_nop 0
	v_addc_co_u32_e32 v3, vcc, 0, v11, vcc
	v_addc_co_u32_e64 v19, s[4:5], 0, v27, s[4:5]
	s_andn2_b64 vcc, exec, s[2:3]
	global_store_dwordx4 v[116:117], v[120:123], off nt
	global_store_dwordx4 v[98:99], v[102:105], off nt
	global_store_dwordx4 v[82:83], v[86:89], off nt
	global_store_dwordx4 v[50:51], v[54:57], off nt
	global_store_dwordx4 v[34:35], v[38:41], off nt
	global_store_dwordx4 v[18:19], v[22:25], off nt
	global_store_dwordx4 v[2:3], v[6:9], off nt
	s_cbranch_vccnz .LBB0_960
	s_andn2_b64 vcc, exec, s[14:15]
	s_cbranch_vccnz .LBB0_959
	s_barrier
	s_branch .LBB0_959

.LBB0_1094:
	s_or_b64 exec, exec, s[4:5]
	v_lshlrev_b64 v[138:139], 2, v[204:205]
	s_waitcnt vmcnt(0) lgkmcnt(0)
	s_barrier
	v_lshl_add_u64 v[0:1], s[12:13], 0, v[138:139]
	global_load_dwordx4 v[12:15], v[0:1], off
	global_load_dwordx4 v[8:11], v[0:1], off offset:16
	global_load_dwordx4 v[4:7], v[0:1], off offset:512
	s_nop 0
	global_load_dwordx4 v[0:3], v[0:1], off offset:528
	v_lshl_add_u32 v142, v192, 2, s81
	ds_read2_b32 v[144:145], v142 offset1:16
	v_and_or_b32 v140, v192, 7, s45
	v_ashrrev_i32_e32 v141, 31, v140
	v_or_b32_e32 v130, 16, v140
	v_lshlrev_b64 v[146:147], 12, v[140:141]
	s_waitcnt lgkmcnt(0)
	v_pk_mul_f32 v[124:125], v[124:125], v[144:145] op_sel_hi:[1,0]
	v_pk_mul_f32 v[126:127], v[126:127], v[144:145] op_sel_hi:[1,0]
	v_pk_mul_f32 v[120:121], v[120:121], v[144:145] op_sel_hi:[1,0]
	v_pk_mul_f32 v[122:123], v[122:123], v[144:145] op_sel_hi:[1,0]
	v_cmp_gt_i32_e32 vcc, 8, v192
	v_ashrrev_i32_e32 v131, 31, v130
	v_lshl_add_u64 v[146:147], s[8:9], 0, v[146:147]
	v_pk_mul_f32 v[116:117], v[116:117], v[144:145] op_sel_hi:[1,0]
	v_pk_mul_f32 v[118:119], v[118:119], v[144:145] op_sel_hi:[1,0]
	v_pk_mul_f32 v[112:113], v[112:113], v[144:145] op_sel_hi:[1,0]
	v_pk_mul_f32 v[114:115], v[114:115], v[144:145] op_sel_hi:[1,0]
	v_cndmask_b32_e64 v192, 16, 0, vcc
	v_lshlrev_b64 v[148:149], 12, v[130:131]
	v_lshl_add_u64 v[130:131], v[146:147], 0, v[138:139]
	v_mov_b32_e32 v144, v145
	v_lshl_add_u64 v[130:131], v[130:131], 0, v[192:193]
	v_pk_mul_f32 v[150:151], v[206:207], v[144:145] op_sel_hi:[1,0]
	v_pk_mul_f32 v[152:153], v[180:181], v[144:145] op_sel_hi:[1,0]
	v_pk_mul_f32 v[154:155], v[208:209], v[144:145] op_sel_hi:[1,0]
	v_pk_mul_f32 v[156:157], v[182:183], v[144:145] op_sel_hi:[1,0]
	v_add_co_u32_e64 v146, s[2:3], s76, v130
	s_waitcnt vmcnt(3)
	v_pk_mul_f32 v[126:127], v[14:15], v[126:127]
	v_pk_mul_f32 v[124:125], v[12:13], v[124:125]
	s_waitcnt vmcnt(2)
	v_pk_mul_f32 v[122:123], v[10:11], v[122:123]
	v_pk_mul_f32 v[120:121], v[8:9], v[120:121]
	s_waitcnt vmcnt(1)
	v_pk_mul_f32 v[158:159], v[6:7], v[118:119]
	v_pk_mul_f32 v[160:161], v[4:5], v[116:117]
	s_waitcnt vmcnt(0)
	v_pk_mul_f32 v[162:163], v[2:3], v[114:115]
	v_pk_mul_f32 v[164:165], v[0:1], v[112:113]
	v_cndmask_b32_e32 v112, v127, v123, vcc
	v_cndmask_b32_e32 v113, v126, v122, vcc
	v_cndmask_b32_e32 v114, v125, v121, vcc
	v_cndmask_b32_e32 v115, v124, v120, vcc
	v_cndmask_b32_e32 v116, v159, v163, vcc
	v_cndmask_b32_e32 v117, v158, v162, vcc
	v_cndmask_b32_e32 v118, v161, v165, vcc
	v_cndmask_b32_e32 v119, v160, v164, vcc
	v_mov_b32_dpp v141, v115 row_ror:8 row_mask:0xf bank_mask:0xf bound_ctrl:1
	v_mov_b32_dpp v143, v114 row_ror:8 row_mask:0xf bank_mask:0xf bound_ctrl:1
	v_mov_b32_dpp v145, v113 row_ror:8 row_mask:0xf bank_mask:0xf bound_ctrl:1
	v_mov_b32_dpp v166, v112 row_ror:8 row_mask:0xf bank_mask:0xf bound_ctrl:1
	v_pk_mul_f32 v[152:153], v[14:15], v[152:153]
	v_pk_mul_f32 v[156:157], v[10:11], v[156:157]
	v_mov_b32_dpp v167, v119 row_ror:8 row_mask:0xf bank_mask:0xf bound_ctrl:1
	v_mov_b32_dpp v168, v118 row_ror:8 row_mask:0xf bank_mask:0xf bound_ctrl:1
	v_mov_b32_dpp v169, v117 row_ror:8 row_mask:0xf bank_mask:0xf bound_ctrl:1
	v_mov_b32_dpp v170, v116 row_ror:8 row_mask:0xf bank_mask:0xf bound_ctrl:1
	v_cndmask_b32_e32 v115, v166, v127, vcc
	v_cndmask_b32_e32 v114, v145, v126, vcc
	v_cndmask_b32_e32 v113, v143, v125, vcc
	v_cndmask_b32_e32 v112, v141, v124, vcc
	v_addc_co_u32_e64 v147, s[2:3], 0, v131, s[2:3]
	v_pk_mul_f32 v[150:151], v[12:13], v[150:151]
	v_pk_mul_f32 v[154:155], v[8:9], v[154:155]
	v_cndmask_b32_e32 v119, v123, v166, vcc
	v_cndmask_b32_e32 v118, v122, v145, vcc
	v_cndmask_b32_e32 v117, v121, v143, vcc
	v_cndmask_b32_e32 v116, v120, v141, vcc
	v_cndmask_b32_e32 v123, v170, v159, vcc
	v_cndmask_b32_e32 v122, v169, v158, vcc
	v_cndmask_b32_e32 v121, v168, v161, vcc
	v_cndmask_b32_e32 v120, v167, v160, vcc
	v_cndmask_b32_e32 v127, v163, v170, vcc
	v_cndmask_b32_e32 v126, v162, v169, vcc
	v_cndmask_b32_e32 v125, v165, v168, vcc
	v_cndmask_b32_e32 v124, v164, v167, vcc
	global_store_dwordx4 v[130:131], v[112:115], off nt
	global_store_dwordx4 v[146:147], v[116:119], off nt
	global_store_dwordx4 v[130:131], v[120:123], off offset:512 nt
	global_store_dwordx4 v[146:147], v[124:127], off offset:512 nt
	v_cndmask_b32_e32 v112, v153, v157, vcc
	v_cndmask_b32_e32 v113, v152, v156, vcc
	v_cndmask_b32_e32 v114, v151, v155, vcc
	v_cndmask_b32_e32 v115, v150, v154, vcc
	v_mov_b32_dpp v120, v113 row_ror:8 row_mask:0xf bank_mask:0xf bound_ctrl:1
	v_mov_b32_dpp v121, v112 row_ror:8 row_mask:0xf bank_mask:0xf bound_ctrl:1
	v_lshl_add_u64 v[112:113], s[8:9], 0, v[148:149]
	v_mov_b32_dpp v118, v115 row_ror:8 row_mask:0xf bank_mask:0xf bound_ctrl:1
	v_mov_b32_dpp v119, v114 row_ror:8 row_mask:0xf bank_mask:0xf bound_ctrl:1
	v_lshl_add_u64 v[112:113], v[112:113], 0, v[138:139]
	v_lshl_add_u64 v[116:117], v[112:113], 0, v[192:193]
	v_cndmask_b32_e32 v115, v121, v153, vcc
	v_cndmask_b32_e32 v114, v120, v152, vcc
	v_cndmask_b32_e32 v113, v119, v151, vcc
	v_cndmask_b32_e32 v112, v118, v150, vcc
	global_store_dwordx4 v[116:117], v[112:115], off nt
	v_pk_mul_f32 v[100:101], v[100:101], v[144:145] op_sel_hi:[1,0]
	v_pk_mul_f32 v[96:97], v[96:97], v[144:145] op_sel_hi:[1,0]
	v_cndmask_b32_e32 v112, v154, v118, vcc
	v_add_co_u32_e64 v118, s[2:3], s76, v116
	v_cndmask_b32_e32 v115, v157, v121, vcc
	v_cndmask_b32_e32 v114, v156, v120, vcc
	v_cndmask_b32_e32 v113, v155, v119, vcc
	v_addc_co_u32_e64 v119, s[2:3], 0, v117, s[2:3]
	global_store_dwordx4 v[118:119], v[112:115], off nt
	v_pk_mul_f32 v[102:103], v[102:103], v[144:145] op_sel_hi:[1,0]
	v_pk_mul_f32 v[100:101], v[4:5], v[100:101]
	v_pk_mul_f32 v[98:99], v[98:99], v[144:145] op_sel_hi:[1,0]
	v_pk_mul_f32 v[114:115], v[0:1], v[96:97]
	v_pk_mul_f32 v[102:103], v[6:7], v[102:103]
	v_pk_mul_f32 v[112:113], v[2:3], v[98:99]
	v_cndmask_b32_e32 v98, v101, v115, vcc
	v_cndmask_b32_e32 v99, v100, v114, vcc
	v_cndmask_b32_e32 v96, v103, v113, vcc
	v_cndmask_b32_e32 v97, v102, v112, vcc
	v_mov_b32_dpp v120, v99 row_ror:8 row_mask:0xf bank_mask:0xf bound_ctrl:1
	v_mov_b32_dpp v121, v98 row_ror:8 row_mask:0xf bank_mask:0xf bound_ctrl:1
	v_mov_b32_dpp v122, v97 row_ror:8 row_mask:0xf bank_mask:0xf bound_ctrl:1
	v_mov_b32_dpp v123, v96 row_ror:8 row_mask:0xf bank_mask:0xf bound_ctrl:1
	v_cndmask_b32_e32 v97, v121, v101, vcc
	v_cndmask_b32_e32 v96, v120, v100, vcc
	ds_read2_b32 v[100:101], v142 offset0:32 offset1:48
	v_cndmask_b32_e32 v99, v123, v103, vcc
	v_cndmask_b32_e32 v98, v122, v102, vcc
	global_store_dwordx4 v[116:117], v[96:99], off offset:512 nt
	s_waitcnt lgkmcnt(0)
	v_pk_mul_f32 v[94:95], v[94:95], v[100:101] op_sel_hi:[1,0]
	v_cndmask_b32_e32 v99, v113, v123, vcc
	v_cndmask_b32_e32 v98, v112, v122, vcc
	v_cndmask_b32_e32 v97, v115, v121, vcc
	v_cndmask_b32_e32 v96, v114, v120, vcc
	global_store_dwordx4 v[118:119], v[96:99], off offset:512 nt
	v_pk_mul_f32 v[90:91], v[90:91], v[100:101] op_sel_hi:[1,0]
	v_pk_mul_f32 v[94:95], v[14:15], v[94:95]
	v_or_b32_e32 v96, 32, v140
	v_ashrrev_i32_e32 v97, 31, v96
	v_pk_mul_f32 v[88:89], v[88:89], v[100:101] op_sel_hi:[1,0]
	v_pk_mul_f32 v[98:99], v[10:11], v[90:91]
	v_lshlrev_b64 v[96:97], 12, v[96:97]
	v_pk_mul_f32 v[92:93], v[92:93], v[100:101] op_sel_hi:[1,0]
	v_pk_mul_f32 v[102:103], v[8:9], v[88:89]
	v_cndmask_b32_e32 v88, v95, v99, vcc
	v_cndmask_b32_e32 v89, v94, v98, vcc
	v_pk_mul_f32 v[92:93], v[12:13], v[92:93]
	v_mov_b32_dpp v115, v88 row_ror:8 row_mask:0xf bank_mask:0xf bound_ctrl:1
	v_mov_b32_dpp v114, v89 row_ror:8 row_mask:0xf bank_mask:0xf bound_ctrl:1
	v_lshl_add_u64 v[88:89], s[8:9], 0, v[96:97]
	v_cndmask_b32_e32 v90, v93, v103, vcc
	v_cndmask_b32_e32 v91, v92, v102, vcc
	v_lshl_add_u64 v[88:89], v[88:89], 0, v[138:139]
	v_mov_b32_dpp v113, v90 row_ror:8 row_mask:0xf bank_mask:0xf bound_ctrl:1
	v_mov_b32_dpp v112, v91 row_ror:8 row_mask:0xf bank_mask:0xf bound_ctrl:1
	v_lshl_add_u64 v[96:97], v[88:89], 0, v[192:193]
	v_cndmask_b32_e32 v91, v115, v95, vcc
	v_cndmask_b32_e32 v90, v114, v94, vcc
	v_cndmask_b32_e32 v89, v113, v93, vcc
	v_cndmask_b32_e32 v88, v112, v92, vcc
	v_add_co_u32_e64 v92, s[2:3], s76, v96
	global_store_dwordx4 v[96:97], v[88:91], off nt
	s_nop 0
	v_addc_co_u32_e64 v93, s[2:3], 0, v97, s[2:3]
	v_cndmask_b32_e32 v91, v99, v115, vcc
	v_cndmask_b32_e32 v90, v98, v114, vcc
	v_cndmask_b32_e32 v89, v103, v113, vcc
	v_cndmask_b32_e32 v88, v102, v112, vcc
	v_pk_mul_f32 v[84:85], v[84:85], v[100:101] op_sel_hi:[1,0]
	v_pk_mul_f32 v[86:87], v[86:87], v[100:101] op_sel_hi:[1,0]
	v_pk_mul_f32 v[80:81], v[80:81], v[100:101] op_sel_hi:[1,0]
	v_pk_mul_f32 v[82:83], v[82:83], v[100:101] op_sel_hi:[1,0]
	global_store_dwordx4 v[92:93], v[88:91], off nt
	v_pk_mul_f32 v[86:87], v[6:7], v[86:87]
	v_pk_mul_f32 v[84:85], v[4:5], v[84:85]
	v_pk_mul_f32 v[88:89], v[2:3], v[82:83]
	v_pk_mul_f32 v[90:91], v[0:1], v[80:81]
	v_cndmask_b32_e32 v80, v87, v89, vcc
	v_cndmask_b32_e32 v81, v86, v88, vcc
	v_cndmask_b32_e32 v82, v85, v91, vcc
	v_cndmask_b32_e32 v83, v84, v90, vcc
	v_mov_b32_dpp v98, v81 row_ror:8 row_mask:0xf bank_mask:0xf bound_ctrl:1
	v_mov_b32_dpp v95, v82 row_ror:8 row_mask:0xf bank_mask:0xf bound_ctrl:1
	v_mov_b32_dpp v94, v83 row_ror:8 row_mask:0xf bank_mask:0xf bound_ctrl:1
	v_mov_b32_dpp v99, v80 row_ror:8 row_mask:0xf bank_mask:0xf bound_ctrl:1
	v_cndmask_b32_e32 v83, v99, v87, vcc
	v_cndmask_b32_e32 v82, v98, v86, vcc
	v_cndmask_b32_e32 v81, v95, v85, vcc
	v_cndmask_b32_e32 v80, v94, v84, vcc
	global_store_dwordx4 v[96:97], v[80:83], off offset:512 nt
	s_nop 1
	v_cndmask_b32_e32 v83, v89, v99, vcc
	v_cndmask_b32_e32 v82, v88, v98, vcc
	v_cndmask_b32_e32 v81, v91, v95, vcc
	v_cndmask_b32_e32 v80, v90, v94, vcc
	global_store_dwordx4 v[92:93], v[80:83], off offset:512 nt
	s_nop 1
	v_mov_b32_e32 v82, v101
	v_or_b32_e32 v80, 48, v140
	v_pk_mul_f32 v[78:79], v[78:79], v[82:83] op_sel_hi:[1,0]
	v_pk_mul_f32 v[74:75], v[74:75], v[82:83] op_sel_hi:[1,0]
	v_ashrrev_i32_e32 v81, 31, v80
	v_pk_mul_f32 v[78:79], v[14:15], v[78:79]
	v_pk_mul_f32 v[72:73], v[72:73], v[82:83] op_sel_hi:[1,0]
	v_pk_mul_f32 v[84:85], v[10:11], v[74:75]
	v_lshlrev_b64 v[80:81], 12, v[80:81]
	v_pk_mul_f32 v[76:77], v[76:77], v[82:83] op_sel_hi:[1,0]
	v_pk_mul_f32 v[86:87], v[8:9], v[72:73]
	v_cndmask_b32_e32 v72, v79, v85, vcc
	v_cndmask_b32_e32 v73, v78, v84, vcc
	v_pk_mul_f32 v[76:77], v[12:13], v[76:77]
	v_mov_b32_dpp v90, v72 row_ror:8 row_mask:0xf bank_mask:0xf bound_ctrl:1
	v_mov_b32_dpp v89, v73 row_ror:8 row_mask:0xf bank_mask:0xf bound_ctrl:1
	v_lshl_add_u64 v[72:73], s[8:9], 0, v[80:81]
	v_cndmask_b32_e32 v74, v77, v87, vcc
	v_cndmask_b32_e32 v75, v76, v86, vcc
	v_lshl_add_u64 v[72:73], v[72:73], 0, v[138:139]
	v_mov_b32_dpp v88, v74 row_ror:8 row_mask:0xf bank_mask:0xf bound_ctrl:1
	v_mov_b32_dpp v83, v75 row_ror:8 row_mask:0xf bank_mask:0xf bound_ctrl:1
	v_lshl_add_u64 v[80:81], v[72:73], 0, v[192:193]
	v_cndmask_b32_e32 v75, v90, v79, vcc
	v_cndmask_b32_e32 v74, v89, v78, vcc
	v_cndmask_b32_e32 v73, v88, v77, vcc
	v_cndmask_b32_e32 v72, v83, v76, vcc
	v_add_co_u32_e64 v76, s[2:3], s76, v80
	global_store_dwordx4 v[80:81], v[72:75], off nt
	s_nop 0
	v_addc_co_u32_e64 v77, s[2:3], 0, v81, s[2:3]
	v_cndmask_b32_e32 v75, v85, v90, vcc
	v_cndmask_b32_e32 v74, v84, v89, vcc
	v_cndmask_b32_e32 v73, v87, v88, vcc
	v_cndmask_b32_e32 v72, v86, v83, vcc
	v_pk_mul_f32 v[68:69], v[68:69], v[82:83] op_sel_hi:[1,0]
	v_pk_mul_f32 v[64:65], v[64:65], v[82:83] op_sel_hi:[1,0]
	global_store_dwordx4 v[76:77], v[72:75], off nt
	v_pk_mul_f32 v[70:71], v[70:71], v[82:83] op_sel_hi:[1,0]
	v_pk_mul_f32 v[68:69], v[4:5], v[68:69]
	v_pk_mul_f32 v[66:67], v[66:67], v[82:83] op_sel_hi:[1,0]
	v_pk_mul_f32 v[74:75], v[0:1], v[64:65]
	v_pk_mul_f32 v[70:71], v[6:7], v[70:71]
	v_pk_mul_f32 v[72:73], v[2:3], v[66:67]
	v_cndmask_b32_e32 v66, v69, v75, vcc
	v_cndmask_b32_e32 v67, v68, v74, vcc
	v_cndmask_b32_e32 v64, v71, v73, vcc
	v_cndmask_b32_e32 v65, v70, v72, vcc
	v_mov_b32_dpp v78, v67 row_ror:8 row_mask:0xf bank_mask:0xf bound_ctrl:1
	v_mov_b32_dpp v79, v66 row_ror:8 row_mask:0xf bank_mask:0xf bound_ctrl:1
	v_mov_b32_dpp v82, v65 row_ror:8 row_mask:0xf bank_mask:0xf bound_ctrl:1
	v_mov_b32_dpp v83, v64 row_ror:8 row_mask:0xf bank_mask:0xf bound_ctrl:1
	v_cndmask_b32_e32 v65, v79, v69, vcc
	v_cndmask_b32_e32 v64, v78, v68, vcc
	ds_read2_b32 v[68:69], v142 offset0:128 offset1:144
	v_cndmask_b32_e32 v67, v83, v71, vcc
	v_cndmask_b32_e32 v66, v82, v70, vcc
	global_store_dwordx4 v[80:81], v[64:67], off offset:512 nt
	v_lshl_add_u64 v[70:71], v[130:131], 0, s[36:37]
	s_waitcnt lgkmcnt(0)
	v_pk_mul_f32 v[60:61], v[60:61], v[68:69] op_sel_hi:[1,0]
	v_cndmask_b32_e32 v67, v73, v83, vcc
	v_cndmask_b32_e32 v66, v72, v82, vcc
	v_cndmask_b32_e32 v65, v75, v79, vcc
	v_cndmask_b32_e32 v64, v74, v78, vcc
	v_pk_mul_f32 v[56:57], v[56:57], v[68:69] op_sel_hi:[1,0]
	global_store_dwordx4 v[76:77], v[64:67], off offset:512 nt
	v_pk_mul_f32 v[62:63], v[62:63], v[68:69] op_sel_hi:[1,0]
	v_pk_mul_f32 v[60:61], v[12:13], v[60:61]
	v_pk_mul_f32 v[58:59], v[58:59], v[68:69] op_sel_hi:[1,0]
	v_pk_mul_f32 v[66:67], v[8:9], v[56:57]
	v_pk_mul_f32 v[62:63], v[14:15], v[62:63]
	v_pk_mul_f32 v[64:65], v[10:11], v[58:59]
	v_cndmask_b32_e32 v59, v60, v66, vcc
	v_cndmask_b32_e32 v56, v63, v65, vcc
	v_cndmask_b32_e32 v57, v62, v64, vcc
	v_cndmask_b32_e32 v58, v61, v67, vcc
	v_mov_b32_dpp v72, v59 row_ror:8 row_mask:0xf bank_mask:0xf bound_ctrl:1
	v_mov_b32_dpp v74, v57 row_ror:8 row_mask:0xf bank_mask:0xf bound_ctrl:1
	v_mov_b32_dpp v73, v58 row_ror:8 row_mask:0xf bank_mask:0xf bound_ctrl:1
	v_mov_b32_dpp v75, v56 row_ror:8 row_mask:0xf bank_mask:0xf bound_ctrl:1
	v_cndmask_b32_e32 v56, v72, v60, vcc
	v_add_co_u32_e64 v60, s[2:3], s89, v130
	v_cndmask_b32_e32 v59, v75, v63, vcc
	v_cndmask_b32_e32 v58, v74, v62, vcc
	v_cndmask_b32_e32 v57, v73, v61, vcc
	v_addc_co_u32_e64 v61, s[2:3], 0, v131, s[2:3]
	global_store_dwordx4 v[60:61], v[56:59], off nt
	v_add_co_u32_e64 v60, s[2:3], s91, v130
	s_nop 0
	v_cndmask_b32_e32 v59, v65, v75, vcc
	v_cndmask_b32_e32 v58, v64, v74, vcc
	v_cndmask_b32_e32 v57, v67, v73, vcc
	v_cndmask_b32_e32 v56, v66, v72, vcc
	v_addc_co_u32_e64 v61, s[2:3], 0, v131, s[2:3]
	v_pk_mul_f32 v[52:53], v[52:53], v[68:69] op_sel_hi:[1,0]
	v_pk_mul_f32 v[54:55], v[54:55], v[68:69] op_sel_hi:[1,0]
	v_pk_mul_f32 v[48:49], v[48:49], v[68:69] op_sel_hi:[1,0]
	v_pk_mul_f32 v[50:51], v[50:51], v[68:69] op_sel_hi:[1,0]
	global_store_dwordx4 v[60:61], v[56:59], off nt
	v_pk_mul_f32 v[54:55], v[6:7], v[54:55]
	v_pk_mul_f32 v[52:53], v[4:5], v[52:53]
	v_pk_mul_f32 v[56:57], v[2:3], v[50:51]
	v_pk_mul_f32 v[58:59], v[0:1], v[48:49]
	v_cndmask_b32_e32 v48, v55, v57, vcc
	v_cndmask_b32_e32 v49, v54, v56, vcc
	v_cndmask_b32_e32 v50, v53, v59, vcc
	v_cndmask_b32_e32 v51, v52, v58, vcc
	v_mov_b32_dpp v64, v49 row_ror:8 row_mask:0xf bank_mask:0xf bound_ctrl:1
	v_mov_b32_dpp v63, v50 row_ror:8 row_mask:0xf bank_mask:0xf bound_ctrl:1
	v_mov_b32_dpp v62, v51 row_ror:8 row_mask:0xf bank_mask:0xf bound_ctrl:1
	v_mov_b32_dpp v65, v48 row_ror:8 row_mask:0xf bank_mask:0xf bound_ctrl:1
	v_cndmask_b32_e32 v51, v65, v55, vcc
	v_cndmask_b32_e32 v50, v64, v54, vcc
	v_cndmask_b32_e32 v49, v63, v53, vcc
	v_cndmask_b32_e32 v48, v62, v52, vcc
	global_store_dwordx4 v[70:71], v[48:51], off offset:512 nt
	v_lshl_add_u64 v[54:55], v[130:131], 0, s[38:39]
	s_nop 0
	v_cndmask_b32_e32 v51, v57, v65, vcc
	v_cndmask_b32_e32 v50, v56, v64, vcc
	v_cndmask_b32_e32 v49, v59, v63, vcc
	v_cndmask_b32_e32 v48, v58, v62, vcc
	global_store_dwordx4 v[60:61], v[48:51], off offset:512 nt
	s_nop 1
	v_mov_b32_e32 v48, v69
	v_pk_mul_f32 v[44:45], v[44:45], v[48:49] op_sel_hi:[1,0]
	v_pk_mul_f32 v[40:41], v[40:41], v[48:49] op_sel_hi:[1,0]
	v_pk_mul_f32 v[46:47], v[46:47], v[48:49] op_sel_hi:[1,0]
	v_pk_mul_f32 v[44:45], v[12:13], v[44:45]
	v_pk_mul_f32 v[42:43], v[42:43], v[48:49] op_sel_hi:[1,0]
	v_pk_mul_f32 v[52:53], v[8:9], v[40:41]
	v_pk_mul_f32 v[46:47], v[14:15], v[46:47]
	v_pk_mul_f32 v[50:51], v[10:11], v[42:43]
	v_cndmask_b32_e32 v43, v44, v52, vcc
	v_cndmask_b32_e32 v40, v47, v51, vcc
	v_cndmask_b32_e32 v41, v46, v50, vcc
	v_cndmask_b32_e32 v42, v45, v53, vcc
	v_mov_b32_dpp v49, v43 row_ror:8 row_mask:0xf bank_mask:0xf bound_ctrl:1
	v_mov_b32_dpp v57, v41 row_ror:8 row_mask:0xf bank_mask:0xf bound_ctrl:1
	v_mov_b32_dpp v56, v42 row_ror:8 row_mask:0xf bank_mask:0xf bound_ctrl:1
	v_mov_b32_dpp v58, v40 row_ror:8 row_mask:0xf bank_mask:0xf bound_ctrl:1
	v_cndmask_b32_e32 v40, v49, v44, vcc
	v_add_co_u32_e64 v44, s[2:3], s92, v130
	v_cndmask_b32_e32 v43, v58, v47, vcc
	v_cndmask_b32_e32 v42, v57, v46, vcc
	v_cndmask_b32_e32 v41, v56, v45, vcc
	v_addc_co_u32_e64 v45, s[2:3], 0, v131, s[2:3]
	global_store_dwordx4 v[44:45], v[40:43], off nt
	v_add_co_u32_e64 v44, s[2:3], s93, v130
	s_nop 0
	v_cndmask_b32_e32 v43, v51, v58, vcc
	v_cndmask_b32_e32 v42, v50, v57, vcc
	v_cndmask_b32_e32 v41, v53, v56, vcc
	v_cndmask_b32_e32 v40, v52, v49, vcc
	v_addc_co_u32_e64 v45, s[2:3], 0, v131, s[2:3]
	v_pk_mul_f32 v[36:37], v[36:37], v[48:49] op_sel_hi:[1,0]
	v_pk_mul_f32 v[32:33], v[32:33], v[48:49] op_sel_hi:[1,0]
	global_store_dwordx4 v[44:45], v[40:43], off nt
	v_pk_mul_f32 v[38:39], v[38:39], v[48:49] op_sel_hi:[1,0]
	v_pk_mul_f32 v[36:37], v[4:5], v[36:37]
	v_pk_mul_f32 v[34:35], v[34:35], v[48:49] op_sel_hi:[1,0]
	v_pk_mul_f32 v[42:43], v[0:1], v[32:33]
	v_pk_mul_f32 v[38:39], v[6:7], v[38:39]
	v_pk_mul_f32 v[40:41], v[2:3], v[34:35]
	v_cndmask_b32_e32 v34, v37, v43, vcc
	v_cndmask_b32_e32 v35, v36, v42, vcc
	v_cndmask_b32_e32 v32, v39, v41, vcc
	v_cndmask_b32_e32 v33, v38, v40, vcc
	v_mov_b32_dpp v46, v35 row_ror:8 row_mask:0xf bank_mask:0xf bound_ctrl:1
	v_mov_b32_dpp v47, v34 row_ror:8 row_mask:0xf bank_mask:0xf bound_ctrl:1
	v_mov_b32_dpp v48, v33 row_ror:8 row_mask:0xf bank_mask:0xf bound_ctrl:1
	v_mov_b32_dpp v49, v32 row_ror:8 row_mask:0xf bank_mask:0xf bound_ctrl:1
	v_cndmask_b32_e32 v33, v47, v37, vcc
	v_cndmask_b32_e32 v32, v46, v36, vcc
	ds_read2_b32 v[36:37], v142 offset0:160 offset1:176
	v_cndmask_b32_e32 v35, v49, v39, vcc
	v_cndmask_b32_e32 v34, v48, v38, vcc
	global_store_dwordx4 v[54:55], v[32:35], off offset:512 nt
	s_waitcnt lgkmcnt(0)
	v_pk_mul_f32 v[30:31], v[30:31], v[36:37] op_sel_hi:[1,0]
	v_cndmask_b32_e32 v35, v41, v49, vcc
	v_cndmask_b32_e32 v34, v40, v48, vcc
	v_cndmask_b32_e32 v33, v43, v47, vcc
	v_cndmask_b32_e32 v32, v42, v46, vcc
	global_store_dwordx4 v[44:45], v[32:35], off offset:512 nt
	v_pk_mul_f32 v[26:27], v[26:27], v[36:37] op_sel_hi:[1,0]
	v_pk_mul_f32 v[30:31], v[14:15], v[30:31]
	v_pk_mul_f32 v[32:33], v[104:105], v[36:37] op_sel_hi:[1,0]
	v_pk_mul_f32 v[26:27], v[10:11], v[26:27]
	v_pk_mul_f32 v[34:35], v[12:13], v[32:33]
	v_pk_mul_f32 v[32:33], v[108:109], v[36:37] op_sel_hi:[1,0]
	v_pk_mul_f32 v[20:21], v[20:21], v[36:37] op_sel_hi:[1,0]
	v_pk_mul_f32 v[38:39], v[8:9], v[32:33]
	v_cndmask_b32_e32 v33, v30, v26, vcc
	v_cndmask_b32_e32 v41, v34, v38, vcc
	v_cndmask_b32_e32 v32, v31, v27, vcc
	v_cndmask_b32_e32 v40, v35, v39, vcc
	v_mov_b32_dpp v42, v41 row_ror:8 row_mask:0xf bank_mask:0xf bound_ctrl:1
	v_mov_b32_dpp v44, v33 row_ror:8 row_mask:0xf bank_mask:0xf bound_ctrl:1
	v_mov_b32_dpp v43, v40 row_ror:8 row_mask:0xf bank_mask:0xf bound_ctrl:1
	v_mov_b32_dpp v45, v32 row_ror:8 row_mask:0xf bank_mask:0xf bound_ctrl:1
	v_cndmask_b32_e32 v32, v44, v30, vcc
	v_cndmask_b32_e32 v30, v42, v34, vcc
	v_add_co_u32_e64 v34, s[2:3], s94, v130
	v_cndmask_b32_e32 v33, v45, v31, vcc
	v_cndmask_b32_e32 v31, v43, v35, vcc
	v_addc_co_u32_e64 v35, s[2:3], 0, v131, s[2:3]
	global_store_dwordx4 v[34:35], v[30:33], off nt
	v_pk_mul_f32 v[22:23], v[22:23], v[36:37] op_sel_hi:[1,0]
	v_pk_mul_f32 v[16:17], v[16:17], v[36:37] op_sel_hi:[1,0]
	v_cndmask_b32_e32 v32, v26, v44, vcc
	v_add_co_u32_e64 v26, s[2:3], s95, v130
	v_cndmask_b32_e32 v33, v27, v45, vcc
	v_cndmask_b32_e32 v31, v39, v43, vcc
	v_cndmask_b32_e32 v30, v38, v42, vcc
	v_addc_co_u32_e64 v27, s[2:3], 0, v131, s[2:3]
	v_pk_mul_f32 v[18:19], v[18:19], v[36:37] op_sel_hi:[1,0]
	global_store_dwordx4 v[26:27], v[30:33], off nt
	v_pk_mul_f32 v[22:23], v[6:7], v[22:23]
	v_pk_mul_f32 v[20:21], v[4:5], v[20:21]
	v_pk_mul_f32 v[30:31], v[2:3], v[18:19]
	v_pk_mul_f32 v[32:33], v[0:1], v[16:17]
	v_cndmask_b32_e32 v16, v23, v31, vcc
	v_cndmask_b32_e32 v17, v22, v30, vcc
	v_cndmask_b32_e32 v18, v21, v33, vcc
	v_cndmask_b32_e32 v19, v20, v32, vcc
	v_mov_b32_dpp v36, v17 row_ror:8 row_mask:0xf bank_mask:0xf bound_ctrl:1
	v_mov_b32_dpp v35, v18 row_ror:8 row_mask:0xf bank_mask:0xf bound_ctrl:1
	v_mov_b32_dpp v34, v19 row_ror:8 row_mask:0xf bank_mask:0xf bound_ctrl:1
	v_mov_b32_dpp v38, v16 row_ror:8 row_mask:0xf bank_mask:0xf bound_ctrl:1
	v_lshl_add_u64 v[40:41], v[130:131], 0, s[40:41]
	v_cndmask_b32_e32 v19, v38, v23, vcc
	v_cndmask_b32_e32 v18, v36, v22, vcc
	v_cndmask_b32_e32 v17, v35, v21, vcc
	v_cndmask_b32_e32 v16, v34, v20, vcc
	global_store_dwordx4 v[40:41], v[16:19], off offset:512 nt
	v_lshl_add_u64 v[22:23], v[130:131], 0, s[42:43]
	s_nop 0
	v_cndmask_b32_e32 v19, v31, v38, vcc
	v_cndmask_b32_e32 v18, v30, v36, vcc
	v_cndmask_b32_e32 v17, v33, v35, vcc
	v_cndmask_b32_e32 v16, v32, v34, vcc
	global_store_dwordx4 v[26:27], v[16:19], off offset:512 nt
	s_nop 1
	v_mov_b32_e32 v16, v37
	v_pk_mul_f32 v[18:19], v[134:135], v[16:17] op_sel_hi:[1,0]
	v_pk_mul_f32 v[20:21], v[110:111], v[16:17] op_sel_hi:[1,0]
	v_pk_mul_f32 v[12:13], v[12:13], v[18:19]
	v_pk_mul_f32 v[18:19], v[136:137], v[16:17] op_sel_hi:[1,0]
	v_pk_mul_f32 v[14:15], v[14:15], v[20:21]
	v_pk_mul_f32 v[20:21], v[132:133], v[16:17] op_sel_hi:[1,0]
	v_pk_mul_f32 v[18:19], v[8:9], v[18:19]
	v_pk_mul_f32 v[20:21], v[10:11], v[20:21]
	v_cndmask_b32_e32 v11, v12, v18, vcc
	v_cndmask_b32_e32 v8, v15, v21, vcc
	v_cndmask_b32_e32 v9, v14, v20, vcc
	v_cndmask_b32_e32 v10, v13, v19, vcc
	v_mov_b32_dpp v17, v11 row_ror:8 row_mask:0xf bank_mask:0xf bound_ctrl:1
	v_mov_b32_dpp v27, v9 row_ror:8 row_mask:0xf bank_mask:0xf bound_ctrl:1
	v_mov_b32_dpp v26, v10 row_ror:8 row_mask:0xf bank_mask:0xf bound_ctrl:1
	v_mov_b32_dpp v30, v8 row_ror:8 row_mask:0xf bank_mask:0xf bound_ctrl:1
	v_cndmask_b32_e32 v8, v17, v12, vcc
	v_add_co_u32_e64 v12, s[2:3], s96, v130
	v_cndmask_b32_e32 v11, v30, v15, vcc
	v_cndmask_b32_e32 v10, v27, v14, vcc
	v_cndmask_b32_e32 v9, v26, v13, vcc
	v_addc_co_u32_e64 v13, s[2:3], 0, v131, s[2:3]
	global_store_dwordx4 v[12:13], v[8:11], off nt
	v_add_co_u32_e64 v12, s[2:3], s97, v130
	s_nop 0
	v_cndmask_b32_e32 v11, v21, v30, vcc
	v_cndmask_b32_e32 v10, v20, v27, vcc
	v_cndmask_b32_e32 v9, v19, v26, vcc
	v_cndmask_b32_e32 v8, v18, v17, vcc
	v_addc_co_u32_e64 v13, s[2:3], 0, v131, s[2:3]
	global_store_dwordx4 v[12:13], v[8:11], off nt
	s_nop 1
	v_pk_mul_f32 v[8:9], v[106:107], v[16:17] op_sel_hi:[1,0]
	v_pk_mul_f32 v[10:11], v[24:25], v[16:17] op_sel_hi:[1,0]
	v_pk_mul_f32 v[4:5], v[4:5], v[8:9]
	v_pk_mul_f32 v[6:7], v[6:7], v[10:11]
	v_pk_mul_f32 v[8:9], v[128:129], v[16:17] op_sel_hi:[1,0]
	v_pk_mul_f32 v[10:11], v[28:29], v[16:17] op_sel_hi:[1,0]
	v_pk_mul_f32 v[8:9], v[0:1], v[8:9]
	v_pk_mul_f32 v[10:11], v[2:3], v[10:11]
	v_cndmask_b32_e32 v2, v5, v9, vcc
	v_cndmask_b32_e32 v0, v7, v11, vcc
	v_cndmask_b32_e32 v1, v6, v10, vcc
	v_cndmask_b32_e32 v3, v4, v8, vcc
	v_mov_b32_dpp v15, v2 row_ror:8 row_mask:0xf bank_mask:0xf bound_ctrl:1
	v_mov_b32_dpp v16, v1 row_ror:8 row_mask:0xf bank_mask:0xf bound_ctrl:1
	v_mov_b32_dpp v14, v3 row_ror:8 row_mask:0xf bank_mask:0xf bound_ctrl:1
	v_mov_b32_dpp v17, v0 row_ror:8 row_mask:0xf bank_mask:0xf bound_ctrl:1
	v_cndmask_b32_e32 v3, v17, v7, vcc
	v_cndmask_b32_e32 v2, v16, v6, vcc
	v_cndmask_b32_e32 v1, v15, v5, vcc
	v_cndmask_b32_e32 v0, v14, v4, vcc
	global_store_dwordx4 v[22:23], v[0:3], off offset:512 nt
	s_nop 1
	v_cndmask_b32_e32 v3, v11, v17, vcc
	v_cndmask_b32_e32 v2, v10, v16, vcc
	v_cndmask_b32_e32 v1, v9, v15, vcc
	v_cndmask_b32_e32 v0, v8, v14, vcc
	global_store_dwordx4 v[12:13], v[0:3], off offset:512 nt
	s_waitcnt lgkmcnt(0)
	s_barrier
	s_andn2_b64 vcc, exec, s[0:1]
	s_mov_b64 s[0:1], -1
	s_cbranch_vccnz .LBB0_1043
	s_andn2_b64 vcc, exec, s[14:15]
	s_cbranch_vccnz .LBB0_1042
	s_barrier
	s_branch .LBB0_1042
